# comb4: early L1 invalidate at barrier arrival + all inter-phase stores sc1 write-through with buffer_wbl2 dropped from grid barriers 2-15
# speedup vs baseline: 1.0509x; 1.0326x over previous
.LBB0_33:
	s_add_i32 s10, s2, s3
	s_lshl_b64 s[14:15], s[10:11], 12
	v_lshl_add_u64 v[8:9], s[14:15], 0, v[144:145]
	v_lshl_add_u64 v[4:5], v[8:9], 2, s[8:9]
	global_load_dwordx4 v[0:3], v[4:5], off
	s_nop 0
	global_load_dwordx4 v[4:7], v[4:5], off offset:16
	v_lshl_add_u64 v[8:9], v[8:9], 1, s[6:7]
	s_mov_b64 s[6:7], 0
	s_waitcnt vmcnt(1)
	v_cvt_pk_bf16_f32 v0, v0, v1
	v_cvt_pk_bf16_f32 v1, v2, v3
	s_waitcnt vmcnt(0)
	v_cvt_pk_bf16_f32 v2, v4, v5
	v_cvt_pk_bf16_f32 v3, v6, v7
	global_store_dwordx4 v[8:9], v[0:3], off sc1

.LBB0_38:
	s_lshl_b32 s8, s3, 1
	s_lshl_b32 s9, s6, 1
	v_or_b32_e32 v3, s8, v15
	v_or_b32_e32 v7, s9, v14
	s_add_i32 s10, s8, 4
	s_add_i32 s14, s9, 4
	s_add_i32 s15, s8, 8
	s_add_i32 s16, s9, 8
	s_add_i32 s17, s8, 12
	s_add_i32 s18, s9, 12
	s_add_i32 s19, s8, 16
	s_add_i32 s20, s9, 16
	s_add_i32 s21, s8, 20
	s_add_i32 s22, s9, 20
	s_add_i32 s23, s8, 24
	s_add_i32 s24, s9, 24
	s_add_i32 s8, s8, 28
	s_add_i32 s9, s9, 28
	v_add_u32_e32 v25, v7, v6
	v_or_b32_e32 v27, s10, v15
	v_or_b32_e32 v29, s14, v14
	v_or_b32_e32 v63, s15, v15
	v_or_b32_e32 v90, s16, v14
	v_or_b32_e32 v91, s17, v15
	v_or_b32_e32 v92, s18, v14
	v_or_b32_e32 v93, s19, v15
	v_or_b32_e32 v94, s20, v14
	v_or_b32_e32 v95, s21, v15
	v_or_b32_e32 v96, s22, v14
	v_or_b32_e32 v97, s23, v15
	v_or_b32_e32 v98, s24, v14
	v_or_b32_e32 v99, s8, v15
	v_or_b32_e32 v100, s9, v14
	v_add_u32_e32 v10, v3, v1
	v_mad_u64_u32 v[44:45], s[8:9], v0, v25, 0
	v_add_u32_e32 v25, v29, v6
	v_add_u32_e32 v46, v27, v1
	v_add_u32_e32 v68, v90, v6
	v_add_u32_e32 v66, v63, v1
	v_add_u32_e32 v72, v92, v6
	v_add_u32_e32 v70, v91, v1
	v_add_u32_e32 v76, v94, v6
	v_add_u32_e32 v74, v93, v1
	v_add_u32_e32 v80, v96, v6
	v_add_u32_e32 v78, v95, v1
	v_add_u32_e32 v84, v98, v6
	v_add_u32_e32 v82, v97, v1
	v_add_u32_e32 v88, v100, v6
	v_add_u32_e32 v86, v99, v1
	v_mad_u64_u32 v[10:11], s[8:9], v2, v10, 0
	v_lshl_add_u64 v[44:45], v[44:45], 2, v[8:9]
	v_mad_u64_u32 v[46:47], s[8:9], v2, v46, 0
	v_mad_u64_u32 v[64:65], s[8:9], v0, v25, 0
	v_mad_u64_u32 v[66:67], s[8:9], v2, v66, 0
	v_mad_u64_u32 v[68:69], s[8:9], v0, v68, 0
	v_mad_u64_u32 v[70:71], s[8:9], v2, v70, 0
	v_mad_u64_u32 v[72:73], s[8:9], v0, v72, 0
	v_mad_u64_u32 v[74:75], s[8:9], v2, v74, 0
	v_mad_u64_u32 v[76:77], s[8:9], v0, v76, 0
	v_mad_u64_u32 v[78:79], s[8:9], v2, v78, 0
	v_mad_u64_u32 v[80:81], s[8:9], v0, v80, 0
	v_mad_u64_u32 v[82:83], s[8:9], v2, v82, 0
	v_mad_u64_u32 v[84:85], s[8:9], v0, v84, 0
	v_mad_u64_u32 v[86:87], s[8:9], v2, v86, 0
	v_mad_u64_u32 v[88:89], s[8:9], v0, v88, 0
	v_lshl_add_u64 v[10:11], v[10:11], 2, v[8:9]
	v_lshl_add_u64 v[64:65], v[64:65], 2, v[8:9]
	v_lshl_add_u64 v[46:47], v[46:47], 2, v[8:9]
	v_lshl_add_u64 v[68:69], v[68:69], 2, v[8:9]
	v_lshl_add_u64 v[66:67], v[66:67], 2, v[8:9]
	v_lshl_add_u64 v[72:73], v[72:73], 2, v[8:9]
	v_lshl_add_u64 v[70:71], v[70:71], 2, v[8:9]
	v_lshl_add_u64 v[76:77], v[76:77], 2, v[8:9]
	v_lshl_add_u64 v[74:75], v[74:75], 2, v[8:9]
	v_lshl_add_u64 v[80:81], v[80:81], 2, v[8:9]
	v_lshl_add_u64 v[78:79], v[78:79], 2, v[8:9]
	v_lshl_add_u64 v[84:85], v[84:85], 2, v[8:9]
	v_lshl_add_u64 v[82:83], v[82:83], 2, v[8:9]
	v_lshl_add_u64 v[88:89], v[88:89], 2, v[8:9]
	v_lshl_add_u64 v[86:87], v[86:87], 2, v[8:9]
	global_load_dword v25, v[44:45], off
	global_load_dword v101, v[10:11], off
	global_load_dword v102, v[64:65], off
	global_load_dword v103, v[46:47], off
	global_load_dword v104, v[68:69], off
	global_load_dword v105, v[66:67], off
	global_load_dword v106, v[72:73], off
	global_load_dword v107, v[70:71], off
	global_load_dword v108, v[76:77], off
	global_load_dword v109, v[74:75], off
	global_load_dword v110, v[80:81], off
	global_load_dword v111, v[78:79], off
	global_load_dword v112, v[84:85], off
	global_load_dword v113, v[82:83], off
	global_load_dword v114, v[88:89], off
	global_load_dword v115, v[86:87], off
	s_add_i32 s6, s6, 16
	s_add_i32 s3, s3, 16
	s_add_i32 s7, s7, -16
	v_mad_u64_u32 v[10:11], s[8:9], v7, s0, v[16:17]
	s_cmp_lg_u32 s7, 0
	v_mad_u64_u32 v[44:45], s[8:9], v3, s0, v[16:17]
	v_mad_u64_u32 v[46:47], s[8:9], v29, s0, v[16:17]
	v_mad_u64_u32 v[64:65], s[8:9], v27, s0, v[16:17]
	v_mad_u64_u32 v[66:67], s[8:9], v90, s0, v[16:17]
	v_mad_u64_u32 v[68:69], s[8:9], v63, s0, v[16:17]
	v_mad_u64_u32 v[70:71], s[8:9], v92, s0, v[16:17]
	v_mad_u64_u32 v[72:73], s[8:9], v91, s0, v[16:17]
	v_mad_u64_u32 v[74:75], s[8:9], v94, s0, v[16:17]
	v_mad_u64_u32 v[76:77], s[8:9], v93, s0, v[16:17]
	v_mad_u64_u32 v[78:79], s[8:9], v96, s0, v[16:17]
	v_mad_u64_u32 v[80:81], s[8:9], v95, s0, v[16:17]
	v_mad_u64_u32 v[82:83], s[8:9], v98, s0, v[16:17]
	v_mad_u64_u32 v[84:85], s[8:9], v97, s0, v[16:17]
	v_mad_u64_u32 v[86:87], s[8:9], v100, s0, v[16:17]
	v_mad_u64_u32 v[88:89], s[8:9], v99, s0, v[16:17]
	s_waitcnt vmcnt(15)
	ds_write_b32 v10, v25
	s_waitcnt vmcnt(14)
	ds_write_b32 v44, v101
	s_waitcnt vmcnt(13)
	ds_write_b32 v46, v102
	s_waitcnt vmcnt(12)
	ds_write_b32 v64, v103
	s_waitcnt vmcnt(11)
	ds_write_b32 v66, v104
	s_waitcnt vmcnt(10)
	ds_write_b32 v68, v105
	s_waitcnt vmcnt(9)
	ds_write_b32 v70, v106
	s_waitcnt vmcnt(8)
	ds_write_b32 v72, v107
	s_waitcnt vmcnt(7)
	ds_write_b32 v74, v108
	s_waitcnt vmcnt(6)
	ds_write_b32 v76, v109
	s_waitcnt vmcnt(5)
	ds_write_b32 v78, v110
	s_waitcnt vmcnt(4)
	ds_write_b32 v80, v111
	s_waitcnt vmcnt(3)
	ds_write_b32 v82, v112
	s_waitcnt vmcnt(2)
	ds_write_b32 v84, v113
	s_waitcnt vmcnt(1)
	ds_write_b32 v86, v114
	s_waitcnt vmcnt(0)
	ds_write_b32 v88, v115
	s_cbranch_scc1 .LBB0_38
	s_waitcnt lgkmcnt(0)
	v_lshl_add_u64 v[0:1], s[56:57], 0, v[4:5]
	v_lshlrev_b32_e32 v2, 1, v6
	ds_read2_b32 v[4:5], v49 offset0:33 offset1:41
	ds_read2_b32 v[6:7], v49 offset1:8
	ds_read2_b32 v[8:9], v49 offset0:66 offset1:74
	ds_read2_b32 v[10:11], v49 offset0:99 offset1:107
	ds_read2_b32 v[44:45], v49 offset0:132 offset1:140
	ds_read2_b32 v[46:47], v49 offset0:165 offset1:173
	ds_read2_b32 v[64:65], v49 offset0:198 offset1:206
	ds_read2_b32 v[66:67], v49 offset0:231 offset1:239
	v_mov_b32_e32 v3, v13
	v_lshl_add_u64 v[0:1], v[0:1], 0, v[2:3]
	v_mov_b32_e32 v27, v13
	v_or_b32_e32 v70, v12, v48
	v_mov_b32_e32 v71, v13
	v_lshl_add_u64 v[68:69], v[0:1], 0, v[26:27]
	v_lshlrev_b64 v[70:71], 11, v[70:71]
	s_waitcnt lgkmcnt(6)
	v_cvt_pk_bf16_f32 v0, v6, v4
	s_waitcnt lgkmcnt(4)
	v_cvt_pk_bf16_f32 v1, v8, v10
	s_waitcnt lgkmcnt(2)
	v_cvt_pk_bf16_f32 v2, v44, v46
	s_waitcnt lgkmcnt(0)
	v_cvt_pk_bf16_f32 v3, v64, v66
	v_lshl_add_u64 v[70:71], v[68:69], 0, v[70:71]
	global_store_dwordx4 v[70:71], v[0:3], off sc1
	v_or_b32_e32 v4, v12, v50
	s_mov_b64 s[6:7], 0
	v_cvt_pk_bf16_f32 v0, v7, v5
	v_cvt_pk_bf16_f32 v1, v9, v11
	v_cvt_pk_bf16_f32 v2, v45, v47
	v_cvt_pk_bf16_f32 v3, v65, v67
	v_mov_b32_e32 v5, v13
	ds_read2_b32 v[6:7], v49 offset0:49 offset1:57
	ds_read2_b32 v[8:9], v49 offset0:16 offset1:24
	ds_read2_b32 v[10:11], v49 offset0:82 offset1:90
	ds_read2_b32 v[44:45], v49 offset0:115 offset1:123
	ds_read2_b32 v[46:47], v49 offset0:148 offset1:156
	ds_read2_b32 v[64:65], v49 offset0:181 offset1:189
	ds_read2_b32 v[66:67], v49 offset0:214 offset1:222
	ds_read2_b32 v[70:71], v49 offset0:247 offset1:255
	v_lshlrev_b64 v[4:5], 11, v[4:5]
	v_lshl_add_u64 v[4:5], v[68:69], 0, v[4:5]
	global_store_dwordx4 v[4:5], v[0:3], off sc1
	v_or_b32_e32 v4, v12, v51
	v_mov_b32_e32 v5, v13
	v_lshlrev_b64 v[4:5], 11, v[4:5]
	s_waitcnt lgkmcnt(6)
	v_cvt_pk_bf16_f32 v0, v8, v6
	s_waitcnt lgkmcnt(4)
	v_cvt_pk_bf16_f32 v1, v10, v44
	s_waitcnt lgkmcnt(2)
	v_cvt_pk_bf16_f32 v2, v46, v64
	s_waitcnt lgkmcnt(0)
	v_cvt_pk_bf16_f32 v3, v66, v70
	v_lshl_add_u64 v[4:5], v[68:69], 0, v[4:5]
	v_or_b32_e32 v12, v12, v52
	global_store_dwordx4 v[4:5], v[0:3], off sc1
	v_lshlrev_b64 v[4:5], 11, v[12:13]
	v_lshl_add_u64 v[4:5], v[68:69], 0, v[4:5]
	v_cvt_pk_bf16_f32 v0, v9, v7
	v_cvt_pk_bf16_f32 v1, v11, v45
	v_cvt_pk_bf16_f32 v2, v47, v65
	v_cvt_pk_bf16_f32 v3, v67, v71
	global_store_dwordx4 v[4:5], v[0:3], off sc1
	s_waitcnt lgkmcnt(0)

.LBB0_45:
	s_or_b64 exec, exec, s[6:7]
	v_mul_f64 v[46:47], v[10:11], v[10:11]
	v_mov_b64_e32 v[70:71], v[30:31]
	v_mul_f64 v[64:65], v[46:47], 0.5
	v_fmac_f64_e32 v[70:71], s[82:83], v[46:47]
	v_mov_b64_e32 v[72:73], v[32:33]
	v_add_f64 v[66:67], -v[64:65], 1.0
	v_fmac_f64_e32 v[72:73], v[46:47], v[70:71]
	v_mov_b64_e32 v[70:71], v[34:35]
	v_add_f64 v[68:69], -v[66:67], 1.0
	v_fmac_f64_e32 v[70:71], v[46:47], v[72:73]
	v_mov_b64_e32 v[72:73], v[36:37]
	v_add_f64 v[64:65], v[68:69], -v[64:65]
	v_fmac_f64_e32 v[72:73], v[46:47], v[70:71]
	v_mov_b64_e32 v[70:71], v[20:21]
	v_mul_f64 v[68:69], v[46:47], v[46:47]
	v_fmac_f64_e32 v[70:71], v[46:47], v[72:73]
	v_fma_f64 v[64:65], v[10:11], -v[44:45], v[64:65]
	v_fmac_f64_e32 v[64:65], v[68:69], v[70:71]
	v_add_f64 v[64:65], v[66:67], v[64:65]
	v_mov_b64_e32 v[66:67], v[38:39]
	v_fmac_f64_e32 v[66:67], s[86:87], v[46:47]
	v_mov_b64_e32 v[68:69], v[40:41]
	v_fmac_f64_e32 v[68:69], v[46:47], v[66:67]
	v_mov_b64_e32 v[66:67], v[42:43]
	v_fmac_f64_e32 v[66:67], v[46:47], v[68:69]
	v_mov_b64_e32 v[68:69], v[18:19]
	v_fmac_f64_e32 v[68:69], v[46:47], v[66:67]
	v_mul_f64 v[66:67], v[10:11], -v[46:47]
	v_mul_f64 v[70:71], v[44:45], 0.5
	v_fmac_f64_e32 v[70:71], v[66:67], v[68:69]
	v_fma_f64 v[44:45], v[46:47], v[70:71], -v[44:45]
	v_fmac_f64_e32 v[44:45], s[84:85], v[66:67]
	v_add_f64 v[10:11], v[10:11], -v[44:45]
	v_and_b32_e32 v29, 1, v27
	v_xor_b32_e32 v11, 0x80000000, v11
	v_cmp_eq_u32_e32 vcc, 0, v29
	v_lshlrev_b32_e32 v27, 30, v27
	s_movk_i32 s3, 0x1f8
	v_cndmask_b32_e32 v11, v11, v65, vcc
	v_cndmask_b32_e32 v10, v10, v64, vcc
	v_bitop3_b32 v11, v11, v27, s1 bitop3:0x78
	v_cmp_class_f64_e64 vcc, v[0:1], s3
	v_lshlrev_b32_e32 v12, 1, v12
	s_nop 0
	v_cndmask_b32_e32 v10, 0, v10, vcc
	v_cndmask_b32_e32 v11, v61, v11, vcc
	v_cvt_f32_f64_e32 v27, v[10:11]
	v_lshl_add_u64 v[10:11], v[12:13], 2, s[34:35]
	global_store_dword v[10:11], v27, off sc1
	s_and_saveexec_b64 s[6:7], s[8:9]
	s_xor_b64 s[92:93], exec, s[6:7]
	s_cbranch_execz .LBB0_47
	v_cmp_ge_f64_e64 s[6:7], |v[0:1]|, s[68:69]
	s_mov_b32 s72, s74
	s_mov_b32 s91, s89
	v_cndmask_b32_e64 v9, v25, v9, s[6:7]
	v_cndmask_b32_e64 v8, v0, v8, s[6:7]
	v_mul_f64 v[46:47], v[6:7], v[8:9]
	v_mul_f64 v[44:45], v[4:5], v[8:9]
	v_fma_f64 v[6:7], v[6:7], v[8:9], -v[46:47]
	v_add_f64 v[64:65], v[44:45], v[6:7]
	v_add_f64 v[72:73], v[64:65], -v[44:45]
	v_add_f64 v[6:7], v[6:7], -v[72:73]
	v_add_f64 v[72:73], v[64:65], -v[72:73]
	v_add_f64 v[72:73], v[44:45], -v[72:73]
	v_fma_f64 v[4:5], v[4:5], v[8:9], -v[44:45]
	v_mul_f64 v[44:45], v[2:3], v[8:9]
	v_add_f64 v[6:7], v[6:7], v[72:73]
	v_add_f64 v[72:73], v[44:45], v[4:5]
	v_add_f64 v[66:67], v[46:47], v[64:65]
	v_add_f64 v[74:75], v[72:73], v[6:7]
	v_ldexp_f64 v[68:69], v[66:67], -2
	v_add_f64 v[46:47], v[66:67], -v[46:47]
	v_add_f64 v[66:67], v[74:75], -v[72:73]
	v_add_f64 v[6:7], v[6:7], -v[66:67]
	v_add_f64 v[66:67], v[74:75], -v[66:67]
	v_add_f64 v[66:67], v[72:73], -v[66:67]
	v_add_f64 v[6:7], v[6:7], v[66:67]
	v_add_f64 v[66:67], v[72:73], -v[44:45]
	v_add_f64 v[4:5], v[4:5], -v[66:67]
	v_add_f64 v[66:67], v[72:73], -v[66:67]
	v_add_f64 v[66:67], v[44:45], -v[66:67]
	v_add_f64 v[4:5], v[4:5], v[66:67]
	v_fract_f64_e32 v[70:71], v[68:69]
	v_add_f64 v[4:5], v[4:5], v[6:7]
	v_fma_f64 v[2:3], v[2:3], v[8:9], -v[44:45]
	v_add_f64 v[46:47], v[64:65], -v[46:47]
	v_add_f64 v[2:3], v[2:3], v[4:5]
	v_ldexp_f64 v[4:5], v[70:71], 2
	v_cmp_neq_f64_e64 s[6:7], |v[68:69]|, s[70:71]
	v_add_f64 v[64:65], v[46:47], v[74:75]
	v_add_f64 v[46:47], v[64:65], -v[46:47]
	v_cndmask_b32_e64 v5, 0, v5, s[6:7]
	v_cndmask_b32_e64 v4, 0, v4, s[6:7]
	v_add_f64 v[6:7], v[64:65], v[4:5]
	v_cmp_gt_f64_e64 s[6:7], 0, v[6:7]
	v_mov_b32_e32 v6, v13
	v_add_f64 v[46:47], v[74:75], -v[46:47]
	v_cndmask_b32_e64 v7, 0, v59, s[6:7]
	v_add_f64 v[4:5], v[4:5], v[6:7]
	v_add_f64 v[6:7], v[64:65], v[4:5]
	v_cvt_i32_f64_e32 v8, v[6:7]
	v_cvt_f64_i32_e32 v[6:7], v8
	v_add_f64 v[4:5], v[4:5], -v[6:7]
	v_add_f64 v[6:7], v[64:65], v[4:5]
	v_add_f64 v[4:5], v[6:7], -v[4:5]
	v_add_f64 v[2:3], v[46:47], v[2:3]
	v_add_f64 v[4:5], v[64:65], -v[4:5]
	v_cmp_le_f64_e64 s[6:7], 0.5, v[6:7]
	v_add_f64 v[2:3], v[2:3], v[4:5]
	v_mov_b32_e32 v4, v13
	v_cndmask_b32_e64 v5, 0, v60, s[6:7]
	v_add_f64 v[4:5], v[6:7], -v[4:5]
	v_add_f64 v[6:7], v[4:5], v[2:3]
	v_add_f64 v[4:5], v[6:7], -v[4:5]
	v_add_f64 v[2:3], v[2:3], -v[4:5]
	v_mul_f64 v[4:5], v[6:7], s[72:73]
	v_addc_co_u32_e64 v12, s[8:9], 0, v8, s[6:7]
	v_fma_f64 v[8:9], v[6:7], s[72:73], -v[4:5]
	v_fmac_f64_e32 v[8:9], s[90:91], v[6:7]
	v_fmac_f64_e32 v[8:9], s[72:73], v[2:3]
	v_add_f64 v[44:45], v[4:5], v[8:9]
	v_add_f64 v[2:3], v[44:45], -v[4:5]
	v_add_f64 v[46:47], v[8:9], -v[2:3]

.LBB0_49:
	s_or_b64 exec, exec, s[6:7]
	v_mul_f64 v[2:3], v[44:45], v[44:45]
	v_mov_b64_e32 v[64:65], v[30:31]
	v_mul_f64 v[4:5], v[2:3], 0.5
	v_fmac_f64_e32 v[64:65], s[82:83], v[2:3]
	v_mov_b64_e32 v[66:67], v[32:33]
	v_add_f64 v[6:7], -v[4:5], 1.0
	v_fmac_f64_e32 v[66:67], v[2:3], v[64:65]
	v_mov_b64_e32 v[64:65], v[34:35]
	v_add_f64 v[8:9], -v[6:7], 1.0
	v_fmac_f64_e32 v[64:65], v[2:3], v[66:67]
	v_mov_b64_e32 v[66:67], v[36:37]
	v_add_f64 v[4:5], v[8:9], -v[4:5]
	v_fmac_f64_e32 v[66:67], v[2:3], v[64:65]
	v_mov_b64_e32 v[64:65], v[20:21]
	v_mul_f64 v[8:9], v[2:3], v[2:3]
	v_fmac_f64_e32 v[64:65], v[2:3], v[66:67]
	v_fma_f64 v[4:5], v[44:45], -v[46:47], v[4:5]
	v_fmac_f64_e32 v[4:5], v[8:9], v[64:65]
	v_add_f64 v[4:5], v[6:7], v[4:5]
	v_mov_b64_e32 v[6:7], v[38:39]
	v_fmac_f64_e32 v[6:7], s[86:87], v[2:3]
	v_mov_b64_e32 v[8:9], v[40:41]
	v_fmac_f64_e32 v[8:9], v[2:3], v[6:7]
	v_mov_b64_e32 v[6:7], v[42:43]
	v_fmac_f64_e32 v[6:7], v[2:3], v[8:9]
	v_mov_b64_e32 v[8:9], v[18:19]
	v_fmac_f64_e32 v[8:9], v[2:3], v[6:7]
	v_mul_f64 v[6:7], v[44:45], -v[2:3]
	v_mul_f64 v[64:65], v[46:47], 0.5
	v_fmac_f64_e32 v[64:65], v[6:7], v[8:9]
	v_fma_f64 v[2:3], v[2:3], v[64:65], -v[46:47]
	v_fmac_f64_e32 v[2:3], s[84:85], v[6:7]
	v_and_b32_e32 v0, 1, v12
	v_add_f64 v[2:3], v[44:45], -v[2:3]
	v_cmp_eq_u32_e64 s[6:7], 0, v0
	s_nop 1
	v_cndmask_b32_e64 v0, v4, v2, s[6:7]
	v_cndmask_b32_e64 v2, v5, v3, s[6:7]
	v_lshlrev_b32_e32 v3, 30, v12
	v_xor_b32_e32 v1, v3, v1
	v_bitop3_b32 v1, v2, v1, s1 bitop3:0x78
	v_cndmask_b32_e32 v0, 0, v0, vcc
	v_cndmask_b32_e32 v1, v61, v1, vcc
	v_cvt_f32_f64_e32 v0, v[0:1]
	global_store_dword v[10:11], v0, off offset:4 sc1

.LBB0_54:
	v_lshl_add_u64 v[46:47], v[44:45], 0, s[8:9]
	s_movk_i32 s7, 0x6000
	v_add_co_u32_e32 v68, vcc, s7, v46
	s_mov_b32 s7, 0xc000
	s_nop 0
	v_addc_co_u32_e32 v69, vcc, 0, v47, vcc
	v_add_co_u32_e32 v72, vcc, s7, v46
	s_mov_b32 s7, 0x12000
	s_nop 0
	v_addc_co_u32_e32 v73, vcc, 0, v47, vcc
	v_add_co_u32_e32 v76, vcc, s7, v46
	s_mov_b32 s7, 0x18000
	s_nop 0
	v_addc_co_u32_e32 v77, vcc, 0, v47, vcc
	global_load_dwordx4 v[64:67], v[46:47], off
	v_add_co_u32_e32 v80, vcc, s7, v46
	s_mov_b32 s7, 0x1e000
	s_nop 0
	v_addc_co_u32_e32 v81, vcc, 0, v47, vcc
	v_add_co_u32_e32 v84, vcc, s7, v46
	s_mov_b32 s7, 0x24000
	s_nop 0
	v_addc_co_u32_e32 v85, vcc, 0, v47, vcc
	v_add_co_u32_e32 v88, vcc, s7, v46
	s_mov_b32 s7, 0x2a000
	s_nop 0
	v_addc_co_u32_e32 v89, vcc, 0, v47, vcc
	v_add_co_u32_e32 v46, vcc, s7, v46
	s_add_u32 s8, s8, 0x30000
	s_nop 0
	v_addc_co_u32_e32 v47, vcc, 0, v47, vcc
	global_load_dwordx4 v[68:71], v[68:69], off
	s_nop 0
	global_load_dwordx4 v[72:75], v[72:73], off
	s_nop 0
	global_load_dwordx4 v[76:79], v[76:77], off
	s_nop 0
	global_load_dwordx4 v[80:83], v[80:81], off
	s_nop 0
	global_load_dwordx4 v[84:87], v[84:85], off
	s_nop 0
	global_load_dwordx4 v[88:91], v[88:89], off
	s_nop 0
	global_load_dwordx4 v[92:95], v[46:47], off
	ds_read_b128 v[96:99], v12
	ds_read_b128 v[100:103], v12 offset:16
	ds_read_b128 v[104:107], v12 offset:4096
	ds_read_b128 v[108:111], v12 offset:4112
	ds_read_b128 v[112:115], v12 offset:8192
	ds_read_b128 v[116:119], v12 offset:8208
	s_waitcnt lgkmcnt(5)
	v_mov_b32_e32 v46, v99
	s_waitcnt lgkmcnt(3)
	v_mov_b32_e32 v120, v107
	s_addc_u32 s9, s9, 0
	s_waitcnt lgkmcnt(1)
	v_mov_b32_e32 v122, v115
	v_mov_b32_e32 v124, v103
	v_mov_b32_e32 v126, v111
	s_waitcnt lgkmcnt(0)
	v_mov_b32_e32 v128, v119
	v_add_u32_e32 v12, 32, v12
	s_cmp_eq_u32 s8, 0xc0000
	s_waitcnt vmcnt(7)
	v_pk_fma_f32 v[2:3], v[66:67], v[96:97], v[2:3] op_sel_hi:[1,0,1]
	v_pk_fma_f32 v[0:1], v[64:65], v[96:97], v[0:1] op_sel_hi:[1,0,1]
	v_pk_fma_f32 v[6:7], v[66:67], v[104:105], v[6:7] op_sel_hi:[1,0,1]
	v_pk_fma_f32 v[4:5], v[64:65], v[104:105], v[4:5] op_sel_hi:[1,0,1]
	v_pk_fma_f32 v[10:11], v[66:67], v[112:113], v[10:11] op_sel_hi:[1,0,1]
	v_pk_fma_f32 v[8:9], v[64:65], v[112:113], v[8:9] op_sel_hi:[1,0,1]
	s_waitcnt vmcnt(6)
	v_pk_fma_f32 v[0:1], v[68:69], v[96:97], v[0:1] op_sel:[0,1,0]
	v_pk_fma_f32 v[2:3], v[70:71], v[96:97], v[2:3] op_sel:[0,1,0]
	v_pk_fma_f32 v[4:5], v[68:69], v[104:105], v[4:5] op_sel:[0,1,0]
	v_pk_fma_f32 v[6:7], v[70:71], v[104:105], v[6:7] op_sel:[0,1,0]
	v_pk_fma_f32 v[8:9], v[68:69], v[112:113], v[8:9] op_sel:[0,1,0]
	v_pk_fma_f32 v[10:11], v[70:71], v[112:113], v[10:11] op_sel:[0,1,0]
	s_waitcnt vmcnt(5)
	v_pk_fma_f32 v[2:3], v[74:75], v[98:99], v[2:3] op_sel_hi:[1,0,1]
	v_pk_fma_f32 v[0:1], v[72:73], v[98:99], v[0:1] op_sel_hi:[1,0,1]
	v_pk_fma_f32 v[6:7], v[74:75], v[106:107], v[6:7] op_sel_hi:[1,0,1]
	v_pk_fma_f32 v[4:5], v[72:73], v[106:107], v[4:5] op_sel_hi:[1,0,1]
	v_pk_fma_f32 v[10:11], v[74:75], v[114:115], v[10:11] op_sel_hi:[1,0,1]
	v_pk_fma_f32 v[8:9], v[72:73], v[114:115], v[8:9] op_sel_hi:[1,0,1]
	s_waitcnt vmcnt(4)
	v_pk_fma_f32 v[2:3], v[78:79], v[46:47], v[2:3] op_sel_hi:[1,0,1]
	v_pk_fma_f32 v[0:1], v[76:77], v[46:47], v[0:1] op_sel_hi:[1,0,1]
	v_pk_fma_f32 v[6:7], v[78:79], v[120:121], v[6:7] op_sel_hi:[1,0,1]
	v_pk_fma_f32 v[4:5], v[76:77], v[120:121], v[4:5] op_sel_hi:[1,0,1]
	v_pk_fma_f32 v[10:11], v[78:79], v[122:123], v[10:11] op_sel_hi:[1,0,1]
	v_pk_fma_f32 v[8:9], v[76:77], v[122:123], v[8:9] op_sel_hi:[1,0,1]
	s_waitcnt vmcnt(3)
	v_pk_fma_f32 v[2:3], v[82:83], v[100:101], v[2:3] op_sel_hi:[1,0,1]
	v_pk_fma_f32 v[0:1], v[80:81], v[100:101], v[0:1] op_sel_hi:[1,0,1]
	v_pk_fma_f32 v[6:7], v[82:83], v[108:109], v[6:7] op_sel_hi:[1,0,1]
	v_pk_fma_f32 v[4:5], v[80:81], v[108:109], v[4:5] op_sel_hi:[1,0,1]
	v_pk_fma_f32 v[10:11], v[82:83], v[116:117], v[10:11] op_sel_hi:[1,0,1]
	v_pk_fma_f32 v[8:9], v[80:81], v[116:117], v[8:9] op_sel_hi:[1,0,1]
	s_waitcnt vmcnt(2)
	v_pk_fma_f32 v[2:3], v[86:87], v[100:101], v[2:3] op_sel:[0,1,0]
	v_pk_fma_f32 v[0:1], v[84:85], v[100:101], v[0:1] op_sel:[0,1,0]
	v_pk_fma_f32 v[6:7], v[86:87], v[108:109], v[6:7] op_sel:[0,1,0]
	v_pk_fma_f32 v[4:5], v[84:85], v[108:109], v[4:5] op_sel:[0,1,0]
	v_pk_fma_f32 v[10:11], v[86:87], v[116:117], v[10:11] op_sel:[0,1,0]
	v_pk_fma_f32 v[8:9], v[84:85], v[116:117], v[8:9] op_sel:[0,1,0]
	s_waitcnt vmcnt(1)
	v_pk_fma_f32 v[2:3], v[90:91], v[102:103], v[2:3] op_sel_hi:[1,0,1]
	v_pk_fma_f32 v[0:1], v[88:89], v[102:103], v[0:1] op_sel_hi:[1,0,1]
	v_pk_fma_f32 v[6:7], v[90:91], v[110:111], v[6:7] op_sel_hi:[1,0,1]
	v_pk_fma_f32 v[4:5], v[88:89], v[110:111], v[4:5] op_sel_hi:[1,0,1]
	v_pk_fma_f32 v[10:11], v[90:91], v[118:119], v[10:11] op_sel_hi:[1,0,1]
	v_pk_fma_f32 v[8:9], v[88:89], v[118:119], v[8:9] op_sel_hi:[1,0,1]
	s_waitcnt vmcnt(0)
	v_pk_fma_f32 v[2:3], v[94:95], v[124:125], v[2:3] op_sel_hi:[1,0,1]
	v_pk_fma_f32 v[0:1], v[92:93], v[124:125], v[0:1] op_sel_hi:[1,0,1]
	v_pk_fma_f32 v[6:7], v[94:95], v[126:127], v[6:7] op_sel_hi:[1,0,1]
	v_pk_fma_f32 v[4:5], v[92:93], v[126:127], v[4:5] op_sel_hi:[1,0,1]
	v_pk_fma_f32 v[10:11], v[94:95], v[128:129], v[10:11] op_sel_hi:[1,0,1]
	v_pk_fma_f32 v[8:9], v[92:93], v[128:129], v[8:9] op_sel_hi:[1,0,1]
	s_cbranch_scc0 .LBB0_54
	ds_write_b128 v56, v[0:3] offset:12288
	ds_write_b128 v56, v[4:7] offset:12544
	ds_write_b128 v56, v[8:11] offset:12800
	s_waitcnt lgkmcnt(0)
	s_barrier
	s_and_saveexec_b64 s[8:9], s[4:5]
	s_cbranch_execz .LBB0_22
	s_mul_i32 s7, s3, 0x1800
	s_add_i32 s7, s7, s6
	v_or_b32_e32 v0, s7, v149
	v_readlane_b32 s12, v219, 9
	v_ashrrev_i32_e32 v1, 31, v0
	v_readlane_b32 s14, v219, 11
	v_readlane_b32 s15, v219, 12
	v_readlane_b32 s13, v219, 10
	v_readlane_b32 s16, v219, 13
	v_lshl_add_u64 v[0:1], v[0:1], 2, s[14:15]
	global_load_dword v12, v[0:1], off
	ds_read2st64_b32 v[0:1], v58 offset0:48 offset1:51
	ds_read2st64_b32 v[2:3], v58 offset0:54 offset1:57
	ds_read2st64_b32 v[4:5], v58 offset0:60 offset1:63
	ds_read2st64_b32 v[6:7], v58 offset0:66 offset1:69
	ds_read2st64_b32 v[8:9], v58 offset0:72 offset1:75
	ds_read2st64_b32 v[10:11], v58 offset0:78 offset1:81
	ds_read2st64_b32 v[44:45], v58 offset0:84 offset1:87
	ds_read2st64_b32 v[46:47], v58 offset0:90 offset1:93
	ds_read2st64_b32 v[64:65], v58 offset0:96 offset1:99
	ds_read2st64_b32 v[66:67], v58 offset0:102 offset1:105
	ds_read2st64_b32 v[68:69], v58 offset0:108 offset1:111
	ds_read2st64_b32 v[70:71], v58 offset0:114 offset1:117
	ds_read2st64_b32 v[72:73], v58 offset0:120 offset1:123
	ds_read2st64_b32 v[74:75], v58 offset0:126 offset1:129
	ds_read2st64_b32 v[76:77], v58 offset0:132 offset1:135
	ds_read2st64_b32 v[78:79], v58 offset0:138 offset1:141
	v_mad_u64_u32 v[80:81], s[14:15], s3, 3, v[148:149]
	s_movk_i32 s3, 0x1800
	v_mul_lo_u32 v25, v80, s3
	v_add_u32_e32 v25, s6, v25
	v_or_b32_e32 v80, v25, v149
	v_ashrrev_i32_e32 v81, 31, v80
	v_readlane_b32 s17, v219, 14
	v_readlane_b32 s18, v219, 15
	v_readlane_b32 s19, v219, 16
	v_readlane_b32 s20, v219, 17
	v_readlane_b32 s21, v219, 18
	v_readlane_b32 s22, v219, 19
	v_readlane_b32 s23, v219, 20
	v_readlane_b32 s24, v219, 21
	v_readlane_b32 s25, v219, 22
	v_readlane_b32 s26, v219, 23
	v_readlane_b32 s27, v219, 24
	s_waitcnt vmcnt(0) lgkmcnt(14)
	v_add_f32_e32 v0, v12, v0
	v_add_f32_e32 v0, v0, v1
	v_add_f32_e32 v0, v0, v2
	v_add_f32_e32 v0, v0, v3
	s_waitcnt lgkmcnt(13)
	v_add_f32_e32 v0, v0, v4
	v_add_f32_e32 v0, v0, v5
	s_waitcnt lgkmcnt(12)
	v_add_f32_e32 v0, v0, v6
	v_add_f32_e32 v0, v0, v7
	s_waitcnt lgkmcnt(11)
	v_add_f32_e32 v0, v0, v8
	v_add_f32_e32 v0, v0, v9
	s_waitcnt lgkmcnt(10)
	v_add_f32_e32 v0, v0, v10
	v_add_f32_e32 v0, v0, v11
	s_waitcnt lgkmcnt(9)
	v_add_f32_e32 v0, v0, v44
	v_add_f32_e32 v0, v0, v45
	s_waitcnt lgkmcnt(8)
	v_add_f32_e32 v0, v0, v46
	v_add_f32_e32 v0, v0, v47
	s_waitcnt lgkmcnt(7)
	v_add_f32_e32 v0, v0, v64
	v_add_f32_e32 v0, v0, v65
	s_waitcnt lgkmcnt(6)
	v_add_f32_e32 v0, v0, v66
	v_add_f32_e32 v0, v0, v67
	s_waitcnt lgkmcnt(5)
	v_add_f32_e32 v0, v0, v68
	v_add_f32_e32 v0, v0, v69
	s_waitcnt lgkmcnt(4)
	v_add_f32_e32 v0, v0, v70
	v_add_f32_e32 v0, v0, v71
	s_waitcnt lgkmcnt(3)
	v_add_f32_e32 v0, v0, v72
	v_add_f32_e32 v0, v0, v73
	s_waitcnt lgkmcnt(2)
	v_add_f32_e32 v0, v0, v74
	v_add_f32_e32 v0, v0, v75
	s_waitcnt lgkmcnt(1)
	v_add_f32_e32 v0, v0, v76
	v_add_f32_e32 v0, v0, v77
	s_waitcnt lgkmcnt(0)
	v_add_f32_e32 v0, v0, v78
	v_add_f32_e32 v2, v0, v79
	v_lshl_add_u64 v[0:1], v[80:81], 2, s[56:57]
	global_store_dword v[0:1], v2, off sc1
	s_branch .LBB0_22

.LBB0_115:
	s_or_b64 exec, exec, s[12:13]
	v_lshl_add_u64 v[56:57], v[60:61], 0, v[32:33]
	global_load_dwordx4 v[72:75], v[56:57], off
	global_load_dwordx4 v[76:79], v[56:57], off offset:16
	global_load_dwordx4 v[80:83], v[56:57], off offset:2048
	global_load_dwordx4 v[84:87], v[56:57], off offset:2064
	s_add_i32 s14, s14, 2
	s_cmp_eq_u32 s14, 4
	s_waitcnt vmcnt(3)
	v_mov_b32_e32 v60, v73
	s_waitcnt vmcnt(2)
	v_mov_b32_e32 v61, v77
	v_mov_b32_e32 v56, v72
	v_mov_b32_e32 v57, v76
	s_waitcnt vmcnt(1)
	v_mov_b32_e32 v94, v81
	s_waitcnt vmcnt(0)
	v_mov_b32_e32 v95, v85
	v_pk_mul_f32 v[60:61], v[60:61], v[60:61]
	v_mov_b32_e32 v88, v74
	v_mov_b32_e32 v89, v78
	v_mov_b32_e32 v92, v80
	v_mov_b32_e32 v93, v84
	v_pk_mul_f32 v[94:95], v[94:95], v[94:95]
	v_pk_fma_f32 v[56:57], v[56:57], v[56:57], v[60:61]
	v_mov_b32_e32 v90, v75
	v_mov_b32_e32 v91, v79
	v_mov_b32_e32 v96, v82
	v_mov_b32_e32 v97, v86
	v_pk_fma_f32 v[60:61], v[92:93], v[92:93], v[94:95]
	v_pk_fma_f32 v[56:57], v[88:89], v[88:89], v[56:57]
	v_mov_b32_e32 v98, v83
	v_mov_b32_e32 v99, v87
	v_pk_fma_f32 v[60:61], v[96:97], v[96:97], v[60:61]
	v_pk_fma_f32 v[56:57], v[90:91], v[90:91], v[56:57]
	v_pk_fma_f32 v[60:61], v[98:99], v[98:99], v[60:61]
	v_add_f32_e32 v56, v56, v57
	v_add_f32_e32 v56, v56, v60
	v_add_f32_e32 v56, v56, v61
	ds_bpermute_b32 v57, v62, v56
	s_waitcnt lgkmcnt(0)
	v_add_f32_e32 v56, v56, v57
	ds_bpermute_b32 v57, v63, v56
	s_waitcnt lgkmcnt(0)
	v_add_f32_e32 v56, v56, v57
	ds_bpermute_b32 v57, v64, v56
	s_waitcnt lgkmcnt(0)
	v_add_f32_e32 v56, v56, v57
	ds_bpermute_b32 v57, v65, v56
	s_waitcnt lgkmcnt(0)
	v_add_f32_e32 v56, v56, v57
	ds_bpermute_b32 v57, v66, v56
	s_waitcnt lgkmcnt(0)
	v_add_f32_e32 v60, v56, v57
	ds_bpermute_b32 v61, v67, v60
	v_lshlrev_b64 v[56:57], 11, v[58:59]
	s_waitcnt lgkmcnt(0)
	v_add_f32_e32 v58, v60, v61
	v_fmamk_f32 v58, v58, 0x3a800000, v70
	v_mul_f32_e32 v59, 0x4b800000, v58
	v_cmp_gt_f32_e32 vcc, s10, v58
	v_lshl_add_u64 v[60:61], v[34:35], 0, v[56:57]
	s_nop 0
	v_cndmask_b32_e32 v58, v58, v59, vcc
	v_rsq_f32_e32 v58, v58
	s_nop 0
	v_mul_f32_e32 v56, 0x45800000, v58
	v_cndmask_b32_e32 v56, v58, v56, vcc
	v_pk_mul_f32 v[58:59], v[74:75], v[56:57] op_sel_hi:[1,0]
	v_pk_mul_f32 v[72:73], v[72:73], v[56:57] op_sel_hi:[1,0]
	v_pk_mul_f32 v[74:75], v[78:79], v[56:57] op_sel_hi:[1,0]
	v_pk_mul_f32 v[76:77], v[76:77], v[56:57] op_sel_hi:[1,0]
	v_pk_mul_f32 v[78:79], v[82:83], v[56:57] op_sel_hi:[1,0]
	v_pk_mul_f32 v[80:81], v[80:81], v[56:57] op_sel_hi:[1,0]
	v_pk_mul_f32 v[82:83], v[86:87], v[56:57] op_sel_hi:[1,0]
	v_pk_mul_f32 v[56:57], v[84:85], v[56:57] op_sel_hi:[1,0]
	v_pk_mul_f32 v[72:73], v[4:5], v[72:73]
	v_pk_mul_f32 v[58:59], v[6:7], v[58:59]
	v_pk_mul_f32 v[76:77], v[0:1], v[76:77]
	v_pk_mul_f32 v[74:75], v[2:3], v[74:75]
	v_pk_mul_f32 v[80:81], v[20:21], v[80:81]
	v_pk_mul_f32 v[78:79], v[22:23], v[78:79]
	v_pk_mul_f32 v[56:57], v[16:17], v[56:57]
	v_pk_mul_f32 v[82:83], v[18:19], v[82:83]
	v_pk_fma_f32 v[58:59], v[40:41], v[58:59], v[14:15]
	v_pk_fma_f32 v[72:73], v[42:43], v[72:73], v[12:13]
	v_pk_fma_f32 v[74:75], v[44:45], v[74:75], v[10:11]
	v_pk_fma_f32 v[76:77], v[46:47], v[76:77], v[8:9]
	v_pk_fma_f32 v[78:79], v[48:49], v[78:79], v[30:31]
	v_pk_fma_f32 v[80:81], v[50:51], v[80:81], v[28:29]
	v_pk_fma_f32 v[82:83], v[52:53], v[82:83], v[26:27]
	v_pk_fma_f32 v[84:85], v[54:55], v[56:57], v[24:25]
	v_cvt_pk_bf16_f32 v56, v72, v73
	v_cvt_pk_bf16_f32 v57, v58, v59
	v_cvt_pk_bf16_f32 v58, v76, v77
	v_cvt_pk_bf16_f32 v59, v74, v75
	v_cvt_pk_bf16_f32 v72, v80, v81
	v_cvt_pk_bf16_f32 v73, v78, v79
	v_cvt_pk_bf16_f32 v74, v84, v85
	v_cvt_pk_bf16_f32 v75, v82, v83
	global_store_dwordx4 v[60:61], v[56:59], off sc1
	global_store_dwordx4 v[60:61], v[72:75], off offset:1024 sc1
	s_cbranch_scc1 .LBB0_113
.LBB0_116:
	v_add_u32_e32 v56, s14, v68
	v_cmp_lt_i32_e32 vcc, s3, v56
	s_and_saveexec_b64 s[12:13], vcc
	s_xor_b64 s[12:13], exec, s[12:13]
	v_add_u32_e32 v58, 0xfffff000, v56
	v_mov_b32_e32 v59, v33
	v_lshlrev_b64 v[58:59], 12, v[58:59]
	v_lshl_add_u64 v[58:59], s[38:39], 0, v[58:59]
	v_mov_b32_e32 v57, v33
	s_andn2_saveexec_b64 s[12:13], s[12:13]
	v_ashrrev_i32_e32 v57, 31, v56
	v_lshlrev_b64 v[58:59], 12, v[56:57]
	v_lshl_add_u64 v[58:59], s[36:37], 0, v[58:59]
	s_or_b64 exec, exec, s[12:13]
	v_lshl_add_u64 v[58:59], v[58:59], 0, v[32:33]
	global_load_dwordx4 v[72:75], v[58:59], off
	global_load_dwordx4 v[76:79], v[58:59], off offset:16
	global_load_dwordx4 v[80:83], v[58:59], off offset:2048
	global_load_dwordx4 v[84:87], v[58:59], off offset:2064
	s_waitcnt vmcnt(3)
	v_mov_b32_e32 v60, v73
	s_waitcnt vmcnt(2)
	v_mov_b32_e32 v61, v77
	v_mov_b32_e32 v58, v72
	v_mov_b32_e32 v59, v76
	s_waitcnt vmcnt(1)
	v_mov_b32_e32 v94, v81
	s_waitcnt vmcnt(0)
	v_mov_b32_e32 v95, v85
	v_pk_mul_f32 v[60:61], v[60:61], v[60:61]
	v_mov_b32_e32 v88, v74
	v_mov_b32_e32 v89, v78
	v_mov_b32_e32 v92, v80
	v_mov_b32_e32 v93, v84
	v_pk_mul_f32 v[94:95], v[94:95], v[94:95]
	v_pk_fma_f32 v[58:59], v[58:59], v[58:59], v[60:61]
	v_mov_b32_e32 v90, v75
	v_mov_b32_e32 v91, v79
	v_mov_b32_e32 v96, v82
	v_mov_b32_e32 v97, v86
	v_pk_fma_f32 v[60:61], v[92:93], v[92:93], v[94:95]
	v_pk_fma_f32 v[58:59], v[88:89], v[88:89], v[58:59]
	v_mov_b32_e32 v98, v83
	v_mov_b32_e32 v99, v87
	v_pk_fma_f32 v[60:61], v[96:97], v[96:97], v[60:61]
	v_pk_fma_f32 v[58:59], v[90:91], v[90:91], v[58:59]
	v_pk_fma_f32 v[60:61], v[98:99], v[98:99], v[60:61]
	v_add_f32_e32 v58, v58, v59
	v_add_f32_e32 v58, v58, v60
	v_add_f32_e32 v58, v58, v61
	ds_bpermute_b32 v59, v62, v58
	v_lshlrev_b64 v[60:61], 11, v[56:57]
	v_lshl_add_u64 v[60:61], v[34:35], 0, v[60:61]
	s_waitcnt lgkmcnt(0)
	v_add_f32_e32 v58, v58, v59
	ds_bpermute_b32 v59, v63, v58
	s_waitcnt lgkmcnt(0)
	v_add_f32_e32 v58, v58, v59
	ds_bpermute_b32 v59, v64, v58
	s_waitcnt lgkmcnt(0)
	v_add_f32_e32 v58, v58, v59
	ds_bpermute_b32 v59, v65, v58
	s_waitcnt lgkmcnt(0)
	v_add_f32_e32 v58, v58, v59
	ds_bpermute_b32 v59, v66, v58
	s_waitcnt lgkmcnt(0)
	v_add_f32_e32 v58, v58, v59
	ds_bpermute_b32 v59, v67, v58
	s_waitcnt lgkmcnt(0)
	v_add_f32_e32 v58, v58, v59
	v_fmamk_f32 v58, v58, 0x3a800000, v70
	v_mul_f32_e32 v59, 0x4b800000, v58
	v_cmp_gt_f32_e32 vcc, s10, v58
	s_nop 1
	v_cndmask_b32_e32 v58, v58, v59, vcc
	v_rsq_f32_e32 v59, v58
	v_add_u32_e32 v58, 1, v56
	v_mul_f32_e32 v57, 0x45800000, v59
	v_cndmask_b32_e32 v88, v59, v57, vcc
	v_pk_mul_f32 v[74:75], v[74:75], v[88:89] op_sel_hi:[1,0]
	v_pk_mul_f32 v[72:73], v[72:73], v[88:89] op_sel_hi:[1,0]
	v_pk_mul_f32 v[78:79], v[78:79], v[88:89] op_sel_hi:[1,0]
	v_pk_mul_f32 v[76:77], v[76:77], v[88:89] op_sel_hi:[1,0]
	v_pk_mul_f32 v[82:83], v[82:83], v[88:89] op_sel_hi:[1,0]
	v_pk_mul_f32 v[80:81], v[80:81], v[88:89] op_sel_hi:[1,0]
	v_pk_mul_f32 v[86:87], v[86:87], v[88:89] op_sel_hi:[1,0]
	v_pk_mul_f32 v[84:85], v[84:85], v[88:89] op_sel_hi:[1,0]
	v_pk_mul_f32 v[72:73], v[4:5], v[72:73]
	v_pk_mul_f32 v[74:75], v[6:7], v[74:75]
	v_pk_mul_f32 v[76:77], v[0:1], v[76:77]
	v_pk_mul_f32 v[78:79], v[2:3], v[78:79]
	v_pk_mul_f32 v[80:81], v[20:21], v[80:81]
	v_pk_mul_f32 v[82:83], v[22:23], v[82:83]
	v_pk_mul_f32 v[84:85], v[16:17], v[84:85]
	v_pk_mul_f32 v[86:87], v[18:19], v[86:87]
	v_pk_fma_f32 v[74:75], v[40:41], v[74:75], v[14:15]
	v_pk_fma_f32 v[72:73], v[42:43], v[72:73], v[12:13]
	v_pk_fma_f32 v[78:79], v[44:45], v[78:79], v[10:11]
	v_pk_fma_f32 v[76:77], v[46:47], v[76:77], v[8:9]
	v_pk_fma_f32 v[82:83], v[48:49], v[82:83], v[30:31]
	v_pk_fma_f32 v[80:81], v[50:51], v[80:81], v[28:29]
	v_pk_fma_f32 v[86:87], v[52:53], v[86:87], v[26:27]
	v_pk_fma_f32 v[84:85], v[54:55], v[84:85], v[24:25]
	v_cvt_pk_bf16_f32 v72, v72, v73
	v_cvt_pk_bf16_f32 v73, v74, v75
	v_cvt_pk_bf16_f32 v74, v76, v77
	v_cvt_pk_bf16_f32 v75, v78, v79
	v_cmp_lt_i32_e32 vcc, s3, v58
	v_cvt_pk_bf16_f32 v76, v80, v81
	v_cvt_pk_bf16_f32 v77, v82, v83
	v_cvt_pk_bf16_f32 v78, v84, v85
	v_cvt_pk_bf16_f32 v79, v86, v87
	global_store_dwordx4 v[60:61], v[72:75], off sc1
	global_store_dwordx4 v[60:61], v[76:79], off offset:1024 sc1
	s_and_saveexec_b64 s[12:13], vcc
	s_xor_b64 s[12:13], exec, s[12:13]
	v_add_u32_e32 v56, 0xfffff001, v56
	v_mov_b32_e32 v57, v33
	v_lshlrev_b64 v[56:57], 12, v[56:57]
	v_lshl_add_u64 v[60:61], s[38:39], 0, v[56:57]
	v_mov_b32_e32 v59, v33
	s_andn2_saveexec_b64 s[12:13], s[12:13]
	s_cbranch_execz .LBB0_115
	v_ashrrev_i32_e32 v59, 31, v58
	v_lshlrev_b64 v[56:57], 12, v[58:59]
	v_lshl_add_u64 v[60:61], s[36:37], 0, v[56:57]
	s_branch .LBB0_115
.LBB0_124:
	s_or_b64 exec, exec, s[4:5]
	s_waitcnt vmcnt(0)
	s_barrier
	s_mov_b64 s[4:5], exec
	v_readlane_b32 s0, v219, 25
	v_readlane_b32 s1, v219, 26
	s_and_b64 s[0:1], s[4:5], s[0:1]
	s_mov_b64 exec, s[0:1]
	s_cbranch_execz .LBB0_176
	v_readlane_b32 s0, v219, 27
	v_readlane_b32 s1, v219, 28
	v_readlane_b32 s2, v219, 29
	v_mov_b32_e32 v0, 0x24000
	s_waitcnt vmcnt(0) lgkmcnt(0)
	buffer_inv sc1
	ds_read_b32 v2, v0
	ds_read_b32 v0, v0 offset:4
	s_lshl_b32 s3, s2, 8
	s_add_i32 s14, s3, 0x2400
	s_add_i32 s3, s3, 0x1400
	v_mov_b32_e32 v1, s3
	s_waitcnt lgkmcnt(0)
	v_readfirstlane_b32 s10, v2
	v_readfirstlane_b32 s11, v0
	v_mov_b32_e32 v0, 1
	s_nop 1
	global_atomic_add v2, v1, v0, s[0:1] sc0
	s_mul_i32 s10, s10, 2
	s_mul_i32 s11, s11, 2
	s_waitcnt vmcnt(0)
	v_readfirstlane_b32 s13, v2
	s_nop 1
	s_add_i32 s13, s13, 1
	s_cmp_lg_u32 s13, s10
	s_cbranch_scc1 .Lnb2_wait
	v_mov_b32_e32 v1, 0x3400
	global_atomic_add v2, v1, v0, s[0:1] sc0
	s_waitcnt vmcnt(0)
	v_readfirstlane_b32 s13, v2
	s_nop 1
	s_add_i32 s13, s13, 1
	s_cmp_lg_u32 s13, s11
	s_cbranch_scc1 .Lnb2_wait
	v_mov_b32_e32 v1, 0x2400
	global_atomic_add v1, v0, s[0:1]
	global_atomic_add v1, v0, s[0:1] offset:256
	global_atomic_add v1, v0, s[0:1] offset:512
	global_atomic_add v1, v0, s[0:1] offset:768
	global_atomic_add v1, v0, s[0:1] offset:1024
	global_atomic_add v1, v0, s[0:1] offset:1280
	global_atomic_add v1, v0, s[0:1] offset:1536
	global_atomic_add v1, v0, s[0:1] offset:1792
	global_atomic_add v1, v0, s[0:1] offset:2048
	global_atomic_add v1, v0, s[0:1] offset:2304
	global_atomic_add v1, v0, s[0:1] offset:2560
	global_atomic_add v1, v0, s[0:1] offset:2816
	global_atomic_add v1, v0, s[0:1] offset:3072
	global_atomic_add v1, v0, s[0:1] offset:3328
	global_atomic_add v1, v0, s[0:1] offset:3584
	global_atomic_add v1, v0, s[0:1] offset:3840
	v_mov_b32_e32 v1, 0x3500
	global_atomic_add v1, v0, s[0:1]

.Lnb2_spin:
	global_load_dword v2, v1, s[0:1] sc1
	s_waitcnt vmcnt(0)
	v_readfirstlane_b32 s13, v2
	s_nop 1
	s_cmp_ge_u32 s13, 2
	s_cbranch_scc1 .Lnb2_done
	s_sleep 1
	s_add_i32 s15, s15, 1
	s_cmp_lt_u32 s15, 0x200000
	s_cbranch_scc1 .Lnb2_spin
.Lnb2_done:
	s_waitcnt vmcnt(0)
.LBB0_176:
	s_or_b64 exec, exec, s[4:5]
	v_and_b32_e32 v182, 7, v168
	s_waitcnt lgkmcnt(0)
	v_lshlrev_b32_e32 v0, 8, v168
	v_bitop3_b32 v1, v162, v182, 3 bitop3:0x6c
	v_bfe_u32 v147, v168, 4, 2
	v_and_b32_e32 v0, 0x3800, v0
	v_lshlrev_b32_e32 v1, 4, v1
	v_readfirstlane_b32 s4, v168
	v_or_b32_e32 v178, v1, v0
	v_bitop3_b32 v179, v1, 64, v0 bitop3:0x36
	s_cmpk_gt_i32 s78, 0x2ff
	v_lshrrev_b32_e32 v170, 1, v167
	v_lshlrev_b32_e32 v146, 2, v147
	v_and_b32_e32 v171, 16, v168
	v_lshlrev_b32_e32 v169, 7, v167
	s_barrier
	s_cbranch_scc1 .LBB0_274
	s_add_u32 s0, s56, 0x100000
	s_addc_u32 s1, s57, 0
	s_lshl_b32 s2, s78, 19
	s_lshr_b32 s5, s4, 6
	s_bfe_u32 s26, s4, 0x10006
	s_lshr_b32 s27, s4, 7
	s_and_b32 s2, s2, 0xf80000
	s_add_u32 s17, s30, s2
	s_addc_u32 s23, s31, 0
	s_lshl_b32 s2, s78, 2
	s_and_b32 s6, s2, 0xffffff80
	s_mov_b32 s91, 0
	s_ashr_i32 s7, s6, 31
	s_lshl_b32 s90, s5, 5
	s_lshl_b32 s3, s5, 12
	s_lshl_b64 s[6:7], s[6:7], 11
	s_add_i32 s16, s3, 0
	s_lshl_b64 s[8:9], s[90:91], 11
	s_add_u32 s10, s17, s8
	s_addc_u32 s11, s23, s9
	s_or_b32 s12, s90, 8
	s_mov_b32 s13, s91
	s_lshl_b64 s[12:13], s[12:13], 11
	s_add_u32 s18, s17, s12
	v_mov_b32_e32 v0, v178
	v_mov_b32_e32 v1, v179
	s_mov_b32 m0, s16
	s_addc_u32 s19, s23, s13
	s_or_b32 s14, s90, 16
	s_mov_b32 s15, s91
	s_barrier
	s_lshl_b64 s[14:15], s[14:15], 11
	global_load_lds_dwordx4 v0, s[10:11]
	s_add_i32 m0, s16, 0x400
	s_add_u32 s20, s17, s14
	s_addc_u32 s21, s23, s15
	s_or_b32 s90, s90, 24
	global_load_lds_dwordx4 v1, s[18:19]
	s_add_i32 m0, s16, 0x800
	s_lshl_b64 s[34:35], s[90:91], 11
	s_add_u32 s22, s17, s34
	global_load_lds_dwordx4 v0, s[20:21]
	s_addc_u32 s23, s23, s35
	s_add_i32 m0, s16, 0xc00
	s_add_u32 s24, s0, s6
	s_addc_u32 s25, s1, s7
	s_lshl_b32 s17, s5, 11
	s_lshl_b32 s90, s5, 4
	s_sub_i32 s28, s16, s17
	global_load_lds_dwordx4 v1, s[22:23]
	s_add_i32 m0, s28, 0x8000
	s_lshl_b64 s[40:41], s[90:91], 11
	s_add_u32 s6, s24, s40
	s_addc_u32 s7, s25, s41
	s_or_b32 s90, s90, 8
	s_lshl_b64 s[42:43], s[90:91], 11
	s_add_u32 s24, s24, s42
	global_load_lds_dwordx4 v0, s[6:7]
	s_addc_u32 s25, s25, s43
	s_add_i32 m0, s28, 0x8400
	v_mov_b32_e32 v150, v178
	v_mov_b32_e32 v0, v179
	v_mov_b32_e32 v151, 0
	global_load_lds_dwordx4 v1, s[24:25]
	s_mov_b64 s[44:45], 0x80
	v_lshl_add_u64 v[2:3], s[10:11], 0, v[150:151]
	s_add_i32 m0, s16, 0xc000
	v_lshl_add_u64 v[2:3], v[2:3], 0, s[44:45]
	v_mov_b32_e32 v1, v151
	global_load_lds_dwordx4 v[2:3], off
	v_lshl_add_u64 v[2:3], s[18:19], 0, v[0:1]
	v_lshl_add_u64 v[2:3], v[2:3], 0, s[44:45]
	s_add_i32 m0, s16, 0xc400
	s_add_i32 s10, s17, 0
	global_load_lds_dwordx4 v[2:3], off
	v_lshl_add_u64 v[2:3], s[20:21], 0, v[150:151]
	v_lshl_add_u64 v[2:3], v[2:3], 0, s[44:45]
	s_add_i32 m0, s16, 0xc800
	v_cmp_eq_u32_e32 vcc, 0, v171
	global_load_lds_dwordx4 v[2:3], off
	v_lshl_add_u64 v[2:3], s[22:23], 0, v[0:1]
	v_lshl_add_u64 v[2:3], v[2:3], 0, s[44:45]
	s_add_i32 m0, s16, 0xcc00
	v_lshl_add_u64 v[0:1], s[24:25], 0, v[0:1]
	global_load_lds_dwordx4 v[2:3], off
	v_lshl_add_u64 v[2:3], s[6:7], 0, v[150:151]
	s_add_i32 m0, s10, 0x14000
	v_lshl_add_u64 v[2:3], v[2:3], 0, s[44:45]
	global_load_lds_dwordx4 v[2:3], off
	v_lshl_add_u64 v[0:1], v[0:1], 0, s[44:45]
	s_add_i32 m0, s10, 0x14400
	s_cmpk_gt_u32 s4, 0xff
	global_load_lds_dwordx4 v[0:1], off
	s_cselect_b64 s[46:47], -1, 0
	s_lshl_b32 s90, s5, 15
	s_lshl_b32 s4, s5, 14
	s_lshl_b32 s18, s27, 6
	s_lshl_b32 s19, s26, 6
	s_lshl_b32 s20, s26, 13
	s_lshl_b32 s21, s27, 13
	s_add_u32 s48, s56, 0x24000
	s_addc_u32 s49, s57, 0
	v_lshl_or_b32 v150, v147, 5, v169
	v_lshl_add_u64 v[152:153], s[48:49], 0, v[150:151]
	s_mov_b64 s[6:7], 0x1000
	v_lshl_add_u64 v[154:155], v[152:153], 0, s[6:7]
	s_mov_b64 s[6:7], 0x1800
	v_lshl_add_u64 v[156:157], v[152:153], 0, s[6:7]
	s_add_u32 s6, s56, s8
	v_writelane_b32 v219, s6, 33
	s_addc_u32 s6, s57, s9
	s_lshl_b32 s24, s78, 8
	s_lshl_b32 s25, s58, 8
	v_writelane_b32 v219, s6, 35
	s_add_u32 s6, s56, s40
	v_writelane_b32 v219, s6, 36
	s_addc_u32 s6, s57, s41
	s_lshl_b32 s28, s58, 2
	s_lshl_b64 s[50:51], s[90:91], 1
	s_mov_b32 s5, s91
	v_writelane_b32 v219, s6, 37
	s_add_u32 s6, s56, s50
	v_writelane_b32 v219, s6, 39
	s_addc_u32 s6, s57, s51
	s_lshl_b64 s[68:69], s[4:5], 1
	v_add_u32_e32 v0, 12, v146
	v_xor_b32_e32 v1, v147, v170
	v_writelane_b32 v219, s6, 40
	s_add_u32 s4, s56, s68
	v_cndmask_b32_e32 v0, v0, v146, vcc
	v_lshlrev_b32_e32 v164, 4, v1
	v_bitop3_b32 v1, v147, v170, 4 bitop3:0x36
	v_writelane_b32 v219, s4, 41
	s_addc_u32 s4, s57, s69
	v_lshlrev_b32_e32 v165, 4, v1
	v_writelane_b32 v219, s4, 42
	s_mov_b64 s[4:5], -1
	s_mov_b64 s[70:71], 0x100
	s_mov_b64 s[72:73], 0x3400180
	s_mov_b64 s[74:75], 0x3404180
	s_mov_b64 s[76:77], 0x3408180
	s_mov_b32 s63, s78
	s_mov_b64 s[78:79], 0x340c180
	s_mov_b64 s[80:81], 0x100180
	s_mov_b64 s[82:83], 0x104180
	v_lshlrev_b32_e32 v158, 2, v146
	v_lshlrev_b32_e32 v160, 1, v0
	s_mov_b32 s90, 0x3e38aa3b
	s_branch .LBB0_179
.LBB0_178:
	v_pk_mul_f32 v[16:17], v[10:11], s[90:91] op_sel_hi:[1,0]
	v_pk_mul_f32 v[18:19], v[8:9], s[90:91] op_sel_hi:[1,0]
	v_cndmask_b32_e64 v11, v11, v17, s[4:5]
	v_cndmask_b32_e64 v10, v10, v16, s[4:5]
	v_cndmask_b32_e64 v9, v9, v19, s[4:5]
	v_cndmask_b32_e64 v8, v8, v18, s[4:5]
	v_cvt_pk_bf16_f32 v8, v8, v9
	v_cvt_pk_bf16_f32 v9, v10, v11
	v_pk_mul_f32 v[10:11], v[6:7], s[90:91] op_sel_hi:[1,0]
	v_pk_mul_f32 v[16:17], v[4:5], s[90:91] op_sel_hi:[1,0]
	v_cndmask_b32_e64 v7, v7, v11, s[4:5]
	v_cndmask_b32_e64 v10, v6, v10, s[4:5]
	v_cndmask_b32_e64 v5, v5, v17, s[4:5]
	v_cndmask_b32_e64 v4, v4, v16, s[4:5]
	v_cvt_pk_bf16_f32 v6, v4, v5
	v_cvt_pk_bf16_f32 v7, v10, v7
	v_pk_mul_f32 v[4:5], v[2:3], s[90:91] op_sel_hi:[1,0]
	v_pk_mul_f32 v[10:11], v[0:1], s[90:91] op_sel_hi:[1,0]
	v_cndmask_b32_e64 v3, v3, v5, s[4:5]
	v_cndmask_b32_e64 v4, v2, v4, s[4:5]
	v_cndmask_b32_e64 v1, v1, v11, s[4:5]
	v_cndmask_b32_e64 v0, v0, v10, s[4:5]
	v_cvt_pk_bf16_f32 v2, v0, v1
	v_cvt_pk_bf16_f32 v3, v4, v3
	v_pk_mul_f32 v[0:1], v[14:15], s[90:91] op_sel_hi:[1,0]
	v_pk_mul_f32 v[4:5], v[12:13], s[90:91] op_sel_hi:[1,0]
	v_cndmask_b32_e64 v10, v14, v0, s[4:5]
	v_cndmask_b32_e64 v0, v13, v5, s[4:5]
	v_cndmask_b32_e64 v4, v12, v4, s[4:5]
	v_cndmask_b32_e64 v1, v15, v1, s[4:5]
	v_cvt_pk_bf16_f32 v0, v4, v0
	v_lshlrev_b64 v[4:5], 11, v[150:151]
	v_cvt_pk_bf16_f32 v1, v10, v1
	v_lshl_add_u64 v[4:5], s[94:95], 0, v[4:5]
	v_mov_b32_e32 v161, v151
	v_permlane16_swap_b32_e32 v0, v2
	v_permlane16_swap_b32_e32 v1, v3
	v_lshl_add_u64 v[4:5], v[4:5], 0, v[160:161]
	v_permlane16_swap_b32_e32 v6, v8
	v_permlane16_swap_b32_e32 v7, v9
	s_add_i32 s24, s24, s25
	s_add_i32 s2, s2, s28
	s_mov_b64 s[4:5], 0
	s_andn2_b64 vcc, exec, s[92:93]
	s_mov_b32 s63, s62
	global_store_dwordx4 v[4:5], v[0:3], off sc1
	global_store_dwordx4 v[4:5], v[6:9], off offset:64 sc1
	s_cbranch_vccz .LBB0_273

.LBB0_191:
	s_and_b64 s[4:5], s[94:95], exec
	s_mov_b32 s4, 0x5400000
	s_cselect_b32 s11, s4, 0x6400000
	s_cmpk_lt_u32 s63, 0x100
	v_pk_mul_f32 v[66:67], v[46:47], s[90:91] op_sel_hi:[1,0]
	v_pk_mul_f32 v[68:69], v[44:45], s[90:91] op_sel_hi:[1,0]
	s_cselect_b64 s[4:5], -1, 0
	v_cndmask_b32_e64 v47, v47, v67, s[4:5]
	v_cndmask_b32_e64 v66, v46, v66, s[4:5]
	v_cndmask_b32_e64 v45, v45, v69, s[4:5]
	v_cndmask_b32_e64 v44, v44, v68, s[4:5]
	v_cvt_pk_bf16_f32 v46, v44, v45
	v_cvt_pk_bf16_f32 v47, v66, v47
	v_pk_mul_f32 v[44:45], v[62:63], s[90:91] op_sel_hi:[1,0]
	v_pk_mul_f32 v[66:67], v[60:61], s[90:91] op_sel_hi:[1,0]
	v_cndmask_b32_e64 v45, v63, v45, s[4:5]
	v_cndmask_b32_e64 v62, v62, v44, s[4:5]
	v_cndmask_b32_e64 v44, v61, v67, s[4:5]
	v_cndmask_b32_e64 v60, v60, v66, s[4:5]
	s_and_b64 s[22:23], s[4:5], exec
	v_cvt_pk_bf16_f32 v44, v60, v44
	v_cvt_pk_bf16_f32 v45, v62, v45
	v_pk_mul_f32 v[60:61], v[42:43], s[90:91] op_sel_hi:[1,0]
	v_pk_mul_f32 v[62:63], v[40:41], s[90:91] op_sel_hi:[1,0]
	s_cselect_b32 s11, 0x4400000, s11
	v_cndmask_b32_e64 v43, v43, v61, s[4:5]
	v_cndmask_b32_e64 v60, v42, v60, s[4:5]
	v_cndmask_b32_e64 v41, v41, v63, s[4:5]
	v_cndmask_b32_e64 v40, v40, v62, s[4:5]
	s_add_u32 s11, s56, s11
	v_cvt_pk_bf16_f32 v42, v40, v41
	v_cvt_pk_bf16_f32 v43, v60, v43
	s_addc_u32 s22, s57, 0
	s_lshl_b32 s10, s10, 1
	v_pk_mul_f32 v[40:41], v[58:59], s[90:91] op_sel_hi:[1,0]
	v_pk_mul_f32 v[60:61], v[56:57], s[90:91] op_sel_hi:[1,0]
	s_add_u32 s94, s11, s10
	v_cndmask_b32_e64 v58, v58, v40, s[4:5]
	v_cndmask_b32_e64 v40, v57, v61, s[4:5]
	v_cndmask_b32_e64 v56, v56, v60, s[4:5]
	s_addc_u32 s95, s22, 0
	v_cndmask_b32_e64 v41, v59, v41, s[4:5]
	v_cvt_pk_bf16_f32 v40, v56, v40
	v_lshlrev_b64 v[56:57], 11, v[150:151]
	v_cvt_pk_bf16_f32 v41, v58, v41
	v_lshl_add_u64 v[56:57], s[94:95], 0, v[56:57]
	v_mov_b32_e32 v161, v151
	v_permlane16_swap_b32_e32 v40, v42
	v_permlane16_swap_b32_e32 v41, v43
	v_lshl_add_u64 v[56:57], v[56:57], 0, v[160:161]
	global_store_dwordx4 v[56:57], v[40:43], off sc1
	v_permlane16_swap_b32_e32 v44, v46
	s_nop 0
	v_or_b32_e32 v40, 16, v150
	v_mov_b32_e32 v41, v151
	v_lshlrev_b64 v[42:43], 12, v[40:41]
	v_permlane16_swap_b32_e32 v45, v47
	s_and_b64 vcc, exec, s[6:7]
	v_lshl_add_u64 v[42:43], v[64:65], 0, v[42:43]
	global_store_dwordx4 v[56:57], v[44:47], off offset:64 sc1
	s_cbranch_vccz .LBB0_263
	s_and_b64 vcc, exec, s[6:7]
	s_cbranch_vccz .LBB0_264

.LBB0_196:
	v_pk_mul_f32 v[42:43], v[30:31], s[90:91] op_sel_hi:[1,0]
	v_pk_mul_f32 v[44:45], v[28:29], s[90:91] op_sel_hi:[1,0]
	v_cndmask_b32_e64 v31, v31, v43, s[4:5]
	v_cndmask_b32_e64 v42, v30, v42, s[4:5]
	v_cndmask_b32_e64 v29, v29, v45, s[4:5]
	v_cndmask_b32_e64 v28, v28, v44, s[4:5]
	v_cvt_pk_bf16_f32 v30, v28, v29
	v_cvt_pk_bf16_f32 v31, v42, v31
	v_pk_mul_f32 v[28:29], v[54:55], s[90:91] op_sel_hi:[1,0]
	v_pk_mul_f32 v[42:43], v[52:53], s[90:91] op_sel_hi:[1,0]
	v_cndmask_b32_e64 v29, v55, v29, s[4:5]
	v_cndmask_b32_e64 v44, v54, v28, s[4:5]
	v_cndmask_b32_e64 v28, v53, v43, s[4:5]
	v_cndmask_b32_e64 v42, v52, v42, s[4:5]
	v_cvt_pk_bf16_f32 v28, v42, v28
	v_cvt_pk_bf16_f32 v29, v44, v29
	v_pk_mul_f32 v[42:43], v[26:27], s[90:91] op_sel_hi:[1,0]
	v_pk_mul_f32 v[44:45], v[24:25], s[90:91] op_sel_hi:[1,0]
	v_cndmask_b32_e64 v27, v27, v43, s[4:5]
	v_cndmask_b32_e64 v42, v26, v42, s[4:5]
	v_cndmask_b32_e64 v25, v25, v45, s[4:5]
	v_cndmask_b32_e64 v24, v24, v44, s[4:5]
	v_cvt_pk_bf16_f32 v26, v24, v25
	v_cvt_pk_bf16_f32 v27, v42, v27
	v_pk_mul_f32 v[24:25], v[50:51], s[90:91] op_sel_hi:[1,0]
	v_pk_mul_f32 v[42:43], v[48:49], s[90:91] op_sel_hi:[1,0]
	v_cndmask_b32_e64 v25, v51, v25, s[4:5]
	v_cndmask_b32_e64 v44, v50, v24, s[4:5]
	v_cndmask_b32_e64 v24, v49, v43, s[4:5]
	v_cndmask_b32_e64 v42, v48, v42, s[4:5]
	v_lshlrev_b64 v[40:41], 11, v[40:41]
	v_cvt_pk_bf16_f32 v24, v42, v24
	v_cvt_pk_bf16_f32 v25, v44, v25
	v_lshl_add_u64 v[40:41], s[94:95], 0, v[40:41]
	v_mov_b32_e32 v161, v151
	v_permlane16_swap_b32_e32 v24, v26
	v_permlane16_swap_b32_e32 v25, v27
	v_lshl_add_u64 v[40:41], v[40:41], 0, v[160:161]
	global_store_dwordx4 v[40:41], v[24:27], off sc1
	v_permlane16_swap_b32_e32 v28, v30
	s_nop 0
	v_or_b32_e32 v24, 32, v150
	v_mov_b32_e32 v25, v151
	v_lshlrev_b64 v[26:27], 12, v[24:25]
	v_permlane16_swap_b32_e32 v29, v31
	s_and_b64 vcc, exec, s[6:7]
	v_lshl_add_u64 v[26:27], v[64:65], 0, v[26:27]
	global_store_dwordx4 v[40:41], v[28:31], off offset:64 sc1
	s_cbranch_vccz .LBB0_266
	s_and_b64 vcc, exec, s[6:7]
	s_cbranch_vccz .LBB0_267

.LBB0_201:
	v_pk_mul_f32 v[26:27], v[22:23], s[90:91] op_sel_hi:[1,0]
	v_pk_mul_f32 v[28:29], v[20:21], s[90:91] op_sel_hi:[1,0]
	v_cndmask_b32_e64 v23, v23, v27, s[4:5]
	v_cndmask_b32_e64 v26, v22, v26, s[4:5]
	v_cndmask_b32_e64 v21, v21, v29, s[4:5]
	v_cndmask_b32_e64 v20, v20, v28, s[4:5]
	v_cvt_pk_bf16_f32 v22, v20, v21
	v_cvt_pk_bf16_f32 v23, v26, v23
	v_pk_mul_f32 v[20:21], v[38:39], s[90:91] op_sel_hi:[1,0]
	v_pk_mul_f32 v[26:27], v[36:37], s[90:91] op_sel_hi:[1,0]
	v_cndmask_b32_e64 v21, v39, v21, s[4:5]
	v_cndmask_b32_e64 v28, v38, v20, s[4:5]
	v_cndmask_b32_e64 v20, v37, v27, s[4:5]
	v_cndmask_b32_e64 v26, v36, v26, s[4:5]
	v_cvt_pk_bf16_f32 v20, v26, v20
	v_cvt_pk_bf16_f32 v21, v28, v21
	v_pk_mul_f32 v[26:27], v[18:19], s[90:91] op_sel_hi:[1,0]
	v_pk_mul_f32 v[28:29], v[16:17], s[90:91] op_sel_hi:[1,0]
	v_cndmask_b32_e64 v19, v19, v27, s[4:5]
	v_cndmask_b32_e64 v26, v18, v26, s[4:5]
	v_cndmask_b32_e64 v17, v17, v29, s[4:5]
	v_cndmask_b32_e64 v16, v16, v28, s[4:5]
	v_cvt_pk_bf16_f32 v18, v16, v17
	v_cvt_pk_bf16_f32 v19, v26, v19
	v_pk_mul_f32 v[16:17], v[34:35], s[90:91] op_sel_hi:[1,0]
	v_pk_mul_f32 v[26:27], v[32:33], s[90:91] op_sel_hi:[1,0]
	v_cndmask_b32_e64 v17, v35, v17, s[4:5]
	v_cndmask_b32_e64 v28, v34, v16, s[4:5]
	v_cndmask_b32_e64 v16, v33, v27, s[4:5]
	v_cndmask_b32_e64 v26, v32, v26, s[4:5]
	v_lshlrev_b64 v[24:25], 11, v[24:25]
	v_cvt_pk_bf16_f32 v16, v26, v16
	v_cvt_pk_bf16_f32 v17, v28, v17
	v_lshl_add_u64 v[24:25], s[94:95], 0, v[24:25]
	v_mov_b32_e32 v161, v151
	v_permlane16_swap_b32_e32 v16, v18
	v_permlane16_swap_b32_e32 v17, v19
	v_lshl_add_u64 v[24:25], v[24:25], 0, v[160:161]
	v_or_b32_e32 v150, 48, v150
	global_store_dwordx4 v[24:25], v[16:19], off sc1
	v_permlane16_swap_b32_e32 v20, v22
	s_nop 0
	v_lshlrev_b64 v[16:17], 12, v[150:151]
	v_permlane16_swap_b32_e32 v21, v23
	s_and_b64 vcc, exec, s[6:7]
	v_lshl_add_u64 v[16:17], v[64:65], 0, v[16:17]
	global_store_dwordx4 v[24:25], v[20:23], off offset:64 sc1
	s_cbranch_vccz .LBB0_269
	s_and_b64 vcc, exec, s[6:7]
	s_cbranch_vccz .LBB0_270

.LBB0_274:
	s_waitcnt vmcnt(0)
	s_waitcnt vmcnt(0) lgkmcnt(0)
	s_barrier
	s_mov_b64 s[4:5], exec
	v_readlane_b32 s0, v219, 25
	v_readlane_b32 s1, v219, 26
	s_and_b64 s[0:1], s[4:5], s[0:1]
	s_mov_b64 exec, s[0:1]
	s_cbranch_execz .LBB0_326
	v_readlane_b32 s0, v219, 27
	v_readlane_b32 s1, v219, 28
	v_readlane_b32 s2, v219, 29
	v_mov_b32_e32 v0, 0x24000
	s_waitcnt vmcnt(0) lgkmcnt(0)
	buffer_inv sc1
	ds_read_b32 v2, v0
	ds_read_b32 v0, v0 offset:4
	s_lshl_b32 s3, s2, 8
	s_add_i32 s14, s3, 0x2400
	s_add_i32 s3, s3, 0x1400
	v_mov_b32_e32 v1, s3
	s_waitcnt lgkmcnt(0)
	v_readfirstlane_b32 s10, v2
	v_readfirstlane_b32 s11, v0
	v_mov_b32_e32 v0, 1
	s_nop 1
	global_atomic_add v2, v1, v0, s[0:1] sc0
	s_mul_i32 s10, s10, 3
	s_mul_i32 s11, s11, 3
	s_waitcnt vmcnt(0)
	v_readfirstlane_b32 s13, v2
	s_nop 1
	s_add_i32 s13, s13, 1
	s_cmp_lg_u32 s13, s10
	s_cbranch_scc1 .Lnb3_wait
	v_mov_b32_e32 v1, 0x3400
	global_atomic_add v2, v1, v0, s[0:1] sc0
	s_waitcnt vmcnt(0)
	v_readfirstlane_b32 s13, v2
	s_nop 1
	s_add_i32 s13, s13, 1
	s_cmp_lg_u32 s13, s11
	s_cbranch_scc1 .Lnb3_wait
	v_mov_b32_e32 v1, 0x2400
	global_atomic_add v1, v0, s[0:1]
	global_atomic_add v1, v0, s[0:1] offset:256
	global_atomic_add v1, v0, s[0:1] offset:512
	global_atomic_add v1, v0, s[0:1] offset:768
	global_atomic_add v1, v0, s[0:1] offset:1024
	global_atomic_add v1, v0, s[0:1] offset:1280
	global_atomic_add v1, v0, s[0:1] offset:1536
	global_atomic_add v1, v0, s[0:1] offset:1792
	global_atomic_add v1, v0, s[0:1] offset:2048
	global_atomic_add v1, v0, s[0:1] offset:2304
	global_atomic_add v1, v0, s[0:1] offset:2560
	global_atomic_add v1, v0, s[0:1] offset:2816
	global_atomic_add v1, v0, s[0:1] offset:3072
	global_atomic_add v1, v0, s[0:1] offset:3328
	global_atomic_add v1, v0, s[0:1] offset:3584
	global_atomic_add v1, v0, s[0:1] offset:3840
	v_mov_b32_e32 v1, 0x3500
	global_atomic_add v1, v0, s[0:1]

.Lnb3_spin:
	global_load_dword v2, v1, s[0:1] sc1
	s_waitcnt vmcnt(0)
	v_readfirstlane_b32 s13, v2
	s_nop 1
	s_cmp_ge_u32 s13, 3
	s_cbranch_scc1 .Lnb3_done
	s_sleep 1
	s_add_i32 s15, s15, 1
	s_cmp_lt_u32 s15, 0x200000
	s_cbranch_scc1 .Lnb3_spin
.Lnb3_done:
	s_waitcnt vmcnt(0)
.LBB0_326:
	s_or_b64 exec, exec, s[4:5]
	v_readlane_b32 s0, v219, 9
	v_lshlrev_b32_e32 v20, 2, v149
	v_readlane_b32 s8, v219, 17
	v_readlane_b32 s9, v219, 18
	s_waitcnt lgkmcnt(0)
	s_barrier
	s_nop 2
	global_load_dword v0, v20, s[8:9]
	global_load_dword v1, v20, s[8:9] offset:256
	global_load_dword v2, v20, s[8:9] offset:512
	global_load_dword v3, v20, s[8:9] offset:768
	v_mbcnt_hi_u32_b32 v4, -1, v163
	v_and_b32_e32 v5, 64, v4
	v_xor_b32_e32 v6, 32, v4
	v_add_u32_e32 v5, 64, v5
	v_cmp_lt_i32_e32 vcc, v6, v5
	v_xor_b32_e32 v7, 16, v4
	v_xor_b32_e32 v8, 8, v4
	v_cndmask_b32_e32 v6, v4, v6, vcc
	v_lshlrev_b32_e32 v172, 2, v6
	v_cmp_lt_i32_e32 vcc, v7, v5
	v_xor_b32_e32 v9, 4, v4
	v_xor_b32_e32 v10, 2, v4
	v_cndmask_b32_e32 v7, v4, v7, vcc
	v_lshlrev_b32_e32 v173, 2, v7
	v_cmp_lt_i32_e32 vcc, v8, v5
	v_xor_b32_e32 v11, 1, v4
	s_bcnt1_i32_b32 s0, s78
	s_bitcmp0_b32 s0, 0
	s_cselect_b64 s[8:9], -1, 0
	v_readlane_b32 s1, v219, 10
	v_readlane_b32 s2, v219, 11
	v_readlane_b32 s3, v219, 12
	v_readlane_b32 s4, v219, 13
	v_readlane_b32 s5, v219, 14
	v_readlane_b32 s6, v219, 15
	v_readlane_b32 s7, v219, 16
	v_readlane_b32 s10, v219, 19
	v_readlane_b32 s11, v219, 20
	v_readlane_b32 s12, v219, 21
	v_readlane_b32 s13, v219, 22
	v_readlane_b32 s14, v219, 23
	v_readlane_b32 s15, v219, 24
	s_waitcnt vmcnt(2)
	v_mul_f32_e32 v6, v0, v1
	ds_bpermute_b32 v6, v172, v6
	s_waitcnt vmcnt(0)
	v_mul_f32_e32 v12, v2, v3
	ds_bpermute_b32 v12, v172, v12
	s_waitcnt lgkmcnt(1)
	v_fmac_f32_e32 v6, v0, v1
	ds_bpermute_b32 v0, v173, v6
	s_waitcnt lgkmcnt(1)
	v_fmac_f32_e32 v12, v2, v3
	ds_bpermute_b32 v1, v173, v12
	v_cndmask_b32_e32 v2, v4, v8, vcc
	v_lshlrev_b32_e32 v174, 2, v2
	s_waitcnt lgkmcnt(1)
	v_add_f32_e32 v0, v6, v0
	ds_bpermute_b32 v2, v174, v0
	s_waitcnt lgkmcnt(1)
	v_add_f32_e32 v1, v12, v1
	ds_bpermute_b32 v3, v174, v1
	v_cmp_lt_i32_e32 vcc, v9, v5
	s_waitcnt lgkmcnt(1)
	v_add_f32_e32 v0, v0, v2
	v_cndmask_b32_e32 v6, v4, v9, vcc
	v_lshlrev_b32_e32 v175, 2, v6
	s_waitcnt lgkmcnt(0)
	v_add_f32_e32 v1, v1, v3
	ds_bpermute_b32 v2, v175, v0
	ds_bpermute_b32 v3, v175, v1
	v_cmp_lt_i32_e32 vcc, v10, v5
	s_waitcnt lgkmcnt(1)
	v_add_f32_e32 v0, v0, v2
	v_cndmask_b32_e32 v6, v4, v10, vcc
	v_lshlrev_b32_e32 v176, 2, v6
	s_waitcnt lgkmcnt(0)
	v_add_f32_e32 v1, v1, v3
	ds_bpermute_b32 v2, v176, v0
	ds_bpermute_b32 v3, v176, v1
	v_cmp_lt_i32_e32 vcc, v11, v5
	s_waitcnt lgkmcnt(1)
	v_add_f32_e32 v21, v0, v2
	v_cndmask_b32_e32 v4, v4, v11, vcc
	v_lshlrev_b32_e32 v177, 2, v4
	s_waitcnt lgkmcnt(0)
	v_add_f32_e32 v22, v1, v3
	ds_bpermute_b32 v23, v177, v21
	ds_bpermute_b32 v24, v177, v22
	s_and_b64 vcc, exec, s[8:9]
	s_cbranch_vccnz .LBB0_347
	s_add_i32 s0, s78, 0xc0
	s_cmpk_gt_i32 s0, 0x25f
	s_waitcnt lgkmcnt(0)
	s_barrier
	s_cbranch_scc1 .LBB0_346
	s_movk_i32 s1, 0x2100
	v_lshrrev_b32_e32 v25, 3, v149
	v_and_b32_e32 v4, 56, v144
	s_cmpk_eq_i32 s58, 0x100
	v_mad_u32_u24 v1, v148, s1, 0
	v_lshrrev_b32_e32 v0, 5, v149
	v_and_b32_e32 v2, 31, v168
	v_mul_u32_u24_e32 v3, 0x84, v4
	v_lshlrev_b32_e32 v7, 2, v25
	s_cselect_b64 s[6:7], -1, 0
	v_mov_b32_e32 v5, 0
	v_lshl_add_u32 v6, v2, 2, v1
	s_movk_i32 s1, 0x84
	v_add3_u32 v26, v1, v3, v7
	v_or_b32_e32 v27, 8, v25
	v_or_b32_e32 v28, 16, v25
	v_or_b32_e32 v29, 24, v25
	v_mov_b32_e32 v1, v0
	s_movk_i32 s2, 0x187f
	s_movk_i32 s3, 0x1ff
	s_movk_i32 s10, 0xcff
	v_lshlrev_b32_e32 v8, 2, v2
	v_lshlrev_b32_e32 v10, 1, v4
	v_mov_b32_e32 v30, 0xffffe780
	v_mov_b32_e32 v31, 0xc00
	v_mov_b32_e32 v32, 0x600
	v_mov_b32_e32 v33, 0x2c0000
	v_mov_b32_e32 v34, 0x1400000
	v_mov_b32_e32 v35, 0x2980000
	v_mov_b32_e32 v36, 0x900000
	v_mov_b32_e32 v37, 0x1e80000
	v_mov_b32_e32 v38, 0x700000
	v_mov_b32_e32 v39, 0x1c80000
	v_mov_b32_e32 v40, 0x100000
	v_mov_b32_e32 v41, 0x1980000
	s_branch .LBB0_330

.LBB0_344:
	s_lshl_b32 s12, s5, 1
	s_lshl_b32 s13, s4, 1
	v_or_b32_e32 v9, s12, v1
	v_or_b32_e32 v11, s13, v0
	s_add_i32 s14, s12, 4
	s_add_i32 s15, s13, 4
	s_add_i32 s16, s12, 8
	s_add_i32 s17, s13, 8
	s_add_i32 s18, s12, 12
	s_add_i32 s19, s13, 12
	s_add_i32 s20, s12, 16
	s_add_i32 s21, s13, 16
	s_add_i32 s22, s12, 20
	s_add_i32 s23, s13, 20
	s_add_i32 s24, s12, 24
	s_add_i32 s25, s13, 24
	s_add_i32 s12, s12, 28
	s_add_i32 s13, s13, 28
	v_add_u32_e32 v17, v9, v7
	v_add_u32_e32 v43, v11, v16
	v_or_b32_e32 v76, s14, v1
	v_or_b32_e32 v77, s15, v0
	v_or_b32_e32 v78, s16, v1
	v_or_b32_e32 v79, s17, v0
	v_or_b32_e32 v80, s18, v1
	v_or_b32_e32 v81, s19, v0
	v_or_b32_e32 v82, s20, v1
	v_or_b32_e32 v83, s21, v0
	v_or_b32_e32 v84, s22, v1
	v_or_b32_e32 v85, s23, v0
	v_or_b32_e32 v86, s24, v1
	v_or_b32_e32 v87, s25, v0
	v_or_b32_e32 v88, s12, v1
	v_or_b32_e32 v89, s13, v0
	v_ashrrev_i32_e32 v48, 31, v43
	v_ashrrev_i32_e32 v49, 31, v17
	v_mul_lo_u32 v90, v3, v17
	v_mad_u64_u32 v[44:45], s[12:13], v2, v17, 0
	v_mul_lo_u32 v17, v13, v43
	v_mad_u64_u32 v[46:47], s[12:13], v12, v43, 0
	v_add_u32_e32 v43, v76, v7
	v_add_u32_e32 v50, v77, v16
	v_add_u32_e32 v52, v78, v7
	v_add_u32_e32 v54, v79, v16
	v_add_u32_e32 v56, v80, v7
	v_add_u32_e32 v58, v81, v16
	v_add_u32_e32 v60, v82, v7
	v_add_u32_e32 v62, v83, v16
	v_add_u32_e32 v64, v84, v7
	v_add_u32_e32 v66, v85, v16
	v_add_u32_e32 v68, v86, v7
	v_add_u32_e32 v70, v87, v16
	v_add_u32_e32 v72, v88, v7
	v_add_u32_e32 v74, v89, v16
	v_mul_lo_u32 v91, v2, v49
	v_mul_lo_u32 v92, v12, v48
	v_ashrrev_i32_e32 v93, 31, v50
	v_ashrrev_i32_e32 v94, 31, v43
	v_ashrrev_i32_e32 v96, 31, v54
	v_ashrrev_i32_e32 v97, 31, v52
	v_ashrrev_i32_e32 v100, 31, v58
	v_ashrrev_i32_e32 v101, 31, v56
	v_ashrrev_i32_e32 v104, 31, v62
	v_ashrrev_i32_e32 v105, 31, v60
	v_ashrrev_i32_e32 v108, 31, v66
	v_ashrrev_i32_e32 v109, 31, v64
	v_ashrrev_i32_e32 v112, 31, v70
	v_ashrrev_i32_e32 v113, 31, v68
	v_ashrrev_i32_e32 v116, 31, v74
	v_ashrrev_i32_e32 v117, 31, v72
	v_mul_lo_u32 v95, v3, v43
	v_mad_u64_u32 v[48:49], s[12:13], v2, v43, 0
	v_mul_lo_u32 v43, v13, v50
	v_mad_u64_u32 v[50:51], s[12:13], v12, v50, 0
	v_mul_lo_u32 v98, v3, v52
	v_mad_u64_u32 v[52:53], s[12:13], v2, v52, 0
	v_mul_lo_u32 v99, v13, v54
	v_mad_u64_u32 v[54:55], s[12:13], v12, v54, 0
	v_mul_lo_u32 v102, v3, v56
	v_mad_u64_u32 v[56:57], s[12:13], v2, v56, 0
	v_mul_lo_u32 v103, v13, v58
	v_mad_u64_u32 v[58:59], s[12:13], v12, v58, 0
	v_mul_lo_u32 v106, v3, v60
	v_mad_u64_u32 v[60:61], s[12:13], v2, v60, 0
	v_mul_lo_u32 v107, v13, v62
	v_mad_u64_u32 v[62:63], s[12:13], v12, v62, 0
	v_mul_lo_u32 v110, v3, v64
	v_mad_u64_u32 v[64:65], s[12:13], v2, v64, 0
	v_mul_lo_u32 v111, v13, v66
	v_mad_u64_u32 v[66:67], s[12:13], v12, v66, 0
	v_mul_lo_u32 v114, v3, v68
	v_mad_u64_u32 v[68:69], s[12:13], v2, v68, 0
	v_mul_lo_u32 v115, v13, v70
	v_mad_u64_u32 v[70:71], s[12:13], v12, v70, 0
	v_mul_lo_u32 v118, v3, v72
	v_mad_u64_u32 v[72:73], s[12:13], v2, v72, 0
	v_mul_lo_u32 v119, v13, v74
	v_mad_u64_u32 v[74:75], s[12:13], v12, v74, 0
	v_add3_u32 v45, v45, v91, v90
	v_add3_u32 v47, v47, v92, v17
	v_mul_lo_u32 v17, v2, v94
	v_mul_lo_u32 v90, v12, v93
	v_mul_lo_u32 v91, v2, v97
	v_mul_lo_u32 v92, v12, v96
	v_mul_lo_u32 v93, v2, v101
	v_mul_lo_u32 v94, v12, v100
	v_mul_lo_u32 v96, v2, v105
	v_mul_lo_u32 v97, v12, v104
	v_mul_lo_u32 v100, v2, v109
	v_mul_lo_u32 v101, v12, v108
	v_mul_lo_u32 v104, v2, v113
	v_mul_lo_u32 v105, v12, v112
	v_mul_lo_u32 v108, v2, v117
	v_mul_lo_u32 v109, v12, v116
	v_lshl_add_u64 v[46:47], v[46:47], 2, v[18:19]
	v_add3_u32 v49, v49, v17, v95
	v_add3_u32 v51, v51, v90, v43
	v_add3_u32 v53, v53, v91, v98
	v_add3_u32 v55, v55, v92, v99
	v_add3_u32 v57, v57, v93, v102
	v_add3_u32 v59, v59, v94, v103
	v_add3_u32 v61, v61, v96, v106
	v_add3_u32 v63, v63, v97, v107
	v_add3_u32 v65, v65, v100, v110
	v_add3_u32 v67, v67, v101, v111
	v_add3_u32 v69, v69, v104, v114
	v_add3_u32 v71, v71, v105, v115
	v_add3_u32 v73, v73, v108, v118
	v_add3_u32 v75, v75, v109, v119
	v_lshl_add_u64 v[44:45], v[44:45], 2, v[18:19]
	v_lshl_add_u64 v[50:51], v[50:51], 2, v[18:19]
	v_lshl_add_u64 v[48:49], v[48:49], 2, v[18:19]
	v_lshl_add_u64 v[54:55], v[54:55], 2, v[18:19]
	v_lshl_add_u64 v[52:53], v[52:53], 2, v[18:19]
	v_lshl_add_u64 v[58:59], v[58:59], 2, v[18:19]
	v_lshl_add_u64 v[56:57], v[56:57], 2, v[18:19]
	v_lshl_add_u64 v[62:63], v[62:63], 2, v[18:19]
	v_lshl_add_u64 v[60:61], v[60:61], 2, v[18:19]
	v_lshl_add_u64 v[66:67], v[66:67], 2, v[18:19]
	v_lshl_add_u64 v[64:65], v[64:65], 2, v[18:19]
	v_lshl_add_u64 v[70:71], v[70:71], 2, v[18:19]
	v_lshl_add_u64 v[68:69], v[68:69], 2, v[18:19]
	v_lshl_add_u64 v[74:75], v[74:75], 2, v[18:19]
	v_lshl_add_u64 v[72:73], v[72:73], 2, v[18:19]
	global_load_dword v17, v[46:47], off
	global_load_dword v43, v[44:45], off
	global_load_dword v90, v[50:51], off
	global_load_dword v91, v[48:49], off
	global_load_dword v92, v[54:55], off
	global_load_dword v93, v[52:53], off
	global_load_dword v94, v[58:59], off
	global_load_dword v95, v[56:57], off
	global_load_dword v96, v[62:63], off
	global_load_dword v97, v[60:61], off
	global_load_dword v98, v[66:67], off
	global_load_dword v99, v[64:65], off
	global_load_dword v100, v[70:71], off
	global_load_dword v101, v[68:69], off
	global_load_dword v102, v[74:75], off
	global_load_dword v103, v[72:73], off
	s_add_i32 s4, s4, 16
	s_add_i32 s5, s5, 16
	s_add_i32 s11, s11, -16
	v_mad_u64_u32 v[44:45], s[12:13], v11, s1, v[6:7]
	s_cmp_lg_u32 s11, 0
	v_mad_u64_u32 v[46:47], s[12:13], v9, s1, v[6:7]
	v_mad_u64_u32 v[48:49], s[12:13], v77, s1, v[6:7]
	v_mad_u64_u32 v[50:51], s[12:13], v76, s1, v[6:7]
	v_mad_u64_u32 v[52:53], s[12:13], v79, s1, v[6:7]
	v_mad_u64_u32 v[54:55], s[12:13], v78, s1, v[6:7]
	v_mad_u64_u32 v[56:57], s[12:13], v81, s1, v[6:7]
	v_mad_u64_u32 v[58:59], s[12:13], v80, s1, v[6:7]
	v_mad_u64_u32 v[60:61], s[12:13], v83, s1, v[6:7]
	v_mad_u64_u32 v[62:63], s[12:13], v82, s1, v[6:7]
	v_mad_u64_u32 v[64:65], s[12:13], v85, s1, v[6:7]
	v_mad_u64_u32 v[66:67], s[12:13], v84, s1, v[6:7]
	v_mad_u64_u32 v[68:69], s[12:13], v87, s1, v[6:7]
	v_mad_u64_u32 v[70:71], s[12:13], v86, s1, v[6:7]
	v_mad_u64_u32 v[72:73], s[12:13], v89, s1, v[6:7]
	v_mad_u64_u32 v[74:75], s[12:13], v88, s1, v[6:7]
	s_waitcnt vmcnt(15)
	ds_write_b32 v44, v17
	s_waitcnt vmcnt(14)
	ds_write_b32 v46, v43
	s_waitcnt vmcnt(13)
	ds_write_b32 v48, v90
	s_waitcnt vmcnt(12)
	ds_write_b32 v50, v91
	s_waitcnt vmcnt(11)
	ds_write_b32 v52, v92
	s_waitcnt vmcnt(10)
	ds_write_b32 v54, v93
	s_waitcnt vmcnt(9)
	ds_write_b32 v56, v94
	s_waitcnt vmcnt(8)
	ds_write_b32 v58, v95
	s_waitcnt vmcnt(7)
	ds_write_b32 v60, v96
	s_waitcnt vmcnt(6)
	ds_write_b32 v62, v97
	s_waitcnt vmcnt(5)
	ds_write_b32 v64, v98
	s_waitcnt vmcnt(4)
	ds_write_b32 v66, v99
	s_waitcnt vmcnt(3)
	ds_write_b32 v68, v100
	s_waitcnt vmcnt(2)
	ds_write_b32 v70, v101
	s_waitcnt vmcnt(1)
	ds_write_b32 v72, v102
	s_waitcnt vmcnt(0)
	ds_write_b32 v74, v103
	s_cbranch_scc1 .LBB0_344
	s_waitcnt lgkmcnt(0)
	v_ashrrev_i32_e32 v17, 31, v16
	v_lshl_add_u64 v[2:3], v[16:17], 1, v[14:15]
	ds_read2_b32 v[16:17], v26 offset0:33 offset1:41
	ds_read2_b32 v[18:19], v26 offset1:8
	ds_read2_b32 v[44:45], v26 offset0:66 offset1:74
	ds_read2_b32 v[46:47], v26 offset0:99 offset1:107
	ds_read2_b32 v[48:49], v26 offset0:132 offset1:140
	ds_read2_b32 v[50:51], v26 offset0:165 offset1:173
	ds_read2_b32 v[52:53], v26 offset0:198 offset1:206
	ds_read2_b32 v[54:55], v26 offset0:231 offset1:239
	v_or_b32_e32 v7, v4, v25
	v_ashrrev_i32_e32 v9, 31, v4
	v_mov_b32_e32 v11, v5
	v_mul_lo_u32 v9, v9, v42
	v_mad_u64_u32 v[56:57], s[4:5], v7, v42, 0
	v_lshl_add_u64 v[2:3], v[2:3], 0, v[10:11]
	v_add_u32_e32 v57, v57, v9
	s_waitcnt lgkmcnt(6)
	v_cvt_pk_bf16_f32 v12, v18, v16
	s_waitcnt lgkmcnt(4)
	v_cvt_pk_bf16_f32 v13, v44, v46
	s_waitcnt lgkmcnt(2)
	v_cvt_pk_bf16_f32 v14, v48, v50
	s_waitcnt lgkmcnt(0)
	v_cvt_pk_bf16_f32 v15, v52, v54
	v_lshl_add_u64 v[56:57], v[56:57], 1, v[2:3]
	global_store_dwordx4 v[56:57], v[12:15], off sc1
	v_or_b32_e32 v7, v4, v27
	s_nop 0
	v_cvt_pk_bf16_f32 v12, v19, v17
	v_cvt_pk_bf16_f32 v13, v45, v47
	v_cvt_pk_bf16_f32 v14, v49, v51
	v_cvt_pk_bf16_f32 v15, v53, v55
	v_mad_u64_u32 v[16:17], s[4:5], v7, v42, 0
	ds_read2_b32 v[18:19], v26 offset0:16 offset1:24
	ds_read2_b32 v[44:45], v26 offset0:49 offset1:57
	ds_read2_b32 v[46:47], v26 offset0:82 offset1:90
	ds_read2_b32 v[48:49], v26 offset0:115 offset1:123
	ds_read2_b32 v[50:51], v26 offset0:148 offset1:156
	ds_read2_b32 v[52:53], v26 offset0:181 offset1:189
	ds_read2_b32 v[54:55], v26 offset0:214 offset1:222
	ds_read2_b32 v[56:57], v26 offset0:247 offset1:255
	v_add_u32_e32 v17, v17, v9
	v_lshl_add_u64 v[16:17], v[16:17], 1, v[2:3]
	v_or_b32_e32 v7, v4, v28
	global_store_dwordx4 v[16:17], v[12:15], off sc1
	v_mad_u64_u32 v[16:17], s[4:5], v7, v42, 0
	v_add_u32_e32 v17, v17, v9
	s_waitcnt lgkmcnt(6)
	v_cvt_pk_bf16_f32 v12, v18, v44
	s_waitcnt lgkmcnt(4)
	v_cvt_pk_bf16_f32 v13, v46, v48
	s_waitcnt lgkmcnt(2)
	v_cvt_pk_bf16_f32 v14, v50, v52
	s_waitcnt lgkmcnt(0)
	v_cvt_pk_bf16_f32 v15, v54, v56
	v_lshl_add_u64 v[16:17], v[16:17], 1, v[2:3]
	v_or_b32_e32 v4, v4, v29
	global_store_dwordx4 v[16:17], v[12:15], off sc1
	v_mad_u64_u32 v[16:17], s[4:5], v4, v42, 0
	v_add_u32_e32 v17, v17, v9
	v_cvt_pk_bf16_f32 v12, v19, v45
	v_cvt_pk_bf16_f32 v13, v47, v49
	v_cvt_pk_bf16_f32 v14, v51, v53
	v_cvt_pk_bf16_f32 v15, v55, v57
	v_lshl_add_u64 v[2:3], v[16:17], 1, v[2:3]
	global_store_dwordx4 v[2:3], v[12:15], off sc1
	s_waitcnt lgkmcnt(0)
	s_branch .LBB0_329

.LBB0_373:
	s_or_b64 exec, exec, s[12:13]
	s_waitcnt lgkmcnt(0)
	s_barrier
	s_and_saveexec_b64 s[12:13], s[4:5]
	s_cbranch_execz .LBB0_349
	ds_read2st64_b32 v[32:33], v194 offset1:1
	ds_read2st64_b32 v[40:41], v194 offset0:2 offset1:3
	ds_read2st64_b32 v[44:45], v194 offset0:4 offset1:5
	ds_read2st64_b32 v[46:47], v194 offset0:6 offset1:7
	s_mov_b32 s41, s15
	s_waitcnt lgkmcnt(3)
	v_pk_fma_f32 v[30:31], v[150:151], v[32:33], v[30:31] neg_lo:[1,0,0] neg_hi:[1,0,0]
	s_waitcnt lgkmcnt(2)
	v_pk_fma_f32 v[32:33], v[150:151], v[40:41], v[28:29] neg_lo:[1,0,0] neg_hi:[1,0,0]
	v_mul_f32_e32 v28, v31, v31
	v_pk_fma_f32 v[28:29], v[30:31], v[30:31], v[28:29] op_sel_hi:[1,1,0]
	v_mul_f32_e32 v40, v33, v33
	v_pk_fma_f32 v[28:29], v[32:33], v[32:33], v[28:29]
	s_waitcnt lgkmcnt(0)
	v_pk_fma_f32 v[38:39], v[150:151], v[46:47], v[38:39] neg_lo:[1,0,0] neg_hi:[1,0,0]
	ds_read2st64_b32 v[46:47], v194 offset0:8 offset1:9
	v_pk_add_f32 v[40:41], v[28:29], v[40:41] op_sel_hi:[1,0]
	v_pk_fma_f32 v[28:29], v[150:151], v[44:45], v[116:117] neg_lo:[1,0,0] neg_hi:[1,0,0]
	ds_read2st64_b32 v[50:51], v194 offset0:10 offset1:11
	ds_read2st64_b32 v[54:55], v194 offset0:12 offset1:13
	ds_read2st64_b32 v[58:59], v194 offset0:14 offset1:15
	v_pk_fma_f32 v[40:41], v[28:29], v[28:29], v[40:41]
	v_mul_f32_e32 v44, v29, v29
	v_pk_add_f32 v[40:41], v[40:41], v[44:45] op_sel_hi:[1,0]
	v_mul_f32_e32 v44, v39, v39
	v_pk_fma_f32 v[40:41], v[38:39], v[38:39], v[40:41]
	s_nop 0
	v_pk_add_f32 v[44:45], v[40:41], v[44:45] op_sel_hi:[1,0]
	s_waitcnt lgkmcnt(3)
	v_pk_fma_f32 v[40:41], v[150:151], v[46:47], v[114:115] neg_lo:[1,0,0] neg_hi:[1,0,0]
	s_nop 0
	v_pk_fma_f32 v[44:45], v[40:41], v[40:41], v[44:45]
	v_mul_f32_e32 v46, v41, v41
	v_pk_add_f32 v[46:47], v[44:45], v[46:47] op_sel_hi:[1,0]
	s_waitcnt lgkmcnt(2)
	v_pk_fma_f32 v[44:45], v[150:151], v[50:51], v[42:43] neg_lo:[1,0,0] neg_hi:[1,0,0]
	s_nop 0
	v_pk_fma_f32 v[42:43], v[44:45], v[44:45], v[46:47]
	v_mul_f32_e32 v46, v45, v45
	v_pk_add_f32 v[46:47], v[42:43], v[46:47] op_sel_hi:[1,0]
	s_waitcnt lgkmcnt(1)
	v_pk_fma_f32 v[42:43], v[150:151], v[54:55], v[112:113] neg_lo:[1,0,0] neg_hi:[1,0,0]
	s_nop 0
	v_pk_fma_f32 v[46:47], v[42:43], v[42:43], v[46:47]
	v_mul_f32_e32 v50, v43, v43
	v_pk_add_f32 v[50:51], v[46:47], v[50:51] op_sel_hi:[1,0]
	s_waitcnt lgkmcnt(0)
	v_pk_fma_f32 v[46:47], v[150:151], v[58:59], v[94:95] neg_lo:[1,0,0] neg_hi:[1,0,0]
	ds_read2st64_b32 v[58:59], v194 offset0:16 offset1:17
	ds_read2st64_b32 v[64:65], v194 offset0:18 offset1:19
	ds_read2st64_b32 v[66:67], v194 offset0:20 offset1:21
	ds_read2st64_b32 v[68:69], v194 offset0:22 offset1:23
	v_pk_fma_f32 v[50:51], v[46:47], v[46:47], v[50:51]
	v_mul_f32_e32 v54, v47, v47
	v_pk_add_f32 v[54:55], v[50:51], v[54:55] op_sel_hi:[1,0]
	s_waitcnt lgkmcnt(3)
	v_pk_fma_f32 v[50:51], v[150:151], v[58:59], v[92:93] neg_lo:[1,0,0] neg_hi:[1,0,0]
	s_waitcnt lgkmcnt(0)
	v_pk_fma_f32 v[62:63], v[150:151], v[68:69], v[62:63] neg_lo:[1,0,0] neg_hi:[1,0,0]
	v_pk_fma_f32 v[54:55], v[50:51], v[50:51], v[54:55]
	v_mul_f32_e32 v58, v51, v51
	v_pk_add_f32 v[58:59], v[54:55], v[58:59] op_sel_hi:[1,0]
	v_pk_fma_f32 v[54:55], v[150:151], v[64:65], v[88:89] neg_lo:[1,0,0] neg_hi:[1,0,0]
	ds_read2st64_b32 v[68:69], v194 offset0:24 offset1:25
	v_pk_fma_f32 v[58:59], v[54:55], v[54:55], v[58:59]
	v_mul_f32_e32 v64, v55, v55
	v_pk_add_f32 v[64:65], v[58:59], v[64:65] op_sel_hi:[1,0]
	v_pk_fma_f32 v[58:59], v[150:151], v[66:67], v[90:91] neg_lo:[1,0,0] neg_hi:[1,0,0]
	ds_read2st64_b32 v[70:71], v194 offset0:26 offset1:27
	ds_read2st64_b32 v[72:73], v194 offset0:28 offset1:29
	ds_read2st64_b32 v[74:75], v194 offset0:30 offset1:31
	v_pk_fma_f32 v[64:65], v[58:59], v[58:59], v[64:65]
	v_mul_f32_e32 v66, v59, v59
	v_pk_add_f32 v[64:65], v[64:65], v[66:67] op_sel_hi:[1,0]
	v_mul_f32_e32 v66, v63, v63
	v_pk_fma_f32 v[64:65], v[62:63], v[62:63], v[64:65]
	s_nop 0
	v_pk_add_f32 v[66:67], v[64:65], v[66:67] op_sel_hi:[1,0]
	s_waitcnt lgkmcnt(3)
	v_pk_fma_f32 v[64:65], v[150:151], v[68:69], v[14:15] neg_lo:[1,0,0] neg_hi:[1,0,0]
	s_waitcnt lgkmcnt(1)
	v_pk_fma_f32 v[68:69], v[150:151], v[72:73], v[12:13] neg_lo:[1,0,0] neg_hi:[1,0,0]
	v_pk_fma_f32 v[14:15], v[64:65], v[64:65], v[66:67]
	v_mul_f32_e32 v66, v65, v65
	v_pk_add_f32 v[14:15], v[14:15], v[66:67] op_sel_hi:[1,0]
	v_pk_fma_f32 v[66:67], v[150:151], v[70:71], v[8:9] neg_lo:[1,0,0] neg_hi:[1,0,0]
	v_mul_f32_e32 v12, v69, v69
	v_pk_fma_f32 v[8:9], v[66:67], v[66:67], v[14:15]
	v_mul_f32_e32 v14, v67, v67
	v_pk_add_f32 v[8:9], v[8:9], v[14:15] op_sel_hi:[1,0]
	s_waitcnt lgkmcnt(0)
	v_pk_fma_f32 v[70:71], v[150:151], v[74:75], v[10:11] neg_lo:[1,0,0] neg_hi:[1,0,0]
	v_pk_fma_f32 v[8:9], v[68:69], v[68:69], v[8:9]
	v_mul_f32_e32 v10, v71, v71
	v_pk_add_f32 v[8:9], v[8:9], v[12:13] op_sel_hi:[1,0]
	ds_read2st64_b32 v[72:73], v194 offset0:32 offset1:33
	v_pk_fma_f32 v[8:9], v[70:71], v[70:71], v[8:9]
	s_waitcnt lgkmcnt(0)
	v_pk_fma_f32 v[72:73], v[150:151], v[72:73], v[86:87] neg_lo:[1,0,0] neg_hi:[1,0,0]
	v_pk_add_f32 v[8:9], v[8:9], v[10:11] op_sel_hi:[1,0]
	v_mul_f32_e32 v86, v73, v73
	v_mov_b32_e32 v9, v8
	s_nop 1
	v_permlane16_swap_b32_e32 v8, v9
	v_add_f32_e32 v89, v8, v9
	global_load_dwordx4 v[12:15], v[158:159], off
	global_load_dwordx4 v[8:11], v[158:159], off offset:64
	ds_read2st64_b32 v[74:75], v194 offset0:34 offset1:35
	ds_read2st64_b32 v[76:77], v194 offset0:36 offset1:37
	ds_read2st64_b32 v[78:79], v194 offset0:38 offset1:39
	v_pk_fma_f32 v[86:87], v[72:73], v[72:73], v[86:87] op_sel_hi:[1,1,0]
	v_mov_b32_e32 v91, v89
	s_waitcnt lgkmcnt(2)
	v_pk_fma_f32 v[74:75], v[150:151], v[74:75], v[82:83] neg_lo:[1,0,0] neg_hi:[1,0,0]
	s_waitcnt lgkmcnt(1)
	v_pk_fma_f32 v[76:77], v[150:151], v[76:77], v[84:85] neg_lo:[1,0,0] neg_hi:[1,0,0]
	v_pk_fma_f32 v[82:83], v[74:75], v[74:75], v[86:87]
	v_mul_f32_e32 v86, v75, v75
	v_pk_add_f32 v[82:83], v[82:83], v[86:87] op_sel_hi:[1,0]
	v_mul_f32_e32 v84, v77, v77
	v_pk_fma_f32 v[82:83], v[76:77], v[76:77], v[82:83]
	s_waitcnt lgkmcnt(0)
	v_pk_fma_f32 v[78:79], v[150:151], v[78:79], v[80:81] neg_lo:[1,0,0] neg_hi:[1,0,0]
	v_pk_add_f32 v[82:83], v[82:83], v[84:85] op_sel_hi:[1,0]
	ds_read2st64_b32 v[84:85], v194 offset0:40 offset1:41
	v_pk_fma_f32 v[80:81], v[78:79], v[78:79], v[82:83]
	v_mul_f32_e32 v82, v79, v79
	v_pk_add_f32 v[80:81], v[80:81], v[82:83] op_sel_hi:[1,0]
	ds_read2st64_b32 v[82:83], v194 offset0:42 offset1:43
	ds_read2st64_b32 v[86:87], v194 offset0:44 offset1:45
	ds_read2st64_b32 v[92:93], v194 offset0:46 offset1:47
	s_waitcnt lgkmcnt(3)
	v_pk_fma_f32 v[60:61], v[150:151], v[84:85], v[60:61] neg_lo:[1,0,0] neg_hi:[1,0,0]
	v_permlane32_swap_b32_e32 v89, v91
	v_pk_fma_f32 v[80:81], v[60:61], v[60:61], v[80:81]
	v_mul_f32_e32 v84, v61, v61
	v_pk_add_f32 v[80:81], v[80:81], v[84:85] op_sel_hi:[1,0]
	s_waitcnt lgkmcnt(2)
	v_pk_fma_f32 v[52:53], v[150:151], v[82:83], v[52:53] neg_lo:[1,0,0] neg_hi:[1,0,0]
	s_waitcnt lgkmcnt(1)
	v_pk_fma_f32 v[56:57], v[150:151], v[86:87], v[56:57] neg_lo:[1,0,0] neg_hi:[1,0,0]
	v_pk_fma_f32 v[80:81], v[52:53], v[52:53], v[80:81]
	v_mul_f32_e32 v82, v53, v53
	v_pk_add_f32 v[80:81], v[80:81], v[82:83] op_sel_hi:[1,0]
	ds_read2st64_b32 v[84:85], v194 offset0:48 offset1:49
	v_pk_fma_f32 v[80:81], v[56:57], v[56:57], v[80:81]
	v_mul_f32_e32 v82, v57, v57
	v_pk_add_f32 v[80:81], v[80:81], v[82:83] op_sel_hi:[1,0]
	s_waitcnt lgkmcnt(1)
	v_pk_fma_f32 v[48:49], v[150:151], v[92:93], v[48:49] neg_lo:[1,0,0] neg_hi:[1,0,0]
	s_waitcnt lgkmcnt(0)
	v_pk_fma_f32 v[36:37], v[150:151], v[84:85], v[36:37] neg_lo:[1,0,0] neg_hi:[1,0,0]
	v_pk_fma_f32 v[80:81], v[48:49], v[48:49], v[80:81]
	v_mul_f32_e32 v82, v49, v49
	v_pk_add_f32 v[80:81], v[80:81], v[82:83] op_sel_hi:[1,0]
	ds_read2st64_b32 v[82:83], v194 offset0:50 offset1:51
	ds_read2st64_b32 v[86:87], v194 offset0:52 offset1:53
	ds_read2st64_b32 v[92:93], v194 offset0:54 offset1:55
	v_pk_fma_f32 v[80:81], v[36:37], v[36:37], v[80:81]
	v_mul_f32_e32 v84, v37, v37
	v_pk_add_f32 v[80:81], v[80:81], v[84:85] op_sel_hi:[1,0]
	s_waitcnt lgkmcnt(2)
	v_pk_fma_f32 v[26:27], v[150:151], v[82:83], v[26:27] neg_lo:[1,0,0] neg_hi:[1,0,0]
	s_waitcnt lgkmcnt(1)
	v_pk_fma_f32 v[34:35], v[150:151], v[86:87], v[34:35] neg_lo:[1,0,0] neg_hi:[1,0,0]
	v_pk_fma_f32 v[80:81], v[26:27], v[26:27], v[80:81]
	v_mul_f32_e32 v82, v27, v27
	v_pk_add_f32 v[80:81], v[80:81], v[82:83] op_sel_hi:[1,0]
	ds_read2st64_b32 v[84:85], v194 offset0:56 offset1:57
	v_pk_fma_f32 v[80:81], v[34:35], v[34:35], v[80:81]
	v_mul_f32_e32 v82, v35, v35
	v_pk_add_f32 v[80:81], v[80:81], v[82:83] op_sel_hi:[1,0]
	s_waitcnt lgkmcnt(1)
	v_pk_fma_f32 v[24:25], v[150:151], v[92:93], v[24:25] neg_lo:[1,0,0] neg_hi:[1,0,0]
	s_waitcnt lgkmcnt(0)
	v_pk_fma_f32 v[22:23], v[150:151], v[84:85], v[22:23] neg_lo:[1,0,0] neg_hi:[1,0,0]
	v_pk_fma_f32 v[80:81], v[24:25], v[24:25], v[80:81]
	v_mul_f32_e32 v82, v25, v25
	v_pk_add_f32 v[80:81], v[80:81], v[82:83] op_sel_hi:[1,0]
	ds_read2st64_b32 v[82:83], v194 offset0:58 offset1:59
	ds_read2st64_b32 v[86:87], v194 offset0:60 offset1:61
	ds_read2st64_b32 v[92:93], v194 offset0:62 offset1:63
	v_pk_fma_f32 v[80:81], v[22:23], v[22:23], v[80:81]
	v_mul_f32_e32 v84, v23, v23
	v_pk_add_f32 v[80:81], v[80:81], v[84:85] op_sel_hi:[1,0]
	s_waitcnt lgkmcnt(2)
	v_pk_fma_f32 v[18:19], v[150:151], v[82:83], v[18:19] neg_lo:[1,0,0] neg_hi:[1,0,0]
	s_waitcnt lgkmcnt(1)
	v_pk_fma_f32 v[20:21], v[150:151], v[86:87], v[20:21] neg_lo:[1,0,0] neg_hi:[1,0,0]
	v_pk_fma_f32 v[80:81], v[18:19], v[18:19], v[80:81]
	v_mul_f32_e32 v82, v19, v19
	v_pk_add_f32 v[80:81], v[80:81], v[82:83] op_sel_hi:[1,0]
	v_mul_f32_e32 v82, v21, v21
	v_pk_fma_f32 v[80:81], v[20:21], v[20:21], v[80:81]
	s_waitcnt lgkmcnt(0)
	v_pk_fma_f32 v[16:17], v[150:151], v[92:93], v[16:17] neg_lo:[1,0,0] neg_hi:[1,0,0]
	v_pk_add_f32 v[80:81], v[80:81], v[82:83] op_sel_hi:[1,0]
	v_mul_f32_e32 v82, v17, v17
	v_pk_fma_f32 v[80:81], v[16:17], v[16:17], v[80:81]
	s_nop 0
	v_pk_add_f32 v[80:81], v[80:81], v[82:83] op_sel_hi:[1,0]
	s_nop 0
	v_mov_b32_e32 v81, v80
	s_nop 1
	v_permlane16_swap_b32_e32 v80, v81
	v_add_f32_e32 v88, v80, v81
	v_mov_b32_e32 v90, v88
	s_nop 1
	v_permlane32_swap_b32_e32 v88, v90
	v_pk_add_f32 v[80:81], v[88:89], v[90:91]
	s_nop 0
	v_pk_fma_f32 v[80:81], v[80:81], s[22:23], v[160:161] op_sel_hi:[1,0,0]
	s_nop 0
	v_mul_f32_e32 v82, 0x4b800000, v81
	v_cmp_gt_f32_e32 vcc, s23, v81
	s_nop 1
	v_cndmask_b32_e32 v81, v81, v82, vcc
	v_rsq_f32_e32 v81, v81
	v_lshl_add_u64 v[82:83], s[40:41], 1, v[156:157]
	v_lshl_add_u64 v[84:85], v[82:83], 0, v[164:165]
	v_mul_f32_e32 v86, 0x45800000, v81
	v_cndmask_b32_e32 v81, v81, v86, vcc
	v_mul_f32_e32 v86, 0x3f4ccccd, v81
	v_pk_mul_f32 v[30:31], v[30:31], v[86:87] op_sel_hi:[1,0]
	v_pk_mul_f32 v[32:33], v[32:33], v[86:87] op_sel_hi:[1,0]
	s_waitcnt vmcnt(1)
	v_pk_mul_f32 v[12:13], v[12:13], v[30:31]
	v_pk_mul_f32 v[14:15], v[14:15], v[32:33]
	v_cvt_pk_bf16_f32 v12, v12, v13
	v_cvt_pk_bf16_f32 v13, v14, v15
	v_pk_mul_f32 v[14:15], v[28:29], v[86:87] op_sel_hi:[1,0]
	v_pk_mul_f32 v[28:29], v[38:39], v[86:87] op_sel_hi:[1,0]
	s_waitcnt vmcnt(0)
	v_pk_mul_f32 v[8:9], v[8:9], v[14:15]
	v_pk_mul_f32 v[10:11], v[10:11], v[28:29]
	v_cvt_pk_bf16_f32 v14, v8, v9
	v_cvt_pk_bf16_f32 v15, v10, v11
	s_nop 0
	v_permlane16_swap_b32_e32 v12, v14
	v_permlane16_swap_b32_e32 v13, v15
	global_store_dwordx4 v[84:85], v[12:15], off sc1
	global_load_dwordx4 v[8:11], v[158:159], off offset:128
	s_nop 0
	global_load_dwordx4 v[12:15], v[158:159], off offset:192
	v_pk_mul_f32 v[28:29], v[40:41], v[86:87] op_sel_hi:[1,0]
	v_pk_mul_f32 v[30:31], v[44:45], v[86:87] op_sel_hi:[1,0]
	v_pk_mul_f32 v[32:33], v[58:59], v[86:87] op_sel_hi:[1,0]
	v_pk_mul_f32 v[38:39], v[62:63], v[86:87] op_sel_hi:[1,0]
	v_cmp_gt_f32_e32 vcc, s23, v80
	s_waitcnt vmcnt(1)
	v_pk_mul_f32 v[10:11], v[10:11], v[30:31]
	v_pk_mul_f32 v[8:9], v[8:9], v[28:29]
	v_pk_mul_f32 v[28:29], v[46:47], v[86:87] op_sel_hi:[1,0]
	v_cvt_pk_bf16_f32 v8, v8, v9
	v_cvt_pk_bf16_f32 v9, v10, v11
	v_pk_mul_f32 v[10:11], v[42:43], v[86:87] op_sel_hi:[1,0]
	s_waitcnt vmcnt(0)
	v_pk_mul_f32 v[14:15], v[14:15], v[28:29]
	v_pk_mul_f32 v[10:11], v[12:13], v[10:11]
	v_pk_mul_f32 v[28:29], v[50:51], v[86:87] op_sel_hi:[1,0]
	v_cvt_pk_bf16_f32 v10, v10, v11
	v_cvt_pk_bf16_f32 v11, v14, v15
	s_nop 0
	v_permlane16_swap_b32_e32 v8, v10
	v_permlane16_swap_b32_e32 v9, v11
	global_store_dwordx4 v[84:85], v[8:11], off offset:64 sc1
	global_load_dwordx4 v[8:11], v[158:159], off offset:256
	s_nop 0
	global_load_dwordx4 v[12:15], v[158:159], off offset:320
	v_pk_mul_f32 v[30:31], v[54:55], v[86:87] op_sel_hi:[1,0]
	s_waitcnt vmcnt(1)
	v_pk_mul_f32 v[8:9], v[8:9], v[28:29]
	v_pk_mul_f32 v[10:11], v[10:11], v[30:31]
	s_waitcnt vmcnt(0)
	v_pk_mul_f32 v[14:15], v[14:15], v[38:39]
	v_pk_mul_f32 v[12:13], v[12:13], v[32:33]
	v_cvt_pk_bf16_f32 v8, v8, v9
	v_cvt_pk_bf16_f32 v9, v10, v11
	v_cvt_pk_bf16_f32 v10, v12, v13
	v_cvt_pk_bf16_f32 v11, v14, v15
	s_nop 0
	v_permlane16_swap_b32_e32 v8, v10
	v_permlane16_swap_b32_e32 v9, v11
	global_store_dwordx4 v[84:85], v[8:11], off offset:128 sc1
	global_load_dwordx4 v[8:11], v[158:159], off offset:384
	s_nop 0
	global_load_dwordx4 v[12:15], v[158:159], off offset:448
	v_pk_mul_f32 v[28:29], v[64:65], v[86:87] op_sel_hi:[1,0]
	v_pk_mul_f32 v[30:31], v[66:67], v[86:87] op_sel_hi:[1,0]
	v_pk_mul_f32 v[32:33], v[68:69], v[86:87] op_sel_hi:[1,0]
	v_pk_mul_f32 v[38:39], v[70:71], v[86:87] op_sel_hi:[1,0]
	s_waitcnt vmcnt(1)
	v_pk_mul_f32 v[10:11], v[30:31], v[10:11]
	v_pk_mul_f32 v[8:9], v[28:29], v[8:9]
	s_waitcnt vmcnt(0)
	v_pk_mul_f32 v[14:15], v[38:39], v[14:15]
	v_pk_mul_f32 v[12:13], v[32:33], v[12:13]
	v_cvt_pk_bf16_f32 v8, v8, v9
	v_cvt_pk_bf16_f32 v9, v10, v11
	v_cvt_pk_bf16_f32 v10, v12, v13
	v_cvt_pk_bf16_f32 v11, v14, v15
	s_nop 0
	v_permlane16_swap_b32_e32 v8, v10
	v_permlane16_swap_b32_e32 v9, v11
	global_store_dwordx4 v[84:85], v[8:11], off offset:192 sc1
	global_load_dwordx4 v[8:11], v[158:159], off
	s_nop 0
	global_load_dwordx4 v[12:15], v[158:159], off offset:64
	v_mul_f32_e32 v28, 0x4b800000, v80
	v_cndmask_b32_e32 v28, v80, v28, vcc
	v_rsq_f32_e32 v30, v28
	v_lshl_add_u64 v[28:29], v[82:83], 0, v[162:163]
	v_mul_f32_e32 v31, 0x45800000, v30
	v_cndmask_b32_e32 v30, v30, v31, vcc
	v_mul_f32_e32 v30, 0x3f4ccccd, v30
	v_pk_mul_f32 v[32:33], v[72:73], v[30:31] op_sel_hi:[1,0]
	v_pk_mul_f32 v[38:39], v[74:75], v[30:31] op_sel_hi:[1,0]
	v_pk_mul_f32 v[40:41], v[76:77], v[30:31] op_sel_hi:[1,0]
	v_pk_mul_f32 v[42:43], v[78:79], v[30:31] op_sel_hi:[1,0]
	v_pk_mul_f32 v[26:27], v[26:27], v[30:31] op_sel_hi:[1,0]
	v_pk_mul_f32 v[34:35], v[34:35], v[30:31] op_sel_hi:[1,0]
	v_pk_mul_f32 v[24:25], v[24:25], v[30:31] op_sel_hi:[1,0]
	v_pk_mul_f32 v[22:23], v[22:23], v[30:31] op_sel_hi:[1,0]
	v_pk_mul_f32 v[18:19], v[18:19], v[30:31] op_sel_hi:[1,0]
	v_pk_mul_f32 v[20:21], v[20:21], v[30:31] op_sel_hi:[1,0]
	v_pk_mul_f32 v[16:17], v[16:17], v[30:31] op_sel_hi:[1,0]
	s_waitcnt vmcnt(1)
	v_pk_mul_f32 v[10:11], v[10:11], v[38:39]
	v_pk_mul_f32 v[8:9], v[8:9], v[32:33]
	s_waitcnt vmcnt(0)
	v_pk_mul_f32 v[14:15], v[14:15], v[42:43]
	v_pk_mul_f32 v[12:13], v[12:13], v[40:41]
	v_cvt_pk_bf16_f32 v8, v8, v9
	v_cvt_pk_bf16_f32 v9, v10, v11
	v_cvt_pk_bf16_f32 v10, v12, v13
	v_cvt_pk_bf16_f32 v11, v14, v15
	s_nop 0
	v_permlane16_swap_b32_e32 v8, v10
	v_permlane16_swap_b32_e32 v9, v11
	global_store_dwordx4 v[28:29], v[8:11], off sc1
	global_load_dwordx4 v[8:11], v[158:159], off offset:128
	s_nop 0
	global_load_dwordx4 v[12:15], v[158:159], off offset:192
	v_pk_mul_f32 v[32:33], v[60:61], v[30:31] op_sel_hi:[1,0]
	v_pk_mul_f32 v[38:39], v[52:53], v[30:31] op_sel_hi:[1,0]
	v_pk_mul_f32 v[40:41], v[56:57], v[30:31] op_sel_hi:[1,0]
	v_pk_mul_f32 v[42:43], v[48:49], v[30:31] op_sel_hi:[1,0]
	s_waitcnt vmcnt(1)
	v_pk_mul_f32 v[10:11], v[10:11], v[38:39]
	v_pk_mul_f32 v[8:9], v[8:9], v[32:33]
	s_waitcnt vmcnt(0)
	v_pk_mul_f32 v[14:15], v[14:15], v[42:43]
	v_pk_mul_f32 v[12:13], v[12:13], v[40:41]
	v_cvt_pk_bf16_f32 v8, v8, v9
	v_cvt_pk_bf16_f32 v9, v10, v11
	v_cvt_pk_bf16_f32 v10, v12, v13
	v_cvt_pk_bf16_f32 v11, v14, v15
	s_nop 0
	v_permlane16_swap_b32_e32 v8, v10
	v_permlane16_swap_b32_e32 v9, v11
	global_store_dwordx4 v[28:29], v[8:11], off offset:64 sc1
	global_load_dwordx4 v[8:11], v[158:159], off offset:256
	s_nop 0
	global_load_dwordx4 v[12:15], v[158:159], off offset:320
	v_pk_mul_f32 v[32:33], v[36:37], v[30:31] op_sel_hi:[1,0]
	s_waitcnt vmcnt(1)
	v_pk_mul_f32 v[10:11], v[10:11], v[26:27]
	v_pk_mul_f32 v[8:9], v[8:9], v[32:33]
	s_waitcnt vmcnt(0)
	v_pk_mul_f32 v[14:15], v[14:15], v[24:25]
	v_pk_mul_f32 v[12:13], v[12:13], v[34:35]
	v_cvt_pk_bf16_f32 v8, v8, v9
	v_cvt_pk_bf16_f32 v9, v10, v11
	v_cvt_pk_bf16_f32 v10, v12, v13
	v_cvt_pk_bf16_f32 v11, v14, v15
	s_nop 0
	v_permlane16_swap_b32_e32 v8, v10
	v_permlane16_swap_b32_e32 v9, v11
	global_store_dwordx4 v[28:29], v[8:11], off offset:128 sc1
	global_load_dwordx4 v[8:11], v[158:159], off offset:384
	s_nop 0
	global_load_dwordx4 v[12:15], v[158:159], off offset:448
	s_waitcnt vmcnt(1)
	v_pk_mul_f32 v[10:11], v[18:19], v[10:11]
	v_pk_mul_f32 v[8:9], v[22:23], v[8:9]
	s_waitcnt vmcnt(0)
	v_pk_mul_f32 v[14:15], v[16:17], v[14:15]
	v_pk_mul_f32 v[12:13], v[20:21], v[12:13]
	v_cvt_pk_bf16_f32 v8, v8, v9
	v_cvt_pk_bf16_f32 v9, v10, v11
	v_cvt_pk_bf16_f32 v10, v12, v13
	v_cvt_pk_bf16_f32 v11, v14, v15
	s_nop 0
	v_permlane16_swap_b32_e32 v8, v10
	v_permlane16_swap_b32_e32 v9, v11
	global_store_dwordx4 v[28:29], v[8:11], off offset:192 sc1
	s_branch .LBB0_349

.LBB0_393:
	s_lshl_b32 s9, s5, 1
	s_lshl_b32 s11, s4, 1
	v_or_b32_e32 v9, s9, v1
	v_or_b32_e32 v11, s11, v0
	s_add_i32 s12, s9, 4
	s_add_i32 s13, s11, 4
	s_add_i32 s14, s9, 8
	s_add_i32 s15, s11, 8
	s_add_i32 s16, s9, 12
	s_add_i32 s17, s11, 12
	s_add_i32 s18, s9, 16
	s_add_i32 s19, s11, 16
	s_add_i32 s20, s9, 20
	s_add_i32 s21, s11, 20
	s_add_i32 s22, s9, 24
	s_add_i32 s23, s11, 24
	s_add_i32 s9, s9, 28
	s_add_i32 s11, s11, 28
	v_add_u32_e32 v17, v9, v7
	v_add_u32_e32 v40, v11, v16
	v_or_b32_e32 v70, s12, v1
	v_or_b32_e32 v71, s13, v0
	v_or_b32_e32 v72, s14, v1
	v_or_b32_e32 v73, s15, v0
	v_or_b32_e32 v74, s16, v1
	v_or_b32_e32 v75, s17, v0
	v_or_b32_e32 v76, s18, v1
	v_or_b32_e32 v77, s19, v0
	v_or_b32_e32 v78, s20, v1
	v_or_b32_e32 v79, s21, v0
	v_or_b32_e32 v80, s22, v1
	v_or_b32_e32 v81, s23, v0
	v_or_b32_e32 v82, s9, v1
	v_or_b32_e32 v83, s11, v0
	v_ashrrev_i32_e32 v42, 31, v40
	v_ashrrev_i32_e32 v43, 31, v17
	v_add_u32_e32 v44, v70, v7
	v_add_u32_e32 v45, v71, v16
	v_add_u32_e32 v46, v72, v7
	v_add_u32_e32 v48, v73, v16
	v_add_u32_e32 v50, v74, v7
	v_add_u32_e32 v52, v75, v16
	v_add_u32_e32 v54, v76, v7
	v_add_u32_e32 v56, v77, v16
	v_add_u32_e32 v58, v78, v7
	v_add_u32_e32 v60, v79, v16
	v_add_u32_e32 v62, v80, v7
	v_add_u32_e32 v64, v81, v16
	v_add_u32_e32 v66, v82, v7
	v_add_u32_e32 v68, v83, v16
	v_mul_lo_u32 v84, v3, v17
	v_mad_u64_u32 v[38:39], s[12:13], v2, v17, 0
	v_mul_lo_u32 v17, v13, v40
	v_mad_u64_u32 v[40:41], s[12:13], v12, v40, 0
	v_mul_lo_u32 v85, v2, v43
	v_mul_lo_u32 v86, v12, v42
	v_ashrrev_i32_e32 v87, 31, v45
	v_ashrrev_i32_e32 v88, 31, v44
	v_ashrrev_i32_e32 v91, 31, v48
	v_ashrrev_i32_e32 v92, 31, v46
	v_ashrrev_i32_e32 v95, 31, v52
	v_ashrrev_i32_e32 v96, 31, v50
	v_ashrrev_i32_e32 v99, 31, v56
	v_ashrrev_i32_e32 v100, 31, v54
	v_ashrrev_i32_e32 v103, 31, v60
	v_ashrrev_i32_e32 v104, 31, v58
	v_ashrrev_i32_e32 v107, 31, v64
	v_ashrrev_i32_e32 v108, 31, v62
	v_ashrrev_i32_e32 v111, 31, v68
	v_ashrrev_i32_e32 v112, 31, v66
	v_mul_lo_u32 v89, v3, v44
	v_mad_u64_u32 v[42:43], s[12:13], v2, v44, 0
	v_mul_lo_u32 v90, v13, v45
	v_mad_u64_u32 v[44:45], s[12:13], v12, v45, 0
	v_mul_lo_u32 v93, v3, v46
	v_mad_u64_u32 v[46:47], s[12:13], v2, v46, 0
	v_mul_lo_u32 v94, v13, v48
	v_mad_u64_u32 v[48:49], s[12:13], v12, v48, 0
	v_mul_lo_u32 v97, v3, v50
	v_mad_u64_u32 v[50:51], s[12:13], v2, v50, 0
	v_mul_lo_u32 v98, v13, v52
	v_mad_u64_u32 v[52:53], s[12:13], v12, v52, 0
	v_mul_lo_u32 v101, v3, v54
	v_mad_u64_u32 v[54:55], s[12:13], v2, v54, 0
	v_mul_lo_u32 v102, v13, v56
	v_mad_u64_u32 v[56:57], s[12:13], v12, v56, 0
	v_mul_lo_u32 v105, v3, v58
	v_mad_u64_u32 v[58:59], s[12:13], v2, v58, 0
	v_mul_lo_u32 v106, v13, v60
	v_mad_u64_u32 v[60:61], s[12:13], v12, v60, 0
	v_mul_lo_u32 v109, v3, v62
	v_mad_u64_u32 v[62:63], s[12:13], v2, v62, 0
	v_mul_lo_u32 v110, v13, v64
	v_mad_u64_u32 v[64:65], s[12:13], v12, v64, 0
	v_mul_lo_u32 v113, v3, v66
	v_mad_u64_u32 v[66:67], s[12:13], v2, v66, 0
	v_mul_lo_u32 v114, v13, v68
	v_mad_u64_u32 v[68:69], s[12:13], v12, v68, 0
	v_add3_u32 v39, v39, v85, v84
	v_add3_u32 v41, v41, v86, v17
	v_mul_lo_u32 v17, v2, v88
	v_mul_lo_u32 v84, v12, v87
	v_mul_lo_u32 v85, v2, v92
	v_mul_lo_u32 v86, v12, v91
	v_mul_lo_u32 v87, v2, v96
	v_mul_lo_u32 v88, v12, v95
	v_mul_lo_u32 v91, v2, v100
	v_mul_lo_u32 v92, v12, v99
	v_mul_lo_u32 v95, v2, v104
	v_mul_lo_u32 v96, v12, v103
	v_mul_lo_u32 v99, v2, v108
	v_mul_lo_u32 v100, v12, v107
	v_mul_lo_u32 v103, v2, v112
	v_mul_lo_u32 v104, v12, v111
	v_lshl_add_u64 v[40:41], v[40:41], 2, v[18:19]
	v_add3_u32 v43, v43, v17, v89
	v_add3_u32 v45, v45, v84, v90
	v_add3_u32 v47, v47, v85, v93
	v_add3_u32 v49, v49, v86, v94
	v_add3_u32 v51, v51, v87, v97
	v_add3_u32 v53, v53, v88, v98
	v_add3_u32 v55, v55, v91, v101
	v_add3_u32 v57, v57, v92, v102
	v_add3_u32 v59, v59, v95, v105
	v_add3_u32 v61, v61, v96, v106
	v_add3_u32 v63, v63, v99, v109
	v_add3_u32 v65, v65, v100, v110
	v_add3_u32 v67, v67, v103, v113
	v_add3_u32 v69, v69, v104, v114
	v_lshl_add_u64 v[38:39], v[38:39], 2, v[18:19]
	v_lshl_add_u64 v[44:45], v[44:45], 2, v[18:19]
	v_lshl_add_u64 v[42:43], v[42:43], 2, v[18:19]
	v_lshl_add_u64 v[48:49], v[48:49], 2, v[18:19]
	v_lshl_add_u64 v[46:47], v[46:47], 2, v[18:19]
	v_lshl_add_u64 v[52:53], v[52:53], 2, v[18:19]
	v_lshl_add_u64 v[50:51], v[50:51], 2, v[18:19]
	v_lshl_add_u64 v[56:57], v[56:57], 2, v[18:19]
	v_lshl_add_u64 v[54:55], v[54:55], 2, v[18:19]
	v_lshl_add_u64 v[60:61], v[60:61], 2, v[18:19]
	v_lshl_add_u64 v[58:59], v[58:59], 2, v[18:19]
	v_lshl_add_u64 v[64:65], v[64:65], 2, v[18:19]
	v_lshl_add_u64 v[62:63], v[62:63], 2, v[18:19]
	v_lshl_add_u64 v[68:69], v[68:69], 2, v[18:19]
	v_lshl_add_u64 v[66:67], v[66:67], 2, v[18:19]
	global_load_dword v17, v[40:41], off
	global_load_dword v84, v[38:39], off
	global_load_dword v85, v[44:45], off
	global_load_dword v86, v[42:43], off
	global_load_dword v87, v[48:49], off
	global_load_dword v88, v[46:47], off
	global_load_dword v89, v[52:53], off
	global_load_dword v90, v[50:51], off
	global_load_dword v91, v[56:57], off
	global_load_dword v92, v[54:55], off
	global_load_dword v93, v[60:61], off
	global_load_dword v94, v[58:59], off
	global_load_dword v95, v[64:65], off
	global_load_dword v96, v[62:63], off
	global_load_dword v97, v[68:69], off
	global_load_dword v98, v[66:67], off
	s_add_i32 s4, s4, 16
	s_add_i32 s5, s5, 16
	s_add_i32 s8, s8, -16
	v_mad_u64_u32 v[38:39], s[12:13], v11, s1, v[6:7]
	s_cmp_lg_u32 s8, 0
	v_mad_u64_u32 v[40:41], s[12:13], v9, s1, v[6:7]
	v_mad_u64_u32 v[42:43], s[12:13], v71, s1, v[6:7]
	v_mad_u64_u32 v[44:45], s[12:13], v70, s1, v[6:7]
	v_mad_u64_u32 v[46:47], s[12:13], v73, s1, v[6:7]
	v_mad_u64_u32 v[48:49], s[12:13], v72, s1, v[6:7]
	v_mad_u64_u32 v[50:51], s[12:13], v75, s1, v[6:7]
	v_mad_u64_u32 v[52:53], s[12:13], v74, s1, v[6:7]
	v_mad_u64_u32 v[54:55], s[12:13], v77, s1, v[6:7]
	v_mad_u64_u32 v[56:57], s[12:13], v76, s1, v[6:7]
	v_mad_u64_u32 v[58:59], s[12:13], v79, s1, v[6:7]
	v_mad_u64_u32 v[60:61], s[12:13], v78, s1, v[6:7]
	v_mad_u64_u32 v[62:63], s[12:13], v81, s1, v[6:7]
	v_mad_u64_u32 v[64:65], s[12:13], v80, s1, v[6:7]
	v_mad_u64_u32 v[66:67], s[12:13], v83, s1, v[6:7]
	v_mad_u64_u32 v[68:69], s[12:13], v82, s1, v[6:7]
	s_waitcnt vmcnt(15)
	ds_write_b32 v38, v17
	s_waitcnt vmcnt(14)
	ds_write_b32 v40, v84
	s_waitcnt vmcnt(13)
	ds_write_b32 v42, v85
	s_waitcnt vmcnt(12)
	ds_write_b32 v44, v86
	s_waitcnt vmcnt(11)
	ds_write_b32 v46, v87
	s_waitcnt vmcnt(10)
	ds_write_b32 v48, v88
	s_waitcnt vmcnt(9)
	ds_write_b32 v50, v89
	s_waitcnt vmcnt(8)
	ds_write_b32 v52, v90
	s_waitcnt vmcnt(7)
	ds_write_b32 v54, v91
	s_waitcnt vmcnt(6)
	ds_write_b32 v56, v92
	s_waitcnt vmcnt(5)
	ds_write_b32 v58, v93
	s_waitcnt vmcnt(4)
	ds_write_b32 v60, v94
	s_waitcnt vmcnt(3)
	ds_write_b32 v62, v95
	s_waitcnt vmcnt(2)
	ds_write_b32 v64, v96
	s_waitcnt vmcnt(1)
	ds_write_b32 v66, v97
	s_waitcnt vmcnt(0)
	ds_write_b32 v68, v98
	s_cbranch_scc1 .LBB0_393
	s_waitcnt lgkmcnt(0)
	v_ashrrev_i32_e32 v17, 31, v16
	v_lshl_add_u64 v[2:3], v[16:17], 1, v[14:15]
	ds_read2_b32 v[16:17], v21 offset0:33 offset1:41
	ds_read2_b32 v[18:19], v21 offset1:8
	ds_read2_b32 v[38:39], v21 offset0:66 offset1:74
	ds_read2_b32 v[40:41], v21 offset0:99 offset1:107
	ds_read2_b32 v[42:43], v21 offset0:132 offset1:140
	ds_read2_b32 v[44:45], v21 offset0:165 offset1:173
	ds_read2_b32 v[46:47], v21 offset0:198 offset1:206
	ds_read2_b32 v[48:49], v21 offset0:231 offset1:239
	v_or_b32_e32 v7, v4, v20
	v_ashrrev_i32_e32 v9, 31, v4
	v_mov_b32_e32 v11, v5
	v_mul_lo_u32 v9, v9, v37
	v_mad_u64_u32 v[50:51], s[4:5], v7, v37, 0
	v_lshl_add_u64 v[2:3], v[2:3], 0, v[10:11]
	v_add_u32_e32 v51, v51, v9
	s_waitcnt lgkmcnt(6)
	v_cvt_pk_bf16_f32 v12, v18, v16
	s_waitcnt lgkmcnt(4)
	v_cvt_pk_bf16_f32 v13, v38, v40
	s_waitcnt lgkmcnt(2)
	v_cvt_pk_bf16_f32 v14, v42, v44
	s_waitcnt lgkmcnt(0)
	v_cvt_pk_bf16_f32 v15, v46, v48
	v_lshl_add_u64 v[50:51], v[50:51], 1, v[2:3]
	global_store_dwordx4 v[50:51], v[12:15], off sc1
	v_or_b32_e32 v7, v4, v22
	s_nop 0
	v_cvt_pk_bf16_f32 v12, v19, v17
	v_cvt_pk_bf16_f32 v13, v39, v41
	v_cvt_pk_bf16_f32 v14, v43, v45
	v_cvt_pk_bf16_f32 v15, v47, v49
	v_mad_u64_u32 v[16:17], s[4:5], v7, v37, 0
	ds_read2_b32 v[18:19], v21 offset0:16 offset1:24
	ds_read2_b32 v[38:39], v21 offset0:49 offset1:57
	ds_read2_b32 v[40:41], v21 offset0:82 offset1:90
	ds_read2_b32 v[42:43], v21 offset0:115 offset1:123
	ds_read2_b32 v[44:45], v21 offset0:148 offset1:156
	ds_read2_b32 v[46:47], v21 offset0:181 offset1:189
	ds_read2_b32 v[48:49], v21 offset0:214 offset1:222
	ds_read2_b32 v[50:51], v21 offset0:247 offset1:255
	v_add_u32_e32 v17, v17, v9
	v_lshl_add_u64 v[16:17], v[16:17], 1, v[2:3]
	v_or_b32_e32 v7, v4, v23
	global_store_dwordx4 v[16:17], v[12:15], off sc1
	v_mad_u64_u32 v[16:17], s[4:5], v7, v37, 0
	v_add_u32_e32 v17, v17, v9
	s_waitcnt lgkmcnt(6)
	v_cvt_pk_bf16_f32 v12, v18, v38
	s_waitcnt lgkmcnt(4)
	v_cvt_pk_bf16_f32 v13, v40, v42
	s_waitcnt lgkmcnt(2)
	v_cvt_pk_bf16_f32 v14, v44, v46
	s_waitcnt lgkmcnt(0)
	v_cvt_pk_bf16_f32 v15, v48, v50
	v_lshl_add_u64 v[16:17], v[16:17], 1, v[2:3]
	v_or_b32_e32 v4, v4, v24
	global_store_dwordx4 v[16:17], v[12:15], off sc1
	v_mad_u64_u32 v[16:17], s[4:5], v4, v37, 0
	v_add_u32_e32 v17, v17, v9
	v_cvt_pk_bf16_f32 v12, v19, v39
	v_cvt_pk_bf16_f32 v13, v41, v43
	v_cvt_pk_bf16_f32 v14, v45, v47
	v_cvt_pk_bf16_f32 v15, v49, v51
	v_lshl_add_u64 v[2:3], v[16:17], 1, v[2:3]
	global_store_dwordx4 v[2:3], v[12:15], off sc1
	s_waitcnt lgkmcnt(0)
	s_branch .LBB0_378

.LBB0_396:
	s_waitcnt vmcnt(0)
	s_waitcnt lgkmcnt(0)
	s_barrier
	s_mov_b64 s[4:5], exec
	v_readlane_b32 s0, v219, 25
	v_readlane_b32 s1, v219, 26
	s_and_b64 s[0:1], s[4:5], s[0:1]
	s_mov_b64 exec, s[0:1]
	s_cbranch_execz .LBB0_448
	v_readlane_b32 s0, v219, 27
	v_readlane_b32 s1, v219, 28
	v_readlane_b32 s2, v219, 29
	v_mov_b32_e32 v0, 0x24000
	s_waitcnt vmcnt(0) lgkmcnt(0)
	buffer_inv sc1
	ds_read_b32 v2, v0
	ds_read_b32 v0, v0 offset:4
	s_lshl_b32 s3, s2, 8
	s_add_i32 s14, s3, 0x2400
	s_add_i32 s3, s3, 0x1400
	v_mov_b32_e32 v1, s3
	s_waitcnt lgkmcnt(0)
	v_readfirstlane_b32 s10, v2
	v_readfirstlane_b32 s11, v0
	v_mov_b32_e32 v0, 1
	s_nop 1
	global_atomic_add v2, v1, v0, s[0:1] sc0
	s_mul_i32 s10, s10, 4
	s_mul_i32 s11, s11, 4
	s_waitcnt vmcnt(0)
	v_readfirstlane_b32 s13, v2
	s_nop 1
	s_add_i32 s13, s13, 1
	s_cmp_lg_u32 s13, s10
	s_cbranch_scc1 .Lnb4_wait
	v_mov_b32_e32 v1, 0x3400
	global_atomic_add v2, v1, v0, s[0:1] sc0
	s_waitcnt vmcnt(0)
	v_readfirstlane_b32 s13, v2
	s_nop 1
	s_add_i32 s13, s13, 1
	s_cmp_lg_u32 s13, s11
	s_cbranch_scc1 .Lnb4_wait
	v_mov_b32_e32 v1, 0x2400
	global_atomic_add v1, v0, s[0:1]
	global_atomic_add v1, v0, s[0:1] offset:256
	global_atomic_add v1, v0, s[0:1] offset:512
	global_atomic_add v1, v0, s[0:1] offset:768
	global_atomic_add v1, v0, s[0:1] offset:1024
	global_atomic_add v1, v0, s[0:1] offset:1280
	global_atomic_add v1, v0, s[0:1] offset:1536
	global_atomic_add v1, v0, s[0:1] offset:1792
	global_atomic_add v1, v0, s[0:1] offset:2048
	global_atomic_add v1, v0, s[0:1] offset:2304
	global_atomic_add v1, v0, s[0:1] offset:2560
	global_atomic_add v1, v0, s[0:1] offset:2816
	global_atomic_add v1, v0, s[0:1] offset:3072
	global_atomic_add v1, v0, s[0:1] offset:3328
	global_atomic_add v1, v0, s[0:1] offset:3584
	global_atomic_add v1, v0, s[0:1] offset:3840
	v_mov_b32_e32 v1, 0x3500
	global_atomic_add v1, v0, s[0:1]

.Lnb4_spin:
	global_load_dword v2, v1, s[0:1] sc1
	s_waitcnt vmcnt(0)
	v_readfirstlane_b32 s13, v2
	s_nop 1
	s_cmp_ge_u32 s13, 4
	s_cbranch_scc1 .Lnb4_done
	s_sleep 1
	s_add_i32 s15, s15, 1
	s_cmp_lt_u32 s15, 0x200000
	s_cbranch_scc1 .Lnb4_spin
.Lnb4_done:
	s_waitcnt vmcnt(0)
.LBB0_448:
	s_or_b64 exec, exec, s[4:5]
	s_cmpk_lt_i32 s78, 0x100
	s_waitcnt lgkmcnt(0)
	v_xor_b32_e32 v0, v180, v182
	s_cselect_b64 s[0:1], -1, 0
	v_lshrrev_b32_e32 v185, 3, v149
	v_lshlrev_b32_e32 v154, 4, v0
	v_lshlrev_b32_e32 v0, 3, v0
	v_writelane_b32 v219, s0, 45
	v_lshlrev_b32_e32 v1, 11, v185
	v_xor_b32_e32 v155, 32, v0
	v_writelane_b32 v219, s1, 46
	v_readfirstlane_b32 s4, v168
	v_or_b32_e32 v162, v154, v1
	s_cmpk_gt_i32 s78, 0xff
	v_lshl_or_b32 v163, v155, 1, v1
	v_writelane_b32 v219, s94, 39
	s_barrier
	v_writelane_b32 v219, s95, 40
	s_cbranch_scc1 .LBB0_512
	s_add_u32 s0, s56, 0x700000
	s_addc_u32 s1, s57, 0
	s_lshl_b32 s2, s78, 19
	s_lshr_b32 s5, s4, 6
	s_bfe_u32 s33, s4, 0x10006
	s_lshr_b32 s46, s4, 7
	s_and_b32 s2, s2, 0xf80000
	s_add_u32 s17, s34, s2
	s_addc_u32 s25, s35, 0
	s_lshl_b32 s2, s78, 2
	s_mov_b32 s91, 0
	s_and_b32 s8, s2, 0xffffff80
	s_lshl_b32 s90, s5, 5
	s_lshl_b32 s3, s5, 12
	s_ashr_i32 s9, s8, 31
	s_add_i32 s16, s3, 0
	s_lshl_b64 s[14:15], s[90:91], 10
	s_lshl_b64 s[6:7], s[90:91], 11
	s_add_u32 s10, s17, s6
	s_addc_u32 s11, s25, s7
	s_or_b32 s42, s90, 8
	s_mov_b32 s43, s91
	s_lshl_b64 s[6:7], s[42:43], 10
	s_lshl_b64 s[12:13], s[42:43], 11
	s_add_u32 s18, s17, s12
	v_mov_b32_e32 v0, v162
	v_mov_b32_e32 v1, v163
	s_mov_b32 m0, s16
	s_addc_u32 s19, s25, s13
	s_or_b32 s44, s90, 16
	s_mov_b32 s45, s91
	s_barrier
	s_lshl_b64 s[12:13], s[44:45], 10
	global_load_lds_dwordx4 v0, s[10:11]
	s_add_i32 m0, s16, 0x400
	s_lshl_b64 s[20:21], s[44:45], 11
	s_add_u32 s20, s17, s20
	s_addc_u32 s21, s25, s21
	s_or_b32 s90, s90, 24
	global_load_lds_dwordx4 v1, s[18:19]
	s_add_i32 m0, s16, 0x800
	s_lshl_b64 s[80:81], s[90:91], 10
	s_lshl_b64 s[22:23], s[90:91], 11
	s_add_u32 s24, s17, s22
	global_load_lds_dwordx4 v0, s[20:21]
	s_addc_u32 s25, s25, s23
	s_add_i32 m0, s16, 0xc00
	s_lshl_b64 s[8:9], s[8:9], 11
	s_add_u32 s28, s0, s8
	s_addc_u32 s29, s1, s9
	s_lshl_b32 s17, s5, 11
	s_lshl_b32 s8, s5, 4
	s_sub_i32 s40, s16, s17
	s_mov_b32 s9, s91
	global_load_lds_dwordx4 v1, s[24:25]
	s_add_i32 m0, s40, 0x8000
	s_lshl_b64 s[82:83], s[8:9], 10
	s_lshl_b64 s[22:23], s[8:9], 11
	s_add_u32 s26, s28, s22
	s_addc_u32 s27, s29, s23
	s_or_b32 s8, s8, 8
	s_lshl_b64 s[84:85], s[8:9], 10
	s_lshl_b64 s[22:23], s[8:9], 11
	s_add_u32 s28, s28, s22
	global_load_lds_dwordx4 v0, s[26:27]
	s_addc_u32 s29, s29, s23
	s_add_i32 m0, s40, 0x8400
	v_mov_b32_e32 v150, v162
	v_mov_b32_e32 v0, v163
	v_mov_b32_e32 v151, 0
	global_load_lds_dwordx4 v1, s[28:29]
	s_mov_b64 s[22:23], 0x80
	v_lshl_add_u64 v[2:3], s[10:11], 0, v[150:151]
	s_add_i32 m0, s16, 0xc000
	v_lshl_add_u64 v[2:3], v[2:3], 0, s[22:23]
	v_mov_b32_e32 v1, v151
	global_load_lds_dwordx4 v[2:3], off
	v_lshl_add_u64 v[2:3], s[18:19], 0, v[0:1]
	v_lshl_add_u64 v[2:3], v[2:3], 0, s[22:23]
	s_add_i32 m0, s16, 0xc400
	s_add_i32 s9, s17, 0
	global_load_lds_dwordx4 v[2:3], off
	v_lshl_add_u64 v[2:3], s[20:21], 0, v[150:151]
	v_lshl_add_u64 v[2:3], v[2:3], 0, s[22:23]
	s_add_i32 m0, s16, 0xc800
	v_cmp_eq_u32_e32 vcc, 0, v171
	global_load_lds_dwordx4 v[2:3], off
	v_lshl_add_u64 v[2:3], s[24:25], 0, v[0:1]
	v_lshl_add_u64 v[2:3], v[2:3], 0, s[22:23]
	s_add_i32 m0, s16, 0xcc00
	v_lshl_add_u64 v[0:1], s[28:29], 0, v[0:1]
	global_load_lds_dwordx4 v[2:3], off
	v_lshl_add_u64 v[2:3], s[26:27], 0, v[150:151]
	s_add_i32 m0, s9, 0x14000
	v_lshl_add_u64 v[2:3], v[2:3], 0, s[22:23]
	global_load_lds_dwordx4 v[2:3], off
	v_lshl_add_u64 v[0:1], v[0:1], 0, s[22:23]
	s_add_i32 m0, s9, 0x14400
	s_cmpk_gt_u32 s4, 0xff
	global_load_lds_dwordx4 v[0:1], off
	s_cselect_b64 s[40:41], -1, 0
	s_lshl_b32 s9, s90, 10
	v_writelane_b32 v219, s9, 37
	s_lshl_b32 s8, s8, 10
	s_lshl_b32 s90, s5, 14
	v_writelane_b32 v219, s8, 41
	s_lshl_b32 s8, s5, 15
	s_lshl_b32 s5, s42, 10
	v_writelane_b32 v219, s5, 42
	s_lshl_b32 s5, s44, 10
	s_lshl_b32 s24, s33, 13
	s_lshl_b32 s25, s46, 13
	v_writelane_b32 v219, s5, 47
	s_lshl_b32 s5, s33, 7
	s_add_u32 s10, s56, s5
	s_addc_u32 s11, s57, 0
	s_lshl_b64 s[4:5], s[4:5], 10
	s_and_b32 s5, s5, 0x3ff
	s_and_b32 s4, s4, 0xffff0000
	s_add_u32 s4, s56, s4
	v_writelane_b32 v219, s4, 48
	s_addc_u32 s4, s57, s5
	s_lshl_b32 s33, s78, 8
	s_lshl_b32 s60, s58, 8
	s_mov_b32 s9, s91
	v_writelane_b32 v219, s4, 49
	s_add_u32 s4, s56, s14
	v_add_u32_e32 v0, 12, v181
	v_writelane_b32 v219, s4, 50
	s_addc_u32 s4, s57, s15
	s_lshl_b32 s63, s58, 2
	s_lshl_b64 s[42:43], s[8:9], 1
	v_cndmask_b32_e32 v0, v0, v181, vcc
	v_xor_b32_e32 v1, v180, v170
	v_writelane_b32 v219, s4, 52
	s_add_u32 s4, s56, s42
	v_lshlrev_b32_e32 v157, 4, v1
	v_bitop3_b32 v1, v180, v170, 4 bitop3:0x36
	v_lshlrev_b32_e32 v150, 1, v0
	v_writelane_b32 v219, s4, 54
	s_addc_u32 s4, s57, s43
	s_lshl_b64 s[44:45], s[90:91], 1
	v_lshlrev_b32_e32 v158, 4, v1
	v_lshl_add_u64 v[0:1], s[10:11], 0, v[150:151]
	s_mov_b64 s[10:11], 0x8400000
	v_writelane_b32 v219, s4, 55
	s_add_u32 s4, s56, s44
	v_lshl_or_b32 v156, s46, 6, v167
	v_lshl_add_u64 v[152:153], v[0:1], 0, s[10:11]
	v_writelane_b32 v219, s4, 56
	s_addc_u32 s62, s57, s45
	s_mov_b64 s[4:5], -1
	s_mov_b64 s[46:47], 0x100
	s_mov_b64 s[48:49], 0x7400180
	s_mov_b64 s[50:51], 0x7404180
	s_mov_b64 s[68:69], 0x7408180
	s_mov_b64 s[70:71], 0x740c180
	s_mov_b64 s[72:73], 0x700180
	s_mov_b64 s[74:75], 0x704180
	s_lshl_b64 s[76:77], s[6:7], 1
	s_mov_b32 s96, s78
	s_lshl_b64 s[78:79], s[12:13], 1
	s_lshl_b64 s[80:81], s[80:81], 1
	s_lshl_b64 s[82:83], s[82:83], 1
	s_lshl_b64 s[84:85], s[84:85], 1
	s_branch .LBB0_451
.LBB0_450:
	v_add_u32_e32 v150, s97, v156
	v_lshl_add_u64 v[64:65], s[88:89], 1, v[152:153]
	v_lshlrev_b64 v[66:67], 11, v[150:151]
	v_cvt_pk_bf16_f32 v48, v48, v49
	v_cvt_pk_bf16_f32 v49, v50, v51
	v_cvt_pk_bf16_f32 v50, v52, v53
	v_cvt_pk_bf16_f32 v51, v54, v55
	v_lshl_add_u64 v[66:67], v[64:65], 0, v[66:67]
	v_permlane16_swap_b32_e32 v48, v50
	v_permlane16_swap_b32_e32 v49, v51
	global_store_dwordx4 v[66:67], v[48:51], off offset:64 sc1
	v_cvt_pk_bf16_f32 v20, v20, v21
	v_cvt_pk_bf16_f32 v21, v22, v23
	v_or_b32_e32 v48, 16, v150
	v_mov_b32_e32 v49, v151
	v_lshlrev_b64 v[48:49], 11, v[48:49]
	v_cvt_pk_bf16_f32 v22, v28, v29
	v_cvt_pk_bf16_f32 v23, v30, v31
	v_lshl_add_u64 v[48:49], v[64:65], 0, v[48:49]
	v_permlane16_swap_b32_e32 v20, v22
	v_permlane16_swap_b32_e32 v21, v23
	global_store_dwordx4 v[48:49], v[20:23], off offset:64 sc1
	v_cvt_pk_bf16_f32 v16, v16, v17
	v_cvt_pk_bf16_f32 v17, v18, v19
	v_or_b32_e32 v20, 32, v150
	v_mov_b32_e32 v21, v151
	v_lshlrev_b64 v[20:21], 11, v[20:21]
	v_cvt_pk_bf16_f32 v18, v24, v25
	v_cvt_pk_bf16_f32 v19, v26, v27
	v_lshl_add_u64 v[28:29], v[64:65], 0, v[20:21]
	v_permlane16_swap_b32_e32 v16, v18
	v_permlane16_swap_b32_e32 v17, v19
	v_or_b32_e32 v150, 48, v150
	v_cvt_pk_bf16_f32 v56, v56, v57
	v_cvt_pk_bf16_f32 v57, v58, v59
	v_cvt_pk_bf16_f32 v58, v60, v61
	v_cvt_pk_bf16_f32 v59, v62, v63
	v_cvt_pk_bf16_f32 v36, v36, v37
	v_cvt_pk_bf16_f32 v37, v38, v39
	v_cvt_pk_bf16_f32 v38, v44, v45
	v_cvt_pk_bf16_f32 v39, v46, v47
	v_cvt_pk_bf16_f32 v20, v32, v33
	v_cvt_pk_bf16_f32 v21, v34, v35
	v_cvt_pk_bf16_f32 v22, v40, v41
	v_cvt_pk_bf16_f32 v23, v42, v43
	global_store_dwordx4 v[28:29], v[16:19], off offset:64 sc1
	v_cvt_pk_bf16_f32 v4, v4, v5
	v_cvt_pk_bf16_f32 v5, v6, v7
	v_lshlrev_b64 v[16:17], 11, v[150:151]
	v_cvt_pk_bf16_f32 v6, v8, v9
	v_cvt_pk_bf16_f32 v7, v10, v11
	v_cvt_pk_bf16_f32 v0, v0, v1
	v_cvt_pk_bf16_f32 v1, v2, v3
	v_cvt_pk_bf16_f32 v2, v12, v13
	v_cvt_pk_bf16_f32 v3, v14, v15
	v_permlane16_swap_b32_e32 v56, v58
	v_permlane16_swap_b32_e32 v57, v59
	v_permlane16_swap_b32_e32 v36, v38
	v_permlane16_swap_b32_e32 v37, v39
	v_permlane16_swap_b32_e32 v20, v22
	v_permlane16_swap_b32_e32 v21, v23
	v_lshl_add_u64 v[16:17], v[64:65], 0, v[16:17]
	v_permlane16_swap_b32_e32 v4, v6
	v_permlane16_swap_b32_e32 v5, v7
	v_permlane16_swap_b32_e32 v0, v2
	v_permlane16_swap_b32_e32 v1, v3
	s_add_i32 s33, s33, s60
	s_add_i32 s2, s2, s63
	s_andn2_b64 vcc, exec, s[86:87]
	s_mov_b64 s[4:5], 0
	global_store_dwordx4 v[66:67], v[56:59], off sc1
	global_store_dwordx4 v[48:49], v[36:39], off sc1
	global_store_dwordx4 v[28:29], v[20:23], off sc1
	global_store_dwordx4 v[16:17], v[4:7], off sc1
	global_store_dwordx4 v[16:17], v[0:3], off offset:64 sc1
	s_cbranch_vccz .LBB0_511

.LBB0_512:
	s_waitcnt vmcnt(0)
	s_waitcnt vmcnt(0) lgkmcnt(0)
	s_barrier
	s_mov_b64 s[4:5], exec
	v_readlane_b32 s0, v219, 25
	v_readlane_b32 s1, v219, 26
	s_and_b64 s[0:1], s[4:5], s[0:1]
	s_mov_b64 exec, s[0:1]
	s_cbranch_execz .LBB0_564
	v_readlane_b32 s0, v219, 27
	v_readlane_b32 s1, v219, 28
	v_readlane_b32 s2, v219, 29
	v_mov_b32_e32 v0, 0x24000
	s_waitcnt vmcnt(0) lgkmcnt(0)
	buffer_inv sc1
	ds_read_b32 v2, v0
	ds_read_b32 v0, v0 offset:4
	s_lshl_b32 s3, s2, 8
	s_add_i32 s14, s3, 0x2400
	s_add_i32 s3, s3, 0x1400
	v_mov_b32_e32 v1, s3
	s_waitcnt lgkmcnt(0)
	v_readfirstlane_b32 s10, v2
	v_readfirstlane_b32 s11, v0
	v_mov_b32_e32 v0, 1
	s_nop 1
	global_atomic_add v2, v1, v0, s[0:1] sc0
	s_mul_i32 s10, s10, 5
	s_mul_i32 s11, s11, 5
	s_waitcnt vmcnt(0)
	v_readfirstlane_b32 s13, v2
	s_nop 1
	s_add_i32 s13, s13, 1
	s_cmp_lg_u32 s13, s10
	s_cbranch_scc1 .Lnb5_wait
	v_mov_b32_e32 v1, 0x3400
	global_atomic_add v2, v1, v0, s[0:1] sc0
	s_waitcnt vmcnt(0)
	v_readfirstlane_b32 s13, v2
	s_nop 1
	s_add_i32 s13, s13, 1
	s_cmp_lg_u32 s13, s11
	s_cbranch_scc1 .Lnb5_wait
	v_mov_b32_e32 v1, 0x2400
	global_atomic_add v1, v0, s[0:1]
	global_atomic_add v1, v0, s[0:1] offset:256
	global_atomic_add v1, v0, s[0:1] offset:512
	global_atomic_add v1, v0, s[0:1] offset:768
	global_atomic_add v1, v0, s[0:1] offset:1024
	global_atomic_add v1, v0, s[0:1] offset:1280
	global_atomic_add v1, v0, s[0:1] offset:1536
	global_atomic_add v1, v0, s[0:1] offset:1792
	global_atomic_add v1, v0, s[0:1] offset:2048
	global_atomic_add v1, v0, s[0:1] offset:2304
	global_atomic_add v1, v0, s[0:1] offset:2560
	global_atomic_add v1, v0, s[0:1] offset:2816
	global_atomic_add v1, v0, s[0:1] offset:3072
	global_atomic_add v1, v0, s[0:1] offset:3328
	global_atomic_add v1, v0, s[0:1] offset:3584
	global_atomic_add v1, v0, s[0:1] offset:3840
	v_mov_b32_e32 v1, 0x3500
	global_atomic_add v1, v0, s[0:1]

.Lnb5_spin:
	global_load_dword v2, v1, s[0:1] sc1
	s_waitcnt vmcnt(0)
	v_readfirstlane_b32 s13, v2
	s_nop 1
	s_cmp_ge_u32 s13, 5
	s_cbranch_scc1 .Lnb5_done
	s_sleep 1
	s_add_i32 s15, s15, 1
	s_cmp_lt_u32 s15, 0x200000
	s_cbranch_scc1 .Lnb5_spin
.Lnb5_done:
	s_waitcnt vmcnt(0)
.LBB0_564:
	s_or_b64 exec, exec, s[4:5]
	s_waitcnt lgkmcnt(0)
	s_barrier
	s_mov_b64 s[4:5], exec
	v_readlane_b32 s0, v219, 31
	v_readlane_b32 s1, v219, 32
	s_and_b64 s[0:1], s[4:5], s[0:1]
	s_mov_b64 exec, s[0:1]
	s_cbranch_execz .LBB0_577
	v_and_b32_e32 v0, 0x1f8, v144
	v_mov_b32_e32 v65, 0
	v_lshlrev_b32_e32 v64, 1, v0
	v_lshl_add_u64 v[2:3], s[56:57], 0, v[64:65]
	s_mov_b64 s[0:1], 0x8400000
	v_readlane_b32 s8, v219, 9
	v_lshl_add_u64 v[66:67], v[2:3], 0, s[0:1]
	s_mov_b64 s[0:1], 0xa400000
	v_readlane_b32 s9, v219, 10
	v_readlane_b32 s10, v219, 11
	v_readlane_b32 s11, v219, 12
	v_readlane_b32 s12, v219, 13
	v_readlane_b32 s13, v219, 14
	v_lshl_add_u64 v[68:69], v[2:3], 0, s[0:1]
	s_lshl_b32 s0, s58, 3
	v_readlane_b32 s14, v219, 15
	v_readlane_b32 s15, v219, 16
	s_mov_b64 s[8:9], s[12:13]
	s_add_u32 s2, s8, 0x1000
	s_addc_u32 s3, s9, 0
	s_add_u32 s8, s8, 0x2000
	v_lshl_add_u64 v[70:71], s[30:31], 0, v[64:65]
	v_or_b32_e32 v2, 0x200, v0
	s_addc_u32 s9, s9, 0
	v_lshlrev_b32_e32 v64, 2, v0
	v_readlane_b32 s22, v219, 23
	v_readlane_b32 s23, v219, 24
	v_lshl_add_u64 v[72:73], s[2:3], 0, v[64:65]
	v_lshl_add_u64 v[74:75], s[8:9], 0, v[64:65]
	v_lshlrev_b32_e32 v64, 2, v2
	s_mov_b64 s[10:11], s[14:15]
	s_mov_b64 s[6:7], 0x2000
	v_lshl_add_u64 v[76:77], s[2:3], 0, v[64:65]
	v_lshl_add_u64 v[78:79], s[8:9], 0, v[64:65]
	v_lshl_add_u32 v104, s78, 5, v166
	s_lshl_b32 s1, s58, 5
	s_mov_b64 s[12:13], 0
	v_mov_b32_e32 v105, 0xfffff000
	s_movk_i32 s2, 0x3ff
	s_mov_b64 s[14:15], 0x3000
	s_mov_b64 s[22:23], 0x4000
	v_lshlrev_b32_e32 v64, 2, v0
	v_lshlrev_b32_e32 v80, 2, v2
	v_mov_b32_e32 v81, v65
	s_movk_i32 s3, 0xfff
	v_mov_b32_e32 v106, 0x358637bd
	s_mov_b32 s8, 0x800000
	s_movk_i32 s9, 0x7ff
	v_mov_b32_e32 v107, v145
	v_readlane_b32 s16, v219, 17
	v_readlane_b32 s17, v219, 18
	v_readlane_b32 s18, v219, 19
	v_readlane_b32 s19, v219, 20
	v_readlane_b32 s20, v219, 21
	v_readlane_b32 s21, v219, 22
	s_branch .LBB0_567

.LBB0_568:
	s_or_b64 exec, exec, s[40:41]
	v_lshlrev_b64 v[98:99], 11, v[102:103]
	v_lshl_add_u64 v[102:103], v[66:67], 0, v[98:99]
	global_load_dwordx4 v[108:111], v[102:103], off
	global_load_dwordx4 v[112:115], v[102:103], off offset:1024
	v_lshl_add_u64 v[124:125], v[100:101], 0, v[64:65]
	global_load_dwordx4 v[100:103], v[124:125], off offset:16
	global_load_dwordx4 v[116:119], v[124:125], off
	global_load_dwordx4 v[120:123], v[124:125], off offset:2064
	s_nop 0
	global_load_dwordx4 v[124:127], v[124:125], off offset:2048
	s_add_i32 s10, s10, 2
	s_cmp_eq_u32 s10, 4
	s_waitcnt vmcnt(5)
	v_and_b32_e32 v131, 0xffff0000, v110
	v_and_b32_e32 v130, 0xffff0000, v108
	v_lshlrev_b32_e32 v129, 16, v110
	v_lshlrev_b32_e32 v128, 16, v108
	v_lshlrev_b32_e32 v132, 16, v109
	v_and_b32_e32 v110, 0xffff0000, v109
	s_waitcnt vmcnt(4)
	v_lshlrev_b32_e32 v109, 16, v112
	v_lshlrev_b32_e32 v108, 16, v114
	v_and_b32_e32 v135, 0xffff0000, v112
	v_and_b32_e32 v134, 0xffff0000, v114
	v_lshlrev_b32_e32 v136, 16, v115
	v_and_b32_e32 v112, 0xffff0000, v115
	v_pk_mul_f32 v[114:115], v[130:131], v[130:131]
	v_lshlrev_b32_e32 v133, 16, v111
	v_pk_mul_f32 v[138:139], v[134:135], v[134:135]
	v_pk_fma_f32 v[114:115], v[128:129], v[128:129], v[114:115]
	v_and_b32_e32 v111, 0xffff0000, v111
	v_lshlrev_b32_e32 v137, 16, v113
	v_pk_fma_f32 v[138:139], v[108:109], v[108:109], v[138:139]
	v_pk_fma_f32 v[114:115], v[132:133], v[132:133], v[114:115]
	v_and_b32_e32 v113, 0xffff0000, v113
	v_pk_fma_f32 v[138:139], v[136:137], v[136:137], v[138:139]
	v_pk_fma_f32 v[114:115], v[110:111], v[110:111], v[114:115]
	v_pk_fma_f32 v[138:139], v[112:113], v[112:113], v[138:139]
	v_add_f32_e32 v114, v114, v115
	v_add_f32_e32 v114, v114, v139
	v_add_f32_e32 v114, v138, v114
	ds_bpermute_b32 v115, v172, v114
	v_mov_b32_e32 v139, v130
	v_mov_b32_e32 v130, v129
	v_mov_b32_e32 v129, v113
	v_mov_b32_e32 v141, v135
	s_waitcnt lgkmcnt(0)
	v_add_f32_e32 v114, v114, v115
	ds_bpermute_b32 v115, v173, v114
	s_waitcnt lgkmcnt(0)
	v_add_f32_e32 v114, v114, v115
	ds_bpermute_b32 v115, v174, v114
	s_waitcnt lgkmcnt(0)
	v_add_f32_e32 v115, v114, v115
	ds_bpermute_b32 v138, v175, v115
	v_mov_b32_e32 v114, v132
	s_waitcnt lgkmcnt(0)
	v_add_f32_e32 v132, v115, v138
	ds_bpermute_b32 v140, v176, v132
	v_mov_b32_e32 v115, v110
	v_mov_b32_e32 v138, v128
	v_mov_b32_e32 v128, v137
	v_mov_b32_e32 v137, v112
	s_waitcnt lgkmcnt(0)
	v_add_f32_e32 v110, v132, v140
	ds_bpermute_b32 v132, v177, v110
	v_mov_b32_e32 v140, v109
	s_waitcnt lgkmcnt(0)
	v_add_f32_e32 v109, v110, v132
	v_fmamk_f32 v109, v109, 0x3a800000, v106
	v_mul_f32_e32 v110, 0x4b800000, v109
	v_cmp_gt_f32_e32 vcc, s8, v109
	s_nop 1
	v_cndmask_b32_e32 v109, v109, v110, vcc
	v_rsq_f32_e32 v113, v109
	v_mov_b32_e32 v109, v134
	v_mov_b32_e32 v110, v133
	v_mul_f32_e32 v112, 0x45800000, v113
	v_cndmask_b32_e32 v112, v113, v112, vcc
	v_pk_mul_f32 v[132:133], v[112:113], v[138:139] op_sel_hi:[0,1]
	v_pk_mul_f32 v[130:131], v[112:113], v[130:131] op_sel_hi:[0,1]
	v_pk_mul_f32 v[114:115], v[112:113], v[114:115] op_sel_hi:[0,1]
	v_pk_mul_f32 v[110:111], v[112:113], v[110:111] op_sel_hi:[0,1]
	v_pk_mul_f32 v[128:129], v[112:113], v[128:129] op_sel_hi:[0,1]
	v_pk_mul_f32 v[134:135], v[112:113], v[140:141] op_sel_hi:[0,1]
	v_pk_mul_f32 v[136:137], v[112:113], v[136:137] op_sel_hi:[0,1]
	v_pk_mul_f32 v[108:109], v[112:113], v[108:109] op_sel_hi:[0,1]
	v_pk_mul_f32 v[112:113], v[4:5], v[132:133]
	v_pk_mul_f32 v[130:131], v[0:1], v[130:131]
	v_pk_mul_f32 v[132:133], v[36:37], v[134:135]
	v_pk_mul_f32 v[108:109], v[32:33], v[108:109]
	s_waitcnt vmcnt(2)
	v_pk_fma_f32 v[112:113], v[12:13], v[112:113], v[116:117]
	v_pk_fma_f32 v[116:117], v[8:9], v[130:131], v[100:101]
	v_pk_mul_f32 v[114:115], v[6:7], v[114:115]
	v_pk_mul_f32 v[110:111], v[2:3], v[110:111]
	s_waitcnt vmcnt(0)
	v_pk_fma_f32 v[124:125], v[44:45], v[132:133], v[124:125]
	v_pk_fma_f32 v[120:121], v[40:41], v[108:109], v[120:121]
	v_mov_b32_e32 v108, v113
	v_mov_b32_e32 v109, v117
	v_pk_mul_f32 v[128:129], v[38:39], v[128:129]
	v_pk_mul_f32 v[134:135], v[34:35], v[136:137]
	v_pk_fma_f32 v[114:115], v[14:15], v[114:115], v[118:119]
	v_pk_fma_f32 v[102:103], v[10:11], v[110:111], v[102:103]
	v_mov_b32_e32 v100, v112
	v_mov_b32_e32 v101, v116
	v_mov_b32_e32 v130, v121
	v_mov_b32_e32 v131, v125
	v_pk_mul_f32 v[108:109], v[108:109], v[108:109]
	v_pk_fma_f32 v[118:119], v[46:47], v[128:129], v[126:127]
	v_pk_fma_f32 v[122:123], v[42:43], v[134:135], v[122:123]
	v_mov_b32_e32 v110, v114
	v_mov_b32_e32 v111, v102
	v_mov_b32_e32 v128, v120
	v_mov_b32_e32 v129, v124
	v_pk_mul_f32 v[130:131], v[130:131], v[130:131]
	v_pk_fma_f32 v[100:101], v[100:101], v[100:101], v[108:109]
	v_mov_b32_e32 v126, v115
	v_mov_b32_e32 v127, v103
	v_mov_b32_e32 v132, v122
	v_mov_b32_e32 v133, v118
	v_pk_fma_f32 v[108:109], v[128:129], v[128:129], v[130:131]
	v_pk_fma_f32 v[100:101], v[110:111], v[110:111], v[100:101]
	v_mov_b32_e32 v134, v123
	v_mov_b32_e32 v135, v119
	v_pk_fma_f32 v[108:109], v[132:133], v[132:133], v[108:109]
	v_pk_fma_f32 v[100:101], v[126:127], v[126:127], v[100:101]
	v_pk_fma_f32 v[108:109], v[134:135], v[134:135], v[108:109]
	v_add_f32_e32 v100, v100, v101
	v_add_f32_e32 v100, v109, v100
	v_add_f32_e32 v100, v108, v100
	ds_bpermute_b32 v101, v172, v100
	v_lshl_add_u64 v[126:127], v[68:69], 0, v[98:99]
	v_lshl_add_u64 v[128:129], v[70:71], 0, v[98:99]
	v_cvt_pk_bf16_f32 v98, v112, v113
	v_cvt_pk_bf16_f32 v99, v114, v115
	s_waitcnt lgkmcnt(0)
	v_add_f32_e32 v100, v100, v101
	ds_bpermute_b32 v101, v173, v100
	v_cvt_pk_bf16_f32 v109, v118, v119
	v_cvt_pk_bf16_f32 v110, v120, v121
	s_waitcnt lgkmcnt(0)
	v_add_f32_e32 v100, v100, v101
	ds_bpermute_b32 v101, v174, v100
	s_waitcnt lgkmcnt(0)
	v_add_f32_e32 v100, v100, v101
	ds_bpermute_b32 v101, v175, v100
	s_waitcnt lgkmcnt(0)
	v_add_f32_e32 v101, v100, v101
	ds_bpermute_b32 v108, v176, v101
	v_cvt_pk_bf16_f32 v100, v116, v117
	s_waitcnt lgkmcnt(0)
	v_add_f32_e32 v111, v101, v108
	ds_bpermute_b32 v130, v177, v111
	v_cvt_pk_bf16_f32 v101, v102, v103
	v_cvt_pk_bf16_f32 v108, v124, v125
	s_waitcnt lgkmcnt(0)
	v_add_f32_e32 v111, v111, v130
	v_fmamk_f32 v111, v111, 0x3a800000, v106
	v_mul_f32_e32 v130, 0x4b800000, v111
	v_cmp_gt_f32_e32 vcc, s8, v111
	s_nop 1
	v_cndmask_b32_e32 v111, v111, v130, vcc
	v_rsq_f32_e32 v130, v111
	v_cvt_pk_bf16_f32 v111, v122, v123
	global_store_dwordx4 v[126:127], v[98:101], off sc1
	global_store_dwordx4 v[126:127], v[108:111], off offset:1024 sc1
	s_nop 0
	v_mul_f32_e32 v98, 0x45800000, v130
	v_cndmask_b32_e32 v98, v130, v98, vcc
	v_pk_mul_f32 v[100:101], v[114:115], v[98:99] op_sel_hi:[1,0]
	v_pk_mul_f32 v[108:109], v[112:113], v[98:99] op_sel_hi:[1,0]
	v_pk_mul_f32 v[102:103], v[102:103], v[98:99] op_sel_hi:[1,0]
	v_pk_mul_f32 v[110:111], v[116:117], v[98:99] op_sel_hi:[1,0]
	v_pk_mul_f32 v[112:113], v[118:119], v[98:99] op_sel_hi:[1,0]
	v_pk_mul_f32 v[114:115], v[124:125], v[98:99] op_sel_hi:[1,0]
	v_pk_mul_f32 v[116:117], v[122:123], v[98:99] op_sel_hi:[1,0]
	v_pk_mul_f32 v[98:99], v[120:121], v[98:99] op_sel_hi:[1,0]
	v_pk_mul_f32 v[108:109], v[20:21], v[108:109]
	v_pk_mul_f32 v[100:101], v[22:23], v[100:101]
	v_pk_mul_f32 v[110:111], v[16:17], v[110:111]
	v_pk_mul_f32 v[102:103], v[18:19], v[102:103]
	v_pk_mul_f32 v[114:115], v[52:53], v[114:115]
	v_pk_mul_f32 v[112:113], v[54:55], v[112:113]
	v_pk_mul_f32 v[98:99], v[48:49], v[98:99]
	v_pk_mul_f32 v[116:117], v[50:51], v[116:117]
	v_pk_fma_f32 v[100:101], v[82:83], v[100:101], v[30:31]
	v_pk_fma_f32 v[108:109], v[84:85], v[108:109], v[28:29]
	v_pk_fma_f32 v[102:103], v[86:87], v[102:103], v[26:27]
	v_pk_fma_f32 v[110:111], v[88:89], v[110:111], v[24:25]
	v_pk_fma_f32 v[112:113], v[90:91], v[112:113], v[62:63]
	v_pk_fma_f32 v[114:115], v[92:93], v[114:115], v[60:61]
	v_pk_fma_f32 v[116:117], v[94:95], v[116:117], v[58:59]
	v_pk_fma_f32 v[118:119], v[96:97], v[98:99], v[56:57]
	v_cvt_pk_bf16_f32 v98, v108, v109
	v_cvt_pk_bf16_f32 v99, v100, v101
	v_cvt_pk_bf16_f32 v100, v110, v111
	v_cvt_pk_bf16_f32 v101, v102, v103
	v_cvt_pk_bf16_f32 v108, v114, v115
	v_cvt_pk_bf16_f32 v109, v112, v113
	v_cvt_pk_bf16_f32 v110, v118, v119
	v_cvt_pk_bf16_f32 v111, v116, v117
	global_store_dwordx4 v[128:129], v[98:101], off sc1
	global_store_dwordx4 v[128:129], v[108:111], off offset:1024 sc1
	s_cbranch_scc1 .LBB0_566
.LBB0_569:
	v_add_u32_e32 v98, s10, v104
	v_cmp_lt_i32_e32 vcc, s3, v98
	s_and_saveexec_b64 s[16:17], vcc
	s_xor_b64 s[40:41], exec, s[16:17]
	v_add_u32_e32 v100, 0xfffff000, v98
	v_mov_b32_e32 v101, v65
	v_lshlrev_b64 v[100:101], 12, v[100:101]
	v_lshl_add_u64 v[102:103], s[38:39], 0, v[100:101]
	v_mov_b32_e32 v99, v65
	s_andn2_saveexec_b64 s[40:41], s[40:41]
	v_ashrrev_i32_e32 v99, 31, v98
	v_lshlrev_b64 v[100:101], 12, v[98:99]
	v_lshl_add_u64 v[102:103], s[36:37], 0, v[100:101]
	s_or_b64 exec, exec, s[40:41]
	v_lshlrev_b64 v[100:101], 11, v[98:99]
	v_lshl_add_u64 v[112:113], v[66:67], 0, v[100:101]
	global_load_dwordx4 v[108:111], v[112:113], off
	s_nop 0
	global_load_dwordx4 v[112:115], v[112:113], off offset:1024
	v_lshl_add_u64 v[102:103], v[102:103], 0, v[64:65]
	global_load_dwordx4 v[116:119], v[102:103], off offset:16
	global_load_dwordx4 v[120:123], v[102:103], off
	global_load_dwordx4 v[124:127], v[102:103], off offset:2064
	global_load_dwordx4 v[128:131], v[102:103], off offset:2048
	s_waitcnt vmcnt(5)
	v_and_b32_e32 v133, 0xffff0000, v110
	v_and_b32_e32 v132, 0xffff0000, v108
	v_lshlrev_b32_e32 v103, 16, v110
	v_lshlrev_b32_e32 v102, 16, v108
	v_lshlrev_b32_e32 v134, 16, v109
	v_and_b32_e32 v110, 0xffff0000, v109
	s_waitcnt vmcnt(4)
	v_lshlrev_b32_e32 v109, 16, v112
	v_lshlrev_b32_e32 v108, 16, v114
	v_and_b32_e32 v137, 0xffff0000, v112
	v_and_b32_e32 v136, 0xffff0000, v114
	v_lshlrev_b32_e32 v138, 16, v115
	v_and_b32_e32 v112, 0xffff0000, v115
	v_pk_mul_f32 v[114:115], v[132:133], v[132:133]
	v_lshlrev_b32_e32 v135, 16, v111
	v_pk_mul_f32 v[140:141], v[136:137], v[136:137]
	v_pk_fma_f32 v[114:115], v[102:103], v[102:103], v[114:115]
	v_and_b32_e32 v111, 0xffff0000, v111
	v_lshlrev_b32_e32 v139, 16, v113
	v_pk_fma_f32 v[140:141], v[108:109], v[108:109], v[140:141]
	v_pk_fma_f32 v[114:115], v[134:135], v[134:135], v[114:115]
	v_and_b32_e32 v113, 0xffff0000, v113
	v_pk_fma_f32 v[140:141], v[138:139], v[138:139], v[140:141]
	v_pk_fma_f32 v[114:115], v[110:111], v[110:111], v[114:115]
	v_pk_fma_f32 v[140:141], v[112:113], v[112:113], v[140:141]
	v_add_f32_e32 v99, v114, v115
	v_add_f32_e32 v99, v99, v141
	v_add_f32_e32 v99, v140, v99
	ds_bpermute_b32 v114, v172, v99
	v_mov_b32_e32 v142, v109
	v_mov_b32_e32 v140, v102
	v_mov_b32_e32 v102, v139
	v_mov_b32_e32 v139, v112
	s_waitcnt lgkmcnt(0)
	v_add_f32_e32 v99, v99, v114
	ds_bpermute_b32 v114, v173, v99
	v_mov_b32_e32 v141, v132
	v_mov_b32_e32 v132, v103
	v_mov_b32_e32 v103, v113
	v_mov_b32_e32 v143, v137
	s_waitcnt lgkmcnt(0)
	v_add_f32_e32 v99, v99, v114
	ds_bpermute_b32 v114, v174, v99
	s_waitcnt lgkmcnt(0)
	v_add_f32_e32 v99, v99, v114
	ds_bpermute_b32 v115, v175, v99
	v_mov_b32_e32 v114, v134
	s_waitcnt lgkmcnt(0)
	v_add_f32_e32 v99, v99, v115
	ds_bpermute_b32 v134, v176, v99
	v_mov_b32_e32 v115, v110
	s_waitcnt lgkmcnt(0)
	v_add_f32_e32 v99, v99, v134
	ds_bpermute_b32 v110, v177, v99
	s_waitcnt lgkmcnt(0)
	v_add_f32_e32 v99, v99, v110
	v_fmamk_f32 v99, v99, 0x3a800000, v106
	v_mul_f32_e32 v109, 0x4b800000, v99
	v_cmp_gt_f32_e32 vcc, s8, v99
	v_mov_b32_e32 v110, v135
	s_nop 0
	v_cndmask_b32_e32 v99, v99, v109, vcc
	v_rsq_f32_e32 v99, v99
	v_mov_b32_e32 v109, v136
	v_mul_f32_e32 v112, 0x45800000, v99
	v_cndmask_b32_e32 v112, v99, v112, vcc
	v_pk_mul_f32 v[134:135], v[112:113], v[140:141] op_sel_hi:[0,1]
	v_pk_mul_f32 v[132:133], v[112:113], v[132:133] op_sel_hi:[0,1]
	v_pk_mul_f32 v[114:115], v[112:113], v[114:115] op_sel_hi:[0,1]
	v_pk_mul_f32 v[110:111], v[112:113], v[110:111] op_sel_hi:[0,1]
	v_pk_mul_f32 v[102:103], v[112:113], v[102:103] op_sel_hi:[0,1]
	v_pk_mul_f32 v[136:137], v[112:113], v[142:143] op_sel_hi:[0,1]
	v_pk_mul_f32 v[138:139], v[112:113], v[138:139] op_sel_hi:[0,1]
	v_pk_mul_f32 v[108:109], v[112:113], v[108:109] op_sel_hi:[0,1]
	v_pk_mul_f32 v[112:113], v[4:5], v[134:135]
	v_pk_mul_f32 v[132:133], v[0:1], v[132:133]
	v_pk_mul_f32 v[134:135], v[36:37], v[136:137]
	v_pk_mul_f32 v[108:109], v[32:33], v[108:109]
	s_waitcnt vmcnt(2)
	v_pk_fma_f32 v[120:121], v[12:13], v[112:113], v[120:121]
	v_pk_fma_f32 v[116:117], v[8:9], v[132:133], v[116:117]
	v_pk_mul_f32 v[114:115], v[6:7], v[114:115]
	v_pk_mul_f32 v[110:111], v[2:3], v[110:111]
	v_pk_mul_f32 v[102:103], v[38:39], v[102:103]
	s_waitcnt vmcnt(0)
	v_pk_fma_f32 v[128:129], v[44:45], v[134:135], v[128:129]
	v_pk_fma_f32 v[124:125], v[40:41], v[108:109], v[124:125]
	v_mov_b32_e32 v108, v121
	v_mov_b32_e32 v109, v117
	v_pk_mul_f32 v[136:137], v[34:35], v[138:139]
	v_pk_fma_f32 v[122:123], v[14:15], v[114:115], v[122:123]
	v_pk_fma_f32 v[118:119], v[10:11], v[110:111], v[118:119]
	v_pk_fma_f32 v[130:131], v[46:47], v[102:103], v[130:131]
	v_mov_b32_e32 v102, v120
	v_mov_b32_e32 v103, v116
	v_mov_b32_e32 v132, v125
	v_mov_b32_e32 v133, v129
	v_pk_mul_f32 v[108:109], v[108:109], v[108:109]
	v_pk_fma_f32 v[126:127], v[42:43], v[136:137], v[126:127]
	v_mov_b32_e32 v110, v122
	v_mov_b32_e32 v111, v118
	v_mov_b32_e32 v114, v124
	v_mov_b32_e32 v115, v128
	v_pk_mul_f32 v[132:133], v[132:133], v[132:133]
	v_pk_fma_f32 v[102:103], v[102:103], v[102:103], v[108:109]
	v_mov_b32_e32 v112, v123
	v_mov_b32_e32 v113, v119
	v_mov_b32_e32 v134, v126
	v_mov_b32_e32 v135, v130
	v_pk_fma_f32 v[108:109], v[114:115], v[114:115], v[132:133]
	v_pk_fma_f32 v[102:103], v[110:111], v[110:111], v[102:103]
	v_mov_b32_e32 v136, v127
	v_mov_b32_e32 v137, v131
	v_pk_fma_f32 v[108:109], v[134:135], v[134:135], v[108:109]
	v_pk_fma_f32 v[102:103], v[112:113], v[112:113], v[102:103]
	v_pk_fma_f32 v[108:109], v[136:137], v[136:137], v[108:109]
	v_add_f32_e32 v99, v102, v103
	v_add_f32_e32 v99, v109, v99
	v_add_f32_e32 v99, v108, v99
	ds_bpermute_b32 v102, v172, v99
	v_lshl_add_u64 v[132:133], v[68:69], 0, v[100:101]
	v_cvt_pk_bf16_f32 v108, v120, v121
	v_cvt_pk_bf16_f32 v109, v122, v123
	v_cvt_pk_bf16_f32 v110, v116, v117
	s_waitcnt lgkmcnt(0)
	v_add_f32_e32 v99, v99, v102
	ds_bpermute_b32 v102, v173, v99
	v_cvt_pk_bf16_f32 v111, v118, v119
	v_cvt_pk_bf16_f32 v112, v128, v129
	v_cvt_pk_bf16_f32 v113, v130, v131
	v_cvt_pk_bf16_f32 v114, v124, v125
	s_waitcnt lgkmcnt(0)
	v_add_f32_e32 v99, v99, v102
	ds_bpermute_b32 v102, v174, v99
	v_cvt_pk_bf16_f32 v115, v126, v127
	global_store_dwordx4 v[132:133], v[108:111], off sc1
	global_store_dwordx4 v[132:133], v[112:115], off offset:1024 sc1
	v_lshl_add_u64 v[100:101], v[70:71], 0, v[100:101]
	s_waitcnt lgkmcnt(0)
	v_add_f32_e32 v99, v99, v102
	ds_bpermute_b32 v103, v175, v99
	v_add_u32_e32 v102, 1, v98
	s_waitcnt lgkmcnt(0)
	v_add_f32_e32 v99, v99, v103
	ds_bpermute_b32 v103, v176, v99
	s_waitcnt lgkmcnt(0)
	v_add_f32_e32 v99, v99, v103
	ds_bpermute_b32 v103, v177, v99
	s_waitcnt lgkmcnt(0)
	v_add_f32_e32 v99, v99, v103
	v_fmamk_f32 v99, v99, 0x3a800000, v106
	v_mul_f32_e32 v103, 0x4b800000, v99
	v_cmp_gt_f32_e32 vcc, s8, v99
	s_nop 1
	v_cndmask_b32_e32 v99, v99, v103, vcc
	v_rsq_f32_e32 v99, v99
	s_nop 0
	v_mul_f32_e32 v103, 0x45800000, v99
	v_cndmask_b32_e32 v108, v99, v103, vcc
	v_pk_mul_f32 v[110:111], v[122:123], v[108:109] op_sel_hi:[1,0]
	v_pk_mul_f32 v[112:113], v[120:121], v[108:109] op_sel_hi:[1,0]
	v_pk_mul_f32 v[114:115], v[118:119], v[108:109] op_sel_hi:[1,0]
	v_pk_mul_f32 v[116:117], v[116:117], v[108:109] op_sel_hi:[1,0]
	v_pk_mul_f32 v[118:119], v[130:131], v[108:109] op_sel_hi:[1,0]
	v_pk_mul_f32 v[120:121], v[128:129], v[108:109] op_sel_hi:[1,0]
	v_pk_mul_f32 v[122:123], v[126:127], v[108:109] op_sel_hi:[1,0]
	v_pk_mul_f32 v[108:109], v[124:125], v[108:109] op_sel_hi:[1,0]
	v_pk_mul_f32 v[112:113], v[20:21], v[112:113]
	v_pk_mul_f32 v[110:111], v[22:23], v[110:111]
	v_pk_mul_f32 v[116:117], v[16:17], v[116:117]
	v_pk_mul_f32 v[114:115], v[18:19], v[114:115]
	v_pk_mul_f32 v[120:121], v[52:53], v[120:121]
	v_pk_mul_f32 v[118:119], v[54:55], v[118:119]
	v_pk_mul_f32 v[108:109], v[48:49], v[108:109]
	v_pk_mul_f32 v[122:123], v[50:51], v[122:123]
	v_pk_fma_f32 v[110:111], v[82:83], v[110:111], v[30:31]
	v_pk_fma_f32 v[112:113], v[84:85], v[112:113], v[28:29]
	v_pk_fma_f32 v[114:115], v[86:87], v[114:115], v[26:27]
	v_pk_fma_f32 v[116:117], v[88:89], v[116:117], v[24:25]
	v_pk_fma_f32 v[118:119], v[90:91], v[118:119], v[62:63]
	v_pk_fma_f32 v[120:121], v[92:93], v[120:121], v[60:61]
	v_pk_fma_f32 v[122:123], v[94:95], v[122:123], v[58:59]
	v_pk_fma_f32 v[124:125], v[96:97], v[108:109], v[56:57]
	v_cvt_pk_bf16_f32 v108, v112, v113
	v_cvt_pk_bf16_f32 v109, v110, v111
	v_cvt_pk_bf16_f32 v110, v116, v117
	v_cvt_pk_bf16_f32 v111, v114, v115
	v_cmp_lt_i32_e32 vcc, s3, v102
	v_cvt_pk_bf16_f32 v112, v120, v121
	v_cvt_pk_bf16_f32 v113, v118, v119
	v_cvt_pk_bf16_f32 v114, v124, v125
	v_cvt_pk_bf16_f32 v115, v122, v123
	global_store_dwordx4 v[100:101], v[108:111], off sc1
	global_store_dwordx4 v[100:101], v[112:115], off offset:1024 sc1
	s_and_saveexec_b64 s[16:17], vcc
	s_xor_b64 s[40:41], exec, s[16:17]
	v_add_u32_e32 v98, 0xfffff001, v98
	v_mov_b32_e32 v99, v65
	v_lshlrev_b64 v[98:99], 12, v[98:99]
	v_lshl_add_u64 v[100:101], s[38:39], 0, v[98:99]
	v_mov_b32_e32 v103, v65
	s_andn2_saveexec_b64 s[40:41], s[40:41]
	s_cbranch_execz .LBB0_568
	v_ashrrev_i32_e32 v103, 31, v102
	v_lshlrev_b64 v[98:99], 12, v[102:103]
	v_lshl_add_u64 v[100:101], s[36:37], 0, v[98:99]
	s_branch .LBB0_568
.LBB0_577:
	s_or_b64 exec, exec, s[4:5]
	s_waitcnt vmcnt(0)
	s_barrier
	s_mov_b64 s[4:5], exec
	v_readlane_b32 s0, v219, 25
	v_readlane_b32 s1, v219, 26
	s_and_b64 s[0:1], s[4:5], s[0:1]
	s_mov_b64 exec, s[0:1]
	s_cbranch_execz .LBB0_629
	v_readlane_b32 s0, v219, 27
	v_readlane_b32 s1, v219, 28
	v_readlane_b32 s2, v219, 29
	v_mov_b32_e32 v0, 0x24000
	s_waitcnt vmcnt(0) lgkmcnt(0)
	buffer_inv sc1
	ds_read_b32 v2, v0
	ds_read_b32 v0, v0 offset:4
	s_lshl_b32 s3, s2, 8
	s_add_i32 s14, s3, 0x2400
	s_add_i32 s3, s3, 0x1400
	v_mov_b32_e32 v1, s3
	s_waitcnt lgkmcnt(0)
	v_readfirstlane_b32 s10, v2
	v_readfirstlane_b32 s11, v0
	v_mov_b32_e32 v0, 1
	s_nop 1
	global_atomic_add v2, v1, v0, s[0:1] sc0
	s_mul_i32 s10, s10, 6
	s_mul_i32 s11, s11, 6
	s_waitcnt vmcnt(0)
	v_readfirstlane_b32 s13, v2
	s_nop 1
	s_add_i32 s13, s13, 1
	s_cmp_lg_u32 s13, s10
	s_cbranch_scc1 .Lnb6_wait
	v_mov_b32_e32 v1, 0x3400
	global_atomic_add v2, v1, v0, s[0:1] sc0
	s_waitcnt vmcnt(0)
	v_readfirstlane_b32 s13, v2
	s_nop 1
	s_add_i32 s13, s13, 1
	s_cmp_lg_u32 s13, s11
	s_cbranch_scc1 .Lnb6_wait
	v_mov_b32_e32 v1, 0x2400
	global_atomic_add v1, v0, s[0:1]
	global_atomic_add v1, v0, s[0:1] offset:256
	global_atomic_add v1, v0, s[0:1] offset:512
	global_atomic_add v1, v0, s[0:1] offset:768
	global_atomic_add v1, v0, s[0:1] offset:1024
	global_atomic_add v1, v0, s[0:1] offset:1280
	global_atomic_add v1, v0, s[0:1] offset:1536
	global_atomic_add v1, v0, s[0:1] offset:1792
	global_atomic_add v1, v0, s[0:1] offset:2048
	global_atomic_add v1, v0, s[0:1] offset:2304
	global_atomic_add v1, v0, s[0:1] offset:2560
	global_atomic_add v1, v0, s[0:1] offset:2816
	global_atomic_add v1, v0, s[0:1] offset:3072
	global_atomic_add v1, v0, s[0:1] offset:3328
	global_atomic_add v1, v0, s[0:1] offset:3584
	global_atomic_add v1, v0, s[0:1] offset:3840
	v_mov_b32_e32 v1, 0x3500
	global_atomic_add v1, v0, s[0:1]

.Lnb6_spin:
	global_load_dword v2, v1, s[0:1] sc1
	s_waitcnt vmcnt(0)
	v_readfirstlane_b32 s13, v2
	s_nop 1
	s_cmp_ge_u32 s13, 6
	s_cbranch_scc1 .Lnb6_done
	s_sleep 1
	s_add_i32 s15, s15, 1
	s_cmp_lt_u32 s15, 0x200000
	s_cbranch_scc1 .Lnb6_spin
.Lnb6_done:
	s_waitcnt vmcnt(0)
.LBB0_629:
	s_or_b64 exec, exec, s[4:5]
	s_cmpk_lt_i32 s78, 0x580
	s_cselect_b64 s[0:1], -1, 0
	v_writelane_b32 v219, s0, 52
	s_cmpk_gt_i32 s78, 0x57f
	v_readfirstlane_b32 s4, v168
	s_waitcnt lgkmcnt(0)
	s_barrier
	v_writelane_b32 v219, s1, 53
	s_cbranch_scc1 .LBB0_693
	s_add_u32 s0, s56, 0x900000
	s_addc_u32 s1, s57, 0
	s_lshl_b32 s2, s78, 19
	s_lshr_b32 s5, s4, 6
	s_bfe_u32 s22, s4, 0x10006
	s_lshr_b32 s23, s4, 7
	s_and_b32 s2, s2, 0xf80000
	s_add_u32 s16, s30, s2
	s_addc_u32 s17, s31, 0
	s_lshl_b32 s2, s78, 2
	s_and_b32 s2, s2, 0xffffff80
	s_ashr_i32 s3, s2, 31
	s_mov_b32 s93, 0
	s_lshl_b64 s[6:7], s[2:3], 11
	s_lshl_b32 s92, s5, 5
	s_lshl_b32 s2, s5, 12
	s_add_i32 s3, s2, 0
	s_lshl_b64 s[14:15], s[92:93], 11
	s_add_u32 s8, s16, s14
	s_addc_u32 s9, s17, s15
	s_or_b32 s10, s92, 8
	s_mov_b32 s11, s93
	s_lshl_b64 s[36:37], s[10:11], 11
	s_add_u32 s10, s16, s36
	v_mov_b32_e32 v0, v178
	v_mov_b32_e32 v1, v179
	s_mov_b32 m0, s3
	s_addc_u32 s11, s17, s37
	s_or_b32 s12, s92, 16
	s_mov_b32 s13, s93
	s_barrier
	s_lshl_b64 s[38:39], s[12:13], 11
	global_load_lds_dwordx4 v0, s[8:9]
	s_add_i32 m0, s3, 0x400
	s_add_u32 s12, s16, s38
	s_addc_u32 s13, s17, s39
	s_or_b32 s92, s92, 24
	global_load_lds_dwordx4 v1, s[10:11]
	s_add_i32 m0, s3, 0x800
	s_lshl_b64 s[40:41], s[92:93], 11
	s_add_u32 s18, s16, s40
	global_load_lds_dwordx4 v0, s[12:13]
	s_addc_u32 s19, s17, s41
	s_add_i32 m0, s3, 0xc00
	s_add_u32 s17, s0, s6
	s_addc_u32 s21, s1, s7
	s_lshl_b32 s16, s5, 11
	s_lshl_b32 s92, s5, 4
	s_sub_i32 s24, s3, s16
	global_load_lds_dwordx4 v1, s[18:19]
	s_add_i32 m0, s24, 0x8000
	s_lshl_b64 s[42:43], s[92:93], 11
	s_add_u32 s6, s17, s42
	s_addc_u32 s7, s21, s43
	s_or_b32 s92, s92, 8
	s_lshl_b64 s[44:45], s[92:93], 11
	s_add_u32 s20, s17, s44
	global_load_lds_dwordx4 v0, s[6:7]
	s_addc_u32 s21, s21, s45
	s_add_i32 m0, s24, 0x8400
	v_mov_b32_e32 v150, v178
	v_mov_b32_e32 v0, v179
	v_mov_b32_e32 v151, 0
	global_load_lds_dwordx4 v1, s[20:21]
	s_mov_b64 s[46:47], 0x80
	v_lshl_add_u64 v[2:3], s[8:9], 0, v[150:151]
	s_add_i32 m0, s3, 0xc000
	v_lshl_add_u64 v[2:3], v[2:3], 0, s[46:47]
	v_mov_b32_e32 v1, v151
	global_load_lds_dwordx4 v[2:3], off
	v_lshl_add_u64 v[2:3], s[10:11], 0, v[0:1]
	v_lshl_add_u64 v[2:3], v[2:3], 0, s[46:47]
	s_add_i32 m0, s3, 0xc400
	s_add_i32 s8, s16, 0
	global_load_lds_dwordx4 v[2:3], off
	v_lshl_add_u64 v[2:3], s[12:13], 0, v[150:151]
	v_lshl_add_u64 v[2:3], v[2:3], 0, s[46:47]
	s_add_i32 m0, s3, 0xc800
	v_lshl_or_b32 v156, s23, 6, v167
	global_load_lds_dwordx4 v[2:3], off
	v_lshl_add_u64 v[2:3], s[18:19], 0, v[0:1]
	v_lshl_add_u64 v[2:3], v[2:3], 0, s[46:47]
	s_add_i32 m0, s3, 0xcc00
	v_lshl_add_u64 v[0:1], s[20:21], 0, v[0:1]
	global_load_lds_dwordx4 v[2:3], off
	v_lshl_add_u64 v[2:3], s[6:7], 0, v[150:151]
	s_add_i32 m0, s8, 0x14000
	v_lshl_add_u64 v[2:3], v[2:3], 0, s[46:47]
	global_load_lds_dwordx4 v[2:3], off
	v_lshl_add_u64 v[0:1], v[0:1], 0, s[46:47]
	s_add_i32 m0, s8, 0x14400
	s_cmpk_gt_u32 s4, 0xff
	global_load_lds_dwordx4 v[0:1], off
	s_cselect_b64 s[48:49], -1, 0
	s_lshl_b32 s92, s5, 15
	s_lshl_b32 s4, s5, 14
	s_lshl_b32 s17, s22, 13
	s_lshl_b32 s18, s23, 13
	s_lshl_b32 s6, s22, 6
	v_readlane_b32 s8, v219, 33
	v_readlane_b32 s9, v219, 34
	s_add_u32 s6, s8, s6
	s_addc_u32 s7, s9, 0
	s_add_u32 s19, s56, s14
	s_addc_u32 s22, s57, s15
	s_lshl_b32 s23, s78, 8
	s_lshl_b32 s24, s58, 8
	s_add_u32 s25, s56, s42
	s_addc_u32 s26, s57, s43
	s_lshl_b64 s[50:51], s[92:93], 1
	s_mov_b32 s5, s93
	v_add_u32_e32 v0, 12, v146
	v_cmp_eq_u32_e32 vcc, 0, v171
	s_add_u32 s27, s56, s50
	v_xor_b32_e32 v1, v147, v170
	v_cndmask_b32_e32 v0, v0, v146, vcc
	s_addc_u32 s28, s57, s51
	s_lshl_b64 s[68:69], s[4:5], 1
	v_lshlrev_b32_e32 v157, 4, v1
	v_bitop3_b32 v1, v147, v170, 4 bitop3:0x36
	v_lshlrev_b32_e32 v150, 1, v0
	s_add_u32 s29, s56, s68
	v_lshlrev_b32_e32 v158, 4, v1
	v_lshl_add_u64 v[152:153], s[6:7], 0, v[150:151]
	s_addc_u32 s33, s57, s69
	s_mov_b64 s[4:5], -1
	s_mov_b64 s[70:71], 0x100
	s_mov_b64 s[72:73], 0x3400180
	s_mov_b64 s[74:75], 0x3404180
	s_mov_b64 s[76:77], 0x3408180
	s_mov_b32 s61, s78
	s_mov_b64 s[78:79], 0x340c180
	s_mov_b64 s[80:81], 0x900180
	s_mov_b64 s[82:83], 0x904180
	s_mov_b64 s[84:85], 0x4000
	s_movk_i32 s60, 0x1600
	s_branch .LBB0_632
.LBB0_631:
	v_mul_f32_e32 v67, 0xbfb8aa3b, v56
	v_exp_f32_e32 v67, v67
	s_lshl_b32 s4, s63, 6
	s_ashr_i32 s5, s4, 31
	v_add_u32_e32 v66, s62, v156
	v_add_f32_e32 v67, 1.0, v67
	v_rcp_f32_e32 v68, v67
	v_mul_f32_e32 v67, 0xbfb8aa3b, v57
	v_exp_f32_e32 v67, v67
	v_lshl_add_u64 v[64:65], s[4:5], 1, v[152:153]
	s_add_i32 s23, s23, s24
	s_andn2_b64 vcc, exec, s[90:91]
	v_add_f32_e32 v67, 1.0, v67
	v_rcp_f32_e32 v69, v67
	s_nop 0
	v_pk_mul_f32 v[56:57], v[56:57], v[68:69]
	s_nop 0
	v_pk_mul_f32 v[56:57], v[60:61], v[56:57]
	s_nop 0
	v_cvt_pk_bf16_f32 v56, v56, v57
	v_mul_f32_e32 v57, 0xbfb8aa3b, v58
	v_exp_f32_e32 v57, v57
	s_nop 0
	v_add_f32_e32 v57, 1.0, v57
	v_rcp_f32_e32 v60, v57
	v_mul_f32_e32 v57, 0xbfb8aa3b, v59
	v_exp_f32_e32 v57, v57
	s_nop 0
	v_add_f32_e32 v57, 1.0, v57
	v_rcp_f32_e32 v61, v57
	s_nop 0
	v_pk_mul_f32 v[58:59], v[58:59], v[60:61]
	s_nop 0
	v_pk_mul_f32 v[58:59], v[62:63], v[58:59]
	s_nop 0
	v_cvt_pk_bf16_f32 v57, v58, v59
	v_mul_f32_e32 v58, 0xbfb8aa3b, v48
	v_mul_f32_e32 v59, 0xbfb8aa3b, v49
	v_exp_f32_e32 v58, v58
	v_exp_f32_e32 v59, v59
	v_add_f32_e32 v58, 1.0, v58
	v_add_f32_e32 v59, 1.0, v59
	v_rcp_f32_e32 v58, v58
	v_rcp_f32_e32 v59, v59
	s_nop 0
	v_pk_mul_f32 v[48:49], v[48:49], v[58:59]
	s_nop 0
	v_pk_mul_f32 v[48:49], v[52:53], v[48:49]
	s_nop 0
	v_cvt_pk_bf16_f32 v58, v48, v49
	v_mul_f32_e32 v48, 0xbfb8aa3b, v50
	v_mul_f32_e32 v49, 0xbfb8aa3b, v51
	v_exp_f32_e32 v48, v48
	v_exp_f32_e32 v49, v49
	v_permlane16_swap_b32_e32 v56, v58
	v_add_f32_e32 v48, 1.0, v48
	v_add_f32_e32 v49, 1.0, v49
	v_rcp_f32_e32 v48, v48
	v_rcp_f32_e32 v49, v49
	s_nop 0
	v_pk_mul_f32 v[48:49], v[50:51], v[48:49]
	s_nop 0
	v_pk_mul_f32 v[48:49], v[54:55], v[48:49]
	s_nop 0
	v_cvt_pk_bf16_f32 v59, v48, v49
	s_nop 1
	v_permlane16_swap_b32_e32 v57, v59
	v_mad_u64_u32 v[48:49], s[4:5], v66, s60, v[64:65]
	global_store_dwordx4 v[48:49], v[56:59], off sc1
	v_mul_f32_e32 v48, 0xbfb8aa3b, v40
	v_mul_f32_e32 v49, 0xbfb8aa3b, v41
	v_exp_f32_e32 v48, v48
	v_exp_f32_e32 v49, v49
	v_add_f32_e32 v48, 1.0, v48
	v_add_f32_e32 v49, 1.0, v49
	v_rcp_f32_e32 v48, v48
	v_rcp_f32_e32 v49, v49
	s_nop 0
	v_pk_mul_f32 v[40:41], v[40:41], v[48:49]
	s_nop 0
	v_pk_mul_f32 v[40:41], v[44:45], v[40:41]
	s_nop 0
	v_cvt_pk_bf16_f32 v40, v40, v41
	v_mul_f32_e32 v41, 0xbfb8aa3b, v42
	v_exp_f32_e32 v41, v41
	s_nop 0
	v_add_f32_e32 v41, 1.0, v41
	v_rcp_f32_e32 v44, v41
	v_mul_f32_e32 v41, 0xbfb8aa3b, v43
	v_exp_f32_e32 v41, v41
	s_nop 0
	v_add_f32_e32 v41, 1.0, v41
	v_rcp_f32_e32 v45, v41
	s_nop 0
	v_pk_mul_f32 v[42:43], v[42:43], v[44:45]
	s_nop 0
	v_pk_mul_f32 v[42:43], v[46:47], v[42:43]
	s_nop 0
	v_cvt_pk_bf16_f32 v41, v42, v43
	v_mul_f32_e32 v42, 0xbfb8aa3b, v32
	v_mul_f32_e32 v43, 0xbfb8aa3b, v33
	v_exp_f32_e32 v42, v42
	v_exp_f32_e32 v43, v43
	v_add_f32_e32 v42, 1.0, v42
	v_add_f32_e32 v43, 1.0, v43
	v_rcp_f32_e32 v42, v42
	v_rcp_f32_e32 v43, v43
	s_nop 0
	v_pk_mul_f32 v[32:33], v[32:33], v[42:43]
	s_nop 0
	v_pk_mul_f32 v[32:33], v[36:37], v[32:33]
	s_nop 0
	v_cvt_pk_bf16_f32 v42, v32, v33
	v_mul_f32_e32 v32, 0xbfb8aa3b, v34
	v_mul_f32_e32 v33, 0xbfb8aa3b, v35
	v_exp_f32_e32 v32, v32
	v_exp_f32_e32 v33, v33
	v_permlane16_swap_b32_e32 v40, v42
	v_add_f32_e32 v32, 1.0, v32
	v_add_f32_e32 v33, 1.0, v33
	v_rcp_f32_e32 v32, v32
	v_rcp_f32_e32 v33, v33
	s_nop 0
	v_pk_mul_f32 v[32:33], v[34:35], v[32:33]
	s_nop 0
	v_pk_mul_f32 v[32:33], v[38:39], v[32:33]
	s_nop 0
	v_cvt_pk_bf16_f32 v43, v32, v33
	v_or_b32_e32 v32, 16, v66
	s_nop 0
	v_permlane16_swap_b32_e32 v41, v43
	v_mad_u64_u32 v[32:33], s[4:5], v32, s60, v[64:65]
	global_store_dwordx4 v[32:33], v[40:43], off sc1
	v_mul_f32_e32 v32, 0xbfb8aa3b, v24
	v_mul_f32_e32 v33, 0xbfb8aa3b, v25
	v_exp_f32_e32 v32, v32
	v_exp_f32_e32 v33, v33
	v_add_f32_e32 v32, 1.0, v32
	v_add_f32_e32 v33, 1.0, v33
	v_rcp_f32_e32 v32, v32
	v_rcp_f32_e32 v33, v33
	s_nop 0
	v_pk_mul_f32 v[24:25], v[24:25], v[32:33]
	s_nop 0
	v_pk_mul_f32 v[24:25], v[28:29], v[24:25]
	s_nop 0
	v_cvt_pk_bf16_f32 v24, v24, v25
	v_mul_f32_e32 v25, 0xbfb8aa3b, v26
	v_exp_f32_e32 v25, v25
	s_nop 0
	v_add_f32_e32 v25, 1.0, v25
	v_rcp_f32_e32 v28, v25
	v_mul_f32_e32 v25, 0xbfb8aa3b, v27
	v_exp_f32_e32 v25, v25
	s_nop 0
	v_add_f32_e32 v25, 1.0, v25
	v_rcp_f32_e32 v29, v25
	s_nop 0
	v_pk_mul_f32 v[26:27], v[26:27], v[28:29]
	s_nop 0
	v_pk_mul_f32 v[26:27], v[30:31], v[26:27]
	s_nop 0
	v_cvt_pk_bf16_f32 v25, v26, v27
	v_mul_f32_e32 v26, 0xbfb8aa3b, v16
	v_mul_f32_e32 v27, 0xbfb8aa3b, v17
	v_exp_f32_e32 v26, v26
	v_exp_f32_e32 v27, v27
	v_add_f32_e32 v26, 1.0, v26
	v_add_f32_e32 v27, 1.0, v27
	v_rcp_f32_e32 v26, v26
	v_rcp_f32_e32 v27, v27
	s_nop 0
	v_pk_mul_f32 v[16:17], v[16:17], v[26:27]
	s_nop 0
	v_pk_mul_f32 v[16:17], v[20:21], v[16:17]
	s_nop 0
	v_cvt_pk_bf16_f32 v26, v16, v17
	v_mul_f32_e32 v16, 0xbfb8aa3b, v18
	v_mul_f32_e32 v17, 0xbfb8aa3b, v19
	v_exp_f32_e32 v16, v16
	v_exp_f32_e32 v17, v17
	v_permlane16_swap_b32_e32 v24, v26
	v_add_f32_e32 v16, 1.0, v16
	v_add_f32_e32 v17, 1.0, v17
	v_rcp_f32_e32 v16, v16
	v_rcp_f32_e32 v17, v17
	s_nop 0
	v_pk_mul_f32 v[16:17], v[18:19], v[16:17]
	s_nop 0
	v_pk_mul_f32 v[16:17], v[22:23], v[16:17]
	s_nop 0
	v_cvt_pk_bf16_f32 v27, v16, v17
	v_or_b32_e32 v16, 32, v66
	s_nop 0
	v_permlane16_swap_b32_e32 v25, v27
	v_mad_u64_u32 v[16:17], s[4:5], v16, s60, v[64:65]
	global_store_dwordx4 v[16:17], v[24:27], off sc1
	v_mul_f32_e32 v16, 0xbfb8aa3b, v8
	v_mul_f32_e32 v17, 0xbfb8aa3b, v9
	v_exp_f32_e32 v16, v16
	v_exp_f32_e32 v17, v17
	v_add_f32_e32 v16, 1.0, v16
	v_add_f32_e32 v17, 1.0, v17
	v_rcp_f32_e32 v16, v16
	v_rcp_f32_e32 v17, v17
	s_nop 0
	v_pk_mul_f32 v[8:9], v[8:9], v[16:17]
	s_nop 0
	v_pk_mul_f32 v[8:9], v[12:13], v[8:9]
	s_nop 0
	v_cvt_pk_bf16_f32 v8, v8, v9
	v_mul_f32_e32 v9, 0xbfb8aa3b, v10
	v_exp_f32_e32 v9, v9
	s_nop 0
	v_add_f32_e32 v9, 1.0, v9
	v_rcp_f32_e32 v12, v9
	v_mul_f32_e32 v9, 0xbfb8aa3b, v11
	v_exp_f32_e32 v9, v9
	s_nop 0
	v_add_f32_e32 v9, 1.0, v9
	v_rcp_f32_e32 v13, v9
	s_nop 0
	v_pk_mul_f32 v[10:11], v[10:11], v[12:13]
	s_nop 0
	v_pk_mul_f32 v[10:11], v[14:15], v[10:11]
	s_nop 0
	v_cvt_pk_bf16_f32 v9, v10, v11
	v_mul_f32_e32 v10, 0xbfb8aa3b, v0
	v_mul_f32_e32 v11, 0xbfb8aa3b, v1
	v_exp_f32_e32 v10, v10
	v_exp_f32_e32 v11, v11
	v_add_f32_e32 v10, 1.0, v10
	v_add_f32_e32 v11, 1.0, v11
	v_rcp_f32_e32 v10, v10
	v_rcp_f32_e32 v11, v11
	s_nop 0
	v_pk_mul_f32 v[0:1], v[0:1], v[10:11]
	s_nop 0
	v_pk_mul_f32 v[0:1], v[4:5], v[0:1]
	s_nop 0
	v_cvt_pk_bf16_f32 v10, v0, v1
	v_mul_f32_e32 v0, 0xbfb8aa3b, v2
	v_mul_f32_e32 v1, 0xbfb8aa3b, v3
	v_exp_f32_e32 v0, v0
	v_exp_f32_e32 v1, v1
	v_permlane16_swap_b32_e32 v8, v10
	v_add_f32_e32 v0, 1.0, v0
	v_add_f32_e32 v1, 1.0, v1
	v_rcp_f32_e32 v0, v0
	v_rcp_f32_e32 v1, v1
	s_nop 0
	v_pk_mul_f32 v[0:1], v[2:3], v[0:1]
	s_nop 0
	v_pk_mul_f32 v[0:1], v[6:7], v[0:1]
	s_nop 0
	v_cvt_pk_bf16_f32 v11, v0, v1
	v_or_b32_e32 v0, 48, v66
	v_mad_u64_u32 v[0:1], s[4:5], v0, s60, v[64:65]
	v_permlane16_swap_b32_e32 v9, v11
	s_mov_b64 s[4:5], 0
	global_store_dwordx4 v[0:1], v[8:11], off sc1
	s_cbranch_vccz .LBB0_692

.Lgu0h_BB0_1032:
	s_lshl_b32 s8, s6, 1
	s_lshl_b32 s9, s5, 1
	v_or_b32_e32 v9, s8, v1
	v_or_b32_e32 v11, s9, v0
	s_add_i32 s10, s8, 4
	s_add_i32 s11, s9, 4
	s_add_i32 s12, s8, 8
	s_add_i32 s13, s9, 8
	s_add_i32 s14, s8, 12
	s_add_i32 s15, s9, 12
	s_add_i32 s16, s8, 16
	s_add_i32 s17, s9, 16
	s_add_i32 s18, s8, 20
	s_add_i32 s19, s9, 20
	s_add_i32 s20, s8, 24
	s_add_i32 s21, s9, 24
	s_add_i32 s8, s8, 28
	s_add_i32 s9, s9, 28
	v_add_u32_e32 v17, v9, v7
	v_add_u32_e32 v37, v11, v16
	v_or_b32_e32 v70, s10, v1
	v_or_b32_e32 v71, s11, v0
	v_or_b32_e32 v72, s12, v1
	v_or_b32_e32 v73, s13, v0
	v_or_b32_e32 v74, s14, v1
	v_or_b32_e32 v75, s15, v0
	v_or_b32_e32 v76, s16, v1
	v_or_b32_e32 v77, s17, v0
	v_or_b32_e32 v78, s18, v1
	v_or_b32_e32 v79, s19, v0
	v_or_b32_e32 v80, s20, v1
	v_or_b32_e32 v81, s21, v0
	v_or_b32_e32 v82, s8, v1
	v_or_b32_e32 v83, s9, v0
	v_ashrrev_i32_e32 v42, 31, v37
	v_ashrrev_i32_e32 v43, 31, v17
	v_mul_lo_u32 v84, v3, v17
	v_mad_u64_u32 v[38:39], s[8:9], v2, v17, 0
	v_mul_lo_u32 v17, v13, v37
	v_mad_u64_u32 v[40:41], s[8:9], v12, v37, 0
	v_add_u32_e32 v37, v70, v7
	v_add_u32_e32 v44, v71, v16
	v_add_u32_e32 v46, v72, v7
	v_add_u32_e32 v48, v73, v16
	v_add_u32_e32 v50, v74, v7
	v_add_u32_e32 v52, v75, v16
	v_add_u32_e32 v54, v76, v7
	v_add_u32_e32 v56, v77, v16
	v_add_u32_e32 v58, v78, v7
	v_add_u32_e32 v60, v79, v16
	v_add_u32_e32 v62, v80, v7
	v_add_u32_e32 v64, v81, v16
	v_add_u32_e32 v66, v82, v7
	v_add_u32_e32 v68, v83, v16
	v_mul_lo_u32 v85, v2, v43
	v_mul_lo_u32 v86, v12, v42
	v_ashrrev_i32_e32 v87, 31, v44
	v_ashrrev_i32_e32 v88, 31, v37
	v_ashrrev_i32_e32 v90, 31, v48
	v_ashrrev_i32_e32 v91, 31, v46
	v_ashrrev_i32_e32 v94, 31, v52
	v_ashrrev_i32_e32 v95, 31, v50
	v_ashrrev_i32_e32 v98, 31, v56
	v_ashrrev_i32_e32 v99, 31, v54
	v_ashrrev_i32_e32 v102, 31, v60
	v_ashrrev_i32_e32 v103, 31, v58
	v_ashrrev_i32_e32 v106, 31, v64
	v_ashrrev_i32_e32 v107, 31, v62
	v_ashrrev_i32_e32 v110, 31, v68
	v_ashrrev_i32_e32 v111, 31, v66
	v_mul_lo_u32 v89, v3, v37
	v_mad_u64_u32 v[42:43], s[8:9], v2, v37, 0
	v_mul_lo_u32 v37, v13, v44
	v_mad_u64_u32 v[44:45], s[8:9], v12, v44, 0
	v_mul_lo_u32 v92, v3, v46
	v_mad_u64_u32 v[46:47], s[8:9], v2, v46, 0
	v_mul_lo_u32 v93, v13, v48
	v_mad_u64_u32 v[48:49], s[8:9], v12, v48, 0
	v_mul_lo_u32 v96, v3, v50
	v_mad_u64_u32 v[50:51], s[8:9], v2, v50, 0
	v_mul_lo_u32 v97, v13, v52
	v_mad_u64_u32 v[52:53], s[8:9], v12, v52, 0
	v_mul_lo_u32 v100, v3, v54
	v_mad_u64_u32 v[54:55], s[8:9], v2, v54, 0
	v_mul_lo_u32 v101, v13, v56
	v_mad_u64_u32 v[56:57], s[8:9], v12, v56, 0
	v_mul_lo_u32 v104, v3, v58
	v_mad_u64_u32 v[58:59], s[8:9], v2, v58, 0
	v_mul_lo_u32 v105, v13, v60
	v_mad_u64_u32 v[60:61], s[8:9], v12, v60, 0
	v_mul_lo_u32 v108, v3, v62
	v_mad_u64_u32 v[62:63], s[8:9], v2, v62, 0
	v_mul_lo_u32 v109, v13, v64
	v_mad_u64_u32 v[64:65], s[8:9], v12, v64, 0
	v_mul_lo_u32 v112, v3, v66
	v_mad_u64_u32 v[66:67], s[8:9], v2, v66, 0
	v_mul_lo_u32 v113, v13, v68
	v_mad_u64_u32 v[68:69], s[8:9], v12, v68, 0
	v_add3_u32 v39, v39, v85, v84
	v_add3_u32 v41, v41, v86, v17
	v_mul_lo_u32 v17, v2, v88
	v_mul_lo_u32 v84, v12, v87
	v_mul_lo_u32 v85, v2, v91
	v_mul_lo_u32 v86, v12, v90
	v_mul_lo_u32 v87, v2, v95
	v_mul_lo_u32 v88, v12, v94
	v_mul_lo_u32 v90, v2, v99
	v_mul_lo_u32 v91, v12, v98
	v_mul_lo_u32 v94, v2, v103
	v_mul_lo_u32 v95, v12, v102
	v_mul_lo_u32 v98, v2, v107
	v_mul_lo_u32 v99, v12, v106
	v_mul_lo_u32 v102, v2, v111
	v_mul_lo_u32 v103, v12, v110
	v_lshl_add_u64 v[40:41], v[40:41], 2, v[18:19]
	v_add3_u32 v43, v43, v17, v89
	v_add3_u32 v45, v45, v84, v37
	v_add3_u32 v47, v47, v85, v92
	v_add3_u32 v49, v49, v86, v93
	v_add3_u32 v51, v51, v87, v96
	v_add3_u32 v53, v53, v88, v97
	v_add3_u32 v55, v55, v90, v100
	v_add3_u32 v57, v57, v91, v101
	v_add3_u32 v59, v59, v94, v104
	v_add3_u32 v61, v61, v95, v105
	v_add3_u32 v63, v63, v98, v108
	v_add3_u32 v65, v65, v99, v109
	v_add3_u32 v67, v67, v102, v112
	v_add3_u32 v69, v69, v103, v113
	v_lshl_add_u64 v[38:39], v[38:39], 2, v[18:19]
	v_lshl_add_u64 v[44:45], v[44:45], 2, v[18:19]
	v_lshl_add_u64 v[42:43], v[42:43], 2, v[18:19]
	v_lshl_add_u64 v[48:49], v[48:49], 2, v[18:19]
	v_lshl_add_u64 v[46:47], v[46:47], 2, v[18:19]
	v_lshl_add_u64 v[52:53], v[52:53], 2, v[18:19]
	v_lshl_add_u64 v[50:51], v[50:51], 2, v[18:19]
	v_lshl_add_u64 v[56:57], v[56:57], 2, v[18:19]
	v_lshl_add_u64 v[54:55], v[54:55], 2, v[18:19]
	v_lshl_add_u64 v[60:61], v[60:61], 2, v[18:19]
	v_lshl_add_u64 v[58:59], v[58:59], 2, v[18:19]
	v_lshl_add_u64 v[64:65], v[64:65], 2, v[18:19]
	v_lshl_add_u64 v[62:63], v[62:63], 2, v[18:19]
	v_lshl_add_u64 v[68:69], v[68:69], 2, v[18:19]
	v_lshl_add_u64 v[66:67], v[66:67], 2, v[18:19]
	global_load_dword v17, v[40:41], off
	global_load_dword v37, v[38:39], off
	global_load_dword v84, v[44:45], off
	global_load_dword v85, v[42:43], off
	global_load_dword v86, v[48:49], off
	global_load_dword v87, v[46:47], off
	global_load_dword v88, v[52:53], off
	global_load_dword v89, v[50:51], off
	global_load_dword v90, v[56:57], off
	global_load_dword v91, v[54:55], off
	global_load_dword v92, v[60:61], off
	global_load_dword v93, v[58:59], off
	global_load_dword v94, v[64:65], off
	global_load_dword v95, v[62:63], off
	global_load_dword v96, v[68:69], off
	global_load_dword v97, v[66:67], off
	s_add_i32 s5, s5, 16
	s_add_i32 s6, s6, 16
	s_add_i32 s7, s7, -16
	v_mad_u64_u32 v[38:39], s[8:9], v11, s1, v[6:7]
	s_cmp_lg_u32 s7, 0
	v_mad_u64_u32 v[40:41], s[8:9], v9, s1, v[6:7]
	v_mad_u64_u32 v[42:43], s[8:9], v71, s1, v[6:7]
	v_mad_u64_u32 v[44:45], s[8:9], v70, s1, v[6:7]
	v_mad_u64_u32 v[46:47], s[8:9], v73, s1, v[6:7]
	v_mad_u64_u32 v[48:49], s[8:9], v72, s1, v[6:7]
	v_mad_u64_u32 v[50:51], s[8:9], v75, s1, v[6:7]
	v_mad_u64_u32 v[52:53], s[8:9], v74, s1, v[6:7]
	v_mad_u64_u32 v[54:55], s[8:9], v77, s1, v[6:7]
	v_mad_u64_u32 v[56:57], s[8:9], v76, s1, v[6:7]
	v_mad_u64_u32 v[58:59], s[8:9], v79, s1, v[6:7]
	v_mad_u64_u32 v[60:61], s[8:9], v78, s1, v[6:7]
	v_mad_u64_u32 v[62:63], s[8:9], v81, s1, v[6:7]
	v_mad_u64_u32 v[64:65], s[8:9], v80, s1, v[6:7]
	v_mad_u64_u32 v[66:67], s[8:9], v83, s1, v[6:7]
	v_mad_u64_u32 v[68:69], s[8:9], v82, s1, v[6:7]
	s_waitcnt vmcnt(15)
	ds_write_b32 v38, v17
	s_waitcnt vmcnt(14)
	ds_write_b32 v40, v37
	s_waitcnt vmcnt(13)
	ds_write_b32 v42, v84
	s_waitcnt vmcnt(12)
	ds_write_b32 v44, v85
	s_waitcnt vmcnt(11)
	ds_write_b32 v46, v86
	s_waitcnt vmcnt(10)
	ds_write_b32 v48, v87
	s_waitcnt vmcnt(9)
	ds_write_b32 v50, v88
	s_waitcnt vmcnt(8)
	ds_write_b32 v52, v89
	s_waitcnt vmcnt(7)
	ds_write_b32 v54, v90
	s_waitcnt vmcnt(6)
	ds_write_b32 v56, v91
	s_waitcnt vmcnt(5)
	ds_write_b32 v58, v92
	s_waitcnt vmcnt(4)
	ds_write_b32 v60, v93
	s_waitcnt vmcnt(3)
	ds_write_b32 v62, v94
	s_waitcnt vmcnt(2)
	ds_write_b32 v64, v95
	s_waitcnt vmcnt(1)
	ds_write_b32 v66, v96
	s_waitcnt vmcnt(0)
	ds_write_b32 v68, v97
	s_cbranch_scc1 .Lgu0h_BB0_1032
	s_waitcnt lgkmcnt(0)
	v_ashrrev_i32_e32 v17, 31, v16
	v_lshl_add_u64 v[2:3], v[16:17], 1, v[14:15]
	ds_read2_b32 v[16:17], v20 offset0:33 offset1:41
	ds_read2_b32 v[18:19], v20 offset1:8
	ds_read2_b32 v[38:39], v20 offset0:66 offset1:74
	ds_read2_b32 v[40:41], v20 offset0:99 offset1:107
	ds_read2_b32 v[42:43], v20 offset0:132 offset1:140
	ds_read2_b32 v[44:45], v20 offset0:165 offset1:173
	ds_read2_b32 v[46:47], v20 offset0:198 offset1:206
	ds_read2_b32 v[48:49], v20 offset0:231 offset1:239
	v_or_b32_e32 v7, v4, v185
	v_ashrrev_i32_e32 v9, 31, v4
	v_mov_b32_e32 v11, v5
	v_mul_lo_u32 v9, v9, v36
	v_mad_u64_u32 v[50:51], s[6:7], v7, v36, 0
	v_lshl_add_u64 v[2:3], v[2:3], 0, v[10:11]
	v_add_u32_e32 v51, v51, v9
	s_waitcnt lgkmcnt(6)
	v_cvt_pk_bf16_f32 v12, v18, v16
	s_waitcnt lgkmcnt(4)
	v_cvt_pk_bf16_f32 v13, v38, v40
	s_waitcnt lgkmcnt(2)
	v_cvt_pk_bf16_f32 v14, v42, v44
	s_waitcnt lgkmcnt(0)
	v_cvt_pk_bf16_f32 v15, v46, v48
	v_lshl_add_u64 v[50:51], v[50:51], 1, v[2:3]
	global_store_dwordx4 v[50:51], v[12:15], off sc1
	v_or_b32_e32 v7, v4, v21
	s_add_i32 s5, s0, 0x80
	v_cvt_pk_bf16_f32 v12, v19, v17
	v_cvt_pk_bf16_f32 v13, v39, v41
	v_cvt_pk_bf16_f32 v14, v43, v45
	v_cvt_pk_bf16_f32 v15, v47, v49
	v_mad_u64_u32 v[16:17], s[6:7], v7, v36, 0
	ds_read2_b32 v[18:19], v20 offset0:16 offset1:24
	ds_read2_b32 v[38:39], v20 offset0:49 offset1:57
	ds_read2_b32 v[40:41], v20 offset0:82 offset1:90
	ds_read2_b32 v[42:43], v20 offset0:115 offset1:123
	ds_read2_b32 v[44:45], v20 offset0:148 offset1:156
	ds_read2_b32 v[46:47], v20 offset0:181 offset1:189
	ds_read2_b32 v[48:49], v20 offset0:214 offset1:222
	ds_read2_b32 v[50:51], v20 offset0:247 offset1:255
	v_add_u32_e32 v17, v17, v9
	v_lshl_add_u64 v[16:17], v[16:17], 1, v[2:3]
	v_or_b32_e32 v7, v4, v22
	global_store_dwordx4 v[16:17], v[12:15], off sc1
	v_mad_u64_u32 v[16:17], s[6:7], v7, v36, 0
	v_add_u32_e32 v17, v17, v9
	s_waitcnt lgkmcnt(6)
	v_cvt_pk_bf16_f32 v12, v18, v38
	s_waitcnt lgkmcnt(4)
	v_cvt_pk_bf16_f32 v13, v40, v42
	s_waitcnt lgkmcnt(2)
	v_cvt_pk_bf16_f32 v14, v44, v46
	s_waitcnt lgkmcnt(0)
	v_cvt_pk_bf16_f32 v15, v48, v50
	v_lshl_add_u64 v[16:17], v[16:17], 1, v[2:3]
	v_or_b32_e32 v4, v4, v23
	global_store_dwordx4 v[16:17], v[12:15], off sc1
	v_mad_u64_u32 v[16:17], s[6:7], v4, v36, 0
	v_add_u32_e32 v17, v17, v9
	v_cvt_pk_bf16_f32 v12, v19, v39
	v_cvt_pk_bf16_f32 v13, v41, v43
	v_cvt_pk_bf16_f32 v14, v45, v47
	v_cvt_pk_bf16_f32 v15, v49, v51
	v_lshl_add_u64 v[2:3], v[16:17], 1, v[2:3]
	global_store_dwordx4 v[2:3], v[12:15], off sc1
	s_waitcnt lgkmcnt(0)
	s_cmpk_gt_i32 s0, 0x38f
	s_mov_b32 s0, s5
	s_cbranch_scc0 .Lgu0h_BB0_1019

.Lgu0h_skip:
	s_waitcnt vmcnt(0)
	s_waitcnt vmcnt(0) lgkmcnt(0)
	s_barrier
	s_mov_b64 s[4:5], exec
	v_readlane_b32 s0, v219, 25
	v_readlane_b32 s1, v219, 26
	s_and_b64 s[0:1], s[4:5], s[0:1]
	s_mov_b64 exec, s[0:1]
	s_cbranch_execz .LBB0_745
	v_readlane_b32 s0, v219, 27
	v_readlane_b32 s1, v219, 28
	v_readlane_b32 s2, v219, 29
	v_mov_b32_e32 v0, 0x24000
	s_waitcnt vmcnt(0) lgkmcnt(0)
	buffer_inv sc1
	ds_read_b32 v2, v0
	ds_read_b32 v0, v0 offset:4
	s_lshl_b32 s3, s2, 8
	s_add_i32 s14, s3, 0x2400
	s_add_i32 s3, s3, 0x1400
	v_mov_b32_e32 v1, s3
	s_waitcnt lgkmcnt(0)
	v_readfirstlane_b32 s10, v2
	v_readfirstlane_b32 s11, v0
	v_mov_b32_e32 v0, 1
	s_nop 1
	global_atomic_add v2, v1, v0, s[0:1] sc0
	s_mul_i32 s10, s10, 7
	s_mul_i32 s11, s11, 7
	s_waitcnt vmcnt(0)
	v_readfirstlane_b32 s13, v2
	s_nop 1
	s_add_i32 s13, s13, 1
	s_cmp_lg_u32 s13, s10
	s_cbranch_scc1 .Lnb7_wait
	v_mov_b32_e32 v1, 0x3400
	global_atomic_add v2, v1, v0, s[0:1] sc0
	s_waitcnt vmcnt(0)
	v_readfirstlane_b32 s13, v2
	s_nop 1
	s_add_i32 s13, s13, 1
	s_cmp_lg_u32 s13, s11
	s_cbranch_scc1 .Lnb7_wait
	v_mov_b32_e32 v1, 0x2400
	global_atomic_add v1, v0, s[0:1]
	global_atomic_add v1, v0, s[0:1] offset:256
	global_atomic_add v1, v0, s[0:1] offset:512
	global_atomic_add v1, v0, s[0:1] offset:768
	global_atomic_add v1, v0, s[0:1] offset:1024
	global_atomic_add v1, v0, s[0:1] offset:1280
	global_atomic_add v1, v0, s[0:1] offset:1536
	global_atomic_add v1, v0, s[0:1] offset:1792
	global_atomic_add v1, v0, s[0:1] offset:2048
	global_atomic_add v1, v0, s[0:1] offset:2304
	global_atomic_add v1, v0, s[0:1] offset:2560
	global_atomic_add v1, v0, s[0:1] offset:2816
	global_atomic_add v1, v0, s[0:1] offset:3072
	global_atomic_add v1, v0, s[0:1] offset:3328
	global_atomic_add v1, v0, s[0:1] offset:3584
	global_atomic_add v1, v0, s[0:1] offset:3840
	v_mov_b32_e32 v1, 0x3500
	global_atomic_add v1, v0, s[0:1]

.Lnb7_spin:
	global_load_dword v2, v1, s[0:1] sc1
	s_waitcnt vmcnt(0)
	v_readfirstlane_b32 s13, v2
	s_nop 1
	s_cmp_ge_u32 s13, 7
	s_cbranch_scc1 .Lnb7_done
	s_sleep 1
	s_add_i32 s15, s15, 1
	s_cmp_lt_u32 s15, 0x200000
	s_cbranch_scc1 .Lnb7_spin
.Lnb7_done:
	s_waitcnt vmcnt(0)
.LBB0_745:
	s_or_b64 exec, exec, s[4:5]
	v_readlane_b32 s2, v219, 45
	v_mul_u32_u24_e32 v1, 0x1600, v185
	v_readlane_b32 s3, v219, 46
	s_waitcnt lgkmcnt(0)
	v_mul_u32_u24_e32 v0, 0xb00, v185
	v_or_b32_e32 v164, v154, v1
	v_cndmask_b32_e64 v1, 0, 1, s[2:3]
	v_or_b32_e32 v0, v155, v0
	v_cmp_ne_u32_e64 s[0:1], 1, v1
	v_readfirstlane_b32 s10, v168
	s_andn2_b64 vcc, exec, s[2:3]
	v_writelane_b32 v219, s0, 50
	v_lshlrev_b32_e32 v165, 1, v0
	s_barrier
	v_writelane_b32 v219, s1, 51
	s_cbranch_vccnz .LBB0_809
	s_add_u32 s0, s56, 0x1400000
	s_addc_u32 s1, s57, 0
	s_lshl_b32 s2, s78, 8
	s_and_b32 s3, s2, 0x1f00
	s_lshr_b32 s33, s10, 6
	s_bfe_u32 s50, s10, 0x10006
	s_lshr_b32 s11, s10, 7
	s_mulk_i32 s3, 0x1600
	v_readlane_b32 s4, v219, 33
	v_readlane_b32 s5, v219, 34
	s_add_u32 s12, s4, s3
	s_addc_u32 s13, s5, 0
	s_lshl_b32 s17, s33, 5
	s_lshl_b32 s3, s78, 2
	s_lshl_b32 s4, s33, 12
	s_mul_hi_u32 s7, s17, 0xb00
	s_mul_i32 s6, s33, 0x16000
	s_and_b32 s16, s3, 0xffffff80
	s_add_i32 s5, s4, 0
	s_lshl_b64 s[14:15], s[6:7], 1
	s_add_u32 s18, s12, s14
	s_addc_u32 s19, s13, s15
	s_or_b32 s8, s17, 8
	s_mul_hi_u32 s9, s8, 0xb00
	s_mulk_i32 s8, 0xb00
	s_lshl_b64 s[36:37], s[8:9], 1
	s_add_u32 s20, s12, s36
	s_addc_u32 s21, s13, s37
	s_or_b32 s8, s17, 16
	v_mov_b32_e32 v0, v165
	v_mov_b32_e32 v1, v164
	s_mov_b32 m0, s5
	s_mul_hi_u32 s9, s8, 0xb00
	s_mulk_i32 s8, 0xb00
	s_barrier
	s_lshl_b64 s[38:39], s[8:9], 1
	global_load_lds_dwordx4 v1, s[18:19]
	s_add_i32 m0, s5, 0x400
	s_add_u32 s24, s12, s38
	s_addc_u32 s25, s13, s39
	s_or_b32 s8, s17, 24
	s_mul_hi_u32 s9, s8, 0xb00
	s_mulk_i32 s8, 0xb00
	global_load_lds_dwordx4 v0, s[20:21]
	s_add_i32 m0, s5, 0x800
	s_lshl_b64 s[40:41], s[8:9], 1
	s_add_u32 s26, s12, s40
	global_load_lds_dwordx4 v1, s[24:25]
	s_addc_u32 s27, s13, s41
	s_add_i32 m0, s5, 0xc00
	s_mul_hi_i32 s9, s16, 0x1600
	s_mulk_i32 s16, 0x1600
	s_add_u32 s17, s0, s16
	s_addc_u32 s9, s1, s9
	s_lshl_b32 s12, s33, 4
	s_lshl_b32 s16, s33, 11
	s_sub_i32 s46, s5, s16
	s_mul_hi_u32 s23, s12, 0xb00
	s_mul_i32 s22, s33, 0xb000
	global_load_lds_dwordx4 v0, s[26:27]
	s_add_i32 m0, s46, 0x8000
	s_lshl_b64 s[42:43], s[22:23], 1
	s_add_u32 s28, s17, s42
	s_addc_u32 s29, s9, s43
	s_or_b32 s12, s12, 8
	s_mul_hi_u32 s13, s12, 0xb00
	s_mulk_i32 s12, 0xb00
	s_lshl_b64 s[44:45], s[12:13], 1
	s_add_u32 s48, s17, s44
	global_load_lds_dwordx4 v1, s[28:29]
	s_addc_u32 s49, s9, s45
	s_add_i32 m0, s46, 0x8400
	v_mov_b32_e32 v150, v164
	global_load_lds_dwordx4 v0, s[48:49]
	v_mov_b32_e32 v0, v165
	v_mov_b32_e32 v151, 0
	s_mov_b64 s[46:47], 0x80
	v_lshl_add_u64 v[2:3], s[18:19], 0, v[150:151]
	s_add_i32 m0, s5, 0xc000
	v_lshl_add_u64 v[2:3], v[2:3], 0, s[46:47]
	v_mov_b32_e32 v1, v151
	global_load_lds_dwordx4 v[2:3], off
	v_lshl_add_u64 v[2:3], s[20:21], 0, v[0:1]
	v_lshl_add_u64 v[2:3], v[2:3], 0, s[46:47]
	s_add_i32 m0, s5, 0xc400
	s_add_i32 s9, s16, 0
	global_load_lds_dwordx4 v[2:3], off
	v_lshl_add_u64 v[2:3], s[24:25], 0, v[150:151]
	v_lshl_add_u64 v[2:3], v[2:3], 0, s[46:47]
	s_add_i32 m0, s5, 0xc800
	v_cmp_eq_u32_e32 vcc, 0, v171
	global_load_lds_dwordx4 v[2:3], off
	v_lshl_add_u64 v[2:3], s[26:27], 0, v[0:1]
	v_lshl_add_u64 v[2:3], v[2:3], 0, s[46:47]
	s_add_i32 m0, s5, 0xcc00
	v_lshl_add_u64 v[0:1], s[48:49], 0, v[0:1]
	global_load_lds_dwordx4 v[2:3], off
	v_lshl_add_u64 v[2:3], s[28:29], 0, v[150:151]
	s_add_i32 m0, s9, 0x14000
	v_lshl_add_u64 v[2:3], v[2:3], 0, s[46:47]
	global_load_lds_dwordx4 v[2:3], off
	v_lshl_add_u64 v[0:1], v[0:1], 0, s[46:47]
	s_add_i32 m0, s9, 0x14400
	s_cmpk_gt_u32 s10, 0xff
	global_load_lds_dwordx4 v[0:1], off
	s_cselect_b64 s[48:49], -1, 0
	v_add_u32_e32 v0, 12, v181
	s_lshl_b32 s17, s50, 13
	s_lshl_b32 s18, s11, 13
	s_add_i32 s10, s8, 0xffff5000
	s_add_i32 s20, s8, 0xffffa800
	s_lshl_b32 s19, s50, 7
	v_cndmask_b32_e32 v0, v0, v181, vcc
	v_xor_b32_e32 v1, v180, v170
	s_add_u32 s24, s56, s19
	v_lshlrev_b32_e32 v155, 4, v1
	v_bitop3_b32 v1, v180, v170, 4 bitop3:0x36
	s_addc_u32 s25, s57, 0
	v_lshlrev_b32_e32 v150, 1, v0
	v_lshlrev_b32_e32 v156, 4, v1
	v_lshl_add_u64 v[0:1], s[24:25], 0, v[150:151]
	s_mov_b64 s[24:25], 0x8400000
	s_mul_hi_u32 s19, s33, 0x2c000
	s_mul_i32 s33, s33, 0x2c000
	v_lshl_add_u64 v[152:153], v[0:1], 0, s[24:25]
	s_add_u32 s24, s56, s33
	v_writelane_b32 v219, s24, 37
	s_addc_u32 s19, s57, s19
	s_lshl_b32 s25, s58, 8
	s_mov_b32 s85, 0
	s_mov_b32 s84, s6
	v_writelane_b32 v219, s19, 41
	s_add_u32 s19, s56, s6
	v_writelane_b32 v219, s19, 42
	s_addc_u32 s7, s57, s7
	s_lshl_b32 s28, s58, 2
	s_lshl_b64 s[50:51], s[84:85], 1
	v_writelane_b32 v219, s7, 47
	s_add_u32 s7, s56, s50
	s_addc_u32 s19, s57, s51
	s_add_u32 s7, s7, 0x4400180
	v_writelane_b32 v219, s7, 48
	s_addc_u32 s7, s19, 0
	s_add_i32 s84, s6, 0x4000
	s_lshl_b64 s[60:61], s[84:85], 1
	v_writelane_b32 v219, s7, 49
	s_add_u32 s7, s56, s60
	s_addc_u32 s19, s57, s61
	s_add_u32 s29, s7, 0x4403180
	s_addc_u32 s33, s19, 0
	s_add_i32 s84, s6, 0xa000
	s_lshl_b64 s[62:63], s[84:85], 1
	s_add_u32 s7, s56, s62
	s_addc_u32 s19, s57, s63
	s_add_u32 s62, s7, 0x4402180
	s_addc_u32 s63, s19, 0
	s_add_i32 s84, s6, 0x10000
	s_lshl_b64 s[6:7], s[84:85], 1
	s_add_u32 s6, s56, s6
	s_addc_u32 s7, s57, s7
	s_mov_b32 s23, s85
	s_add_u32 s64, s6, 0x4401180
	s_addc_u32 s65, s7, 0
	s_lshl_b64 s[68:69], s[22:23], 1
	s_add_u32 s6, s56, s68
	s_addc_u32 s7, s57, s69
	s_add_u32 s66, s6, 0x1400180
	s_addc_u32 s67, s7, 0
	s_add_i32 s84, s22, 0x5000
	s_lshl_b64 s[6:7], s[84:85], 1
	s_add_u32 s6, s56, s6
	s_addc_u32 s7, s57, s7
	s_mov_b32 s9, s85
	s_mov_b32 s13, s85
	v_lshl_or_b32 v154, s11, 6, v167
	s_mov_b32 s11, s85
	s_mov_b32 s21, s85
	s_add_u32 s84, s6, 0x1401180
	s_addc_u32 s86, s7, 0
	s_mov_b64 s[6:7], -1
	s_mov_b64 s[70:71], 0x100
	s_lshl_b64 s[72:73], s[8:9], 1
	s_lshl_b64 s[74:75], s[12:13], 1
	s_lshl_b64 s[76:77], s[10:11], 1
	s_mov_b32 s87, s78
	s_lshl_b64 s[78:79], s[20:21], 1
	s_branch .LBB0_748
.LBB0_747:
	v_add_u32_e32 v150, s88, v154
	v_lshl_add_u64 v[64:65], s[82:83], 1, v[152:153]
	v_lshlrev_b64 v[66:67], 11, v[150:151]
	v_cvt_pk_bf16_f32 v48, v48, v49
	v_cvt_pk_bf16_f32 v49, v50, v51
	v_cvt_pk_bf16_f32 v50, v52, v53
	v_cvt_pk_bf16_f32 v51, v54, v55
	v_lshl_add_u64 v[66:67], v[64:65], 0, v[66:67]
	v_permlane16_swap_b32_e32 v48, v50
	v_permlane16_swap_b32_e32 v49, v51
	global_store_dwordx4 v[66:67], v[48:51], off offset:64 sc1
	v_cvt_pk_bf16_f32 v20, v20, v21
	v_cvt_pk_bf16_f32 v21, v22, v23
	v_or_b32_e32 v48, 16, v150
	v_mov_b32_e32 v49, v151
	v_lshlrev_b64 v[48:49], 11, v[48:49]
	v_cvt_pk_bf16_f32 v22, v28, v29
	v_cvt_pk_bf16_f32 v23, v30, v31
	v_lshl_add_u64 v[48:49], v[64:65], 0, v[48:49]
	v_permlane16_swap_b32_e32 v20, v22
	v_permlane16_swap_b32_e32 v21, v23
	global_store_dwordx4 v[48:49], v[20:23], off offset:64 sc1
	v_cvt_pk_bf16_f32 v16, v16, v17
	v_cvt_pk_bf16_f32 v17, v18, v19
	v_or_b32_e32 v20, 32, v150
	v_mov_b32_e32 v21, v151
	v_lshlrev_b64 v[20:21], 11, v[20:21]
	v_cvt_pk_bf16_f32 v18, v24, v25
	v_cvt_pk_bf16_f32 v19, v26, v27
	v_lshl_add_u64 v[28:29], v[64:65], 0, v[20:21]
	v_permlane16_swap_b32_e32 v16, v18
	v_permlane16_swap_b32_e32 v17, v19
	v_or_b32_e32 v150, 48, v150
	v_cvt_pk_bf16_f32 v56, v56, v57
	v_cvt_pk_bf16_f32 v57, v58, v59
	v_cvt_pk_bf16_f32 v58, v60, v61
	v_cvt_pk_bf16_f32 v59, v62, v63
	v_cvt_pk_bf16_f32 v36, v36, v37
	v_cvt_pk_bf16_f32 v37, v38, v39
	v_cvt_pk_bf16_f32 v38, v44, v45
	v_cvt_pk_bf16_f32 v39, v46, v47
	v_cvt_pk_bf16_f32 v20, v32, v33
	v_cvt_pk_bf16_f32 v21, v34, v35
	v_cvt_pk_bf16_f32 v22, v40, v41
	v_cvt_pk_bf16_f32 v23, v42, v43
	global_store_dwordx4 v[28:29], v[16:19], off offset:64 sc1
	v_cvt_pk_bf16_f32 v4, v4, v5
	v_cvt_pk_bf16_f32 v5, v6, v7
	v_lshlrev_b64 v[16:17], 11, v[150:151]
	v_cvt_pk_bf16_f32 v6, v8, v9
	v_cvt_pk_bf16_f32 v7, v10, v11
	v_cvt_pk_bf16_f32 v0, v0, v1
	v_cvt_pk_bf16_f32 v1, v2, v3
	v_cvt_pk_bf16_f32 v2, v12, v13
	v_cvt_pk_bf16_f32 v3, v14, v15
	v_permlane16_swap_b32_e32 v56, v58
	v_permlane16_swap_b32_e32 v57, v59
	v_permlane16_swap_b32_e32 v36, v38
	v_permlane16_swap_b32_e32 v37, v39
	v_permlane16_swap_b32_e32 v20, v22
	v_permlane16_swap_b32_e32 v21, v23
	v_lshl_add_u64 v[16:17], v[64:65], 0, v[16:17]
	v_permlane16_swap_b32_e32 v4, v6
	v_permlane16_swap_b32_e32 v5, v7
	v_permlane16_swap_b32_e32 v0, v2
	v_permlane16_swap_b32_e32 v1, v3
	s_add_i32 s2, s2, s25
	s_add_i32 s3, s3, s28
	s_andn2_b64 vcc, exec, s[80:81]
	s_mov_b64 s[6:7], 0
	global_store_dwordx4 v[66:67], v[56:59], off sc1
	global_store_dwordx4 v[48:49], v[36:39], off sc1
	global_store_dwordx4 v[28:29], v[20:23], off sc1
	global_store_dwordx4 v[16:17], v[4:7], off sc1
	global_store_dwordx4 v[16:17], v[0:3], off offset:64 sc1
	s_cbranch_vccz .LBB0_808

.LBB0_809:
	s_waitcnt vmcnt(0)
	s_waitcnt vmcnt(0) lgkmcnt(0)
	s_barrier
	s_mov_b64 s[6:7], exec
	v_readlane_b32 s0, v219, 25
	v_readlane_b32 s1, v219, 26
	s_and_b64 s[0:1], s[6:7], s[0:1]
	s_mov_b64 exec, s[0:1]
	s_cbranch_execz .LBB0_861
	v_readlane_b32 s0, v219, 27
	v_readlane_b32 s1, v219, 28
	v_readlane_b32 s2, v219, 29
	v_mov_b32_e32 v0, 0x24000
	s_waitcnt vmcnt(0) lgkmcnt(0)
	buffer_inv sc1
	ds_read_b32 v2, v0
	ds_read_b32 v0, v0 offset:4
	s_lshl_b32 s3, s2, 8
	s_add_i32 s14, s3, 0x2400
	s_add_i32 s3, s3, 0x1400
	v_mov_b32_e32 v1, s3
	s_waitcnt lgkmcnt(0)
	v_readfirstlane_b32 s10, v2
	v_readfirstlane_b32 s11, v0
	v_mov_b32_e32 v0, 1
	s_nop 1
	global_atomic_add v2, v1, v0, s[0:1] sc0
	s_mul_i32 s10, s10, 8
	s_mul_i32 s11, s11, 8
	s_waitcnt vmcnt(0)
	v_readfirstlane_b32 s13, v2
	s_nop 1
	s_add_i32 s13, s13, 1
	s_cmp_lg_u32 s13, s10
	s_cbranch_scc1 .Lnb8_wait
	v_mov_b32_e32 v1, 0x3400
	global_atomic_add v2, v1, v0, s[0:1] sc0
	s_waitcnt vmcnt(0)
	v_readfirstlane_b32 s13, v2
	s_nop 1
	s_add_i32 s13, s13, 1
	s_cmp_lg_u32 s13, s11
	s_cbranch_scc1 .Lnb8_wait
	v_mov_b32_e32 v1, 0x2400
	global_atomic_add v1, v0, s[0:1]
	global_atomic_add v1, v0, s[0:1] offset:256
	global_atomic_add v1, v0, s[0:1] offset:512
	global_atomic_add v1, v0, s[0:1] offset:768
	global_atomic_add v1, v0, s[0:1] offset:1024
	global_atomic_add v1, v0, s[0:1] offset:1280
	global_atomic_add v1, v0, s[0:1] offset:1536
	global_atomic_add v1, v0, s[0:1] offset:1792
	global_atomic_add v1, v0, s[0:1] offset:2048
	global_atomic_add v1, v0, s[0:1] offset:2304
	global_atomic_add v1, v0, s[0:1] offset:2560
	global_atomic_add v1, v0, s[0:1] offset:2816
	global_atomic_add v1, v0, s[0:1] offset:3072
	global_atomic_add v1, v0, s[0:1] offset:3328
	global_atomic_add v1, v0, s[0:1] offset:3584
	global_atomic_add v1, v0, s[0:1] offset:3840
	v_mov_b32_e32 v1, 0x3500
	global_atomic_add v1, v0, s[0:1]

.Lnb8_spin:
	global_load_dword v2, v1, s[0:1] sc1
	s_waitcnt vmcnt(0)
	v_readfirstlane_b32 s13, v2
	s_nop 1
	s_cmp_ge_u32 s13, 8
	s_cbranch_scc1 .Lnb8_done
	s_sleep 1
	s_add_i32 s15, s15, 1
	s_cmp_lt_u32 s15, 0x200000
	s_cbranch_scc1 .Lnb8_spin
.Lnb8_done:
	s_waitcnt vmcnt(0)
.LBB0_861:
	s_or_b64 exec, exec, s[6:7]
	s_waitcnt lgkmcnt(0)
	s_barrier
	s_mov_b64 s[6:7], exec
	v_readlane_b32 s0, v219, 31
	v_readlane_b32 s1, v219, 32
	s_and_b64 s[0:1], s[6:7], s[0:1]
	s_mov_b64 exec, s[0:1]
	s_cbranch_execz .LBB0_866
	v_and_b32_e32 v0, 0x1f8, v144
	v_mov_b32_e32 v65, 0
	v_lshlrev_b32_e32 v64, 1, v0
	v_lshl_add_u64 v[2:3], s[56:57], 0, v[64:65]
	s_mov_b64 s[0:1], 0xa400000
	v_readlane_b32 s8, v219, 9
	v_lshl_add_u64 v[66:67], v[2:3], 0, s[0:1]
	s_mov_b64 s[0:1], 0x8400000
	v_readlane_b32 s9, v219, 10
	v_readlane_b32 s10, v219, 11
	v_readlane_b32 s11, v219, 12
	v_readlane_b32 s12, v219, 13
	v_readlane_b32 s13, v219, 14
	v_lshl_add_u64 v[68:69], v[2:3], 0, s[0:1]
	s_lshl_b32 s0, s58, 3
	v_readlane_b32 s14, v219, 15
	v_readlane_b32 s15, v219, 16
	s_mov_b64 s[8:9], s[12:13]
	s_add_u32 s2, s8, 0x3000
	s_addc_u32 s3, s9, 0
	s_add_u32 s4, s8, 0x4000
	v_lshl_add_u64 v[70:71], s[30:31], 0, v[64:65]
	v_or_b32_e32 v2, 0x200, v0
	s_addc_u32 s5, s9, 0
	v_lshlrev_b32_e32 v64, 2, v0
	v_lshl_add_u64 v[72:73], s[2:3], 0, v[64:65]
	v_lshl_add_u64 v[74:75], s[4:5], 0, v[64:65]
	v_lshlrev_b32_e32 v64, 2, v2
	s_mov_b64 s[10:11], s[14:15]
	v_lshl_add_u64 v[76:77], s[2:3], 0, v[64:65]
	v_lshl_add_u64 v[78:79], s[4:5], 0, v[64:65]
	v_lshl_add_u32 v102, s78, 5, v166
	s_lshl_b32 s1, s58, 5
	s_mov_b64 s[8:9], 0
	v_mov_b32_e32 v103, 0xfffff000
	s_movk_i32 s2, 0x3ff
	s_mov_b64 s[12:13], 0x5000
	s_mov_b64 s[14:15], 0x1000
	v_lshlrev_b32_e32 v64, 2, v0
	v_lshlrev_b32_e32 v80, 2, v2
	v_mov_b32_e32 v81, v65
	v_mov_b32_e32 v104, 0x358637bd
	s_mov_b32 s3, 0x800000
	s_movk_i32 s4, 0x7ff
	v_mov_b32_e32 v105, v145
	v_readlane_b32 s16, v219, 17
	v_readlane_b32 s17, v219, 18
	v_readlane_b32 s18, v219, 19
	v_readlane_b32 s19, v219, 20
	v_readlane_b32 s20, v219, 21
	v_readlane_b32 s21, v219, 22
	v_readlane_b32 s22, v219, 23
	v_readlane_b32 s23, v219, 24

.LBB0_864:
	v_add_u32_e32 v98, s5, v102
	v_ashrrev_i32_e32 v99, 31, v98
	v_add_u32_e32 v100, 1, v98
	v_lshlrev_b64 v[98:99], 11, v[98:99]
	v_lshl_add_u64 v[122:123], v[66:67], 0, v[98:99]
	v_lshl_add_u64 v[118:119], v[68:69], 0, v[98:99]
	global_load_dwordx4 v[106:109], v[122:123], off
	global_load_dwordx4 v[110:113], v[122:123], off offset:1024
	global_load_dwordx4 v[114:117], v[118:119], off
	s_nop 0
	global_load_dwordx4 v[118:121], v[118:119], off offset:1024
	v_ashrrev_i32_e32 v101, 31, v100
	v_lshl_add_u64 v[124:125], v[70:71], 0, v[98:99]
	v_lshlrev_b64 v[98:99], 11, v[100:101]
	v_lshl_add_u64 v[100:101], v[66:67], 0, v[98:99]
	v_lshl_add_u64 v[126:127], v[68:69], 0, v[98:99]
	s_add_i32 s5, s5, 2
	s_cmp_eq_u32 s5, 4
	v_lshl_add_u64 v[98:99], v[70:71], 0, v[98:99]
	s_waitcnt vmcnt(3)
	v_lshlrev_b32_e32 v128, 16, v106
	v_and_b32_e32 v129, 0xffff0000, v106
	s_waitcnt vmcnt(1)
	v_and_b32_e32 v139, 0xffff0000, v116
	v_and_b32_e32 v138, 0xffff0000, v114
	v_lshlrev_b32_e32 v137, 16, v116
	v_lshlrev_b32_e32 v136, 16, v114
	v_lshlrev_b32_e32 v140, 16, v115
	v_and_b32_e32 v116, 0xffff0000, v115
	s_waitcnt vmcnt(0)
	v_lshlrev_b32_e32 v115, 16, v118
	v_lshlrev_b32_e32 v114, 16, v120
	v_and_b32_e32 v143, 0xffff0000, v118
	v_and_b32_e32 v142, 0xffff0000, v120
	v_lshlrev_b32_e32 v150, 16, v121
	v_and_b32_e32 v118, 0xffff0000, v121
	v_pk_mul_f32 v[120:121], v[138:139], v[138:139]
	v_lshlrev_b32_e32 v141, 16, v117
	v_pk_mul_f32 v[152:153], v[142:143], v[142:143]
	v_pk_fma_f32 v[120:121], v[136:137], v[136:137], v[120:121]
	v_and_b32_e32 v117, 0xffff0000, v117
	v_lshlrev_b32_e32 v151, 16, v119
	v_mov_b32_e32 v156, v136
	v_mov_b32_e32 v157, v138
	v_mov_b32_e32 v138, v137
	v_pk_fma_f32 v[136:137], v[114:115], v[114:115], v[152:153]
	v_pk_fma_f32 v[120:121], v[140:141], v[140:141], v[120:121]
	v_and_b32_e32 v119, 0xffff0000, v119
	v_pk_fma_f32 v[136:137], v[150:151], v[150:151], v[136:137]
	v_pk_fma_f32 v[120:121], v[116:117], v[116:117], v[120:121]
	v_mov_b32_e32 v158, v151
	v_mov_b32_e32 v159, v119
	v_mov_b32_e32 v151, v118
	v_pk_fma_f32 v[118:119], v[118:119], v[118:119], v[136:137]
	v_add_f32_e32 v120, v120, v121
	v_add_f32_e32 v119, v120, v119
	v_add_f32_e32 v118, v118, v119
	ds_bpermute_b32 v119, v172, v118
	v_mov_b32_e32 v154, v140
	v_mov_b32_e32 v155, v116
	v_mov_b32_e32 v116, v141
	v_mov_b32_e32 v186, v115
	s_waitcnt lgkmcnt(0)
	v_add_f32_e32 v118, v118, v119
	ds_bpermute_b32 v119, v173, v118
	v_mov_b32_e32 v187, v143
	v_mov_b32_e32 v115, v142
	v_lshlrev_b32_e32 v106, 16, v107
	v_and_b32_e32 v107, 0xffff0000, v107
	s_waitcnt lgkmcnt(0)
	v_add_f32_e32 v118, v118, v119
	ds_bpermute_b32 v119, v174, v118
	v_lshlrev_b32_e32 v130, 16, v108
	v_and_b32_e32 v131, 0xffff0000, v108
	v_lshlrev_b32_e32 v108, 16, v109
	v_and_b32_e32 v109, 0xffff0000, v109
	s_waitcnt lgkmcnt(0)
	v_add_f32_e32 v118, v118, v119
	ds_bpermute_b32 v119, v175, v118
	v_lshlrev_b32_e32 v132, 16, v110
	v_and_b32_e32 v133, 0xffff0000, v110
	v_lshlrev_b32_e32 v110, 16, v111
	v_and_b32_e32 v111, 0xffff0000, v111
	s_waitcnt lgkmcnt(0)
	v_add_f32_e32 v118, v118, v119
	ds_bpermute_b32 v119, v176, v118
	v_lshlrev_b32_e32 v134, 16, v112
	v_and_b32_e32 v135, 0xffff0000, v112
	v_lshlrev_b32_e32 v112, 16, v113
	v_and_b32_e32 v113, 0xffff0000, v113
	s_waitcnt lgkmcnt(0)
	v_add_f32_e32 v118, v118, v119
	ds_bpermute_b32 v119, v177, v118
	s_waitcnt lgkmcnt(0)
	v_add_f32_e32 v118, v118, v119
	v_fmamk_f32 v118, v118, 0x3a800000, v104
	v_mul_f32_e32 v119, 0x4b800000, v118
	v_cmp_gt_f32_e32 vcc, s3, v118
	s_nop 1
	v_cndmask_b32_e32 v118, v118, v119, vcc
	v_rsq_f32_e32 v118, v118
	s_nop 0
	v_mul_f32_e32 v119, 0x45800000, v118
	v_cndmask_b32_e32 v118, v118, v119, vcc
	v_pk_mul_f32 v[120:121], v[118:119], v[154:155] op_sel_hi:[0,1]
	v_pk_mul_f32 v[136:137], v[118:119], v[156:157] op_sel_hi:[0,1]
	v_pk_mul_f32 v[116:117], v[118:119], v[116:117] op_sel_hi:[0,1]
	v_pk_mul_f32 v[138:139], v[118:119], v[138:139] op_sel_hi:[0,1]
	v_pk_mul_f32 v[140:141], v[118:119], v[158:159] op_sel_hi:[0,1]
	v_pk_mul_f32 v[142:143], v[118:119], v[186:187] op_sel_hi:[0,1]
	v_pk_mul_f32 v[150:151], v[118:119], v[150:151] op_sel_hi:[0,1]
	v_pk_mul_f32 v[114:115], v[118:119], v[114:115] op_sel_hi:[0,1]
	v_pk_mul_f32 v[118:119], v[4:5], v[136:137]
	v_pk_mul_f32 v[120:121], v[6:7], v[120:121]
	v_pk_mul_f32 v[136:137], v[0:1], v[138:139]
	v_pk_mul_f32 v[116:117], v[2:3], v[116:117]
	v_pk_mul_f32 v[138:139], v[36:37], v[142:143]
	v_pk_mul_f32 v[140:141], v[38:39], v[140:141]
	v_pk_mul_f32 v[114:115], v[32:33], v[114:115]
	v_pk_mul_f32 v[142:143], v[34:35], v[150:151]
	v_pk_fma_f32 v[120:121], v[14:15], v[120:121], v[106:107]
	v_pk_fma_f32 v[118:119], v[12:13], v[118:119], v[128:129]
	v_pk_fma_f32 v[116:117], v[10:11], v[116:117], v[108:109]
	v_pk_fma_f32 v[128:129], v[8:9], v[136:137], v[130:131]
	v_pk_fma_f32 v[130:131], v[46:47], v[140:141], v[110:111]
	v_pk_fma_f32 v[132:133], v[44:45], v[138:139], v[132:133]
	v_pk_fma_f32 v[136:137], v[42:43], v[142:143], v[112:113]
	v_pk_fma_f32 v[114:115], v[40:41], v[114:115], v[134:135]
	v_cvt_pk_bf16_f32 v106, v118, v119
	v_cvt_pk_bf16_f32 v107, v120, v121
	v_cvt_pk_bf16_f32 v108, v128, v129
	v_cvt_pk_bf16_f32 v109, v116, v117
	v_mov_b32_e32 v138, v119
	v_mov_b32_e32 v139, v129
	v_cvt_pk_bf16_f32 v110, v132, v133
	v_cvt_pk_bf16_f32 v111, v130, v131
	v_cvt_pk_bf16_f32 v112, v114, v115
	v_cvt_pk_bf16_f32 v113, v136, v137
	v_mov_b32_e32 v134, v118
	v_mov_b32_e32 v135, v128
	v_mov_b32_e32 v152, v115
	v_mov_b32_e32 v153, v133
	global_store_dwordx4 v[122:123], v[106:109], off sc1
	global_store_dwordx4 v[122:123], v[110:113], off offset:1024 sc1
	v_mov_b32_e32 v140, v120
	v_pk_mul_f32 v[106:107], v[138:139], v[138:139]
	v_mov_b32_e32 v141, v116
	v_mov_b32_e32 v150, v114
	v_mov_b32_e32 v151, v132
	v_pk_mul_f32 v[108:109], v[152:153], v[152:153]
	v_pk_fma_f32 v[106:107], v[134:135], v[134:135], v[106:107]
	v_mov_b32_e32 v142, v121
	v_mov_b32_e32 v143, v117
	v_mov_b32_e32 v154, v136
	v_mov_b32_e32 v155, v130
	v_pk_fma_f32 v[108:109], v[150:151], v[150:151], v[108:109]
	v_pk_fma_f32 v[106:107], v[140:141], v[140:141], v[106:107]
	v_mov_b32_e32 v156, v137
	v_mov_b32_e32 v157, v131
	v_pk_fma_f32 v[108:109], v[154:155], v[154:155], v[108:109]
	v_pk_fma_f32 v[106:107], v[142:143], v[142:143], v[106:107]
	v_pk_fma_f32 v[108:109], v[156:157], v[156:157], v[108:109]
	v_add_f32_e32 v106, v106, v107
	v_add_f32_e32 v106, v109, v106
	v_add_f32_e32 v106, v108, v106
	ds_bpermute_b32 v107, v172, v106
	s_waitcnt lgkmcnt(0)
	v_add_f32_e32 v106, v106, v107
	ds_bpermute_b32 v107, v173, v106
	s_waitcnt lgkmcnt(0)
	v_add_f32_e32 v106, v106, v107
	ds_bpermute_b32 v107, v174, v106
	s_waitcnt lgkmcnt(0)
	v_add_f32_e32 v106, v106, v107
	ds_bpermute_b32 v107, v175, v106
	s_waitcnt lgkmcnt(0)
	v_add_f32_e32 v106, v106, v107
	ds_bpermute_b32 v107, v176, v106
	s_waitcnt lgkmcnt(0)
	v_add_f32_e32 v106, v106, v107
	ds_bpermute_b32 v107, v177, v106
	s_waitcnt lgkmcnt(0)
	v_add_f32_e32 v106, v106, v107
	v_fmamk_f32 v106, v106, 0x3a800000, v104
	v_mul_f32_e32 v107, 0x4b800000, v106
	v_cmp_gt_f32_e32 vcc, s3, v106
	s_nop 1
	v_cndmask_b32_e32 v106, v106, v107, vcc
	v_rsq_f32_e32 v106, v106
	s_nop 0
	v_mul_f32_e32 v107, 0x45800000, v106
	v_cndmask_b32_e32 v106, v106, v107, vcc
	v_pk_mul_f32 v[108:109], v[120:121], v[106:107] op_sel_hi:[1,0]
	v_pk_mul_f32 v[110:111], v[118:119], v[106:107] op_sel_hi:[1,0]
	v_pk_mul_f32 v[112:113], v[116:117], v[106:107] op_sel_hi:[1,0]
	v_pk_mul_f32 v[116:117], v[128:129], v[106:107] op_sel_hi:[1,0]
	v_pk_mul_f32 v[118:119], v[130:131], v[106:107] op_sel_hi:[1,0]
	v_pk_mul_f32 v[120:121], v[132:133], v[106:107] op_sel_hi:[1,0]
	v_pk_mul_f32 v[122:123], v[136:137], v[106:107] op_sel_hi:[1,0]
	v_pk_mul_f32 v[106:107], v[114:115], v[106:107] op_sel_hi:[1,0]
	v_pk_mul_f32 v[110:111], v[20:21], v[110:111]
	v_pk_mul_f32 v[108:109], v[22:23], v[108:109]
	v_pk_mul_f32 v[114:115], v[16:17], v[116:117]
	v_pk_mul_f32 v[112:113], v[18:19], v[112:113]
	v_pk_mul_f32 v[116:117], v[52:53], v[120:121]
	v_pk_mul_f32 v[118:119], v[54:55], v[118:119]
	v_pk_mul_f32 v[106:107], v[48:49], v[106:107]
	v_pk_mul_f32 v[120:121], v[50:51], v[122:123]
	v_pk_fma_f32 v[108:109], v[82:83], v[108:109], v[30:31]
	v_pk_fma_f32 v[110:111], v[84:85], v[110:111], v[28:29]
	v_pk_fma_f32 v[112:113], v[86:87], v[112:113], v[26:27]
	v_pk_fma_f32 v[114:115], v[88:89], v[114:115], v[24:25]
	v_pk_fma_f32 v[118:119], v[90:91], v[118:119], v[62:63]
	v_pk_fma_f32 v[116:117], v[92:93], v[116:117], v[60:61]
	v_pk_fma_f32 v[120:121], v[94:95], v[120:121], v[58:59]
	v_pk_fma_f32 v[122:123], v[96:97], v[106:107], v[56:57]
	v_cvt_pk_bf16_f32 v106, v110, v111
	v_cvt_pk_bf16_f32 v107, v108, v109
	v_cvt_pk_bf16_f32 v108, v114, v115
	v_cvt_pk_bf16_f32 v109, v112, v113
	v_cvt_pk_bf16_f32 v110, v116, v117
	v_cvt_pk_bf16_f32 v111, v118, v119
	v_cvt_pk_bf16_f32 v112, v122, v123
	v_cvt_pk_bf16_f32 v113, v120, v121
	global_store_dwordx4 v[124:125], v[106:109], off sc1
	global_store_dwordx4 v[124:125], v[110:113], off offset:1024 sc1
	global_load_dwordx4 v[106:109], v[100:101], off
	s_nop 0
	global_load_dwordx4 v[110:113], v[100:101], off offset:1024
	global_load_dwordx4 v[114:117], v[126:127], off
	global_load_dwordx4 v[118:121], v[126:127], off offset:1024
	s_waitcnt vmcnt(3)
	v_lshlrev_b32_e32 v122, 16, v106
	v_and_b32_e32 v123, 0xffff0000, v106
	s_waitcnt vmcnt(1)
	v_and_b32_e32 v133, 0xffff0000, v116
	v_and_b32_e32 v132, 0xffff0000, v114
	v_lshlrev_b32_e32 v131, 16, v116
	v_lshlrev_b32_e32 v130, 16, v114
	v_lshlrev_b32_e32 v134, 16, v115
	v_and_b32_e32 v116, 0xffff0000, v115
	s_waitcnt vmcnt(0)
	v_lshlrev_b32_e32 v115, 16, v118
	v_lshlrev_b32_e32 v114, 16, v120
	v_and_b32_e32 v137, 0xffff0000, v118
	v_and_b32_e32 v136, 0xffff0000, v120
	v_lshlrev_b32_e32 v138, 16, v121
	v_and_b32_e32 v118, 0xffff0000, v121
	v_pk_mul_f32 v[120:121], v[132:133], v[132:133]
	v_lshlrev_b32_e32 v135, 16, v117
	v_pk_mul_f32 v[140:141], v[136:137], v[136:137]
	v_pk_fma_f32 v[120:121], v[130:131], v[130:131], v[120:121]
	v_and_b32_e32 v117, 0xffff0000, v117
	v_lshlrev_b32_e32 v139, 16, v119
	v_mov_b32_e32 v150, v130
	v_mov_b32_e32 v151, v132
	v_mov_b32_e32 v132, v131
	v_pk_fma_f32 v[130:131], v[114:115], v[114:115], v[140:141]
	v_pk_fma_f32 v[120:121], v[134:135], v[134:135], v[120:121]
	v_and_b32_e32 v119, 0xffff0000, v119
	v_pk_fma_f32 v[130:131], v[138:139], v[138:139], v[130:131]
	v_pk_fma_f32 v[120:121], v[116:117], v[116:117], v[120:121]
	v_mov_b32_e32 v152, v139
	v_mov_b32_e32 v153, v119
	v_mov_b32_e32 v139, v118
	v_pk_fma_f32 v[118:119], v[118:119], v[118:119], v[130:131]
	v_add_f32_e32 v120, v120, v121
	v_add_f32_e32 v119, v120, v119
	v_add_f32_e32 v118, v118, v119
	ds_bpermute_b32 v119, v172, v118
	v_mov_b32_e32 v142, v134
	v_mov_b32_e32 v143, v116
	v_mov_b32_e32 v116, v135
	v_mov_b32_e32 v154, v115
	s_waitcnt lgkmcnt(0)
	v_add_f32_e32 v118, v118, v119
	ds_bpermute_b32 v119, v173, v118
	v_mov_b32_e32 v155, v137
	v_mov_b32_e32 v115, v136
	v_lshlrev_b32_e32 v106, 16, v107
	v_and_b32_e32 v107, 0xffff0000, v107
	s_waitcnt lgkmcnt(0)
	v_add_f32_e32 v118, v118, v119
	ds_bpermute_b32 v119, v174, v118
	v_lshlrev_b32_e32 v124, 16, v108
	v_and_b32_e32 v125, 0xffff0000, v108
	v_lshlrev_b32_e32 v108, 16, v109
	v_and_b32_e32 v109, 0xffff0000, v109
	s_waitcnt lgkmcnt(0)
	v_add_f32_e32 v118, v118, v119
	ds_bpermute_b32 v119, v175, v118
	v_lshlrev_b32_e32 v126, 16, v110
	v_and_b32_e32 v127, 0xffff0000, v110
	v_lshlrev_b32_e32 v110, 16, v111
	v_and_b32_e32 v111, 0xffff0000, v111
	s_waitcnt lgkmcnt(0)
	v_add_f32_e32 v118, v118, v119
	ds_bpermute_b32 v119, v176, v118
	v_lshlrev_b32_e32 v128, 16, v112
	v_and_b32_e32 v129, 0xffff0000, v112
	v_lshlrev_b32_e32 v112, 16, v113
	v_and_b32_e32 v113, 0xffff0000, v113
	s_waitcnt lgkmcnt(0)
	v_add_f32_e32 v118, v118, v119
	ds_bpermute_b32 v119, v177, v118
	s_waitcnt lgkmcnt(0)
	v_add_f32_e32 v118, v118, v119
	v_fmamk_f32 v118, v118, 0x3a800000, v104
	v_mul_f32_e32 v119, 0x4b800000, v118
	v_cmp_gt_f32_e32 vcc, s3, v118
	s_nop 1
	v_cndmask_b32_e32 v118, v118, v119, vcc
	v_rsq_f32_e32 v118, v118
	s_nop 0
	v_mul_f32_e32 v119, 0x45800000, v118
	v_cndmask_b32_e32 v118, v118, v119, vcc
	v_pk_mul_f32 v[120:121], v[118:119], v[142:143] op_sel_hi:[0,1]
	v_pk_mul_f32 v[130:131], v[118:119], v[150:151] op_sel_hi:[0,1]
	v_pk_mul_f32 v[116:117], v[118:119], v[116:117] op_sel_hi:[0,1]
	v_pk_mul_f32 v[132:133], v[118:119], v[132:133] op_sel_hi:[0,1]
	v_pk_mul_f32 v[134:135], v[118:119], v[152:153] op_sel_hi:[0,1]
	v_pk_mul_f32 v[136:137], v[118:119], v[154:155] op_sel_hi:[0,1]
	v_pk_mul_f32 v[138:139], v[118:119], v[138:139] op_sel_hi:[0,1]
	v_pk_mul_f32 v[114:115], v[118:119], v[114:115] op_sel_hi:[0,1]
	v_pk_mul_f32 v[118:119], v[4:5], v[130:131]
	v_pk_mul_f32 v[120:121], v[6:7], v[120:121]
	v_pk_mul_f32 v[130:131], v[0:1], v[132:133]
	v_pk_mul_f32 v[116:117], v[2:3], v[116:117]
	v_pk_mul_f32 v[132:133], v[36:37], v[136:137]
	v_pk_mul_f32 v[134:135], v[38:39], v[134:135]
	v_pk_mul_f32 v[114:115], v[32:33], v[114:115]
	v_pk_mul_f32 v[136:137], v[34:35], v[138:139]
	v_pk_fma_f32 v[120:121], v[14:15], v[120:121], v[106:107]
	v_pk_fma_f32 v[118:119], v[12:13], v[118:119], v[122:123]
	v_pk_fma_f32 v[116:117], v[10:11], v[116:117], v[108:109]
	v_pk_fma_f32 v[122:123], v[8:9], v[130:131], v[124:125]
	v_pk_fma_f32 v[124:125], v[46:47], v[134:135], v[110:111]
	v_pk_fma_f32 v[126:127], v[44:45], v[132:133], v[126:127]
	v_pk_fma_f32 v[130:131], v[42:43], v[136:137], v[112:113]
	v_pk_fma_f32 v[114:115], v[40:41], v[114:115], v[128:129]
	v_cvt_pk_bf16_f32 v106, v118, v119
	v_cvt_pk_bf16_f32 v107, v120, v121
	v_cvt_pk_bf16_f32 v108, v122, v123
	v_cvt_pk_bf16_f32 v109, v116, v117
	v_mov_b32_e32 v132, v119
	v_mov_b32_e32 v133, v123
	v_cvt_pk_bf16_f32 v110, v126, v127
	v_cvt_pk_bf16_f32 v111, v124, v125
	v_cvt_pk_bf16_f32 v112, v114, v115
	v_cvt_pk_bf16_f32 v113, v130, v131
	v_mov_b32_e32 v128, v118
	v_mov_b32_e32 v129, v122
	v_mov_b32_e32 v140, v115
	v_mov_b32_e32 v141, v127
	global_store_dwordx4 v[100:101], v[106:109], off sc1
	global_store_dwordx4 v[100:101], v[110:113], off offset:1024 sc1
	v_pk_mul_f32 v[100:101], v[132:133], v[132:133]
	v_mov_b32_e32 v134, v120
	v_mov_b32_e32 v135, v116
	v_mov_b32_e32 v138, v114
	v_mov_b32_e32 v139, v126
	v_pk_mul_f32 v[106:107], v[140:141], v[140:141]
	v_pk_fma_f32 v[100:101], v[128:129], v[128:129], v[100:101]
	v_mov_b32_e32 v136, v121
	v_mov_b32_e32 v137, v117
	v_mov_b32_e32 v142, v130
	v_mov_b32_e32 v143, v124
	v_pk_fma_f32 v[106:107], v[138:139], v[138:139], v[106:107]
	v_pk_fma_f32 v[100:101], v[134:135], v[134:135], v[100:101]
	v_mov_b32_e32 v150, v131
	v_mov_b32_e32 v151, v125
	v_pk_fma_f32 v[106:107], v[142:143], v[142:143], v[106:107]
	v_pk_fma_f32 v[100:101], v[136:137], v[136:137], v[100:101]
	v_pk_fma_f32 v[106:107], v[150:151], v[150:151], v[106:107]
	v_add_f32_e32 v100, v100, v101
	v_add_f32_e32 v100, v107, v100
	v_add_f32_e32 v100, v106, v100
	ds_bpermute_b32 v101, v172, v100
	s_waitcnt lgkmcnt(0)
	v_add_f32_e32 v100, v100, v101
	ds_bpermute_b32 v101, v173, v100
	s_waitcnt lgkmcnt(0)
	v_add_f32_e32 v100, v100, v101
	ds_bpermute_b32 v101, v174, v100
	s_waitcnt lgkmcnt(0)
	v_add_f32_e32 v100, v100, v101
	ds_bpermute_b32 v101, v175, v100
	s_waitcnt lgkmcnt(0)
	v_add_f32_e32 v100, v100, v101
	ds_bpermute_b32 v101, v176, v100
	s_waitcnt lgkmcnt(0)
	v_add_f32_e32 v100, v100, v101
	ds_bpermute_b32 v101, v177, v100
	s_waitcnt lgkmcnt(0)
	v_add_f32_e32 v100, v100, v101
	v_fmamk_f32 v100, v100, 0x3a800000, v104
	v_mul_f32_e32 v101, 0x4b800000, v100
	v_cmp_gt_f32_e32 vcc, s3, v100
	s_nop 1
	v_cndmask_b32_e32 v100, v100, v101, vcc
	v_rsq_f32_e32 v100, v100
	s_nop 0
	v_mul_f32_e32 v101, 0x45800000, v100
	v_cndmask_b32_e32 v100, v100, v101, vcc
	v_pk_mul_f32 v[106:107], v[120:121], v[100:101] op_sel_hi:[1,0]
	v_pk_mul_f32 v[108:109], v[118:119], v[100:101] op_sel_hi:[1,0]
	v_pk_mul_f32 v[110:111], v[116:117], v[100:101] op_sel_hi:[1,0]
	v_pk_mul_f32 v[112:113], v[122:123], v[100:101] op_sel_hi:[1,0]
	v_pk_mul_f32 v[116:117], v[124:125], v[100:101] op_sel_hi:[1,0]
	v_pk_mul_f32 v[118:119], v[126:127], v[100:101] op_sel_hi:[1,0]
	v_pk_mul_f32 v[120:121], v[130:131], v[100:101] op_sel_hi:[1,0]
	v_pk_mul_f32 v[100:101], v[114:115], v[100:101] op_sel_hi:[1,0]
	v_pk_mul_f32 v[108:109], v[20:21], v[108:109]
	v_pk_mul_f32 v[106:107], v[22:23], v[106:107]
	v_pk_mul_f32 v[112:113], v[16:17], v[112:113]
	v_pk_mul_f32 v[110:111], v[18:19], v[110:111]
	v_pk_mul_f32 v[114:115], v[52:53], v[118:119]
	v_pk_mul_f32 v[116:117], v[54:55], v[116:117]
	v_pk_mul_f32 v[100:101], v[48:49], v[100:101]
	v_pk_mul_f32 v[118:119], v[50:51], v[120:121]
	v_pk_fma_f32 v[120:121], v[82:83], v[106:107], v[30:31]
	v_pk_fma_f32 v[106:107], v[84:85], v[108:109], v[28:29]
	v_pk_fma_f32 v[110:111], v[86:87], v[110:111], v[26:27]
	v_pk_fma_f32 v[108:109], v[88:89], v[112:113], v[24:25]
	v_pk_fma_f32 v[112:113], v[90:91], v[116:117], v[62:63]
	v_pk_fma_f32 v[114:115], v[92:93], v[114:115], v[60:61]
	v_pk_fma_f32 v[116:117], v[94:95], v[118:119], v[58:59]
	v_pk_fma_f32 v[100:101], v[96:97], v[100:101], v[56:57]
	v_cvt_pk_bf16_f32 v106, v106, v107
	v_cvt_pk_bf16_f32 v107, v120, v121
	v_cvt_pk_bf16_f32 v108, v108, v109
	v_cvt_pk_bf16_f32 v109, v110, v111
	v_cvt_pk_bf16_f32 v110, v114, v115
	v_cvt_pk_bf16_f32 v111, v112, v113
	v_cvt_pk_bf16_f32 v112, v100, v101
	v_cvt_pk_bf16_f32 v113, v116, v117
	global_store_dwordx4 v[98:99], v[106:109], off sc1
	global_store_dwordx4 v[98:99], v[110:113], off offset:1024 sc1
	s_cbranch_scc0 .LBB0_864
	v_add_u32_e32 v105, s0, v105
	v_cmp_lt_i32_e32 vcc, s4, v105
	s_or_b64 s[8:9], vcc, s[8:9]
	v_add_u32_e32 v102, s1, v102
	s_andn2_b64 exec, exec, s[8:9]
	s_cbranch_execnz .LBB0_863
.LBB0_866:
	s_or_b64 exec, exec, s[6:7]
	s_waitcnt vmcnt(0)
	s_barrier
	s_mov_b64 s[6:7], exec
	v_readlane_b32 s0, v219, 25
	v_readlane_b32 s1, v219, 26
	s_and_b64 s[0:1], s[6:7], s[0:1]
	s_mov_b64 exec, s[0:1]
	s_cbranch_execz .LBB0_918
	v_readlane_b32 s0, v219, 27
	v_readlane_b32 s1, v219, 28
	v_readlane_b32 s2, v219, 29
	v_mov_b32_e32 v0, 0x24000
	s_waitcnt vmcnt(0) lgkmcnt(0)
	buffer_inv sc1
	ds_read_b32 v2, v0
	ds_read_b32 v0, v0 offset:4
	s_lshl_b32 s3, s2, 8
	s_add_i32 s14, s3, 0x2400
	s_add_i32 s3, s3, 0x1400
	v_mov_b32_e32 v1, s3
	s_waitcnt lgkmcnt(0)
	v_readfirstlane_b32 s10, v2
	v_readfirstlane_b32 s11, v0
	v_mov_b32_e32 v0, 1
	s_nop 1
	global_atomic_add v2, v1, v0, s[0:1] sc0
	s_mul_i32 s10, s10, 9
	s_mul_i32 s11, s11, 9
	s_waitcnt vmcnt(0)
	v_readfirstlane_b32 s13, v2
	s_nop 1
	s_add_i32 s13, s13, 1
	s_cmp_lg_u32 s13, s10
	s_cbranch_scc1 .Lnb9_wait
	v_mov_b32_e32 v1, 0x3400
	global_atomic_add v2, v1, v0, s[0:1] sc0
	s_waitcnt vmcnt(0)
	v_readfirstlane_b32 s13, v2
	s_nop 1
	s_add_i32 s13, s13, 1
	s_cmp_lg_u32 s13, s11
	s_cbranch_scc1 .Lnb9_wait
	v_mov_b32_e32 v1, 0x2400
	global_atomic_add v1, v0, s[0:1]
	global_atomic_add v1, v0, s[0:1] offset:256
	global_atomic_add v1, v0, s[0:1] offset:512
	global_atomic_add v1, v0, s[0:1] offset:768
	global_atomic_add v1, v0, s[0:1] offset:1024
	global_atomic_add v1, v0, s[0:1] offset:1280
	global_atomic_add v1, v0, s[0:1] offset:1536
	global_atomic_add v1, v0, s[0:1] offset:1792
	global_atomic_add v1, v0, s[0:1] offset:2048
	global_atomic_add v1, v0, s[0:1] offset:2304
	global_atomic_add v1, v0, s[0:1] offset:2560
	global_atomic_add v1, v0, s[0:1] offset:2816
	global_atomic_add v1, v0, s[0:1] offset:3072
	global_atomic_add v1, v0, s[0:1] offset:3328
	global_atomic_add v1, v0, s[0:1] offset:3584
	global_atomic_add v1, v0, s[0:1] offset:3840
	v_mov_b32_e32 v1, 0x3500
	global_atomic_add v1, v0, s[0:1]

.Lnb9_spin:
	global_load_dword v2, v1, s[0:1] sc1
	s_waitcnt vmcnt(0)
	v_readfirstlane_b32 s13, v2
	s_nop 1
	s_cmp_ge_u32 s13, 9
	s_cbranch_scc1 .Lnb9_done
	s_sleep 1
	s_add_i32 s15, s15, 1
	s_cmp_lt_u32 s15, 0x200000
	s_cbranch_scc1 .Lnb9_spin
.Lnb9_done:
	s_waitcnt vmcnt(0)
.LBB0_918:
	s_or_b64 exec, exec, s[6:7]
	s_cmpk_gt_i32 s78, 0x17f
	v_readfirstlane_b32 s0, v168
	s_waitcnt lgkmcnt(0)
	s_barrier
	s_cbranch_scc1 .LBB0_1016
	s_add_u32 s29, s56, 0x1980000
	s_addc_u32 s4, s57, 0
	s_lshl_b32 s2, s78, 19
	s_lshr_b32 s1, s0, 6
	s_bfe_u32 s18, s0, 0x10006
	s_lshr_b32 s19, s0, 7
	s_and_b32 s2, s2, 0xf80000
	s_add_u32 s12, s30, s2
	s_addc_u32 s13, s31, 0
	s_lshl_b32 s5, s78, 2
	s_and_b32 s2, s5, 0xffffff80
	s_mov_b32 s93, 0
	s_ashr_i32 s3, s2, 31
	s_lshl_b32 s92, s1, 5
	s_lshl_b32 s60, s1, 12
	s_lshl_b64 s[2:3], s[2:3], 11
	s_add_i32 s61, s60, 0
	s_lshl_b64 s[14:15], s[92:93], 11
	s_add_u32 s6, s12, s14
	s_addc_u32 s7, s13, s15
	s_or_b32 s8, s92, 8
	s_mov_b32 s9, s93
	s_lshl_b64 s[36:37], s[8:9], 11
	s_add_u32 s8, s12, s36
	v_mov_b32_e32 v0, v178
	v_mov_b32_e32 v1, v179
	s_mov_b32 m0, s61
	s_addc_u32 s9, s13, s37
	s_or_b32 s10, s92, 16
	s_mov_b32 s11, s93
	s_barrier
	s_lshl_b64 s[38:39], s[10:11], 11
	global_load_lds_dwordx4 v0, s[6:7]
	s_add_i32 m0, s61, 0x400
	s_add_u32 s10, s12, s38
	s_addc_u32 s11, s13, s39
	s_or_b32 s92, s92, 24
	global_load_lds_dwordx4 v1, s[8:9]
	s_add_i32 m0, s61, 0x800
	s_lshl_b64 s[40:41], s[92:93], 11
	s_add_u32 s12, s12, s40
	global_load_lds_dwordx4 v0, s[10:11]
	s_addc_u32 s13, s13, s41
	s_add_i32 m0, s61, 0xc00
	s_add_u32 s16, s29, s2
	s_addc_u32 s17, s4, s3
	s_lshl_b32 s62, s1, 11
	s_lshl_b32 s92, s1, 4
	s_sub_i32 s20, s61, s62
	global_load_lds_dwordx4 v1, s[12:13]
	s_add_i32 m0, s20, 0x8000
	s_lshl_b64 s[42:43], s[92:93], 11
	s_add_u32 s2, s16, s42
	s_addc_u32 s3, s17, s43
	s_or_b32 s92, s92, 8
	s_lshl_b64 s[44:45], s[92:93], 11
	s_add_u32 s16, s16, s44
	global_load_lds_dwordx4 v0, s[2:3]
	s_addc_u32 s17, s17, s45
	s_add_i32 m0, s20, 0x8400
	v_mov_b32_e32 v150, v178
	v_mov_b32_e32 v0, v179
	v_mov_b32_e32 v151, 0
	global_load_lds_dwordx4 v1, s[16:17]
	s_mov_b64 s[46:47], 0x80
	v_lshl_add_u64 v[2:3], s[6:7], 0, v[150:151]
	s_add_i32 m0, s61, 0xc000
	v_lshl_add_u64 v[2:3], v[2:3], 0, s[46:47]
	v_mov_b32_e32 v1, v151
	global_load_lds_dwordx4 v[2:3], off
	v_lshl_add_u64 v[2:3], s[8:9], 0, v[0:1]
	v_lshl_add_u64 v[2:3], v[2:3], 0, s[46:47]
	s_add_i32 m0, s61, 0xc400
	s_add_i32 s6, s62, 0
	global_load_lds_dwordx4 v[2:3], off
	v_lshl_add_u64 v[2:3], s[10:11], 0, v[150:151]
	v_lshl_add_u64 v[2:3], v[2:3], 0, s[46:47]
	s_add_i32 m0, s61, 0xc800
	s_mov_b32 s7, s93
	global_load_lds_dwordx4 v[2:3], off
	v_lshl_add_u64 v[2:3], s[12:13], 0, v[0:1]
	v_lshl_add_u64 v[2:3], v[2:3], 0, s[46:47]
	s_add_i32 m0, s61, 0xcc00
	v_lshl_add_u64 v[0:1], s[16:17], 0, v[0:1]
	global_load_lds_dwordx4 v[2:3], off
	v_lshl_add_u64 v[2:3], s[2:3], 0, v[150:151]
	s_add_i32 m0, s6, 0x14000
	v_lshl_add_u64 v[2:3], v[2:3], 0, s[46:47]
	global_load_lds_dwordx4 v[2:3], off
	v_lshl_add_u64 v[0:1], v[0:1], 0, s[46:47]
	s_add_i32 m0, s6, 0x14400
	s_cmpk_gt_u32 s0, 0xff
	global_load_lds_dwordx4 v[0:1], off
	v_xor_b32_e32 v1, v147, v170
	s_cselect_b64 s[2:3], -1, 0
	s_lshl_b32 s92, s1, 15
	s_lshl_b32 s6, s1, 14
	s_lshl_b32 s63, s19, 6
	s_lshl_b32 s64, s18, 6
	s_lshl_b32 s65, s18, 13
	v_lshlrev_b32_e32 v186, 4, v1
	s_lshl_b32 s66, s19, 13
	v_bitop3_b32 v1, v147, v170, 4 bitop3:0x36
	v_lshlrev_b32_e32 v187, 4, v1
	v_or_b32_e32 v1, v146, v161
	s_add_u32 s50, s56, 0x24000
	s_addc_u32 s51, s57, 0
	v_lshlrev_b32_e32 v150, 3, v1
	v_lshl_add_u64 v[152:153], s[50:51], 0, v[150:151]
	s_mov_b64 s[0:1], 0x1000
	v_writelane_b32 v219, s2, 37
	v_lshl_add_u64 v[154:155], v[152:153], 0, s[0:1]
	s_mov_b64 s[0:1], 0x1800
	v_writelane_b32 v219, s3, 38
	v_lshl_add_u64 v[156:157], v[152:153], 0, s[0:1]
	s_add_u32 s0, s56, s14
	v_writelane_b32 v219, s0, 41
	s_addc_u32 s0, s57, s15
	s_lshl_b32 s91, s78, 8
	s_lshl_b32 s3, s58, 8
	v_writelane_b32 v219, s0, 42
	s_add_u32 s0, s56, s42
	v_writelane_b32 v219, s0, 47
	s_addc_u32 s33, s57, s43
	s_lshl_b32 s0, s58, 2
	s_lshl_b64 s[68:69], s[92:93], 1
	s_add_u32 s1, s56, s68
	v_add_u32_e32 v0, 12, v146
	v_cmp_eq_u32_e32 vcc, 0, v171
	s_addc_u32 s28, s57, s69
	s_lshl_b64 s[70:71], s[6:7], 1
	v_cndmask_b32_e32 v0, v0, v146, vcc
	s_add_u32 s67, s56, s70
	s_addc_u32 s90, s57, s71
	s_mov_b64 s[6:7], -1
	s_mov_b64 s[72:73], 0x100
	s_mov_b64 s[74:75], 0x3400180
	s_mov_b64 s[76:77], 0x3404180
	s_mov_b32 s18, s78
	s_mov_b64 s[78:79], 0x3408180
	s_mov_b64 s[80:81], 0x340c180
	s_mov_b64 s[82:83], 0x1980180
	s_mov_b64 s[84:85], 0x1984180
	v_lshlrev_b32_e32 v158, 2, v146
	s_mov_b32 s92, 0x3e38aa3b
	v_lshlrev_b32_e32 v160, 1, v0
	s_branch .LBB0_921
.LBB0_920:
	v_pk_mul_f32 v[16:17], v[10:11], s[92:93] op_sel_hi:[1,0]
	v_pk_mul_f32 v[18:19], v[8:9], s[92:93] op_sel_hi:[1,0]
	v_cndmask_b32_e64 v11, v11, v17, s[6:7]
	v_cndmask_b32_e64 v10, v10, v16, s[6:7]
	v_cndmask_b32_e64 v9, v9, v19, s[6:7]
	v_cndmask_b32_e64 v8, v8, v18, s[6:7]
	v_cvt_pk_bf16_f32 v8, v8, v9
	v_cvt_pk_bf16_f32 v9, v10, v11
	v_pk_mul_f32 v[10:11], v[6:7], s[92:93] op_sel_hi:[1,0]
	v_pk_mul_f32 v[16:17], v[4:5], s[92:93] op_sel_hi:[1,0]
	v_cndmask_b32_e64 v7, v7, v11, s[6:7]
	v_cndmask_b32_e64 v10, v6, v10, s[6:7]
	v_cndmask_b32_e64 v5, v5, v17, s[6:7]
	v_cndmask_b32_e64 v4, v4, v16, s[6:7]
	v_cvt_pk_bf16_f32 v6, v4, v5
	v_cvt_pk_bf16_f32 v7, v10, v7
	v_pk_mul_f32 v[4:5], v[2:3], s[92:93] op_sel_hi:[1,0]
	v_pk_mul_f32 v[10:11], v[0:1], s[92:93] op_sel_hi:[1,0]
	v_cndmask_b32_e64 v3, v3, v5, s[6:7]
	v_cndmask_b32_e64 v4, v2, v4, s[6:7]
	v_cndmask_b32_e64 v1, v1, v11, s[6:7]
	v_cndmask_b32_e64 v0, v0, v10, s[6:7]
	v_cvt_pk_bf16_f32 v2, v0, v1
	v_cvt_pk_bf16_f32 v3, v4, v3
	v_pk_mul_f32 v[0:1], v[14:15], s[92:93] op_sel_hi:[1,0]
	v_pk_mul_f32 v[4:5], v[12:13], s[92:93] op_sel_hi:[1,0]
	v_cndmask_b32_e64 v10, v14, v0, s[6:7]
	v_cndmask_b32_e64 v0, v13, v5, s[6:7]
	v_cndmask_b32_e64 v4, v12, v4, s[6:7]
	v_cndmask_b32_e64 v1, v15, v1, s[6:7]
	v_cvt_pk_bf16_f32 v0, v4, v0
	v_lshlrev_b64 v[4:5], s10, v[150:151]
	v_cvt_pk_bf16_f32 v1, v10, v1
	v_lshl_add_u64 v[4:5], v[4:5], 1, s[12:13]
	v_mov_b32_e32 v161, v151
	v_permlane16_swap_b32_e32 v0, v2
	v_permlane16_swap_b32_e32 v1, v3
	v_lshl_add_u64 v[4:5], v[4:5], 0, v[160:161]
	v_permlane16_swap_b32_e32 v6, v8
	v_permlane16_swap_b32_e32 v7, v9
	s_add_i32 s91, s91, s3
	s_add_i32 s5, s5, s0
	s_andn2_b64 vcc, exec, s[94:95]
	s_mov_b64 s[6:7], 0
	global_store_dwordx4 v[4:5], v[0:3], off sc1
	global_store_dwordx4 v[4:5], v[6:9], off offset:64 sc1
	s_cbranch_vccz .LBB0_1015

.LBB0_933:
	s_and_b64 s[16:17], s[6:7], exec
	s_cselect_b32 s16, s10, s22
	s_and_b64 s[10:11], s[12:13], exec
	s_mov_b32 s2, 0x5400000
	v_pk_mul_f32 v[42:43], v[38:39], s[92:93] op_sel_hi:[1,0]
	v_pk_mul_f32 v[44:45], v[36:37], s[92:93] op_sel_hi:[1,0]
	s_cselect_b32 s2, s2, 0x6400000
	s_and_b64 s[10:11], s[6:7], exec
	v_cndmask_b32_e64 v39, v39, v43, s[6:7]
	v_cndmask_b32_e64 v42, v38, v42, s[6:7]
	v_cndmask_b32_e64 v37, v37, v45, s[6:7]
	v_cndmask_b32_e64 v36, v36, v44, s[6:7]
	s_cselect_b32 s2, 0x4400000, s2
	v_cvt_pk_bf16_f32 v38, v36, v37
	v_cvt_pk_bf16_f32 v39, v42, v39
	v_pk_mul_f32 v[36:37], v[78:79], s[92:93] op_sel_hi:[1,0]
	v_pk_mul_f32 v[42:43], v[76:77], s[92:93] op_sel_hi:[1,0]
	s_add_u32 s2, s56, s2
	v_cndmask_b32_e64 v37, v79, v37, s[6:7]
	v_cndmask_b32_e64 v44, v78, v36, s[6:7]
	v_cndmask_b32_e64 v36, v77, v43, s[6:7]
	v_cndmask_b32_e64 v42, v76, v42, s[6:7]
	s_addc_u32 s19, s57, 0
	v_cvt_pk_bf16_f32 v36, v42, v36
	v_cvt_pk_bf16_f32 v37, v44, v37
	v_pk_mul_f32 v[42:43], v[34:35], s[92:93] op_sel_hi:[1,0]
	v_pk_mul_f32 v[44:45], v[32:33], s[92:93] op_sel_hi:[1,0]
	s_and_b64 s[10:11], s[6:7], exec
	v_cndmask_b32_e64 v35, v35, v43, s[6:7]
	v_cndmask_b32_e64 v42, v34, v42, s[6:7]
	v_cndmask_b32_e64 v33, v33, v45, s[6:7]
	v_cndmask_b32_e64 v32, v32, v44, s[6:7]
	s_cselect_b32 s10, 10, 8
	s_ashr_i32 s17, s16, 31
	v_cvt_pk_bf16_f32 v34, v32, v33
	v_cvt_pk_bf16_f32 v35, v42, v35
	s_lshl_b64 s[12:13], s[16:17], 1
	v_pk_mul_f32 v[32:33], v[74:75], s[92:93] op_sel_hi:[1,0]
	v_pk_mul_f32 v[42:43], v[72:73], s[92:93] op_sel_hi:[1,0]
	s_add_u32 s12, s2, s12
	v_cndmask_b32_e64 v44, v74, v32, s[6:7]
	v_cndmask_b32_e64 v32, v73, v43, s[6:7]
	v_cndmask_b32_e64 v42, v72, v42, s[6:7]
	s_addc_u32 s13, s19, s13
	v_cndmask_b32_e64 v33, v75, v33, s[6:7]
	v_cvt_pk_bf16_f32 v32, v42, v32
	v_lshlrev_b64 v[42:43], s10, v[150:151]
	v_cvt_pk_bf16_f32 v33, v44, v33
	v_lshl_add_u64 v[42:43], v[42:43], 1, s[12:13]
	v_mov_b32_e32 v161, v151
	v_permlane16_swap_b32_e32 v32, v34
	v_permlane16_swap_b32_e32 v33, v35
	v_lshl_add_u64 v[42:43], v[42:43], 0, v[160:161]
	global_store_dwordx4 v[42:43], v[32:35], off sc1
	v_permlane16_swap_b32_e32 v36, v38
	s_nop 0
	v_or_b32_e32 v32, 16, v150
	v_mov_b32_e32 v33, v151
	v_lshlrev_b64 v[34:35], 10, v[32:33]
	v_permlane16_swap_b32_e32 v37, v39
	s_and_b64 vcc, exec, s[8:9]
	v_lshl_add_u64 v[34:35], v[40:41], 0, v[34:35]
	global_store_dwordx4 v[42:43], v[36:39], off offset:64 sc1
	s_cbranch_vccz .LBB0_1005
	s_and_b64 vcc, exec, s[8:9]
	s_cbranch_vccz .LBB0_1006

.LBB0_938:
	v_pk_mul_f32 v[34:35], v[30:31], s[92:93] op_sel_hi:[1,0]
	v_pk_mul_f32 v[36:37], v[28:29], s[92:93] op_sel_hi:[1,0]
	v_cndmask_b32_e64 v31, v31, v35, s[6:7]
	v_cndmask_b32_e64 v34, v30, v34, s[6:7]
	v_cndmask_b32_e64 v29, v29, v37, s[6:7]
	v_cndmask_b32_e64 v28, v28, v36, s[6:7]
	v_cvt_pk_bf16_f32 v30, v28, v29
	v_cvt_pk_bf16_f32 v31, v34, v31
	v_pk_mul_f32 v[28:29], v[70:71], s[92:93] op_sel_hi:[1,0]
	v_pk_mul_f32 v[34:35], v[68:69], s[92:93] op_sel_hi:[1,0]
	v_cndmask_b32_e64 v29, v71, v29, s[6:7]
	v_cndmask_b32_e64 v36, v70, v28, s[6:7]
	v_cndmask_b32_e64 v28, v69, v35, s[6:7]
	v_cndmask_b32_e64 v34, v68, v34, s[6:7]
	v_cvt_pk_bf16_f32 v28, v34, v28
	v_cvt_pk_bf16_f32 v29, v36, v29
	v_pk_mul_f32 v[34:35], v[26:27], s[92:93] op_sel_hi:[1,0]
	v_pk_mul_f32 v[36:37], v[24:25], s[92:93] op_sel_hi:[1,0]
	v_cndmask_b32_e64 v27, v27, v35, s[6:7]
	v_cndmask_b32_e64 v34, v26, v34, s[6:7]
	v_cndmask_b32_e64 v25, v25, v37, s[6:7]
	v_cndmask_b32_e64 v24, v24, v36, s[6:7]
	v_cvt_pk_bf16_f32 v26, v24, v25
	v_cvt_pk_bf16_f32 v27, v34, v27
	v_pk_mul_f32 v[24:25], v[66:67], s[92:93] op_sel_hi:[1,0]
	v_pk_mul_f32 v[34:35], v[64:65], s[92:93] op_sel_hi:[1,0]
	v_cndmask_b32_e64 v25, v67, v25, s[6:7]
	v_cndmask_b32_e64 v36, v66, v24, s[6:7]
	v_cndmask_b32_e64 v24, v65, v35, s[6:7]
	v_cndmask_b32_e64 v34, v64, v34, s[6:7]
	v_lshlrev_b64 v[32:33], s10, v[32:33]
	v_cvt_pk_bf16_f32 v24, v34, v24
	v_cvt_pk_bf16_f32 v25, v36, v25
	v_lshl_add_u64 v[32:33], v[32:33], 1, s[12:13]
	v_mov_b32_e32 v161, v151
	v_permlane16_swap_b32_e32 v24, v26
	v_permlane16_swap_b32_e32 v25, v27
	v_lshl_add_u64 v[32:33], v[32:33], 0, v[160:161]
	global_store_dwordx4 v[32:33], v[24:27], off sc1
	v_permlane16_swap_b32_e32 v28, v30
	s_nop 0
	v_or_b32_e32 v24, 32, v150
	v_mov_b32_e32 v25, v151
	v_lshlrev_b64 v[26:27], 10, v[24:25]
	v_permlane16_swap_b32_e32 v29, v31
	s_and_b64 vcc, exec, s[8:9]
	v_lshl_add_u64 v[26:27], v[40:41], 0, v[26:27]
	global_store_dwordx4 v[32:33], v[28:31], off offset:64 sc1
	s_cbranch_vccz .LBB0_1008
	s_and_b64 vcc, exec, s[8:9]
	s_cbranch_vccz .LBB0_1009

.LBB0_943:
	v_pk_mul_f32 v[26:27], v[22:23], s[92:93] op_sel_hi:[1,0]
	v_pk_mul_f32 v[28:29], v[20:21], s[92:93] op_sel_hi:[1,0]
	v_cndmask_b32_e64 v23, v23, v27, s[6:7]
	v_cndmask_b32_e64 v26, v22, v26, s[6:7]
	v_cndmask_b32_e64 v21, v21, v29, s[6:7]
	v_cndmask_b32_e64 v20, v20, v28, s[6:7]
	v_cvt_pk_bf16_f32 v22, v20, v21
	v_cvt_pk_bf16_f32 v23, v26, v23
	v_pk_mul_f32 v[20:21], v[60:61], s[92:93] op_sel_hi:[1,0]
	v_pk_mul_f32 v[26:27], v[58:59], s[92:93] op_sel_hi:[1,0]
	v_cndmask_b32_e64 v21, v61, v21, s[6:7]
	v_cndmask_b32_e64 v28, v60, v20, s[6:7]
	v_cndmask_b32_e64 v20, v59, v27, s[6:7]
	v_cndmask_b32_e64 v26, v58, v26, s[6:7]
	v_cvt_pk_bf16_f32 v20, v26, v20
	v_cvt_pk_bf16_f32 v21, v28, v21
	v_pk_mul_f32 v[26:27], v[18:19], s[92:93] op_sel_hi:[1,0]
	v_pk_mul_f32 v[28:29], v[16:17], s[92:93] op_sel_hi:[1,0]
	v_cndmask_b32_e64 v19, v19, v27, s[6:7]
	v_cndmask_b32_e64 v26, v18, v26, s[6:7]
	v_cndmask_b32_e64 v17, v17, v29, s[6:7]
	v_cndmask_b32_e64 v16, v16, v28, s[6:7]
	v_cvt_pk_bf16_f32 v18, v16, v17
	v_cvt_pk_bf16_f32 v19, v26, v19
	v_pk_mul_f32 v[16:17], v[56:57], s[92:93] op_sel_hi:[1,0]
	v_pk_mul_f32 v[26:27], v[54:55], s[92:93] op_sel_hi:[1,0]
	v_cndmask_b32_e64 v17, v57, v17, s[6:7]
	v_cndmask_b32_e64 v28, v56, v16, s[6:7]
	v_cndmask_b32_e64 v16, v55, v27, s[6:7]
	v_cndmask_b32_e64 v26, v54, v26, s[6:7]
	v_lshlrev_b64 v[24:25], s10, v[24:25]
	v_cvt_pk_bf16_f32 v16, v26, v16
	v_cvt_pk_bf16_f32 v17, v28, v17
	v_lshl_add_u64 v[24:25], v[24:25], 1, s[12:13]
	v_mov_b32_e32 v161, v151
	v_permlane16_swap_b32_e32 v16, v18
	v_permlane16_swap_b32_e32 v17, v19
	v_lshl_add_u64 v[24:25], v[24:25], 0, v[160:161]
	v_or_b32_e32 v150, 48, v150
	global_store_dwordx4 v[24:25], v[16:19], off sc1
	v_permlane16_swap_b32_e32 v20, v22
	s_nop 0
	v_lshlrev_b64 v[16:17], 10, v[150:151]
	v_permlane16_swap_b32_e32 v21, v23
	s_and_b64 vcc, exec, s[8:9]
	v_lshl_add_u64 v[16:17], v[40:41], 0, v[16:17]
	global_store_dwordx4 v[24:25], v[20:23], off offset:64 sc1
	s_cbranch_vccz .LBB0_1011
	s_and_b64 vcc, exec, s[8:9]
	s_cbranch_vccz .LBB0_1012

.LBB0_1032:
	s_lshl_b32 s8, s6, 1
	s_lshl_b32 s9, s5, 1
	v_or_b32_e32 v9, s8, v1
	v_or_b32_e32 v11, s9, v0
	s_add_i32 s10, s8, 4
	s_add_i32 s11, s9, 4
	s_add_i32 s12, s8, 8
	s_add_i32 s13, s9, 8
	s_add_i32 s14, s8, 12
	s_add_i32 s15, s9, 12
	s_add_i32 s16, s8, 16
	s_add_i32 s17, s9, 16
	s_add_i32 s18, s8, 20
	s_add_i32 s19, s9, 20
	s_add_i32 s20, s8, 24
	s_add_i32 s21, s9, 24
	s_add_i32 s8, s8, 28
	s_add_i32 s9, s9, 28
	v_add_u32_e32 v17, v9, v7
	v_add_u32_e32 v37, v11, v16
	v_or_b32_e32 v70, s10, v1
	v_or_b32_e32 v71, s11, v0
	v_or_b32_e32 v72, s12, v1
	v_or_b32_e32 v73, s13, v0
	v_or_b32_e32 v74, s14, v1
	v_or_b32_e32 v75, s15, v0
	v_or_b32_e32 v76, s16, v1
	v_or_b32_e32 v77, s17, v0
	v_or_b32_e32 v78, s18, v1
	v_or_b32_e32 v79, s19, v0
	v_or_b32_e32 v80, s20, v1
	v_or_b32_e32 v81, s21, v0
	v_or_b32_e32 v82, s8, v1
	v_or_b32_e32 v83, s9, v0
	v_ashrrev_i32_e32 v42, 31, v37
	v_ashrrev_i32_e32 v43, 31, v17
	v_mul_lo_u32 v84, v3, v17
	v_mad_u64_u32 v[38:39], s[8:9], v2, v17, 0
	v_mul_lo_u32 v17, v13, v37
	v_mad_u64_u32 v[40:41], s[8:9], v12, v37, 0
	v_add_u32_e32 v37, v70, v7
	v_add_u32_e32 v44, v71, v16
	v_add_u32_e32 v46, v72, v7
	v_add_u32_e32 v48, v73, v16
	v_add_u32_e32 v50, v74, v7
	v_add_u32_e32 v52, v75, v16
	v_add_u32_e32 v54, v76, v7
	v_add_u32_e32 v56, v77, v16
	v_add_u32_e32 v58, v78, v7
	v_add_u32_e32 v60, v79, v16
	v_add_u32_e32 v62, v80, v7
	v_add_u32_e32 v64, v81, v16
	v_add_u32_e32 v66, v82, v7
	v_add_u32_e32 v68, v83, v16
	v_mul_lo_u32 v85, v2, v43
	v_mul_lo_u32 v86, v12, v42
	v_ashrrev_i32_e32 v87, 31, v44
	v_ashrrev_i32_e32 v88, 31, v37
	v_ashrrev_i32_e32 v90, 31, v48
	v_ashrrev_i32_e32 v91, 31, v46
	v_ashrrev_i32_e32 v94, 31, v52
	v_ashrrev_i32_e32 v95, 31, v50
	v_ashrrev_i32_e32 v98, 31, v56
	v_ashrrev_i32_e32 v99, 31, v54
	v_ashrrev_i32_e32 v102, 31, v60
	v_ashrrev_i32_e32 v103, 31, v58
	v_ashrrev_i32_e32 v106, 31, v64
	v_ashrrev_i32_e32 v107, 31, v62
	v_ashrrev_i32_e32 v110, 31, v68
	v_ashrrev_i32_e32 v111, 31, v66
	v_mul_lo_u32 v89, v3, v37
	v_mad_u64_u32 v[42:43], s[8:9], v2, v37, 0
	v_mul_lo_u32 v37, v13, v44
	v_mad_u64_u32 v[44:45], s[8:9], v12, v44, 0
	v_mul_lo_u32 v92, v3, v46
	v_mad_u64_u32 v[46:47], s[8:9], v2, v46, 0
	v_mul_lo_u32 v93, v13, v48
	v_mad_u64_u32 v[48:49], s[8:9], v12, v48, 0
	v_mul_lo_u32 v96, v3, v50
	v_mad_u64_u32 v[50:51], s[8:9], v2, v50, 0
	v_mul_lo_u32 v97, v13, v52
	v_mad_u64_u32 v[52:53], s[8:9], v12, v52, 0
	v_mul_lo_u32 v100, v3, v54
	v_mad_u64_u32 v[54:55], s[8:9], v2, v54, 0
	v_mul_lo_u32 v101, v13, v56
	v_mad_u64_u32 v[56:57], s[8:9], v12, v56, 0
	v_mul_lo_u32 v104, v3, v58
	v_mad_u64_u32 v[58:59], s[8:9], v2, v58, 0
	v_mul_lo_u32 v105, v13, v60
	v_mad_u64_u32 v[60:61], s[8:9], v12, v60, 0
	v_mul_lo_u32 v108, v3, v62
	v_mad_u64_u32 v[62:63], s[8:9], v2, v62, 0
	v_mul_lo_u32 v109, v13, v64
	v_mad_u64_u32 v[64:65], s[8:9], v12, v64, 0
	v_mul_lo_u32 v112, v3, v66
	v_mad_u64_u32 v[66:67], s[8:9], v2, v66, 0
	v_mul_lo_u32 v113, v13, v68
	v_mad_u64_u32 v[68:69], s[8:9], v12, v68, 0
	v_add3_u32 v39, v39, v85, v84
	v_add3_u32 v41, v41, v86, v17
	v_mul_lo_u32 v17, v2, v88
	v_mul_lo_u32 v84, v12, v87
	v_mul_lo_u32 v85, v2, v91
	v_mul_lo_u32 v86, v12, v90
	v_mul_lo_u32 v87, v2, v95
	v_mul_lo_u32 v88, v12, v94
	v_mul_lo_u32 v90, v2, v99
	v_mul_lo_u32 v91, v12, v98
	v_mul_lo_u32 v94, v2, v103
	v_mul_lo_u32 v95, v12, v102
	v_mul_lo_u32 v98, v2, v107
	v_mul_lo_u32 v99, v12, v106
	v_mul_lo_u32 v102, v2, v111
	v_mul_lo_u32 v103, v12, v110
	v_lshl_add_u64 v[40:41], v[40:41], 2, v[18:19]
	v_add3_u32 v43, v43, v17, v89
	v_add3_u32 v45, v45, v84, v37
	v_add3_u32 v47, v47, v85, v92
	v_add3_u32 v49, v49, v86, v93
	v_add3_u32 v51, v51, v87, v96
	v_add3_u32 v53, v53, v88, v97
	v_add3_u32 v55, v55, v90, v100
	v_add3_u32 v57, v57, v91, v101
	v_add3_u32 v59, v59, v94, v104
	v_add3_u32 v61, v61, v95, v105
	v_add3_u32 v63, v63, v98, v108
	v_add3_u32 v65, v65, v99, v109
	v_add3_u32 v67, v67, v102, v112
	v_add3_u32 v69, v69, v103, v113
	v_lshl_add_u64 v[38:39], v[38:39], 2, v[18:19]
	v_lshl_add_u64 v[44:45], v[44:45], 2, v[18:19]
	v_lshl_add_u64 v[42:43], v[42:43], 2, v[18:19]
	v_lshl_add_u64 v[48:49], v[48:49], 2, v[18:19]
	v_lshl_add_u64 v[46:47], v[46:47], 2, v[18:19]
	v_lshl_add_u64 v[52:53], v[52:53], 2, v[18:19]
	v_lshl_add_u64 v[50:51], v[50:51], 2, v[18:19]
	v_lshl_add_u64 v[56:57], v[56:57], 2, v[18:19]
	v_lshl_add_u64 v[54:55], v[54:55], 2, v[18:19]
	v_lshl_add_u64 v[60:61], v[60:61], 2, v[18:19]
	v_lshl_add_u64 v[58:59], v[58:59], 2, v[18:19]
	v_lshl_add_u64 v[64:65], v[64:65], 2, v[18:19]
	v_lshl_add_u64 v[62:63], v[62:63], 2, v[18:19]
	v_lshl_add_u64 v[68:69], v[68:69], 2, v[18:19]
	v_lshl_add_u64 v[66:67], v[66:67], 2, v[18:19]
	global_load_dword v17, v[40:41], off
	global_load_dword v37, v[38:39], off
	global_load_dword v84, v[44:45], off
	global_load_dword v85, v[42:43], off
	global_load_dword v86, v[48:49], off
	global_load_dword v87, v[46:47], off
	global_load_dword v88, v[52:53], off
	global_load_dword v89, v[50:51], off
	global_load_dword v90, v[56:57], off
	global_load_dword v91, v[54:55], off
	global_load_dword v92, v[60:61], off
	global_load_dword v93, v[58:59], off
	global_load_dword v94, v[64:65], off
	global_load_dword v95, v[62:63], off
	global_load_dword v96, v[68:69], off
	global_load_dword v97, v[66:67], off
	s_add_i32 s5, s5, 16
	s_add_i32 s6, s6, 16
	s_add_i32 s7, s7, -16
	v_mad_u64_u32 v[38:39], s[8:9], v11, s1, v[6:7]
	s_cmp_lg_u32 s7, 0
	v_mad_u64_u32 v[40:41], s[8:9], v9, s1, v[6:7]
	v_mad_u64_u32 v[42:43], s[8:9], v71, s1, v[6:7]
	v_mad_u64_u32 v[44:45], s[8:9], v70, s1, v[6:7]
	v_mad_u64_u32 v[46:47], s[8:9], v73, s1, v[6:7]
	v_mad_u64_u32 v[48:49], s[8:9], v72, s1, v[6:7]
	v_mad_u64_u32 v[50:51], s[8:9], v75, s1, v[6:7]
	v_mad_u64_u32 v[52:53], s[8:9], v74, s1, v[6:7]
	v_mad_u64_u32 v[54:55], s[8:9], v77, s1, v[6:7]
	v_mad_u64_u32 v[56:57], s[8:9], v76, s1, v[6:7]
	v_mad_u64_u32 v[58:59], s[8:9], v79, s1, v[6:7]
	v_mad_u64_u32 v[60:61], s[8:9], v78, s1, v[6:7]
	v_mad_u64_u32 v[62:63], s[8:9], v81, s1, v[6:7]
	v_mad_u64_u32 v[64:65], s[8:9], v80, s1, v[6:7]
	v_mad_u64_u32 v[66:67], s[8:9], v83, s1, v[6:7]
	v_mad_u64_u32 v[68:69], s[8:9], v82, s1, v[6:7]
	s_waitcnt vmcnt(15)
	ds_write_b32 v38, v17
	s_waitcnt vmcnt(14)
	ds_write_b32 v40, v37
	s_waitcnt vmcnt(13)
	ds_write_b32 v42, v84
	s_waitcnt vmcnt(12)
	ds_write_b32 v44, v85
	s_waitcnt vmcnt(11)
	ds_write_b32 v46, v86
	s_waitcnt vmcnt(10)
	ds_write_b32 v48, v87
	s_waitcnt vmcnt(9)
	ds_write_b32 v50, v88
	s_waitcnt vmcnt(8)
	ds_write_b32 v52, v89
	s_waitcnt vmcnt(7)
	ds_write_b32 v54, v90
	s_waitcnt vmcnt(6)
	ds_write_b32 v56, v91
	s_waitcnt vmcnt(5)
	ds_write_b32 v58, v92
	s_waitcnt vmcnt(4)
	ds_write_b32 v60, v93
	s_waitcnt vmcnt(3)
	ds_write_b32 v62, v94
	s_waitcnt vmcnt(2)
	ds_write_b32 v64, v95
	s_waitcnt vmcnt(1)
	ds_write_b32 v66, v96
	s_waitcnt vmcnt(0)
	ds_write_b32 v68, v97
	s_cbranch_scc1 .LBB0_1032
	s_waitcnt lgkmcnt(0)
	v_ashrrev_i32_e32 v17, 31, v16
	v_lshl_add_u64 v[2:3], v[16:17], 1, v[14:15]
	ds_read2_b32 v[16:17], v20 offset0:33 offset1:41
	ds_read2_b32 v[18:19], v20 offset1:8
	ds_read2_b32 v[38:39], v20 offset0:66 offset1:74
	ds_read2_b32 v[40:41], v20 offset0:99 offset1:107
	ds_read2_b32 v[42:43], v20 offset0:132 offset1:140
	ds_read2_b32 v[44:45], v20 offset0:165 offset1:173
	ds_read2_b32 v[46:47], v20 offset0:198 offset1:206
	ds_read2_b32 v[48:49], v20 offset0:231 offset1:239
	v_or_b32_e32 v7, v4, v185
	v_ashrrev_i32_e32 v9, 31, v4
	v_mov_b32_e32 v11, v5
	v_mul_lo_u32 v9, v9, v36
	v_mad_u64_u32 v[50:51], s[6:7], v7, v36, 0
	v_lshl_add_u64 v[2:3], v[2:3], 0, v[10:11]
	v_add_u32_e32 v51, v51, v9
	s_waitcnt lgkmcnt(6)
	v_cvt_pk_bf16_f32 v12, v18, v16
	s_waitcnt lgkmcnt(4)
	v_cvt_pk_bf16_f32 v13, v38, v40
	s_waitcnt lgkmcnt(2)
	v_cvt_pk_bf16_f32 v14, v42, v44
	s_waitcnt lgkmcnt(0)
	v_cvt_pk_bf16_f32 v15, v46, v48
	v_lshl_add_u64 v[50:51], v[50:51], 1, v[2:3]
	global_store_dwordx4 v[50:51], v[12:15], off sc1
	v_or_b32_e32 v7, v4, v21
	s_add_i32 s5, s0, 0x80
	v_cvt_pk_bf16_f32 v12, v19, v17
	v_cvt_pk_bf16_f32 v13, v39, v41
	v_cvt_pk_bf16_f32 v14, v43, v45
	v_cvt_pk_bf16_f32 v15, v47, v49
	v_mad_u64_u32 v[16:17], s[6:7], v7, v36, 0
	ds_read2_b32 v[18:19], v20 offset0:16 offset1:24
	ds_read2_b32 v[38:39], v20 offset0:49 offset1:57
	ds_read2_b32 v[40:41], v20 offset0:82 offset1:90
	ds_read2_b32 v[42:43], v20 offset0:115 offset1:123
	ds_read2_b32 v[44:45], v20 offset0:148 offset1:156
	ds_read2_b32 v[46:47], v20 offset0:181 offset1:189
	ds_read2_b32 v[48:49], v20 offset0:214 offset1:222
	ds_read2_b32 v[50:51], v20 offset0:247 offset1:255
	v_add_u32_e32 v17, v17, v9
	v_lshl_add_u64 v[16:17], v[16:17], 1, v[2:3]
	v_or_b32_e32 v7, v4, v22
	global_store_dwordx4 v[16:17], v[12:15], off sc1
	v_mad_u64_u32 v[16:17], s[6:7], v7, v36, 0
	v_add_u32_e32 v17, v17, v9
	s_waitcnt lgkmcnt(6)
	v_cvt_pk_bf16_f32 v12, v18, v38
	s_waitcnt lgkmcnt(4)
	v_cvt_pk_bf16_f32 v13, v40, v42
	s_waitcnt lgkmcnt(2)
	v_cvt_pk_bf16_f32 v14, v44, v46
	s_waitcnt lgkmcnt(0)
	v_cvt_pk_bf16_f32 v15, v48, v50
	v_lshl_add_u64 v[16:17], v[16:17], 1, v[2:3]
	v_or_b32_e32 v4, v4, v23
	global_store_dwordx4 v[16:17], v[12:15], off sc1
	v_mad_u64_u32 v[16:17], s[6:7], v4, v36, 0
	v_add_u32_e32 v17, v17, v9
	v_cvt_pk_bf16_f32 v12, v19, v39
	v_cvt_pk_bf16_f32 v13, v41, v43
	v_cvt_pk_bf16_f32 v14, v45, v47
	v_cvt_pk_bf16_f32 v15, v49, v51
	v_lshl_add_u64 v[2:3], v[16:17], 1, v[2:3]
	global_store_dwordx4 v[2:3], v[12:15], off sc1
	s_waitcnt lgkmcnt(0)
	s_cmpk_gt_i32 s0, 0x53f
	s_mov_b32 s0, s5
	s_cbranch_scc0 .LBB0_1019

.LBB0_1035:
	s_waitcnt vmcnt(0)
	s_waitcnt vmcnt(0) lgkmcnt(0)
	s_barrier
	s_mov_b64 s[6:7], exec
	v_readlane_b32 s0, v219, 25
	v_readlane_b32 s1, v219, 26
	s_and_b64 s[0:1], s[6:7], s[0:1]
	s_mov_b64 exec, s[0:1]
	s_cbranch_execz .LBB0_1087
	v_readlane_b32 s0, v219, 27
	v_readlane_b32 s1, v219, 28
	v_readlane_b32 s2, v219, 29
	v_mov_b32_e32 v0, 0x24000
	s_waitcnt vmcnt(0) lgkmcnt(0)
	buffer_inv sc1
	ds_read_b32 v2, v0
	ds_read_b32 v0, v0 offset:4
	s_lshl_b32 s3, s2, 8
	s_add_i32 s14, s3, 0x2400
	s_add_i32 s3, s3, 0x1400
	v_mov_b32_e32 v1, s3
	s_waitcnt lgkmcnt(0)
	v_readfirstlane_b32 s10, v2
	v_readfirstlane_b32 s11, v0
	v_mov_b32_e32 v0, 1
	s_nop 1
	global_atomic_add v2, v1, v0, s[0:1] sc0
	s_mul_i32 s10, s10, 10
	s_mul_i32 s11, s11, 10
	s_waitcnt vmcnt(0)
	v_readfirstlane_b32 s13, v2
	s_nop 1
	s_add_i32 s13, s13, 1
	s_cmp_lg_u32 s13, s10
	s_cbranch_scc1 .Lnb10_wait
	v_mov_b32_e32 v1, 0x3400
	global_atomic_add v2, v1, v0, s[0:1] sc0
	s_waitcnt vmcnt(0)
	v_readfirstlane_b32 s13, v2
	s_nop 1
	s_add_i32 s13, s13, 1
	s_cmp_lg_u32 s13, s11
	s_cbranch_scc1 .Lnb10_wait
	v_mov_b32_e32 v1, 0x2400
	global_atomic_add v1, v0, s[0:1]
	global_atomic_add v1, v0, s[0:1] offset:256
	global_atomic_add v1, v0, s[0:1] offset:512
	global_atomic_add v1, v0, s[0:1] offset:768
	global_atomic_add v1, v0, s[0:1] offset:1024
	global_atomic_add v1, v0, s[0:1] offset:1280
	global_atomic_add v1, v0, s[0:1] offset:1536
	global_atomic_add v1, v0, s[0:1] offset:1792
	global_atomic_add v1, v0, s[0:1] offset:2048
	global_atomic_add v1, v0, s[0:1] offset:2304
	global_atomic_add v1, v0, s[0:1] offset:2560
	global_atomic_add v1, v0, s[0:1] offset:2816
	global_atomic_add v1, v0, s[0:1] offset:3072
	global_atomic_add v1, v0, s[0:1] offset:3328
	global_atomic_add v1, v0, s[0:1] offset:3584
	global_atomic_add v1, v0, s[0:1] offset:3840
	v_mov_b32_e32 v1, 0x3500
	global_atomic_add v1, v0, s[0:1]

.Lnb10_spin:
	global_load_dword v2, v1, s[0:1] sc1
	s_waitcnt vmcnt(0)
	v_readfirstlane_b32 s13, v2
	s_nop 1
	s_cmp_ge_u32 s13, 10
	s_cbranch_scc1 .Lnb10_done
	s_sleep 1
	s_add_i32 s15, s15, 1
	s_cmp_lt_u32 s15, 0x200000
	s_cbranch_scc1 .Lnb10_spin
.Lnb10_done:
	s_waitcnt vmcnt(0)
.LBB0_1087:
	s_or_b64 exec, exec, s[6:7]
	v_readlane_b32 s0, v219, 43
	v_readlane_b32 s1, v219, 44
	s_andn2_b64 vcc, exec, s[0:1]
	s_waitcnt lgkmcnt(0)
	s_barrier
	s_cbranch_vccnz .LBB0_1120
	v_lshrrev_b32_e32 v7, 3, v168
	v_lshlrev_b32_e32 v1, 4, v168
	v_lshlrev_b32_e32 v0, 7, v7
	v_xor_b32_e32 v1, v1, v168
	s_movk_i32 s0, 0x70
	v_readlane_b32 s6, v219, 33
	v_and_or_b32 v134, v1, s0, v0
	v_lshlrev_b32_e32 v0, 3, v182
	v_cmp_eq_u32_e32 vcc, 0, v147
	v_lshlrev_b32_e32 v4, 4, v147
	v_mov_b32_e32 v5, 0
	v_readlane_b32 s7, v219, 34
	v_lshl_or_b32 v6, v7, 8, v0
	v_cndmask_b32_e64 v0, 0, 1.0, vcc
	v_lshrrev_b32_e32 v1, 2, v168
	s_movk_i32 s5, 0xe0
	v_lshl_add_u64 v[124:125], s[6:7], 0, v[4:5]
	v_mov_b32_e32 v4, 0x3f80
	v_cmp_eq_u32_e32 vcc, 0, v167
	v_lshlrev_b32_e32 v8, 4, v182
	v_and_or_b32 v135, v1, s5, v167
	v_cndmask_b32_e32 v4, 0, v4, vcc
	s_movk_i32 s5, 0xa0
	s_mov_b32 s6, 0x5040100
	v_mad_u32_u24 v136, v7, s5, v8
	v_perm_b32 v8, v4, v4, s6
	v_add_u32_e32 v4, 12, v146
	v_cmp_eq_u32_e32 vcc, 0, v171
	s_add_u32 s1, s56, 0x3300000
	s_addc_u32 s2, s57, 0
	v_cndmask_b32_e32 v4, v4, v146, vcc
	v_xor_b32_e32 v7, v147, v170
	v_lshlrev_b32_e32 v4, 1, v4
	s_add_u32 s3, s56, 0x3380000
	v_lshlrev_b32_e32 v137, 4, v7
	v_bitop3_b32 v7, v147, v170, 4 bitop3:0x36
	v_lshl_add_u64 v[126:127], s[34:35], 0, v[4:5]
	v_or_b32_e32 v4, v146, v184
	s_addc_u32 s4, s57, 0
	s_mov_b32 s19, 0
	v_mov_b32_e32 v1, v5
	v_mov_b32_e32 v2, v5
	v_mov_b32_e32 v3, v5
	v_lshlrev_b32_e32 v138, 4, v7
	v_mov_b32_e32 v9, v8
	v_mov_b32_e32 v10, v8
	v_mov_b32_e32 v11, v8
	v_and_b32_e32 v139, 24, v144
	v_mul_u32_u24_e32 v140, 0xa0, v4
	s_movk_i32 s10, 0x80
	v_lshlrev_b32_e32 v141, 1, v6
	v_add_u32_e32 v142, 0, v134
	v_add_u32_e32 v143, 0, v136
	s_mov_b32 s11, 0xf149f2ca
	s_movk_i32 s16, 0xff80
	s_movk_i32 s17, 0xff81
	s_movk_i32 s28, 0xff82
	s_movk_i32 s29, 0xff83
	s_movk_i32 s33, 0xff91
	s_movk_i32 s48, 0xff92
	s_movk_i32 s49, 0xff93
	s_movk_i32 s50, 0xff9f
	s_movk_i32 s51, 0xffa1
	s_movk_i32 s52, 0xffa2
	s_movk_i32 s53, 0xffa3
	s_movk_i32 s60, 0x82
	s_movk_i32 s61, 0x83
	s_movk_i32 s62, 0x84
	s_movk_i32 s63, 0x90
	s_movk_i32 s64, 0x92
	s_movk_i32 s65, 0x93
	s_movk_i32 s66, 0x94
	s_movk_i32 s67, 0xa2
	s_movk_i32 s68, 0xa3
	s_movk_i32 s69, 0xa4
	s_mov_b32 s70, 0xff61b1e6
	s_mov_b32 s71, 0x41000000
	v_mov_b32_e32 v148, 0xf149f2ca
	s_mov_b32 s72, s78
	s_branch .LBB0_1091

.LBB0_1090:
	v_mov_b32_e32 v4, v72
	s_nop 1
	v_permlane16_swap_b32_e32 v72, v4
	s_waitcnt vmcnt(1)
	v_mov_b32_e32 v20, v68
	v_add_f32_e32 v4, v72, v4
	s_nop 0
	v_permlane16_swap_b32_e32 v68, v20
	v_mov_b32_e32 v6, v4
	v_add_f32_e32 v20, v68, v20
	s_nop 0
	v_permlane32_swap_b32_e32 v4, v6
	v_mov_b32_e32 v21, v20
	v_add_f32_e32 v4, v4, v6
	s_nop 0
	v_permlane32_swap_b32_e32 v20, v21
	v_rcp_f32_e32 v4, v4
	v_add_f32_e32 v20, v20, v21
	v_rcp_f32_e32 v20, v20
	s_add_i32 s72, s72, s58
	v_pk_mul_f32 v[6:7], v[66:67], v[4:5] op_sel_hi:[1,0]
	v_pk_mul_f32 v[12:13], v[64:65], v[4:5] op_sel_hi:[1,0]
	v_pk_mul_f32 v[16:17], v[62:63], v[4:5] op_sel_hi:[1,0]
	v_pk_mul_f32 v[14:15], v[60:61], v[4:5] op_sel_hi:[1,0]
	s_waitcnt vmcnt(0)
	v_pk_mul_f32 v[24:25], v[42:43], v[4:5] op_sel_hi:[1,0]
	v_pk_mul_f32 v[26:27], v[40:41], v[4:5] op_sel_hi:[1,0]
	v_pk_mul_f32 v[32:33], v[54:55], v[20:21] op_sel_hi:[1,0]
	v_pk_mul_f32 v[34:35], v[52:53], v[20:21] op_sel_hi:[1,0]
	v_pk_mul_f32 v[36:37], v[50:51], v[20:21] op_sel_hi:[1,0]
	v_pk_mul_f32 v[38:39], v[48:49], v[20:21] op_sel_hi:[1,0]
	v_pk_mul_f32 v[40:41], v[46:47], v[20:21] op_sel_hi:[1,0]
	v_pk_mul_f32 v[42:43], v[44:45], v[20:21] op_sel_hi:[1,0]
	v_pk_mul_f32 v[30:31], v[30:31], v[20:21] op_sel_hi:[1,0]
	v_pk_mul_f32 v[20:21], v[28:29], v[20:21] op_sel_hi:[1,0]
	v_lshl_add_u64 v[28:29], v[128:129], 1, v[126:127]
	v_cvt_pk_bf16_f32 v12, v12, v13
	v_cvt_pk_bf16_f32 v13, v6, v7
	v_cvt_pk_bf16_f32 v14, v14, v15
	v_cvt_pk_bf16_f32 v15, v16, v17
	v_pk_mul_f32 v[18:19], v[58:59], v[4:5] op_sel_hi:[1,0]
	v_pk_mul_f32 v[22:23], v[56:57], v[4:5] op_sel_hi:[1,0]
	v_lshl_add_u64 v[44:45], v[28:29], 0, v[130:131]
	v_permlane16_swap_b32_e32 v12, v14
	v_permlane16_swap_b32_e32 v13, v15
	global_store_dwordx4 v[44:45], v[12:15], off sc1
	v_lshl_add_u64 v[6:7], v[28:29], 0, v[132:133]
	s_cmpk_gt_i32 s72, 0x1ff
	v_cvt_pk_bf16_f32 v12, v22, v23
	v_cvt_pk_bf16_f32 v13, v18, v19
	v_cvt_pk_bf16_f32 v14, v26, v27
	v_cvt_pk_bf16_f32 v15, v24, v25
	s_nop 0
	v_permlane16_swap_b32_e32 v12, v14
	v_permlane16_swap_b32_e32 v13, v15
	global_store_dwordx4 v[44:45], v[12:15], off offset:64 sc1
	s_nop 1
	v_cvt_pk_bf16_f32 v12, v34, v35
	v_cvt_pk_bf16_f32 v13, v32, v33
	v_cvt_pk_bf16_f32 v14, v38, v39
	v_cvt_pk_bf16_f32 v15, v36, v37
	s_nop 0
	v_permlane16_swap_b32_e32 v12, v14
	v_permlane16_swap_b32_e32 v13, v15
	global_store_dwordx4 v[6:7], v[12:15], off sc1
	s_nop 1
	v_cvt_pk_bf16_f32 v12, v42, v43
	v_cvt_pk_bf16_f32 v13, v40, v41
	v_cvt_pk_bf16_f32 v14, v20, v21
	v_cvt_pk_bf16_f32 v15, v30, v31
	s_nop 0
	v_permlane16_swap_b32_e32 v12, v14
	v_permlane16_swap_b32_e32 v13, v15
	global_store_dwordx4 v[6:7], v[12:15], off offset:64 sc1
	s_cbranch_scc1 .LBB0_1120

.LBB0_1120:
	s_waitcnt vmcnt(0)
	s_barrier
	s_mov_b64 s[6:7], exec
	v_readlane_b32 s0, v219, 25
	v_readlane_b32 s1, v219, 26
	s_and_b64 s[0:1], s[6:7], s[0:1]
	s_mov_b64 exec, s[0:1]
	s_cbranch_execz .LBB0_1172
	v_readlane_b32 s0, v219, 27
	v_readlane_b32 s1, v219, 28
	v_readlane_b32 s2, v219, 29
	v_mov_b32_e32 v0, 0x24000
	s_waitcnt vmcnt(0) lgkmcnt(0)
	buffer_inv sc1
	ds_read_b32 v2, v0
	ds_read_b32 v0, v0 offset:4
	s_lshl_b32 s3, s2, 8
	s_add_i32 s14, s3, 0x2400
	s_add_i32 s3, s3, 0x1400
	v_mov_b32_e32 v1, s3
	s_waitcnt lgkmcnt(0)
	v_readfirstlane_b32 s10, v2
	v_readfirstlane_b32 s11, v0
	v_mov_b32_e32 v0, 1
	s_nop 1
	global_atomic_add v2, v1, v0, s[0:1] sc0
	s_mul_i32 s10, s10, 11
	s_mul_i32 s11, s11, 11
	s_waitcnt vmcnt(0)
	v_readfirstlane_b32 s13, v2
	s_nop 1
	s_add_i32 s13, s13, 1
	s_cmp_lg_u32 s13, s10
	s_cbranch_scc1 .Lnb11_wait
	v_mov_b32_e32 v1, 0x3400
	global_atomic_add v2, v1, v0, s[0:1] sc0
	s_waitcnt vmcnt(0)
	v_readfirstlane_b32 s13, v2
	s_nop 1
	s_add_i32 s13, s13, 1
	s_cmp_lg_u32 s13, s11
	s_cbranch_scc1 .Lnb11_wait
	v_mov_b32_e32 v1, 0x2400
	global_atomic_add v1, v0, s[0:1]
	global_atomic_add v1, v0, s[0:1] offset:256
	global_atomic_add v1, v0, s[0:1] offset:512
	global_atomic_add v1, v0, s[0:1] offset:768
	global_atomic_add v1, v0, s[0:1] offset:1024
	global_atomic_add v1, v0, s[0:1] offset:1280
	global_atomic_add v1, v0, s[0:1] offset:1536
	global_atomic_add v1, v0, s[0:1] offset:1792
	global_atomic_add v1, v0, s[0:1] offset:2048
	global_atomic_add v1, v0, s[0:1] offset:2304
	global_atomic_add v1, v0, s[0:1] offset:2560
	global_atomic_add v1, v0, s[0:1] offset:2816
	global_atomic_add v1, v0, s[0:1] offset:3072
	global_atomic_add v1, v0, s[0:1] offset:3328
	global_atomic_add v1, v0, s[0:1] offset:3584
	global_atomic_add v1, v0, s[0:1] offset:3840
	v_mov_b32_e32 v1, 0x3500
	global_atomic_add v1, v0, s[0:1]

.Lnb11_spin:
	global_load_dword v2, v1, s[0:1] sc1
	s_waitcnt vmcnt(0)
	v_readfirstlane_b32 s13, v2
	s_nop 1
	s_cmp_ge_u32 s13, 11
	s_cbranch_scc1 .Lnb11_done
	s_sleep 1
	s_add_i32 s15, s15, 1
	s_cmp_lt_u32 s15, 0x200000
	s_cbranch_scc1 .Lnb11_spin
.Lnb11_done:
	s_waitcnt vmcnt(0)
.LBB0_1172:
	s_or_b64 exec, exec, s[6:7]
	v_readlane_b32 s0, v219, 50
	v_readlane_b32 s1, v219, 51
	s_and_b64 vcc, exec, s[0:1]
	v_readfirstlane_b32 s6, v168
	s_waitcnt lgkmcnt(0)
	s_barrier
	s_cbranch_vccnz .LBB0_1236
	s_add_u32 s0, s56, 0x1c80000
	s_addc_u32 s1, s57, 0
	s_lshl_b32 s2, s78, 19
	s_lshr_b32 s7, s6, 6
	s_bfe_u32 s38, s6, 0x10006
	s_lshr_b32 s33, s6, 7
	s_and_b32 s2, s2, 0xf80000
	s_add_u32 s5, s34, s2
	s_addc_u32 s28, s35, 0
	s_lshl_b32 s2, s78, 2
	s_mov_b32 s73, 0
	s_and_b32 s10, s2, 0xffffff80
	s_lshl_b32 s72, s7, 5
	s_lshl_b32 s3, s7, 12
	s_ashr_i32 s11, s10, 31
	s_add_i32 s4, s3, 0
	s_lshl_b64 s[12:13], s[72:73], 10
	s_lshl_b64 s[8:9], s[72:73], 11
	s_add_u32 s14, s5, s8
	s_addc_u32 s15, s28, s9
	s_or_b32 s24, s72, 8
	s_mov_b32 s25, s73
	s_lshl_b64 s[8:9], s[24:25], 10
	s_lshl_b64 s[16:17], s[24:25], 11
	s_add_u32 s16, s5, s16
	v_mov_b32_e32 v0, v162
	v_mov_b32_e32 v1, v163
	s_mov_b32 m0, s4
	s_addc_u32 s17, s28, s17
	s_or_b32 s26, s72, 16
	s_mov_b32 s27, s73
	s_barrier
	s_lshl_b64 s[22:23], s[26:27], 10
	global_load_lds_dwordx4 v0, s[14:15]
	s_add_i32 m0, s4, 0x400
	s_lshl_b64 s[18:19], s[26:27], 11
	s_add_u32 s18, s5, s18
	s_addc_u32 s19, s28, s19
	s_or_b32 s72, s72, 24
	global_load_lds_dwordx4 v1, s[16:17]
	s_add_i32 m0, s4, 0x800
	s_lshl_b64 s[60:61], s[72:73], 10
	s_lshl_b64 s[20:21], s[72:73], 11
	s_add_u32 s20, s5, s20
	global_load_lds_dwordx4 v0, s[18:19]
	s_addc_u32 s21, s28, s21
	s_add_i32 m0, s4, 0xc00
	s_lshl_b64 s[10:11], s[10:11], 11
	s_add_u32 s25, s0, s10
	s_addc_u32 s27, s1, s11
	s_lshl_b32 s5, s7, 11
	s_lshl_b32 s10, s7, 4
	s_sub_i32 s39, s4, s5
	s_mov_b32 s11, s73
	global_load_lds_dwordx4 v1, s[20:21]
	s_add_i32 m0, s39, 0x8000
	s_lshl_b64 s[62:63], s[10:11], 10
	s_lshl_b64 s[28:29], s[10:11], 11
	s_add_u32 s28, s25, s28
	s_addc_u32 s29, s27, s29
	s_or_b32 s10, s10, 8
	s_lshl_b64 s[64:65], s[10:11], 10
	s_lshl_b64 s[36:37], s[10:11], 11
	s_add_u32 s36, s25, s36
	global_load_lds_dwordx4 v0, s[28:29]
	s_addc_u32 s37, s27, s37
	s_add_i32 m0, s39, 0x8400
	v_mov_b32_e32 v148, v162
	v_mov_b32_e32 v0, v163
	v_mov_b32_e32 v149, 0
	global_load_lds_dwordx4 v1, s[36:37]
	s_add_i32 m0, s4, 0xc000
	v_lshl_add_u64 v[2:3], s[14:15], 0, v[148:149]
	s_mov_b64 s[14:15], 0x80
	v_lshl_add_u64 v[2:3], v[2:3], 0, s[14:15]
	v_mov_b32_e32 v1, v149
	global_load_lds_dwordx4 v[2:3], off
	v_lshl_add_u64 v[2:3], s[16:17], 0, v[0:1]
	v_lshl_add_u64 v[2:3], v[2:3], 0, s[14:15]
	s_add_i32 m0, s4, 0xc400
	s_add_i32 s11, s5, 0
	global_load_lds_dwordx4 v[2:3], off
	v_lshl_add_u64 v[2:3], s[18:19], 0, v[148:149]
	v_lshl_add_u64 v[2:3], v[2:3], 0, s[14:15]
	s_add_i32 m0, s4, 0xc800
	s_mov_b32 s87, s78
	global_load_lds_dwordx4 v[2:3], off
	v_lshl_add_u64 v[2:3], s[20:21], 0, v[0:1]
	v_lshl_add_u64 v[2:3], v[2:3], 0, s[14:15]
	s_add_i32 m0, s4, 0xcc00
	v_lshl_add_u64 v[0:1], s[36:37], 0, v[0:1]
	global_load_lds_dwordx4 v[2:3], off
	v_lshl_add_u64 v[2:3], s[28:29], 0, v[148:149]
	s_add_i32 m0, s11, 0x14000
	v_lshl_add_u64 v[2:3], v[2:3], 0, s[14:15]
	global_load_lds_dwordx4 v[2:3], off
	v_lshl_add_u64 v[0:1], v[0:1], 0, s[14:15]
	s_add_i32 m0, s11, 0x14400
	s_cmpk_gt_u32 s6, 0xff
	global_load_lds_dwordx4 v[0:1], off
	s_cselect_b64 s[18:19], -1, 0
	s_lshl_b32 s11, s72, 10
	v_writelane_b32 v219, s11, 35
	s_lshl_b32 s10, s10, 10
	s_lshl_b32 s72, s7, 14
	v_writelane_b32 v219, s10, 36
	s_lshl_b32 s10, s7, 15
	s_lshl_b32 s7, s24, 10
	v_writelane_b32 v219, s7, 0
	s_lshl_b32 s7, s26, 10
	s_lshl_b32 s28, s38, 13
	s_lshl_b32 s29, s33, 13
	v_writelane_b32 v219, s7, 37
	s_lshl_b32 s7, s38, 7
	s_add_u32 s20, s56, s7
	s_addc_u32 s21, s57, 0
	s_lshl_b64 s[6:7], s[6:7], 10
	s_and_b32 s7, s7, 0x3ff
	s_and_b32 s6, s6, 0xffff0000
	s_add_u32 s6, s56, s6
	s_addc_u32 s78, s57, s7
	s_lshl_b32 s79, s87, 8
	s_lshl_b32 s80, s58, 8
	s_mov_b32 s11, s73
	s_add_u32 s81, s56, s12
	v_add_u32_e32 v0, 12, v181
	v_cmp_eq_u32_e32 vcc, 0, v171
	s_addc_u32 s82, s57, s13
	s_lshl_b32 s83, s58, 2
	s_lshl_b64 s[24:25], s[10:11], 1
	v_cndmask_b32_e32 v0, v0, v181, vcc
	v_xor_b32_e32 v1, v180, v170
	s_add_u32 s84, s56, s24
	v_lshlrev_b32_e32 v153, 4, v1
	v_bitop3_b32 v1, v180, v170, 4 bitop3:0x36
	v_lshlrev_b32_e32 v148, 1, v0
	s_addc_u32 s85, s57, s25
	s_lshl_b64 s[26:27], s[72:73], 1
	v_lshlrev_b32_e32 v154, 4, v1
	v_lshl_add_u64 v[0:1], s[20:21], 0, v[148:149]
	s_mov_b64 s[20:21], 0x8400000
	s_add_u32 s72, s56, s26
	v_lshl_or_b32 v152, s33, 6, v167
	v_lshl_add_u64 v[150:151], v[0:1], 0, s[20:21]
	v_writelane_b32 v219, s6, 39
	s_addc_u32 s86, s57, s27
	s_mov_b64 s[6:7], -1
	s_mov_b64 s[36:37], 0x100
	s_mov_b64 s[38:39], 0x7400180
	s_mov_b64 s[40:41], 0x7404180
	s_mov_b64 s[42:43], 0x7408180
	s_mov_b64 s[44:45], 0x740c180
	s_mov_b64 s[46:47], 0x1c80180
	s_mov_b64 s[48:49], 0x1c84180
	s_lshl_b64 s[50:51], s[8:9], 1
	s_lshl_b64 s[52:53], s[22:23], 1
	s_lshl_b64 s[60:61], s[60:61], 1
	s_lshl_b64 s[62:63], s[62:63], 1
	s_lshl_b64 s[64:65], s[64:65], 1
	s_branch .LBB0_1175
.LBB0_1174:
	v_add_u32_e32 v148, s88, v152
	v_lshl_add_u64 v[64:65], s[68:69], 1, v[150:151]
	v_lshlrev_b64 v[66:67], 11, v[148:149]
	v_cvt_pk_bf16_f32 v48, v48, v49
	v_cvt_pk_bf16_f32 v49, v50, v51
	v_cvt_pk_bf16_f32 v50, v52, v53
	v_cvt_pk_bf16_f32 v51, v54, v55
	v_lshl_add_u64 v[66:67], v[64:65], 0, v[66:67]
	v_permlane16_swap_b32_e32 v48, v50
	v_permlane16_swap_b32_e32 v49, v51
	global_store_dwordx4 v[66:67], v[48:51], off offset:64 sc1
	v_cvt_pk_bf16_f32 v20, v20, v21
	v_cvt_pk_bf16_f32 v21, v22, v23
	v_or_b32_e32 v48, 16, v148
	v_mov_b32_e32 v49, v149
	v_lshlrev_b64 v[48:49], 11, v[48:49]
	v_cvt_pk_bf16_f32 v22, v28, v29
	v_cvt_pk_bf16_f32 v23, v30, v31
	v_lshl_add_u64 v[48:49], v[64:65], 0, v[48:49]
	v_permlane16_swap_b32_e32 v20, v22
	v_permlane16_swap_b32_e32 v21, v23
	global_store_dwordx4 v[48:49], v[20:23], off offset:64 sc1
	v_cvt_pk_bf16_f32 v16, v16, v17
	v_cvt_pk_bf16_f32 v17, v18, v19
	v_or_b32_e32 v20, 32, v148
	v_mov_b32_e32 v21, v149
	v_lshlrev_b64 v[20:21], 11, v[20:21]
	v_cvt_pk_bf16_f32 v18, v24, v25
	v_cvt_pk_bf16_f32 v19, v26, v27
	v_lshl_add_u64 v[28:29], v[64:65], 0, v[20:21]
	v_permlane16_swap_b32_e32 v16, v18
	v_permlane16_swap_b32_e32 v17, v19
	v_or_b32_e32 v148, 48, v148
	v_cvt_pk_bf16_f32 v56, v56, v57
	v_cvt_pk_bf16_f32 v57, v58, v59
	v_cvt_pk_bf16_f32 v58, v60, v61
	v_cvt_pk_bf16_f32 v59, v62, v63
	v_cvt_pk_bf16_f32 v36, v36, v37
	v_cvt_pk_bf16_f32 v37, v38, v39
	v_cvt_pk_bf16_f32 v38, v44, v45
	v_cvt_pk_bf16_f32 v39, v46, v47
	v_cvt_pk_bf16_f32 v20, v32, v33
	v_cvt_pk_bf16_f32 v21, v34, v35
	v_cvt_pk_bf16_f32 v22, v40, v41
	v_cvt_pk_bf16_f32 v23, v42, v43
	global_store_dwordx4 v[28:29], v[16:19], off offset:64 sc1
	v_cvt_pk_bf16_f32 v4, v4, v5
	v_cvt_pk_bf16_f32 v5, v6, v7
	v_lshlrev_b64 v[16:17], 11, v[148:149]
	v_cvt_pk_bf16_f32 v6, v8, v9
	v_cvt_pk_bf16_f32 v7, v10, v11
	v_cvt_pk_bf16_f32 v0, v0, v1
	v_cvt_pk_bf16_f32 v1, v2, v3
	v_cvt_pk_bf16_f32 v2, v12, v13
	v_cvt_pk_bf16_f32 v3, v14, v15
	v_permlane16_swap_b32_e32 v56, v58
	v_permlane16_swap_b32_e32 v57, v59
	v_permlane16_swap_b32_e32 v36, v38
	v_permlane16_swap_b32_e32 v37, v39
	v_permlane16_swap_b32_e32 v20, v22
	v_permlane16_swap_b32_e32 v21, v23
	v_lshl_add_u64 v[16:17], v[64:65], 0, v[16:17]
	v_permlane16_swap_b32_e32 v4, v6
	v_permlane16_swap_b32_e32 v5, v7
	v_permlane16_swap_b32_e32 v0, v2
	v_permlane16_swap_b32_e32 v1, v3
	s_add_i32 s79, s79, s80
	s_add_i32 s2, s2, s83
	s_andn2_b64 vcc, exec, s[66:67]
	s_mov_b64 s[6:7], 0
	global_store_dwordx4 v[66:67], v[56:59], off sc1
	global_store_dwordx4 v[48:49], v[36:39], off sc1
	global_store_dwordx4 v[28:29], v[20:23], off sc1
	global_store_dwordx4 v[16:17], v[4:7], off sc1
	global_store_dwordx4 v[16:17], v[0:3], off offset:64 sc1
	s_cbranch_vccz .LBB0_1235

.LBB0_1236:
	s_waitcnt vmcnt(0)
	s_waitcnt vmcnt(0) lgkmcnt(0)
	s_barrier
	s_mov_b64 s[6:7], exec
	v_readlane_b32 s0, v219, 25
	v_readlane_b32 s1, v219, 26
	s_and_b64 s[0:1], s[6:7], s[0:1]
	s_mov_b64 exec, s[0:1]
	s_cbranch_execz .LBB0_1288
	v_readlane_b32 s0, v219, 27
	v_readlane_b32 s1, v219, 28
	v_readlane_b32 s2, v219, 29
	v_mov_b32_e32 v0, 0x24000
	s_waitcnt vmcnt(0) lgkmcnt(0)
	buffer_inv sc1
	ds_read_b32 v2, v0
	ds_read_b32 v0, v0 offset:4
	s_lshl_b32 s3, s2, 8
	s_add_i32 s14, s3, 0x2400
	s_add_i32 s3, s3, 0x1400
	v_mov_b32_e32 v1, s3
	s_waitcnt lgkmcnt(0)
	v_readfirstlane_b32 s10, v2
	v_readfirstlane_b32 s11, v0
	v_mov_b32_e32 v0, 1
	s_nop 1
	global_atomic_add v2, v1, v0, s[0:1] sc0
	s_mul_i32 s10, s10, 12
	s_mul_i32 s11, s11, 12
	s_waitcnt vmcnt(0)
	v_readfirstlane_b32 s13, v2
	s_nop 1
	s_add_i32 s13, s13, 1
	s_cmp_lg_u32 s13, s10
	s_cbranch_scc1 .Lnb12_wait
	v_mov_b32_e32 v1, 0x3400
	global_atomic_add v2, v1, v0, s[0:1] sc0
	s_waitcnt vmcnt(0)
	v_readfirstlane_b32 s13, v2
	s_nop 1
	s_add_i32 s13, s13, 1
	s_cmp_lg_u32 s13, s11
	s_cbranch_scc1 .Lnb12_wait
	v_mov_b32_e32 v1, 0x2400
	global_atomic_add v1, v0, s[0:1]
	global_atomic_add v1, v0, s[0:1] offset:256
	global_atomic_add v1, v0, s[0:1] offset:512
	global_atomic_add v1, v0, s[0:1] offset:768
	global_atomic_add v1, v0, s[0:1] offset:1024
	global_atomic_add v1, v0, s[0:1] offset:1280
	global_atomic_add v1, v0, s[0:1] offset:1536
	global_atomic_add v1, v0, s[0:1] offset:1792
	global_atomic_add v1, v0, s[0:1] offset:2048
	global_atomic_add v1, v0, s[0:1] offset:2304
	global_atomic_add v1, v0, s[0:1] offset:2560
	global_atomic_add v1, v0, s[0:1] offset:2816
	global_atomic_add v1, v0, s[0:1] offset:3072
	global_atomic_add v1, v0, s[0:1] offset:3328
	global_atomic_add v1, v0, s[0:1] offset:3584
	global_atomic_add v1, v0, s[0:1] offset:3840
	v_mov_b32_e32 v1, 0x3500
	global_atomic_add v1, v0, s[0:1]

.Lnb12_spin:
	global_load_dword v2, v1, s[0:1] sc1
	s_waitcnt vmcnt(0)
	v_readfirstlane_b32 s13, v2
	s_nop 1
	s_cmp_ge_u32 s13, 12
	s_cbranch_scc1 .Lnb12_done
	s_sleep 1
	s_add_i32 s15, s15, 1
	s_cmp_lt_u32 s15, 0x200000
	s_cbranch_scc1 .Lnb12_spin
.Lnb12_done:
	s_waitcnt vmcnt(0)
.LBB0_1288:
	s_or_b64 exec, exec, s[6:7]
	s_waitcnt lgkmcnt(0)
	s_barrier
	s_mov_b64 s[6:7], exec
	v_readlane_b32 s0, v219, 31
	v_readlane_b32 s1, v219, 32
	s_and_b64 s[0:1], s[6:7], s[0:1]
	s_mov_b64 exec, s[0:1]
	s_cbranch_execz .LBB0_1293
	v_and_b32_e32 v0, 0x1f8, v144
	v_mov_b32_e32 v65, 0
	v_lshlrev_b32_e32 v64, 1, v0
	v_lshl_add_u64 v[2:3], s[56:57], 0, v[64:65]
	s_mov_b64 s[0:1], 0x8400000
	v_readlane_b32 s8, v219, 9
	v_lshl_add_u64 v[66:67], v[2:3], 0, s[0:1]
	s_mov_b64 s[0:1], 0xa400000
	v_readlane_b32 s12, v219, 13
	v_readlane_b32 s13, v219, 14
	v_lshl_add_u64 v[68:69], v[2:3], 0, s[0:1]
	s_lshl_b32 s0, s58, 3
	s_mov_b64 s[4:5], s[12:13]
	s_add_u32 s2, s4, 0x5000
	s_addc_u32 s3, s5, 0
	s_add_u32 s4, s4, 0x6000
	v_lshl_add_u64 v[70:71], s[30:31], 0, v[64:65]
	v_or_b32_e32 v2, 0x200, v0
	s_addc_u32 s5, s5, 0
	v_lshlrev_b32_e32 v64, 2, v0
	v_readlane_b32 s9, v219, 10
	v_readlane_b32 s14, v219, 15
	v_readlane_b32 s15, v219, 16
	v_readlane_b32 s18, v219, 19
	v_readlane_b32 s19, v219, 20
	v_lshl_add_u64 v[72:73], s[2:3], 0, v[64:65]
	v_lshl_add_u64 v[74:75], s[4:5], 0, v[64:65]
	v_lshlrev_b32_e32 v64, 2, v2
	v_lshl_add_u64 v[76:77], s[2:3], 0, v[64:65]
	v_lshl_add_u64 v[78:79], s[4:5], 0, v[64:65]
	v_lshl_add_u32 v102, s78, 5, v166
	s_lshl_b32 s1, s58, 5
	s_mov_b64 s[8:9], 0
	v_mov_b32_e32 v103, 0xfffff000
	s_movk_i32 s2, 0x3ff
	s_mov_b64 s[12:13], 0x2000
	s_mov_b64 s[14:15], 0x3000
	s_mov_b64 s[18:19], 0x4000
	v_lshlrev_b32_e32 v64, 2, v0
	v_lshlrev_b32_e32 v80, 2, v2
	v_mov_b32_e32 v81, v65
	v_mov_b32_e32 v104, 0x358637bd
	s_mov_b32 s3, 0x800000
	s_movk_i32 s4, 0x7ff
	v_mov_b32_e32 v105, v145
	v_readlane_b32 s10, v219, 11
	v_readlane_b32 s11, v219, 12
	v_readlane_b32 s16, v219, 17
	v_readlane_b32 s17, v219, 18
	v_readlane_b32 s20, v219, 21
	v_readlane_b32 s21, v219, 22
	v_readlane_b32 s22, v219, 23
	v_readlane_b32 s23, v219, 24

.LBB0_1291:
	v_add_u32_e32 v98, s5, v102
	v_ashrrev_i32_e32 v99, 31, v98
	v_add_u32_e32 v100, 1, v98
	v_lshlrev_b64 v[98:99], 11, v[98:99]
	v_lshl_add_u64 v[122:123], v[68:69], 0, v[98:99]
	v_lshl_add_u64 v[118:119], v[66:67], 0, v[98:99]
	global_load_dwordx4 v[106:109], v[122:123], off
	global_load_dwordx4 v[110:113], v[122:123], off offset:1024
	global_load_dwordx4 v[114:117], v[118:119], off
	s_nop 0
	global_load_dwordx4 v[118:121], v[118:119], off offset:1024
	v_ashrrev_i32_e32 v101, 31, v100
	v_lshl_add_u64 v[124:125], v[70:71], 0, v[98:99]
	v_lshlrev_b64 v[98:99], 11, v[100:101]
	v_lshl_add_u64 v[100:101], v[68:69], 0, v[98:99]
	v_lshl_add_u64 v[126:127], v[66:67], 0, v[98:99]
	s_add_i32 s5, s5, 2
	s_cmp_eq_u32 s5, 4
	v_lshl_add_u64 v[98:99], v[70:71], 0, v[98:99]
	s_waitcnt vmcnt(3)
	v_lshlrev_b32_e32 v128, 16, v106
	v_and_b32_e32 v129, 0xffff0000, v106
	s_waitcnt vmcnt(1)
	v_and_b32_e32 v139, 0xffff0000, v116
	v_and_b32_e32 v138, 0xffff0000, v114
	v_lshlrev_b32_e32 v137, 16, v116
	v_lshlrev_b32_e32 v136, 16, v114
	v_lshlrev_b32_e32 v140, 16, v115
	v_and_b32_e32 v116, 0xffff0000, v115
	s_waitcnt vmcnt(0)
	v_lshlrev_b32_e32 v115, 16, v118
	v_lshlrev_b32_e32 v114, 16, v120
	v_and_b32_e32 v143, 0xffff0000, v118
	v_and_b32_e32 v142, 0xffff0000, v120
	v_lshlrev_b32_e32 v148, 16, v121
	v_and_b32_e32 v118, 0xffff0000, v121
	v_pk_mul_f32 v[120:121], v[138:139], v[138:139]
	v_lshlrev_b32_e32 v141, 16, v117
	v_pk_mul_f32 v[150:151], v[142:143], v[142:143]
	v_pk_fma_f32 v[120:121], v[136:137], v[136:137], v[120:121]
	v_and_b32_e32 v117, 0xffff0000, v117
	v_lshlrev_b32_e32 v149, 16, v119
	v_mov_b32_e32 v154, v136
	v_mov_b32_e32 v155, v138
	v_mov_b32_e32 v138, v137
	v_pk_fma_f32 v[136:137], v[114:115], v[114:115], v[150:151]
	v_pk_fma_f32 v[120:121], v[140:141], v[140:141], v[120:121]
	v_and_b32_e32 v119, 0xffff0000, v119
	v_pk_fma_f32 v[136:137], v[148:149], v[148:149], v[136:137]
	v_pk_fma_f32 v[120:121], v[116:117], v[116:117], v[120:121]
	v_mov_b32_e32 v156, v149
	v_mov_b32_e32 v157, v119
	v_mov_b32_e32 v149, v118
	v_pk_fma_f32 v[118:119], v[118:119], v[118:119], v[136:137]
	v_add_f32_e32 v120, v120, v121
	v_add_f32_e32 v119, v120, v119
	v_add_f32_e32 v118, v118, v119
	ds_bpermute_b32 v119, v172, v118
	v_mov_b32_e32 v152, v140
	v_mov_b32_e32 v153, v116
	v_mov_b32_e32 v116, v141
	v_mov_b32_e32 v158, v115
	s_waitcnt lgkmcnt(0)
	v_add_f32_e32 v118, v118, v119
	ds_bpermute_b32 v119, v173, v118
	v_mov_b32_e32 v159, v143
	v_mov_b32_e32 v115, v142
	v_lshlrev_b32_e32 v106, 16, v107
	v_and_b32_e32 v107, 0xffff0000, v107
	s_waitcnt lgkmcnt(0)
	v_add_f32_e32 v118, v118, v119
	ds_bpermute_b32 v119, v174, v118
	v_lshlrev_b32_e32 v130, 16, v108
	v_and_b32_e32 v131, 0xffff0000, v108
	v_lshlrev_b32_e32 v108, 16, v109
	v_and_b32_e32 v109, 0xffff0000, v109
	s_waitcnt lgkmcnt(0)
	v_add_f32_e32 v118, v118, v119
	ds_bpermute_b32 v119, v175, v118
	v_lshlrev_b32_e32 v132, 16, v110
	v_and_b32_e32 v133, 0xffff0000, v110
	v_lshlrev_b32_e32 v110, 16, v111
	v_and_b32_e32 v111, 0xffff0000, v111
	s_waitcnt lgkmcnt(0)
	v_add_f32_e32 v118, v118, v119
	ds_bpermute_b32 v119, v176, v118
	v_lshlrev_b32_e32 v134, 16, v112
	v_and_b32_e32 v135, 0xffff0000, v112
	v_lshlrev_b32_e32 v112, 16, v113
	v_and_b32_e32 v113, 0xffff0000, v113
	s_waitcnt lgkmcnt(0)
	v_add_f32_e32 v118, v118, v119
	ds_bpermute_b32 v119, v177, v118
	s_waitcnt lgkmcnt(0)
	v_add_f32_e32 v118, v118, v119
	v_fmamk_f32 v118, v118, 0x3a800000, v104
	v_mul_f32_e32 v119, 0x4b800000, v118
	v_cmp_gt_f32_e32 vcc, s3, v118
	s_nop 1
	v_cndmask_b32_e32 v118, v118, v119, vcc
	v_rsq_f32_e32 v118, v118
	s_nop 0
	v_mul_f32_e32 v119, 0x45800000, v118
	v_cndmask_b32_e32 v118, v118, v119, vcc
	v_pk_mul_f32 v[120:121], v[118:119], v[152:153] op_sel_hi:[0,1]
	v_pk_mul_f32 v[136:137], v[118:119], v[154:155] op_sel_hi:[0,1]
	v_pk_mul_f32 v[116:117], v[118:119], v[116:117] op_sel_hi:[0,1]
	v_pk_mul_f32 v[138:139], v[118:119], v[138:139] op_sel_hi:[0,1]
	v_pk_mul_f32 v[140:141], v[118:119], v[156:157] op_sel_hi:[0,1]
	v_pk_mul_f32 v[142:143], v[118:119], v[158:159] op_sel_hi:[0,1]
	v_pk_mul_f32 v[148:149], v[118:119], v[148:149] op_sel_hi:[0,1]
	v_pk_mul_f32 v[114:115], v[118:119], v[114:115] op_sel_hi:[0,1]
	v_pk_mul_f32 v[118:119], v[4:5], v[136:137]
	v_pk_mul_f32 v[120:121], v[6:7], v[120:121]
	v_pk_mul_f32 v[136:137], v[0:1], v[138:139]
	v_pk_mul_f32 v[116:117], v[2:3], v[116:117]
	v_pk_mul_f32 v[138:139], v[36:37], v[142:143]
	v_pk_mul_f32 v[140:141], v[38:39], v[140:141]
	v_pk_mul_f32 v[114:115], v[32:33], v[114:115]
	v_pk_mul_f32 v[142:143], v[34:35], v[148:149]
	v_pk_fma_f32 v[120:121], v[14:15], v[120:121], v[106:107]
	v_pk_fma_f32 v[118:119], v[12:13], v[118:119], v[128:129]
	v_pk_fma_f32 v[116:117], v[10:11], v[116:117], v[108:109]
	v_pk_fma_f32 v[128:129], v[8:9], v[136:137], v[130:131]
	v_pk_fma_f32 v[130:131], v[46:47], v[140:141], v[110:111]
	v_pk_fma_f32 v[132:133], v[44:45], v[138:139], v[132:133]
	v_pk_fma_f32 v[136:137], v[42:43], v[142:143], v[112:113]
	v_pk_fma_f32 v[114:115], v[40:41], v[114:115], v[134:135]
	v_cvt_pk_bf16_f32 v106, v118, v119
	v_cvt_pk_bf16_f32 v107, v120, v121
	v_cvt_pk_bf16_f32 v108, v128, v129
	v_cvt_pk_bf16_f32 v109, v116, v117
	v_mov_b32_e32 v138, v119
	v_mov_b32_e32 v139, v129
	v_cvt_pk_bf16_f32 v110, v132, v133
	v_cvt_pk_bf16_f32 v111, v130, v131
	v_cvt_pk_bf16_f32 v112, v114, v115
	v_cvt_pk_bf16_f32 v113, v136, v137
	v_mov_b32_e32 v134, v118
	v_mov_b32_e32 v135, v128
	v_mov_b32_e32 v150, v115
	v_mov_b32_e32 v151, v133
	global_store_dwordx4 v[122:123], v[106:109], off sc1
	global_store_dwordx4 v[122:123], v[110:113], off offset:1024 sc1
	v_mov_b32_e32 v140, v120
	v_pk_mul_f32 v[106:107], v[138:139], v[138:139]
	v_mov_b32_e32 v141, v116
	v_mov_b32_e32 v148, v114
	v_mov_b32_e32 v149, v132
	v_pk_mul_f32 v[108:109], v[150:151], v[150:151]
	v_pk_fma_f32 v[106:107], v[134:135], v[134:135], v[106:107]
	v_mov_b32_e32 v142, v121
	v_mov_b32_e32 v143, v117
	v_mov_b32_e32 v152, v136
	v_mov_b32_e32 v153, v130
	v_pk_fma_f32 v[108:109], v[148:149], v[148:149], v[108:109]
	v_pk_fma_f32 v[106:107], v[140:141], v[140:141], v[106:107]
	v_mov_b32_e32 v154, v137
	v_mov_b32_e32 v155, v131
	v_pk_fma_f32 v[108:109], v[152:153], v[152:153], v[108:109]
	v_pk_fma_f32 v[106:107], v[142:143], v[142:143], v[106:107]
	v_pk_fma_f32 v[108:109], v[154:155], v[154:155], v[108:109]
	v_add_f32_e32 v106, v106, v107
	v_add_f32_e32 v106, v109, v106
	v_add_f32_e32 v106, v108, v106
	ds_bpermute_b32 v107, v172, v106
	s_waitcnt lgkmcnt(0)
	v_add_f32_e32 v106, v106, v107
	ds_bpermute_b32 v107, v173, v106
	s_waitcnt lgkmcnt(0)
	v_add_f32_e32 v106, v106, v107
	ds_bpermute_b32 v107, v174, v106
	s_waitcnt lgkmcnt(0)
	v_add_f32_e32 v106, v106, v107
	ds_bpermute_b32 v107, v175, v106
	s_waitcnt lgkmcnt(0)
	v_add_f32_e32 v106, v106, v107
	ds_bpermute_b32 v107, v176, v106
	s_waitcnt lgkmcnt(0)
	v_add_f32_e32 v106, v106, v107
	ds_bpermute_b32 v107, v177, v106
	s_waitcnt lgkmcnt(0)
	v_add_f32_e32 v106, v106, v107
	v_fmamk_f32 v106, v106, 0x3a800000, v104
	v_mul_f32_e32 v107, 0x4b800000, v106
	v_cmp_gt_f32_e32 vcc, s3, v106
	s_nop 1
	v_cndmask_b32_e32 v106, v106, v107, vcc
	v_rsq_f32_e32 v106, v106
	s_nop 0
	v_mul_f32_e32 v107, 0x45800000, v106
	v_cndmask_b32_e32 v106, v106, v107, vcc
	v_pk_mul_f32 v[108:109], v[120:121], v[106:107] op_sel_hi:[1,0]
	v_pk_mul_f32 v[110:111], v[118:119], v[106:107] op_sel_hi:[1,0]
	v_pk_mul_f32 v[112:113], v[116:117], v[106:107] op_sel_hi:[1,0]
	v_pk_mul_f32 v[116:117], v[128:129], v[106:107] op_sel_hi:[1,0]
	v_pk_mul_f32 v[118:119], v[130:131], v[106:107] op_sel_hi:[1,0]
	v_pk_mul_f32 v[120:121], v[132:133], v[106:107] op_sel_hi:[1,0]
	v_pk_mul_f32 v[122:123], v[136:137], v[106:107] op_sel_hi:[1,0]
	v_pk_mul_f32 v[106:107], v[114:115], v[106:107] op_sel_hi:[1,0]
	v_pk_mul_f32 v[110:111], v[20:21], v[110:111]
	v_pk_mul_f32 v[108:109], v[22:23], v[108:109]
	v_pk_mul_f32 v[114:115], v[16:17], v[116:117]
	v_pk_mul_f32 v[112:113], v[18:19], v[112:113]
	v_pk_mul_f32 v[116:117], v[52:53], v[120:121]
	v_pk_mul_f32 v[118:119], v[54:55], v[118:119]
	v_pk_mul_f32 v[106:107], v[48:49], v[106:107]
	v_pk_mul_f32 v[120:121], v[50:51], v[122:123]
	v_pk_fma_f32 v[108:109], v[82:83], v[108:109], v[30:31]
	v_pk_fma_f32 v[110:111], v[84:85], v[110:111], v[28:29]
	v_pk_fma_f32 v[112:113], v[86:87], v[112:113], v[26:27]
	v_pk_fma_f32 v[114:115], v[88:89], v[114:115], v[24:25]
	v_pk_fma_f32 v[118:119], v[90:91], v[118:119], v[62:63]
	v_pk_fma_f32 v[116:117], v[92:93], v[116:117], v[60:61]
	v_pk_fma_f32 v[120:121], v[94:95], v[120:121], v[58:59]
	v_pk_fma_f32 v[122:123], v[96:97], v[106:107], v[56:57]
	v_cvt_pk_bf16_f32 v106, v110, v111
	v_cvt_pk_bf16_f32 v107, v108, v109
	v_cvt_pk_bf16_f32 v108, v114, v115
	v_cvt_pk_bf16_f32 v109, v112, v113
	v_cvt_pk_bf16_f32 v110, v116, v117
	v_cvt_pk_bf16_f32 v111, v118, v119
	v_cvt_pk_bf16_f32 v112, v122, v123
	v_cvt_pk_bf16_f32 v113, v120, v121
	global_store_dwordx4 v[124:125], v[106:109], off sc1
	global_store_dwordx4 v[124:125], v[110:113], off offset:1024 sc1
	global_load_dwordx4 v[106:109], v[100:101], off
	s_nop 0
	global_load_dwordx4 v[110:113], v[100:101], off offset:1024
	global_load_dwordx4 v[114:117], v[126:127], off
	global_load_dwordx4 v[118:121], v[126:127], off offset:1024
	s_waitcnt vmcnt(3)
	v_lshlrev_b32_e32 v122, 16, v106
	v_and_b32_e32 v123, 0xffff0000, v106
	s_waitcnt vmcnt(1)
	v_and_b32_e32 v133, 0xffff0000, v116
	v_and_b32_e32 v132, 0xffff0000, v114
	v_lshlrev_b32_e32 v131, 16, v116
	v_lshlrev_b32_e32 v130, 16, v114
	v_lshlrev_b32_e32 v134, 16, v115
	v_and_b32_e32 v116, 0xffff0000, v115
	s_waitcnt vmcnt(0)
	v_lshlrev_b32_e32 v115, 16, v118
	v_lshlrev_b32_e32 v114, 16, v120
	v_and_b32_e32 v137, 0xffff0000, v118
	v_and_b32_e32 v136, 0xffff0000, v120
	v_lshlrev_b32_e32 v138, 16, v121
	v_and_b32_e32 v118, 0xffff0000, v121
	v_pk_mul_f32 v[120:121], v[132:133], v[132:133]
	v_lshlrev_b32_e32 v135, 16, v117
	v_pk_mul_f32 v[140:141], v[136:137], v[136:137]
	v_pk_fma_f32 v[120:121], v[130:131], v[130:131], v[120:121]
	v_and_b32_e32 v117, 0xffff0000, v117
	v_lshlrev_b32_e32 v139, 16, v119
	v_mov_b32_e32 v148, v130
	v_mov_b32_e32 v149, v132
	v_mov_b32_e32 v132, v131
	v_pk_fma_f32 v[130:131], v[114:115], v[114:115], v[140:141]
	v_pk_fma_f32 v[120:121], v[134:135], v[134:135], v[120:121]
	v_and_b32_e32 v119, 0xffff0000, v119
	v_pk_fma_f32 v[130:131], v[138:139], v[138:139], v[130:131]
	v_pk_fma_f32 v[120:121], v[116:117], v[116:117], v[120:121]
	v_mov_b32_e32 v150, v139
	v_mov_b32_e32 v151, v119
	v_mov_b32_e32 v139, v118
	v_pk_fma_f32 v[118:119], v[118:119], v[118:119], v[130:131]
	v_add_f32_e32 v120, v120, v121
	v_add_f32_e32 v119, v120, v119
	v_add_f32_e32 v118, v118, v119
	ds_bpermute_b32 v119, v172, v118
	v_mov_b32_e32 v142, v134
	v_mov_b32_e32 v143, v116
	v_mov_b32_e32 v116, v135
	v_mov_b32_e32 v152, v115
	s_waitcnt lgkmcnt(0)
	v_add_f32_e32 v118, v118, v119
	ds_bpermute_b32 v119, v173, v118
	v_mov_b32_e32 v153, v137
	v_mov_b32_e32 v115, v136
	v_lshlrev_b32_e32 v106, 16, v107
	v_and_b32_e32 v107, 0xffff0000, v107
	s_waitcnt lgkmcnt(0)
	v_add_f32_e32 v118, v118, v119
	ds_bpermute_b32 v119, v174, v118
	v_lshlrev_b32_e32 v124, 16, v108
	v_and_b32_e32 v125, 0xffff0000, v108
	v_lshlrev_b32_e32 v108, 16, v109
	v_and_b32_e32 v109, 0xffff0000, v109
	s_waitcnt lgkmcnt(0)
	v_add_f32_e32 v118, v118, v119
	ds_bpermute_b32 v119, v175, v118
	v_lshlrev_b32_e32 v126, 16, v110
	v_and_b32_e32 v127, 0xffff0000, v110
	v_lshlrev_b32_e32 v110, 16, v111
	v_and_b32_e32 v111, 0xffff0000, v111
	s_waitcnt lgkmcnt(0)
	v_add_f32_e32 v118, v118, v119
	ds_bpermute_b32 v119, v176, v118
	v_lshlrev_b32_e32 v128, 16, v112
	v_and_b32_e32 v129, 0xffff0000, v112
	v_lshlrev_b32_e32 v112, 16, v113
	v_and_b32_e32 v113, 0xffff0000, v113
	s_waitcnt lgkmcnt(0)
	v_add_f32_e32 v118, v118, v119
	ds_bpermute_b32 v119, v177, v118
	s_waitcnt lgkmcnt(0)
	v_add_f32_e32 v118, v118, v119
	v_fmamk_f32 v118, v118, 0x3a800000, v104
	v_mul_f32_e32 v119, 0x4b800000, v118
	v_cmp_gt_f32_e32 vcc, s3, v118
	s_nop 1
	v_cndmask_b32_e32 v118, v118, v119, vcc
	v_rsq_f32_e32 v118, v118
	s_nop 0
	v_mul_f32_e32 v119, 0x45800000, v118
	v_cndmask_b32_e32 v118, v118, v119, vcc
	v_pk_mul_f32 v[120:121], v[118:119], v[142:143] op_sel_hi:[0,1]
	v_pk_mul_f32 v[130:131], v[118:119], v[148:149] op_sel_hi:[0,1]
	v_pk_mul_f32 v[116:117], v[118:119], v[116:117] op_sel_hi:[0,1]
	v_pk_mul_f32 v[132:133], v[118:119], v[132:133] op_sel_hi:[0,1]
	v_pk_mul_f32 v[134:135], v[118:119], v[150:151] op_sel_hi:[0,1]
	v_pk_mul_f32 v[136:137], v[118:119], v[152:153] op_sel_hi:[0,1]
	v_pk_mul_f32 v[138:139], v[118:119], v[138:139] op_sel_hi:[0,1]
	v_pk_mul_f32 v[114:115], v[118:119], v[114:115] op_sel_hi:[0,1]
	v_pk_mul_f32 v[118:119], v[4:5], v[130:131]
	v_pk_mul_f32 v[120:121], v[6:7], v[120:121]
	v_pk_mul_f32 v[130:131], v[0:1], v[132:133]
	v_pk_mul_f32 v[116:117], v[2:3], v[116:117]
	v_pk_mul_f32 v[132:133], v[36:37], v[136:137]
	v_pk_mul_f32 v[134:135], v[38:39], v[134:135]
	v_pk_mul_f32 v[114:115], v[32:33], v[114:115]
	v_pk_mul_f32 v[136:137], v[34:35], v[138:139]
	v_pk_fma_f32 v[120:121], v[14:15], v[120:121], v[106:107]
	v_pk_fma_f32 v[118:119], v[12:13], v[118:119], v[122:123]
	v_pk_fma_f32 v[116:117], v[10:11], v[116:117], v[108:109]
	v_pk_fma_f32 v[122:123], v[8:9], v[130:131], v[124:125]
	v_pk_fma_f32 v[124:125], v[46:47], v[134:135], v[110:111]
	v_pk_fma_f32 v[126:127], v[44:45], v[132:133], v[126:127]
	v_pk_fma_f32 v[130:131], v[42:43], v[136:137], v[112:113]
	v_pk_fma_f32 v[114:115], v[40:41], v[114:115], v[128:129]
	v_cvt_pk_bf16_f32 v106, v118, v119
	v_cvt_pk_bf16_f32 v107, v120, v121
	v_cvt_pk_bf16_f32 v108, v122, v123
	v_cvt_pk_bf16_f32 v109, v116, v117
	v_mov_b32_e32 v132, v119
	v_mov_b32_e32 v133, v123
	v_cvt_pk_bf16_f32 v110, v126, v127
	v_cvt_pk_bf16_f32 v111, v124, v125
	v_cvt_pk_bf16_f32 v112, v114, v115
	v_cvt_pk_bf16_f32 v113, v130, v131
	v_mov_b32_e32 v128, v118
	v_mov_b32_e32 v129, v122
	v_mov_b32_e32 v140, v115
	v_mov_b32_e32 v141, v127
	global_store_dwordx4 v[100:101], v[106:109], off sc1
	global_store_dwordx4 v[100:101], v[110:113], off offset:1024 sc1
	v_pk_mul_f32 v[100:101], v[132:133], v[132:133]
	v_mov_b32_e32 v134, v120
	v_mov_b32_e32 v135, v116
	v_mov_b32_e32 v138, v114
	v_mov_b32_e32 v139, v126
	v_pk_mul_f32 v[106:107], v[140:141], v[140:141]
	v_pk_fma_f32 v[100:101], v[128:129], v[128:129], v[100:101]
	v_mov_b32_e32 v136, v121
	v_mov_b32_e32 v137, v117
	v_mov_b32_e32 v142, v130
	v_mov_b32_e32 v143, v124
	v_pk_fma_f32 v[106:107], v[138:139], v[138:139], v[106:107]
	v_pk_fma_f32 v[100:101], v[134:135], v[134:135], v[100:101]
	v_mov_b32_e32 v148, v131
	v_mov_b32_e32 v149, v125
	v_pk_fma_f32 v[106:107], v[142:143], v[142:143], v[106:107]
	v_pk_fma_f32 v[100:101], v[136:137], v[136:137], v[100:101]
	v_pk_fma_f32 v[106:107], v[148:149], v[148:149], v[106:107]
	v_add_f32_e32 v100, v100, v101
	v_add_f32_e32 v100, v107, v100
	v_add_f32_e32 v100, v106, v100
	ds_bpermute_b32 v101, v172, v100
	s_waitcnt lgkmcnt(0)
	v_add_f32_e32 v100, v100, v101
	ds_bpermute_b32 v101, v173, v100
	s_waitcnt lgkmcnt(0)
	v_add_f32_e32 v100, v100, v101
	ds_bpermute_b32 v101, v174, v100
	s_waitcnt lgkmcnt(0)
	v_add_f32_e32 v100, v100, v101
	ds_bpermute_b32 v101, v175, v100
	s_waitcnt lgkmcnt(0)
	v_add_f32_e32 v100, v100, v101
	ds_bpermute_b32 v101, v176, v100
	s_waitcnt lgkmcnt(0)
	v_add_f32_e32 v100, v100, v101
	ds_bpermute_b32 v101, v177, v100
	s_waitcnt lgkmcnt(0)
	v_add_f32_e32 v100, v100, v101
	v_fmamk_f32 v100, v100, 0x3a800000, v104
	v_mul_f32_e32 v101, 0x4b800000, v100
	v_cmp_gt_f32_e32 vcc, s3, v100
	s_nop 1
	v_cndmask_b32_e32 v100, v100, v101, vcc
	v_rsq_f32_e32 v100, v100
	s_nop 0
	v_mul_f32_e32 v101, 0x45800000, v100
	v_cndmask_b32_e32 v100, v100, v101, vcc
	v_pk_mul_f32 v[106:107], v[120:121], v[100:101] op_sel_hi:[1,0]
	v_pk_mul_f32 v[108:109], v[118:119], v[100:101] op_sel_hi:[1,0]
	v_pk_mul_f32 v[110:111], v[116:117], v[100:101] op_sel_hi:[1,0]
	v_pk_mul_f32 v[112:113], v[122:123], v[100:101] op_sel_hi:[1,0]
	v_pk_mul_f32 v[116:117], v[124:125], v[100:101] op_sel_hi:[1,0]
	v_pk_mul_f32 v[118:119], v[126:127], v[100:101] op_sel_hi:[1,0]
	v_pk_mul_f32 v[120:121], v[130:131], v[100:101] op_sel_hi:[1,0]
	v_pk_mul_f32 v[100:101], v[114:115], v[100:101] op_sel_hi:[1,0]
	v_pk_mul_f32 v[108:109], v[20:21], v[108:109]
	v_pk_mul_f32 v[106:107], v[22:23], v[106:107]
	v_pk_mul_f32 v[112:113], v[16:17], v[112:113]
	v_pk_mul_f32 v[110:111], v[18:19], v[110:111]
	v_pk_mul_f32 v[114:115], v[52:53], v[118:119]
	v_pk_mul_f32 v[116:117], v[54:55], v[116:117]
	v_pk_mul_f32 v[100:101], v[48:49], v[100:101]
	v_pk_mul_f32 v[118:119], v[50:51], v[120:121]
	v_pk_fma_f32 v[120:121], v[82:83], v[106:107], v[30:31]
	v_pk_fma_f32 v[106:107], v[84:85], v[108:109], v[28:29]
	v_pk_fma_f32 v[110:111], v[86:87], v[110:111], v[26:27]
	v_pk_fma_f32 v[108:109], v[88:89], v[112:113], v[24:25]
	v_pk_fma_f32 v[112:113], v[90:91], v[116:117], v[62:63]
	v_pk_fma_f32 v[114:115], v[92:93], v[114:115], v[60:61]
	v_pk_fma_f32 v[116:117], v[94:95], v[118:119], v[58:59]
	v_pk_fma_f32 v[100:101], v[96:97], v[100:101], v[56:57]
	v_cvt_pk_bf16_f32 v106, v106, v107
	v_cvt_pk_bf16_f32 v107, v120, v121
	v_cvt_pk_bf16_f32 v108, v108, v109
	v_cvt_pk_bf16_f32 v109, v110, v111
	v_cvt_pk_bf16_f32 v110, v114, v115
	v_cvt_pk_bf16_f32 v111, v112, v113
	v_cvt_pk_bf16_f32 v112, v100, v101
	v_cvt_pk_bf16_f32 v113, v116, v117
	global_store_dwordx4 v[98:99], v[106:109], off sc1
	global_store_dwordx4 v[98:99], v[110:113], off offset:1024 sc1
	s_cbranch_scc0 .LBB0_1291
	v_add_u32_e32 v105, s0, v105
	v_cmp_lt_i32_e32 vcc, s4, v105
	s_or_b64 s[8:9], vcc, s[8:9]
	v_add_u32_e32 v102, s1, v102
	s_andn2_b64 exec, exec, s[8:9]
	s_cbranch_execnz .LBB0_1290
.LBB0_1293:
	s_or_b64 exec, exec, s[6:7]
	s_waitcnt vmcnt(0)
	s_barrier
	s_mov_b64 s[6:7], exec
	v_readlane_b32 s0, v219, 25
	v_readlane_b32 s1, v219, 26
	s_and_b64 s[0:1], s[6:7], s[0:1]
	s_mov_b64 exec, s[0:1]
	s_cbranch_execz .LBB0_1345
	v_readlane_b32 s0, v219, 27
	v_readlane_b32 s1, v219, 28
	v_readlane_b32 s2, v219, 29
	v_mov_b32_e32 v0, 0x24000
	s_waitcnt vmcnt(0) lgkmcnt(0)
	buffer_inv sc1
	ds_read_b32 v2, v0
	ds_read_b32 v0, v0 offset:4
	s_lshl_b32 s3, s2, 8
	s_add_i32 s14, s3, 0x2400
	s_add_i32 s3, s3, 0x1400
	v_mov_b32_e32 v1, s3
	s_waitcnt lgkmcnt(0)
	v_readfirstlane_b32 s10, v2
	v_readfirstlane_b32 s11, v0
	v_mov_b32_e32 v0, 1
	s_nop 1
	global_atomic_add v2, v1, v0, s[0:1] sc0
	s_mul_i32 s10, s10, 13
	s_mul_i32 s11, s11, 13
	s_waitcnt vmcnt(0)
	v_readfirstlane_b32 s13, v2
	s_nop 1
	s_add_i32 s13, s13, 1
	s_cmp_lg_u32 s13, s10
	s_cbranch_scc1 .Lnb13_wait
	v_mov_b32_e32 v1, 0x3400
	global_atomic_add v2, v1, v0, s[0:1] sc0
	s_waitcnt vmcnt(0)
	v_readfirstlane_b32 s13, v2
	s_nop 1
	s_add_i32 s13, s13, 1
	s_cmp_lg_u32 s13, s11
	s_cbranch_scc1 .Lnb13_wait
	v_mov_b32_e32 v1, 0x2400
	global_atomic_add v1, v0, s[0:1]
	global_atomic_add v1, v0, s[0:1] offset:256
	global_atomic_add v1, v0, s[0:1] offset:512
	global_atomic_add v1, v0, s[0:1] offset:768
	global_atomic_add v1, v0, s[0:1] offset:1024
	global_atomic_add v1, v0, s[0:1] offset:1280
	global_atomic_add v1, v0, s[0:1] offset:1536
	global_atomic_add v1, v0, s[0:1] offset:1792
	global_atomic_add v1, v0, s[0:1] offset:2048
	global_atomic_add v1, v0, s[0:1] offset:2304
	global_atomic_add v1, v0, s[0:1] offset:2560
	global_atomic_add v1, v0, s[0:1] offset:2816
	global_atomic_add v1, v0, s[0:1] offset:3072
	global_atomic_add v1, v0, s[0:1] offset:3328
	global_atomic_add v1, v0, s[0:1] offset:3584
	global_atomic_add v1, v0, s[0:1] offset:3840
	v_mov_b32_e32 v1, 0x3500
	global_atomic_add v1, v0, s[0:1]

.Lnb13_spin:
	global_load_dword v2, v1, s[0:1] sc1
	s_waitcnt vmcnt(0)
	v_readfirstlane_b32 s13, v2
	s_nop 1
	s_cmp_ge_u32 s13, 13
	s_cbranch_scc1 .Lnb13_done
	s_sleep 1
	s_add_i32 s15, s15, 1
	s_cmp_lt_u32 s15, 0x200000
	s_cbranch_scc1 .Lnb13_spin
.Lnb13_done:
	s_waitcnt vmcnt(0)
.LBB0_1345:
	s_or_b64 exec, exec, s[6:7]
	v_readlane_b32 s0, v219, 52
	v_readlane_b32 s1, v219, 53
	s_andn2_b64 vcc, exec, s[0:1]
	v_readfirstlane_b32 s5, v168
	s_waitcnt lgkmcnt(0)
	s_barrier
	s_cbranch_vccnz .LBB0_1409
	s_add_u32 s0, s56, 0x1e80000
	s_addc_u32 s1, s57, 0
	s_lshl_b32 s2, s78, 19
	s_lshr_b32 s33, s5, 6
	s_bfe_u32 s38, s5, 0x10006
	s_lshr_b32 s39, s5, 7
	s_and_b32 s2, s2, 0xf80000
	s_add_u32 s4, s30, s2
	s_addc_u32 s21, s31, 0
	s_lshl_b32 s2, s78, 2
	s_and_b32 s2, s2, 0xffffff80
	s_ashr_i32 s3, s2, 31
	s_mov_b32 s73, 0
	s_lshl_b64 s[6:7], s[2:3], 11
	s_lshl_b32 s72, s33, 5
	s_lshl_b32 s2, s33, 12
	s_add_i32 s3, s2, 0
	s_lshl_b64 s[12:13], s[72:73], 11
	s_add_u32 s8, s4, s12
	s_addc_u32 s9, s21, s13
	s_or_b32 s10, s72, 8
	s_mov_b32 s11, s73
	s_lshl_b64 s[14:15], s[10:11], 11
	s_add_u32 s10, s4, s14
	v_mov_b32_e32 v0, v178
	v_mov_b32_e32 v1, v179
	s_mov_b32 m0, s3
	s_addc_u32 s11, s21, s15
	s_or_b32 s16, s72, 16
	s_mov_b32 s17, s73
	s_barrier
	s_lshl_b64 s[18:19], s[16:17], 11
	global_load_lds_dwordx4 v0, s[8:9]
	s_add_i32 m0, s3, 0x400
	s_add_u32 s16, s4, s18
	s_addc_u32 s17, s21, s19
	s_or_b32 s72, s72, 24
	global_load_lds_dwordx4 v1, s[10:11]
	s_add_i32 m0, s3, 0x800
	s_lshl_b64 s[22:23], s[72:73], 11
	s_add_u32 s20, s4, s22
	global_load_lds_dwordx4 v0, s[16:17]
	s_addc_u32 s21, s21, s23
	s_add_i32 m0, s3, 0xc00
	s_add_u32 s28, s0, s6
	s_addc_u32 s29, s1, s7
	s_lshl_b32 s4, s33, 11
	s_lshl_b32 s72, s33, 4
	s_sub_i32 s34, s3, s4
	global_load_lds_dwordx4 v1, s[20:21]
	s_add_i32 m0, s34, 0x8000
	s_lshl_b64 s[24:25], s[72:73], 11
	s_add_u32 s6, s28, s24
	s_addc_u32 s7, s29, s25
	s_or_b32 s72, s72, 8
	s_lshl_b64 s[26:27], s[72:73], 11
	s_add_u32 s28, s28, s26
	global_load_lds_dwordx4 v0, s[6:7]
	s_addc_u32 s29, s29, s27
	s_add_i32 m0, s34, 0x8400
	v_mov_b32_e32 v148, v178
	v_mov_b32_e32 v0, v179
	v_mov_b32_e32 v149, 0
	global_load_lds_dwordx4 v1, s[28:29]
	s_mov_b64 s[34:35], 0x80
	v_lshl_add_u64 v[2:3], s[8:9], 0, v[148:149]
	s_add_i32 m0, s3, 0xc000
	v_lshl_add_u64 v[2:3], v[2:3], 0, s[34:35]
	v_mov_b32_e32 v1, v149
	global_load_lds_dwordx4 v[2:3], off
	v_lshl_add_u64 v[2:3], s[10:11], 0, v[0:1]
	v_lshl_add_u64 v[2:3], v[2:3], 0, s[34:35]
	s_add_i32 m0, s3, 0xc400
	s_add_i32 s8, s4, 0
	global_load_lds_dwordx4 v[2:3], off
	v_lshl_add_u64 v[2:3], s[16:17], 0, v[148:149]
	v_lshl_add_u64 v[2:3], v[2:3], 0, s[34:35]
	s_add_i32 m0, s3, 0xc800
	v_readlane_b32 s10, v219, 33
	global_load_lds_dwordx4 v[2:3], off
	v_lshl_add_u64 v[2:3], s[20:21], 0, v[0:1]
	v_lshl_add_u64 v[2:3], v[2:3], 0, s[34:35]
	s_add_i32 m0, s3, 0xcc00
	v_lshl_add_u64 v[0:1], s[28:29], 0, v[0:1]
	global_load_lds_dwordx4 v[2:3], off
	v_lshl_add_u64 v[2:3], s[6:7], 0, v[148:149]
	s_add_i32 m0, s8, 0x14000
	v_lshl_add_u64 v[2:3], v[2:3], 0, s[34:35]
	global_load_lds_dwordx4 v[2:3], off
	v_lshl_add_u64 v[0:1], v[0:1], 0, s[34:35]
	s_add_i32 m0, s8, 0x14400
	s_cmpk_gt_u32 s5, 0xff
	global_load_lds_dwordx4 v[0:1], off
	s_cselect_b64 s[36:37], -1, 0
	s_lshl_b32 s72, s33, 15
	s_lshl_b32 s6, s33, 14
	s_lshl_b32 s5, s38, 13
	s_lshl_b32 s16, s39, 13
	s_lshl_b32 s8, s38, 6
	v_readlane_b32 s11, v219, 34
	s_add_u32 s8, s10, s8
	s_addc_u32 s9, s11, 0
	s_add_u32 s17, s56, s12
	s_addc_u32 s28, s57, s13
	s_lshl_b32 s29, s78, 8
	s_lshl_b32 s33, s58, 8
	s_add_u32 s76, s56, s24
	v_lshl_or_b32 v150, s39, 6, v167
	s_addc_u32 s77, s57, s25
	s_lshl_b64 s[38:39], s[72:73], 1
	s_mov_b32 s7, s73
	v_add_u32_e32 v0, 12, v146
	v_cmp_eq_u32_e32 vcc, 0, v171
	s_mov_b32 s83, s78
	s_add_u32 s78, s56, s38
	v_cndmask_b32_e32 v0, v0, v146, vcc
	v_xor_b32_e32 v1, v147, v170
	s_addc_u32 s79, s57, s39
	s_lshl_b64 s[40:41], s[6:7], 1
	v_lshlrev_b32_e32 v151, 4, v1
	v_bitop3_b32 v1, v147, v170, 4 bitop3:0x36
	v_lshlrev_b32_e32 v148, 1, v0
	s_add_u32 s80, s56, s40
	v_lshlrev_b32_e32 v152, 4, v1
	v_lshl_add_u64 v[146:147], s[8:9], 0, v[148:149]
	s_addc_u32 s81, s57, s41
	s_mov_b64 s[6:7], -1
	s_mov_b64 s[42:43], 0x100
	s_mov_b64 s[44:45], 0x3400180
	s_mov_b64 s[46:47], 0x3404180
	s_mov_b64 s[48:49], 0x3408180
	s_mov_b64 s[50:51], 0x340c180
	s_mov_b64 s[52:53], 0x1e80180
	s_mov_b64 s[60:61], 0x1e84180
	s_mov_b64 s[62:63], 0x4000
	s_mov_b64 s[64:65], 0x8000
	s_movk_i32 s82, 0x1600
	s_branch .LBB0_1348
.LBB0_1347:
	v_mul_f32_e32 v64, 0xbfb8aa3b, v56
	v_exp_f32_e32 v66, v64
	v_mul_f32_e32 v64, 0xbfb8aa3b, v57
	v_exp_f32_e32 v67, v64
	v_mul_f32_e32 v68, 0xbfb8aa3b, v58
	v_add_f32_e32 v66, 1.0, v66
	v_rcp_f32_e32 v66, v66
	v_add_f32_e32 v67, 1.0, v67
	v_mul_f32_e32 v69, 0xbfb8aa3b, v59
	v_rcp_f32_e32 v67, v67
	v_exp_f32_e32 v68, v68
	v_exp_f32_e32 v69, v69
	s_lshl_b32 s6, s85, 6
	v_pk_mul_f32 v[56:57], v[56:57], v[66:67]
	v_add_f32_e32 v68, 1.0, v68
	v_add_f32_e32 v69, 1.0, v69
	v_pk_mul_f32 v[56:57], v[60:61], v[56:57]
	v_rcp_f32_e32 v68, v68
	v_rcp_f32_e32 v69, v69
	v_cvt_pk_bf16_f32 v56, v56, v57
	v_mul_f32_e32 v57, 0xbfb8aa3b, v48
	v_exp_f32_e32 v60, v57
	v_mul_f32_e32 v57, 0xbfb8aa3b, v49
	v_exp_f32_e32 v61, v57
	v_pk_mul_f32 v[58:59], v[58:59], v[68:69]
	s_ashr_i32 s7, s6, 31
	v_pk_mul_f32 v[58:59], v[62:63], v[58:59]
	v_add_u32_e32 v70, s84, v150
	v_cvt_pk_bf16_f32 v57, v58, v59
	v_add_f32_e32 v58, 1.0, v60
	v_add_f32_e32 v59, 1.0, v61
	v_mul_f32_e32 v60, 0xbfb8aa3b, v50
	v_mul_f32_e32 v61, 0xbfb8aa3b, v51
	v_exp_f32_e32 v60, v60
	v_exp_f32_e32 v61, v61
	v_rcp_f32_e32 v58, v58
	v_rcp_f32_e32 v59, v59
	v_add_f32_e32 v60, 1.0, v60
	v_add_f32_e32 v61, 1.0, v61
	v_rcp_f32_e32 v60, v60
	v_rcp_f32_e32 v61, v61
	v_pk_mul_f32 v[48:49], v[48:49], v[58:59]
	v_lshl_add_u64 v[64:65], s[6:7], 1, v[146:147]
	v_pk_mul_f32 v[48:49], v[52:53], v[48:49]
	s_add_i32 s29, s29, s33
	v_cvt_pk_bf16_f32 v58, v48, v49
	v_pk_mul_f32 v[48:49], v[50:51], v[60:61]
	v_mul_f32_e32 v50, 0xbfb8aa3b, v40
	v_mul_f32_e32 v51, 0xbfb8aa3b, v41
	v_exp_f32_e32 v50, v50
	v_exp_f32_e32 v51, v51
	v_pk_mul_f32 v[48:49], v[54:55], v[48:49]
	v_permlane16_swap_b32_e32 v56, v58
	v_cvt_pk_bf16_f32 v59, v48, v49
	s_nop 1
	v_permlane16_swap_b32_e32 v57, v59
	v_mad_u64_u32 v[48:49], s[6:7], v70, s82, v[64:65]
	global_store_dwordx4 v[48:49], v[56:59], off sc1
	v_add_f32_e32 v48, 1.0, v50
	v_add_f32_e32 v49, 1.0, v51
	v_rcp_f32_e32 v48, v48
	v_mul_f32_e32 v50, 0xbfb8aa3b, v42
	v_mul_f32_e32 v51, 0xbfb8aa3b, v43
	v_rcp_f32_e32 v49, v49
	v_exp_f32_e32 v50, v50
	v_exp_f32_e32 v51, v51
	s_andn2_b64 vcc, exec, s[68:69]
	v_pk_mul_f32 v[40:41], v[40:41], v[48:49]
	v_add_f32_e32 v50, 1.0, v50
	v_add_f32_e32 v51, 1.0, v51
	v_pk_mul_f32 v[40:41], v[44:45], v[40:41]
	v_rcp_f32_e32 v50, v50
	v_rcp_f32_e32 v51, v51
	v_cvt_pk_bf16_f32 v40, v40, v41
	v_mul_f32_e32 v41, 0xbfb8aa3b, v32
	v_exp_f32_e32 v44, v41
	v_mul_f32_e32 v41, 0xbfb8aa3b, v33
	v_exp_f32_e32 v45, v41
	v_pk_mul_f32 v[42:43], v[42:43], v[50:51]
	s_nop 0
	v_pk_mul_f32 v[42:43], v[46:47], v[42:43]
	s_nop 0
	v_cvt_pk_bf16_f32 v41, v42, v43
	v_add_f32_e32 v42, 1.0, v44
	v_add_f32_e32 v43, 1.0, v45
	v_mul_f32_e32 v44, 0xbfb8aa3b, v34
	v_mul_f32_e32 v45, 0xbfb8aa3b, v35
	v_exp_f32_e32 v44, v44
	v_exp_f32_e32 v45, v45
	v_rcp_f32_e32 v42, v42
	v_rcp_f32_e32 v43, v43
	v_add_f32_e32 v44, 1.0, v44
	v_add_f32_e32 v45, 1.0, v45
	v_rcp_f32_e32 v44, v44
	v_rcp_f32_e32 v45, v45
	v_pk_mul_f32 v[32:33], v[32:33], v[42:43]
	s_nop 0
	v_pk_mul_f32 v[32:33], v[36:37], v[32:33]
	s_nop 0
	v_cvt_pk_bf16_f32 v42, v32, v33
	v_pk_mul_f32 v[32:33], v[34:35], v[44:45]
	v_mul_f32_e32 v34, 0xbfb8aa3b, v24
	v_mul_f32_e32 v35, 0xbfb8aa3b, v25
	v_exp_f32_e32 v34, v34
	v_exp_f32_e32 v35, v35
	v_pk_mul_f32 v[32:33], v[38:39], v[32:33]
	v_permlane16_swap_b32_e32 v40, v42
	v_cvt_pk_bf16_f32 v43, v32, v33
	v_or_b32_e32 v32, 16, v70
	s_nop 0
	v_permlane16_swap_b32_e32 v41, v43
	v_mad_u64_u32 v[32:33], s[6:7], v32, s82, v[64:65]
	global_store_dwordx4 v[32:33], v[40:43], off sc1
	v_add_f32_e32 v32, 1.0, v34
	v_add_f32_e32 v33, 1.0, v35
	v_rcp_f32_e32 v32, v32
	v_mul_f32_e32 v34, 0xbfb8aa3b, v26
	v_mul_f32_e32 v35, 0xbfb8aa3b, v27
	v_rcp_f32_e32 v33, v33
	v_exp_f32_e32 v34, v34
	v_exp_f32_e32 v35, v35
	v_pk_mul_f32 v[24:25], v[24:25], v[32:33]
	v_add_f32_e32 v34, 1.0, v34
	v_add_f32_e32 v35, 1.0, v35
	v_pk_mul_f32 v[24:25], v[28:29], v[24:25]
	v_rcp_f32_e32 v34, v34
	v_rcp_f32_e32 v35, v35
	v_cvt_pk_bf16_f32 v24, v24, v25
	v_mul_f32_e32 v25, 0xbfb8aa3b, v16
	v_exp_f32_e32 v28, v25
	v_mul_f32_e32 v25, 0xbfb8aa3b, v17
	v_exp_f32_e32 v29, v25
	v_pk_mul_f32 v[26:27], v[26:27], v[34:35]
	s_nop 0
	v_pk_mul_f32 v[26:27], v[30:31], v[26:27]
	s_nop 0
	v_cvt_pk_bf16_f32 v25, v26, v27
	v_add_f32_e32 v26, 1.0, v28
	v_add_f32_e32 v27, 1.0, v29
	v_mul_f32_e32 v28, 0xbfb8aa3b, v18
	v_mul_f32_e32 v29, 0xbfb8aa3b, v19
	v_exp_f32_e32 v28, v28
	v_exp_f32_e32 v29, v29
	v_rcp_f32_e32 v26, v26
	v_rcp_f32_e32 v27, v27
	v_add_f32_e32 v28, 1.0, v28
	v_add_f32_e32 v29, 1.0, v29
	v_rcp_f32_e32 v28, v28
	v_rcp_f32_e32 v29, v29
	v_pk_mul_f32 v[16:17], v[16:17], v[26:27]
	s_nop 0
	v_pk_mul_f32 v[16:17], v[20:21], v[16:17]
	s_nop 0
	v_cvt_pk_bf16_f32 v26, v16, v17
	v_pk_mul_f32 v[16:17], v[18:19], v[28:29]
	v_mul_f32_e32 v18, 0xbfb8aa3b, v8
	v_mul_f32_e32 v19, 0xbfb8aa3b, v9
	v_exp_f32_e32 v18, v18
	v_exp_f32_e32 v19, v19
	v_pk_mul_f32 v[16:17], v[22:23], v[16:17]
	v_permlane16_swap_b32_e32 v24, v26
	v_cvt_pk_bf16_f32 v27, v16, v17
	v_or_b32_e32 v16, 32, v70
	s_nop 0
	v_permlane16_swap_b32_e32 v25, v27
	v_mad_u64_u32 v[16:17], s[6:7], v16, s82, v[64:65]
	global_store_dwordx4 v[16:17], v[24:27], off sc1
	v_add_f32_e32 v16, 1.0, v18
	v_add_f32_e32 v17, 1.0, v19
	v_rcp_f32_e32 v16, v16
	v_mul_f32_e32 v18, 0xbfb8aa3b, v10
	v_mul_f32_e32 v19, 0xbfb8aa3b, v11
	v_rcp_f32_e32 v17, v17
	v_exp_f32_e32 v18, v18
	v_exp_f32_e32 v19, v19
	v_pk_mul_f32 v[8:9], v[8:9], v[16:17]
	v_add_f32_e32 v18, 1.0, v18
	v_add_f32_e32 v19, 1.0, v19
	v_pk_mul_f32 v[8:9], v[12:13], v[8:9]
	v_rcp_f32_e32 v18, v18
	v_rcp_f32_e32 v19, v19
	v_cvt_pk_bf16_f32 v8, v8, v9
	v_mul_f32_e32 v9, 0xbfb8aa3b, v0
	v_exp_f32_e32 v12, v9
	v_mul_f32_e32 v9, 0xbfb8aa3b, v1
	v_exp_f32_e32 v13, v9
	v_pk_mul_f32 v[10:11], v[10:11], v[18:19]
	s_nop 0
	v_pk_mul_f32 v[10:11], v[14:15], v[10:11]
	s_nop 0
	v_cvt_pk_bf16_f32 v9, v10, v11
	v_add_f32_e32 v10, 1.0, v12
	v_add_f32_e32 v11, 1.0, v13
	v_mul_f32_e32 v12, 0xbfb8aa3b, v2
	v_mul_f32_e32 v13, 0xbfb8aa3b, v3
	v_exp_f32_e32 v12, v12
	v_exp_f32_e32 v13, v13
	v_rcp_f32_e32 v10, v10
	v_rcp_f32_e32 v11, v11
	v_add_f32_e32 v12, 1.0, v12
	v_add_f32_e32 v13, 1.0, v13
	v_rcp_f32_e32 v12, v12
	v_rcp_f32_e32 v13, v13
	v_pk_mul_f32 v[0:1], v[0:1], v[10:11]
	s_nop 0
	v_pk_mul_f32 v[0:1], v[4:5], v[0:1]
	s_nop 0
	v_cvt_pk_bf16_f32 v10, v0, v1
	v_pk_mul_f32 v[0:1], v[2:3], v[12:13]
	s_nop 0
	v_permlane16_swap_b32_e32 v8, v10
	v_pk_mul_f32 v[0:1], v[6:7], v[0:1]
	s_nop 0
	v_cvt_pk_bf16_f32 v11, v0, v1
	v_or_b32_e32 v0, 48, v70
	v_mad_u64_u32 v[0:1], s[6:7], v0, s82, v[64:65]
	v_permlane16_swap_b32_e32 v9, v11
	s_mov_b64 s[6:7], 0
	global_store_dwordx4 v[0:1], v[8:11], off sc1
	s_cbranch_vccz .LBB0_1408

.LBB0_1409:
	s_waitcnt vmcnt(0)
	s_waitcnt vmcnt(0) lgkmcnt(0)
	s_barrier
	s_mov_b64 s[6:7], exec
	v_readlane_b32 s0, v219, 25
	v_readlane_b32 s1, v219, 26
	s_and_b64 s[0:1], s[6:7], s[0:1]
	s_mov_b64 exec, s[0:1]
	s_cbranch_execz .LBB0_1461
	v_readlane_b32 s0, v219, 27
	v_readlane_b32 s1, v219, 28
	v_readlane_b32 s2, v219, 29
	v_mov_b32_e32 v0, 0x24000
	s_waitcnt vmcnt(0) lgkmcnt(0)
	buffer_inv sc1
	ds_read_b32 v2, v0
	ds_read_b32 v0, v0 offset:4
	s_lshl_b32 s3, s2, 8
	s_add_i32 s14, s3, 0x2400
	s_add_i32 s3, s3, 0x1400
	v_mov_b32_e32 v1, s3
	s_waitcnt lgkmcnt(0)
	v_readfirstlane_b32 s10, v2
	v_readfirstlane_b32 s11, v0
	v_mov_b32_e32 v0, 1
	s_nop 1
	global_atomic_add v2, v1, v0, s[0:1] sc0
	s_mul_i32 s10, s10, 14
	s_mul_i32 s11, s11, 14
	s_waitcnt vmcnt(0)
	v_readfirstlane_b32 s13, v2
	s_nop 1
	s_add_i32 s13, s13, 1
	s_cmp_lg_u32 s13, s10
	s_cbranch_scc1 .Lnb14_wait
	v_mov_b32_e32 v1, 0x3400
	global_atomic_add v2, v1, v0, s[0:1] sc0
	s_waitcnt vmcnt(0)
	v_readfirstlane_b32 s13, v2
	s_nop 1
	s_add_i32 s13, s13, 1
	s_cmp_lg_u32 s13, s11
	s_cbranch_scc1 .Lnb14_wait
	v_mov_b32_e32 v1, 0x2400
	global_atomic_add v1, v0, s[0:1]
	global_atomic_add v1, v0, s[0:1] offset:256
	global_atomic_add v1, v0, s[0:1] offset:512
	global_atomic_add v1, v0, s[0:1] offset:768
	global_atomic_add v1, v0, s[0:1] offset:1024
	global_atomic_add v1, v0, s[0:1] offset:1280
	global_atomic_add v1, v0, s[0:1] offset:1536
	global_atomic_add v1, v0, s[0:1] offset:1792
	global_atomic_add v1, v0, s[0:1] offset:2048
	global_atomic_add v1, v0, s[0:1] offset:2304
	global_atomic_add v1, v0, s[0:1] offset:2560
	global_atomic_add v1, v0, s[0:1] offset:2816
	global_atomic_add v1, v0, s[0:1] offset:3072
	global_atomic_add v1, v0, s[0:1] offset:3328
	global_atomic_add v1, v0, s[0:1] offset:3584
	global_atomic_add v1, v0, s[0:1] offset:3840
	v_mov_b32_e32 v1, 0x3500
	global_atomic_add v1, v0, s[0:1]

.Lnb14_spin:
	global_load_dword v2, v1, s[0:1] sc1
	s_waitcnt vmcnt(0)
	v_readfirstlane_b32 s13, v2
	s_nop 1
	s_cmp_ge_u32 s13, 14
	s_cbranch_scc1 .Lnb14_done
	s_sleep 1
	s_add_i32 s15, s15, 1
	s_cmp_lt_u32 s15, 0x200000
	s_cbranch_scc1 .Lnb14_spin
.Lnb14_done:
	s_waitcnt vmcnt(0)
.LBB0_1461:
	s_or_b64 exec, exec, s[6:7]
	v_readlane_b32 s0, v219, 50
	v_readlane_b32 s1, v219, 51
	s_and_b64 vcc, exec, s[0:1]
	v_readfirstlane_b32 s10, v168
	s_waitcnt lgkmcnt(0)
	s_barrier
	s_cbranch_vccnz .LBB0_1525
	s_add_u32 s0, s56, 0x2980000
	s_addc_u32 s1, s57, 0
	s_lshl_b32 s2, s78, 8
	s_and_b32 s3, s2, 0x1f00
	s_lshr_b32 s46, s10, 6
	s_bfe_u32 s47, s10, 0x10006
	s_lshr_b32 s11, s10, 7
	s_mulk_i32 s3, 0x1600
	v_readlane_b32 s4, v219, 33
	v_readlane_b32 s5, v219, 34
	s_add_u32 s22, s4, s3
	s_addc_u32 s23, s5, 0
	s_lshl_b32 s18, s46, 5
	s_lshl_b32 s3, s78, 2
	s_lshl_b32 s16, s46, 12
	s_mul_hi_u32 s5, s18, 0xb00
	s_mul_i32 s4, s46, 0x16000
	s_and_b32 s24, s3, 0xffffff80
	s_add_i32 s17, s16, 0
	s_lshl_b64 s[8:9], s[4:5], 1
	s_add_u32 s20, s22, s8
	s_addc_u32 s21, s23, s9
	s_or_b32 s6, s18, 8
	s_mul_hi_u32 s7, s6, 0xb00
	s_mulk_i32 s6, 0xb00
	s_lshl_b64 s[12:13], s[6:7], 1
	s_add_u32 s30, s22, s12
	s_addc_u32 s31, s23, s13
	s_or_b32 s6, s18, 16
	v_mov_b32_e32 v0, v165
	v_mov_b32_e32 v1, v164
	s_mov_b32 m0, s17
	s_mul_hi_u32 s7, s6, 0xb00
	s_mulk_i32 s6, 0xb00
	s_barrier
	s_lshl_b64 s[14:15], s[6:7], 1
	global_load_lds_dwordx4 v1, s[20:21]
	s_add_i32 m0, s17, 0x400
	s_add_u32 s34, s22, s14
	s_addc_u32 s35, s23, s15
	s_or_b32 s6, s18, 24
	s_mul_hi_u32 s7, s6, 0xb00
	s_mulk_i32 s6, 0xb00
	global_load_lds_dwordx4 v0, s[30:31]
	s_add_i32 m0, s17, 0x800
	s_lshl_b64 s[18:19], s[6:7], 1
	s_add_u32 s36, s22, s18
	global_load_lds_dwordx4 v1, s[34:35]
	s_addc_u32 s37, s23, s19
	s_add_i32 m0, s17, 0xc00
	s_mul_hi_i32 s7, s24, 0x1600
	s_mulk_i32 s24, 0x1600
	s_add_u32 s26, s0, s24
	s_addc_u32 s7, s1, s7
	s_lshl_b32 s24, s46, 4
	s_lshl_b32 s28, s46, 11
	s_sub_i32 s27, s17, s28
	s_mul_hi_u32 s39, s24, 0xb00
	s_mul_i32 s38, s46, 0xb000
	global_load_lds_dwordx4 v0, s[36:37]
	s_add_i32 m0, s27, 0x8000
	s_lshl_b64 s[22:23], s[38:39], 1
	s_add_u32 s40, s26, s22
	s_addc_u32 s41, s7, s23
	s_or_b32 s24, s24, 8
	s_mul_hi_u32 s43, s24, 0xb00
	s_mul_i32 s42, s24, 0xb00
	s_lshl_b64 s[24:25], s[42:43], 1
	s_add_u32 s44, s26, s24
	global_load_lds_dwordx4 v1, s[40:41]
	s_addc_u32 s45, s7, s25
	s_add_i32 m0, s27, 0x8400
	v_mov_b32_e32 v146, v164
	global_load_lds_dwordx4 v0, s[44:45]
	v_mov_b32_e32 v0, v165
	v_mov_b32_e32 v147, 0
	s_mov_b64 s[26:27], 0x80
	v_lshl_add_u64 v[2:3], s[20:21], 0, v[146:147]
	s_add_i32 m0, s17, 0xc000
	v_lshl_add_u64 v[2:3], v[2:3], 0, s[26:27]
	v_mov_b32_e32 v1, v147
	global_load_lds_dwordx4 v[2:3], off
	v_lshl_add_u64 v[2:3], s[30:31], 0, v[0:1]
	v_lshl_add_u64 v[2:3], v[2:3], 0, s[26:27]
	s_add_i32 m0, s17, 0xc400
	s_add_i32 s7, s28, 0
	global_load_lds_dwordx4 v[2:3], off
	v_lshl_add_u64 v[2:3], s[34:35], 0, v[146:147]
	v_lshl_add_u64 v[2:3], v[2:3], 0, s[26:27]
	s_add_i32 m0, s17, 0xc800
	v_cmp_eq_u32_e32 vcc, 0, v171
	global_load_lds_dwordx4 v[2:3], off
	v_lshl_add_u64 v[2:3], s[36:37], 0, v[0:1]
	v_lshl_add_u64 v[2:3], v[2:3], 0, s[26:27]
	s_add_i32 m0, s17, 0xcc00
	v_lshl_add_u64 v[0:1], s[44:45], 0, v[0:1]
	global_load_lds_dwordx4 v[2:3], off
	v_lshl_add_u64 v[2:3], s[40:41], 0, v[146:147]
	s_add_i32 m0, s7, 0x14000
	v_lshl_add_u64 v[2:3], v[2:3], 0, s[26:27]
	global_load_lds_dwordx4 v[2:3], off
	v_lshl_add_u64 v[0:1], v[0:1], 0, s[26:27]
	s_add_i32 m0, s7, 0x14400
	s_cmpk_gt_u32 s10, 0xff
	global_load_lds_dwordx4 v[0:1], off
	s_cselect_b64 s[30:31], -1, 0
	v_add_u32_e32 v0, 12, v181
	s_lshl_b32 s29, s47, 13
	s_lshl_b32 s33, s11, 13
	s_add_i32 s10, s6, 0xffff5000
	s_add_i32 s20, s6, 0xffffa800
	s_lshl_b32 s34, s47, 7
	v_cndmask_b32_e32 v0, v0, v181, vcc
	v_xor_b32_e32 v1, v180, v170
	s_add_u32 s34, s56, s34
	v_lshlrev_b32_e32 v151, 4, v1
	v_bitop3_b32 v1, v180, v170, 4 bitop3:0x36
	s_addc_u32 s35, s57, 0
	v_lshlrev_b32_e32 v146, 1, v0
	v_lshlrev_b32_e32 v152, 4, v1
	v_lshl_add_u64 v[0:1], s[34:35], 0, v[146:147]
	s_mov_b64 s[34:35], 0x8400000
	v_lshl_add_u64 v[148:149], v[0:1], 0, s[34:35]
	s_mul_hi_u32 s34, s46, 0x2c000
	s_mul_i32 s46, s46, 0x2c000
	s_add_u32 s62, s56, s46
	s_addc_u32 s63, s57, s34
	s_lshl_b32 s64, s58, 8
	s_mov_b32 s61, 0
	s_mov_b32 s60, s4
	s_add_u32 s65, s56, s4
	s_addc_u32 s66, s57, s5
	s_lshl_b32 s67, s58, 2
	s_lshl_b64 s[34:35], s[60:61], 1
	s_add_u32 s5, s56, s34
	s_addc_u32 s36, s57, s35
	s_add_u32 s68, s5, 0x4400180
	s_addc_u32 s69, s36, 0
	s_add_i32 s60, s4, 0x4000
	s_lshl_b64 s[36:37], s[60:61], 1
	s_add_u32 s5, s56, s36
	s_addc_u32 s36, s57, s37
	s_add_u32 s70, s5, 0x4403180
	s_addc_u32 s71, s36, 0
	s_add_i32 s60, s4, 0xa000
	s_lshl_b64 s[36:37], s[60:61], 1
	s_add_u32 s5, s56, s36
	s_addc_u32 s36, s57, s37
	s_add_u32 s72, s5, 0x4402180
	s_addc_u32 s73, s36, 0
	s_add_i32 s60, s4, 0x10000
	s_lshl_b64 s[4:5], s[60:61], 1
	s_add_u32 s4, s56, s4
	s_addc_u32 s5, s57, s5
	s_mov_b32 s39, s61
	s_add_u32 s74, s4, 0x4401180
	s_addc_u32 s75, s5, 0
	s_lshl_b64 s[36:37], s[38:39], 1
	s_add_u32 s4, s56, s36
	s_addc_u32 s5, s57, s37
	s_add_u32 s76, s4, 0x2980180
	s_addc_u32 s77, s5, 0
	s_add_i32 s60, s38, 0x5000
	s_lshl_b64 s[4:5], s[60:61], 1
	s_add_u32 s4, s56, s4
	s_addc_u32 s5, s57, s5
	s_mov_b32 s7, s61
	s_mov_b32 s43, s61
	v_lshl_or_b32 v150, s11, 6, v167
	s_mov_b32 s11, s61
	s_mov_b32 s21, s61
	s_mov_b32 s80, s78
	s_add_u32 s78, s4, 0x2981180
	s_addc_u32 s79, s5, 0
	s_mov_b64 s[4:5], -1
	s_mov_b64 s[38:39], 0x100
	s_lshl_b64 s[40:41], s[6:7], 1
	s_lshl_b64 s[42:43], s[42:43], 1
	s_lshl_b64 s[44:45], s[10:11], 1
	s_lshl_b64 s[46:47], s[20:21], 1
	s_branch .LBB0_1464
.LBB0_1463:
	v_add_u32_e32 v146, s81, v150
	v_lshl_add_u64 v[64:65], s[50:51], 1, v[148:149]
	v_lshlrev_b64 v[66:67], 11, v[146:147]
	v_cvt_pk_bf16_f32 v48, v48, v49
	v_cvt_pk_bf16_f32 v49, v50, v51
	v_cvt_pk_bf16_f32 v50, v52, v53
	v_cvt_pk_bf16_f32 v51, v54, v55
	v_lshl_add_u64 v[66:67], v[64:65], 0, v[66:67]
	v_permlane16_swap_b32_e32 v48, v50
	v_permlane16_swap_b32_e32 v49, v51
	global_store_dwordx4 v[66:67], v[48:51], off offset:64 sc1
	v_cvt_pk_bf16_f32 v20, v20, v21
	v_cvt_pk_bf16_f32 v21, v22, v23
	v_or_b32_e32 v48, 16, v146
	v_mov_b32_e32 v49, v147
	v_lshlrev_b64 v[48:49], 11, v[48:49]
	v_cvt_pk_bf16_f32 v22, v28, v29
	v_cvt_pk_bf16_f32 v23, v30, v31
	v_lshl_add_u64 v[48:49], v[64:65], 0, v[48:49]
	v_permlane16_swap_b32_e32 v20, v22
	v_permlane16_swap_b32_e32 v21, v23
	global_store_dwordx4 v[48:49], v[20:23], off offset:64 sc1
	v_cvt_pk_bf16_f32 v16, v16, v17
	v_cvt_pk_bf16_f32 v17, v18, v19
	v_or_b32_e32 v20, 32, v146
	v_mov_b32_e32 v21, v147
	v_lshlrev_b64 v[20:21], 11, v[20:21]
	v_cvt_pk_bf16_f32 v18, v24, v25
	v_cvt_pk_bf16_f32 v19, v26, v27
	v_lshl_add_u64 v[28:29], v[64:65], 0, v[20:21]
	v_permlane16_swap_b32_e32 v16, v18
	v_permlane16_swap_b32_e32 v17, v19
	v_or_b32_e32 v146, 48, v146
	v_cvt_pk_bf16_f32 v56, v56, v57
	v_cvt_pk_bf16_f32 v57, v58, v59
	v_cvt_pk_bf16_f32 v58, v60, v61
	v_cvt_pk_bf16_f32 v59, v62, v63
	v_cvt_pk_bf16_f32 v36, v36, v37
	v_cvt_pk_bf16_f32 v37, v38, v39
	v_cvt_pk_bf16_f32 v38, v44, v45
	v_cvt_pk_bf16_f32 v39, v46, v47
	v_cvt_pk_bf16_f32 v20, v32, v33
	v_cvt_pk_bf16_f32 v21, v34, v35
	v_cvt_pk_bf16_f32 v22, v40, v41
	v_cvt_pk_bf16_f32 v23, v42, v43
	global_store_dwordx4 v[28:29], v[16:19], off offset:64 sc1
	v_cvt_pk_bf16_f32 v4, v4, v5
	v_cvt_pk_bf16_f32 v5, v6, v7
	v_lshlrev_b64 v[16:17], 11, v[146:147]
	v_cvt_pk_bf16_f32 v6, v8, v9
	v_cvt_pk_bf16_f32 v7, v10, v11
	v_cvt_pk_bf16_f32 v0, v0, v1
	v_cvt_pk_bf16_f32 v1, v2, v3
	v_cvt_pk_bf16_f32 v2, v12, v13
	v_cvt_pk_bf16_f32 v3, v14, v15
	v_permlane16_swap_b32_e32 v56, v58
	v_permlane16_swap_b32_e32 v57, v59
	v_permlane16_swap_b32_e32 v36, v38
	v_permlane16_swap_b32_e32 v37, v39
	v_permlane16_swap_b32_e32 v20, v22
	v_permlane16_swap_b32_e32 v21, v23
	v_lshl_add_u64 v[16:17], v[64:65], 0, v[16:17]
	v_permlane16_swap_b32_e32 v4, v6
	v_permlane16_swap_b32_e32 v5, v7
	v_permlane16_swap_b32_e32 v0, v2
	v_permlane16_swap_b32_e32 v1, v3
	s_add_i32 s2, s2, s64
	s_add_i32 s3, s3, s67
	s_andn2_b64 vcc, exec, s[48:49]
	s_mov_b64 s[4:5], 0
	global_store_dwordx4 v[66:67], v[56:59], off sc1
	global_store_dwordx4 v[48:49], v[36:39], off sc1
	global_store_dwordx4 v[28:29], v[20:23], off sc1
	global_store_dwordx4 v[16:17], v[4:7], off sc1
	global_store_dwordx4 v[16:17], v[0:3], off offset:64 sc1
	s_cbranch_vccz .LBB0_1524

.LBB0_1525:
	s_waitcnt vmcnt(0)
	s_waitcnt vmcnt(0) lgkmcnt(0)
	s_barrier
	s_mov_b64 s[4:5], exec
	v_readlane_b32 s0, v219, 25
	v_readlane_b32 s1, v219, 26
	s_and_b64 s[0:1], s[4:5], s[0:1]
	s_mov_b64 exec, s[0:1]
	s_cbranch_execz .LBB0_1577
	v_readlane_b32 s0, v219, 27
	v_readlane_b32 s1, v219, 28
	v_readlane_b32 s2, v219, 29
	v_mov_b32_e32 v0, 0x24000
	s_waitcnt vmcnt(0) lgkmcnt(0)
	buffer_inv sc1
	ds_read_b32 v2, v0
	ds_read_b32 v0, v0 offset:4
	s_lshl_b32 s3, s2, 8
	s_add_i32 s14, s3, 0x2400
	s_add_i32 s3, s3, 0x1400
	v_mov_b32_e32 v1, s3
	s_waitcnt lgkmcnt(0)
	v_readfirstlane_b32 s10, v2
	v_readfirstlane_b32 s11, v0
	v_mov_b32_e32 v0, 1
	s_nop 1
	global_atomic_add v2, v1, v0, s[0:1] sc0
	s_mul_i32 s10, s10, 15
	s_mul_i32 s11, s11, 15
	s_waitcnt vmcnt(0)
	v_readfirstlane_b32 s13, v2
	s_nop 1
	s_add_i32 s13, s13, 1
	s_cmp_lg_u32 s13, s10
	s_cbranch_scc1 .Lnb15_wait
	v_mov_b32_e32 v1, 0x3400
	global_atomic_add v2, v1, v0, s[0:1] sc0
	s_waitcnt vmcnt(0)
	v_readfirstlane_b32 s13, v2
	s_nop 1
	s_add_i32 s13, s13, 1
	s_cmp_lg_u32 s13, s11
	s_cbranch_scc1 .Lnb15_wait
	v_mov_b32_e32 v1, 0x2400
	global_atomic_add v1, v0, s[0:1]
	global_atomic_add v1, v0, s[0:1] offset:256
	global_atomic_add v1, v0, s[0:1] offset:512
	global_atomic_add v1, v0, s[0:1] offset:768
	global_atomic_add v1, v0, s[0:1] offset:1024
	global_atomic_add v1, v0, s[0:1] offset:1280
	global_atomic_add v1, v0, s[0:1] offset:1536
	global_atomic_add v1, v0, s[0:1] offset:1792
	global_atomic_add v1, v0, s[0:1] offset:2048
	global_atomic_add v1, v0, s[0:1] offset:2304
	global_atomic_add v1, v0, s[0:1] offset:2560
	global_atomic_add v1, v0, s[0:1] offset:2816
	global_atomic_add v1, v0, s[0:1] offset:3072
	global_atomic_add v1, v0, s[0:1] offset:3328
	global_atomic_add v1, v0, s[0:1] offset:3584
	global_atomic_add v1, v0, s[0:1] offset:3840
	v_mov_b32_e32 v1, 0x3500
	global_atomic_add v1, v0, s[0:1]

.Lnb15_spin:
	global_load_dword v2, v1, s[0:1] sc1
	s_waitcnt vmcnt(0)
	v_readfirstlane_b32 s13, v2
	s_nop 1
	s_cmp_ge_u32 s13, 15
	s_cbranch_scc1 .Lnb15_done
	s_sleep 1
	s_add_i32 s15, s15, 1
	s_cmp_lt_u32 s15, 0x200000
	s_cbranch_scc1 .Lnb15_spin
.Lnb15_done:
	s_waitcnt vmcnt(0)
.LBB0_1577:
	s_or_b64 exec, exec, s[4:5]
	v_readlane_b32 s2, v219, 31
	v_readlane_b32 s3, v219, 32
	s_waitcnt lgkmcnt(0)
	s_barrier
	s_and_saveexec_b64 s[0:1], s[2:3]
	s_cbranch_execz .LBB0_1582
	v_and_b32_e32 v0, 0x1f8, v144
	v_mov_b32_e32 v33, 0
	v_lshlrev_b32_e32 v32, 1, v0
	v_readlane_b32 s8, v219, 9
	v_lshl_add_u64 v[2:3], s[56:57], 0, v[32:33]
	s_mov_b64 s[0:1], 0xa400000
	v_readlane_b32 s9, v219, 10
	v_readlane_b32 s12, v219, 13
	v_readlane_b32 s13, v219, 14
	v_lshl_add_u64 v[34:35], v[2:3], 0, s[0:1]
	s_mov_b64 s[0:1], 0x8400000
	s_lshl_b32 s4, s58, 3
	s_mov_b64 s[8:9], s[12:13]
	v_lshl_add_u64 v[36:37], v[2:3], 0, s[0:1]
	v_or_b32_e32 v2, 0x200, v0
	s_add_u32 s0, s8, 0x7000
	s_addc_u32 s1, s9, 0
	v_lshlrev_b32_e32 v32, 2, v0
	v_lshlrev_b32_e32 v4, 2, v2
	v_mov_b32_e32 v5, v33
	v_lshl_add_u64 v[38:39], s[0:1], 0, v[32:33]
	v_lshl_add_u64 v[40:41], s[0:1], 0, v[4:5]
	v_lshl_add_u64 v[42:43], s[54:55], 0, v[32:33]
	v_lshl_add_u32 v48, s78, 5, v166
	s_lshl_b32 s5, s58, 5
	s_mov_b64 s[0:1], 0
	v_mov_b32_e32 v49, 0xfffff000
	s_movk_i32 s6, 0x3ff
	s_mov_b64 s[2:3], 0x5000
	v_lshlrev_b32_e32 v32, 2, v0
	v_lshlrev_b32_e32 v44, 2, v2
	v_mov_b32_e32 v45, v33
	v_mov_b32_e32 v50, 0x358637bd
	s_mov_b32 s7, 0x800000
	s_movk_i32 s8, 0x7ff
	v_readlane_b32 s10, v219, 11
	v_readlane_b32 s11, v219, 12
	v_readlane_b32 s14, v219, 15
	v_readlane_b32 s15, v219, 16
	v_readlane_b32 s16, v219, 17
	v_readlane_b32 s17, v219, 18
	v_readlane_b32 s18, v219, 19
	v_readlane_b32 s19, v219, 20
	v_readlane_b32 s20, v219, 21
	v_readlane_b32 s21, v219, 22
	v_readlane_b32 s22, v219, 23
	v_readlane_b32 s23, v219, 24
